# per-half K-loop barriers (waves 0-3 keep the post-MMA barriers and run their MMA segments at priority 0, waves 4-7 keep the post-load barriers), stagger/alignment barriers removed, hand-off trimmed
# baseline (speedup 1.0000x reference)
_Z9trunk_fwd4Args:
	v_readfirstlane_b32 s100, v0
	s_nop 3
	s_lshr_b32 s100, s100, 8
	s_load_dword s33, s[0:1], 0x128
	v_writelane_b32 v254, s2, 0
	s_add_u32 s2, s0, 0x128
	s_addc_u32 s3, s1, 0
	v_writelane_b32 v254, s2, 1
	s_nop 1
	v_writelane_b32 v254, s3, 2
	s_movk_i32 s2, 0x80
	v_cmp_gt_u32_e32 vcc, s2, v0
	s_and_saveexec_b64 s[2:3], vcc
	v_lshl_add_u32 v1, v0, 2, 0
	v_add_u32_e32 v1, 0x23e00, v1
	v_mov_b32_e32 v2, 0
	ds_write_b32 v1, v2
	s_or_b64 exec, exec, s[2:3]
	s_load_dwordx2 s[2:3], s[0:1], 0x118
	s_waitcnt lgkmcnt(0)
	s_barrier
	s_getreg_b32 s4, hwreg(HW_REG_XCC_ID, 0, 4)
	s_add_u32 s10, s2, 0x4000
	s_addc_u32 s11, s3, 0
	s_and_b32 s20, s4, 15
	v_cmp_eq_u32_e32 vcc, 0, v0
	s_and_saveexec_b64 s[4:5], vcc
	s_cbranch_execz .LBB0_5
	s_mov_b64 s[6:7], exec
	v_mbcnt_lo_u32_b32 v1, s6, 0
	v_mbcnt_hi_u32_b32 v1, s7, v1
	v_cmp_eq_u32_e32 vcc, 0, v1
	s_and_b64 s[8:9], exec, vcc
	s_mov_b64 exec, s[8:9]
	s_cbranch_execz .LBB0_5
	s_lshl_b32 s8, s20, 8
	s_bcnt1_i32_b64 s6, s[6:7]
	v_mov_b32_e32 v1, s8
	v_mov_b32_e32 v2, s6
	global_atomic_add v1, v2, s[10:11] offset:1024

.LBB0_539:
	v_readlane_b32 s8, v255, 41
	s_lshl_b32 s8, s8, 22
	s_andn2_b64 vcc, exec, s[24:25]
	s_cbranch_vccnz .LBB0_719
	v_ashrrev_i32_e32 v3, 31, v11
	v_lshrrev_b32_e32 v3, 26, v3
	v_add_u32_e32 v3, v11, v3
	v_ashrrev_i32_e32 v10, 6, v3
	v_bfe_i32 v3, v11, 27, 1
	v_lshlrev_b32_e32 v2, 4, v11
	v_lshrrev_b32_e32 v3, 22, v3
	v_add_u32_e32 v3, v2, v3
	v_and_b32_e32 v3, 0xfffffc00, v3
	v_sub_u32_e32 v3, v2, v3
	v_lshrrev_b32_e32 v4, 4, v3
	v_bitop3_b32 v3, v4, v3, 32 bitop3:0x6c
	v_ashrrev_i32_e32 v5, 31, v3
	v_lshrrev_b32_e32 v5, 26, v5
	v_add_u32_e32 v5, v3, v5
	v_lshlrev_b32_e32 v4, 3, v10
	v_ashrrev_i32_e32 v12, 6, v5
	v_and_b32_e32 v5, 0xc0, v5
	v_and_b32_e32 v4, -16, v4
	v_sub_u32_e32 v3, v3, v5
	v_add_u32_e32 v4, v12, v4
	v_ashrrev_i16_sdwa v3, v224, sext(v3) dst_sel:DWORD dst_unused:UNUSED_PAD src0_sel:DWORD src1_sel:BYTE_0
	v_lshlrev_b32_e32 v6, 5, v10
	v_bfe_i32 v13, v3, 0, 16
	v_lshlrev_b32_e32 v3, 1, v4
	v_lshrrev_b32_e32 v5, 2, v4
	v_and_b32_e32 v7, 3, v12
	s_mov_b32 s9, 0xfffe0
	v_and_b32_e32 v6, 32, v6
	v_and_b32_e32 v3, 24, v3
	v_and_b32_e32 v5, 4, v5
	v_and_or_b32 v7, v4, s9, v7
	v_or3_b32 v3, v7, v5, v3
	v_add_lshl_u32 v5, v6, v13, 1
	v_add_u32_e32 v2, 0x2000, v2
	s_waitcnt vmcnt(0)
	v_lshl_add_u32 v134, v3, 12, v5
	v_ashrrev_i32_e32 v3, 31, v2
	v_lshrrev_b32_e32 v3, 22, v3
	v_add_u32_e32 v3, v2, v3
	v_ashrrev_i32_e32 v14, 10, v3
	v_mul_i32_i24_e32 v3, 0x400, v14
	v_sub_u32_e32 v2, v2, v3
	v_lshrrev_b32_e32 v3, 4, v2
	v_bitop3_b32 v2, v3, v2, 32 bitop3:0x6c
	v_lshl_add_u32 v132, v4, 12, v5
	v_ashrrev_i32_e32 v4, 31, v2
	v_lshrrev_b32_e32 v4, 26, v4
	v_lshlrev_b32_e32 v3, 3, v14
	v_add_u32_e32 v4, v2, v4
	v_and_b32_e32 v3, -16, v3
	v_ashrrev_i32_e32 v15, 6, v4
	v_add_u32_e32 v3, v15, v3
	v_and_b32_e32 v6, 3, v15
	s_ashr_i32 s34, s30, 6
	s_ashr_i32 s31, s30, 8
	v_and_or_b32 v6, v3, s9, v6
	s_lshl_b32 s9, s34, 10
	s_add_u32 s12, s28, 0x1de00000
	v_and_b32_e32 v4, 0xc0, v4
	s_addc_u32 s21, s29, 0
	s_ashr_i32 s43, s42, 31
	s_ashr_i32 s41, s40, 31
	v_sub_u32_e32 v2, v2, v4
	s_lshl_b64 s[26:27], s[42:43], 20
	s_lshl_b64 s[38:39], s[40:41], 20
	v_ashrrev_i16_sdwa v2, v224, sext(v2) dst_sel:DWORD dst_unused:UNUSED_PAD src0_sel:DWORD src1_sel:BYTE_0
	s_add_u32 s54, s18, s38
	v_lshlrev_b32_e32 v5, 5, v14
	v_bfe_i32 v16, v2, 0, 16
	v_lshlrev_b32_e32 v2, 1, v3
	v_lshrrev_b32_e32 v4, 2, v3
	s_addc_u32 s55, s19, s39
	s_add_i32 s58, s9, 0
	v_and_b32_e32 v5, 32, v5
	v_and_b32_e32 v2, 24, v2
	v_and_b32_e32 v4, 4, v4
	s_add_i32 m0, s58, 0x10000
	v_or3_b32 v2, v6, v4, v2
	v_add_lshl_u32 v4, v5, v16, 1
	global_load_lds_dwordx4 v134, s[54:55]
	s_add_i32 m0, s58, 0x12000
	v_lshl_add_u32 v138, v2, 12, v4
	s_add_u32 s38, s54, 0x80000
	global_load_lds_dwordx4 v138, s[54:55]
	s_addc_u32 s39, s55, 0
	s_add_i32 m0, s58, 0x14000
	v_lshl_add_u32 v136, v3, 12, v4
	global_load_lds_dwordx4 v134, s[38:39]
	s_add_i32 m0, s58, 0x16000
	s_add_u32 s44, s12, s26
	s_addc_u32 s45, s21, s27
	s_add_i32 s59, s58, 0x2000
	global_load_lds_dwordx4 v138, s[38:39]
	s_mov_b32 m0, s58
	s_add_u32 s26, s44, 0x80000
	global_load_lds_dwordx4 v132, s[44:45]
	s_mov_b32 m0, s59
	s_addc_u32 s27, s45, 0
	s_add_i32 s60, s58, 0x4000
	global_load_lds_dwordx4 v136, s[44:45]
	s_mov_b32 m0, s60
	s_add_i32 s61, s58, 0x6000
	global_load_lds_dwordx4 v132, s[26:27]
	s_mov_b32 m0, s61
	v_mov_b32_e32 v135, v181
	global_load_lds_dwordx4 v136, s[26:27]
	v_mov_b32_e32 v139, v181
	v_mov_b32_e32 v133, v181
	v_mov_b32_e32 v137, v181
	s_cmp_eq_u32 s31, 1
	v_lshl_add_u64 v[8:9], s[54:55], 0, v[134:135]
	v_lshl_add_u64 v[6:7], s[54:55], 0, v[138:139]
	v_lshl_add_u64 v[2:3], s[44:45], 0, v[132:133]
	s_cselect_b64 s[26:27], -1, 0
	s_cmp_lg_u32 s31, 1
	v_lshl_add_u64 v[4:5], s[44:45], 0, v[136:137]
	s_cbranch_scc1 .LBB0_542
.LBB0_542:
	v_bfe_u32 v158, v11, 4, 2
	v_and_b32_e32 v131, 15, v11
	v_lshlrev_b32_e32 v17, 4, v158
	v_lshlrev_b32_e32 v11, 2, v11
	s_lshl_b32 s62, s31, 6
	v_lshl_or_b32 v17, v131, 6, v17
	s_lshl_b32 s31, s31, 13
	v_and_b32_e32 v11, 32, v11
	v_bitop3_b32 v18, v17, s31, v11 bitop3:0xde
	s_lshl_b32 s31, s34, 5
	s_and_b32 s63, s31, 0x60
	s_lshl_b32 s31, s63, 7
	s_add_u32 s28, s28, 0x37200000
	s_addc_u32 s29, s29, 0
	s_add_i32 m0, s58, 0x18000
	v_lshl_add_u64 v[8:9], v[8:9], 0, s[16:17]
	s_waitcnt vmcnt(2)
	s_barrier
	global_load_lds_dwordx4 v[8:9], off
	v_lshl_add_u64 v[6:7], v[6:7], 0, s[16:17]
	s_add_i32 m0, s58, 0x1a000
	s_add_i32 s64, s58, 0x8000
	s_add_i32 s69, s58, 0xa000
	global_load_lds_dwordx4 v[6:7], off
	v_lshl_add_u64 v[2:3], v[2:3], 0, s[16:17]
	s_mov_b32 m0, s64
	s_add_u32 s34, s54, 0x80080
	global_load_lds_dwordx4 v[2:3], off
	v_lshl_add_u64 v[2:3], v[4:5], 0, s[16:17]
	s_mov_b32 m0, s69
	s_addc_u32 s35, s55, 0
	global_load_lds_dwordx4 v[2:3], off
	s_add_i32 m0, s58, 0x1c000
	v_lshl_add_u64 v[2:3], s[34:35], 0, v[134:135]
	global_load_lds_dwordx4 v[2:3], off
	v_lshl_add_u64 v[2:3], s[34:35], 0, v[138:139]
	s_add_i32 m0, s58, 0x1e000
	s_cmpk_lt_u32 s30, 0x100
	global_load_lds_dwordx4 v[2:3], off
	v_lshlrev_b32_e32 v2, 15, v10
	v_and_b32_e32 v2, 0xffff0000, v2
	v_lshl_add_u32 v2, v12, 12, v2
	v_and_b32_e32 v3, 1, v10
	v_lshl_or_b32 v2, v3, 6, v2
	v_lshl_add_u32 v140, v13, 1, v2
	v_lshlrev_b32_e32 v2, 15, v14
	v_and_b32_e32 v2, 0xffff0000, v2
	s_waitcnt vmcnt(6)
	v_lshl_add_u32 v2, v15, 12, v2
	v_and_b32_e32 v3, 1, v14
	v_lshl_or_b32 v2, v3, 6, v2
	v_bitop3_b32 v159, v17, s31, v11 bitop3:0xde
	s_cselect_b64 s[30:31], -1, 0
	s_ashr_i32 s70, s7, 31
	v_mov_b32_e32 v141, v181
	v_lshl_add_u32 v142, v16, 1, v2
	v_mov_b32_e32 v143, v181
	s_mov_b32 s71, 0
	v_add_u32_e32 v160, 0, v18
	s_barrier
	s_branch .LBB0_545

.LBB0_552:
	s_add_u32 s54, s44, 0xfff80080
	s_addc_u32 s55, s45, -1
	s_waitcnt lgkmcnt(0)
	s_add_i32 s82, 0, 0x10000
	s_cmp_eq_u32 s76, 28
	s_cselect_b32 s57, s41, s55
	s_cselect_b32 s56, s43, s54
	v_add_u32_e32 v161, s82, v159
	s_cselect_b32 s55, s35, s75
	s_cselect_b32 s54, s47, s74
	s_add_i32 vcc_lo, 0, 0x14000
	ds_read_b128 v[144:147], v161
	ds_read_b128 v[148:151], v161 offset:1024
	ds_read_b128 v[152:155], v161 offset:2048
	ds_read_b128 v[162:165], v161 offset:3072
	v_add_u32_e32 v161, vcc_lo, v159
	ds_read_b128 v[166:169], v161
	ds_read_b128 v[170:173], v161 offset:1024
	ds_read_b128 v[174:177], v161 offset:2048
	ds_read_b128 v[190:193], v161 offset:3072
	v_lshl_add_u64 v[178:179], s[44:45], 0, v[140:141]
	s_add_i32 m0, s58, 0xc000
	ds_read_b128 v[194:197], v160
	ds_read_b128 v[198:201], v160 offset:1024
	ds_read_b128 v[202:205], v160 offset:2048
	ds_read_b128 v[206:209], v160 offset:3072
	ds_read_b128 v[210:213], v160 offset:4096
	ds_read_b128 v[214:217], v160 offset:5120
	ds_read_b128 v[218:221], v160 offset:6144
	ds_read_b128 v[238:241], v160 offset:7168
	global_load_lds_dwordx4 v[178:179], off
	v_lshl_add_u64 v[178:179], s[44:45], 0, v[142:143]
	s_add_i32 m0, s58, 0xe000
	s_nop 0
	global_load_lds_dwordx4 v[178:179], off
	s_waitcnt vmcnt(8)
	s_waitcnt lgkmcnt(0)
	s_cmp_eq_u32 s100, 0
	s_cbranch_scc1 .Lmy_h2_1
	s_setprio 1
	s_barrier
.Lmy_h2_1:
	v_mfma_f32_16x16x32_bf16 v[126:129], v[144:147], v[194:197], v[126:129]
	v_mfma_f32_16x16x32_bf16 v[122:125], v[152:155], v[194:197], v[122:125]
	v_mfma_f32_16x16x32_bf16 v[110:113], v[144:147], v[202:205], v[110:113]
	v_mfma_f32_16x16x32_bf16 v[106:109], v[152:155], v[202:205], v[106:109]
	v_mfma_f32_16x16x32_bf16 v[94:97], v[144:147], v[210:213], v[94:97]
	v_mfma_f32_16x16x32_bf16 v[90:93], v[152:155], v[210:213], v[90:93]
	v_mfma_f32_16x16x32_bf16 v[78:81], v[144:147], v[218:221], v[78:81]
	v_mfma_f32_16x16x32_bf16 v[74:77], v[152:155], v[218:221], v[74:77]
	v_mfma_f32_16x16x32_bf16 v[126:129], v[148:151], v[198:201], v[126:129]
	v_mfma_f32_16x16x32_bf16 v[122:125], v[162:165], v[198:201], v[122:125]
	v_mfma_f32_16x16x32_bf16 v[110:113], v[148:151], v[206:209], v[110:113]
	v_mfma_f32_16x16x32_bf16 v[106:109], v[162:165], v[206:209], v[106:109]
	v_mfma_f32_16x16x32_bf16 v[94:97], v[148:151], v[214:217], v[94:97]
	v_mfma_f32_16x16x32_bf16 v[90:93], v[162:165], v[214:217], v[90:93]
	v_mfma_f32_16x16x32_bf16 v[78:81], v[148:151], v[238:241], v[78:81]
	v_mfma_f32_16x16x32_bf16 v[74:77], v[162:165], v[238:241], v[74:77]
	v_mfma_f32_16x16x32_bf16 v[118:121], v[166:169], v[194:197], v[118:121]
	v_mfma_f32_16x16x32_bf16 v[114:117], v[174:177], v[194:197], v[114:117]
	v_mfma_f32_16x16x32_bf16 v[102:105], v[166:169], v[202:205], v[102:105]
	v_mfma_f32_16x16x32_bf16 v[98:101], v[174:177], v[202:205], v[98:101]
	v_mfma_f32_16x16x32_bf16 v[86:89], v[166:169], v[210:213], v[86:89]
	v_mfma_f32_16x16x32_bf16 v[82:85], v[174:177], v[210:213], v[82:85]
	v_mfma_f32_16x16x32_bf16 v[70:73], v[166:169], v[218:221], v[70:73]
	v_mfma_f32_16x16x32_bf16 v[66:69], v[174:177], v[218:221], v[66:69]
	v_mfma_f32_16x16x32_bf16 v[118:121], v[170:173], v[198:201], v[118:121]
	v_mfma_f32_16x16x32_bf16 v[114:117], v[190:193], v[198:201], v[114:117]
	v_mfma_f32_16x16x32_bf16 v[102:105], v[170:173], v[206:209], v[102:105]
	v_mfma_f32_16x16x32_bf16 v[98:101], v[190:193], v[206:209], v[98:101]
	v_mfma_f32_16x16x32_bf16 v[86:89], v[170:173], v[214:217], v[86:89]
	v_mfma_f32_16x16x32_bf16 v[82:85], v[190:193], v[214:217], v[82:85]
	v_mfma_f32_16x16x32_bf16 v[70:73], v[170:173], v[238:241], v[70:73]
	v_mfma_f32_16x16x32_bf16 v[66:69], v[190:193], v[238:241], v[66:69]
	s_cmp_lg_u32 s100, 0
	s_cbranch_scc1 .Lmy_h2_2
	s_barrier
.Lmy_h2_2:
	s_setprio 0
	s_add_i32 s82, s82, s9
	v_lshl_add_u64 v[178:179], s[54:55], 0, v[134:135]
	s_mov_b32 m0, s82
	ds_read_b128 v[194:197], v160 offset:16384
	ds_read_b128 v[198:201], v160 offset:17408
	ds_read_b128 v[202:205], v160 offset:18432
	ds_read_b128 v[206:209], v160 offset:19456
	ds_read_b128 v[210:213], v160 offset:20480
	ds_read_b128 v[214:217], v160 offset:21504
	ds_read_b128 v[218:221], v160 offset:22528
	ds_read_b128 v[238:241], v160 offset:23552
	global_load_lds_dwordx4 v[178:179], off
	s_add_i32 m0, s82, 0x2000
	s_add_u32 s82, s54, 0x80000
	v_lshl_add_u64 v[222:223], s[54:55], 0, v[138:139]
	s_addc_u32 s83, s55, 0
	s_add_i32 vcc_lo, vcc_lo, s9
	global_load_lds_dwordx4 v[222:223], off
	v_lshl_add_u64 v[242:243], s[82:83], 0, v[134:135]
	s_mov_b32 m0, vcc_lo
	v_lshl_add_u64 v[244:245], s[56:57], 0, v[136:137]
	global_load_lds_dwordx4 v[242:243], off
	v_lshl_add_u64 v[242:243], s[82:83], 0, v[138:139]
	s_add_i32 m0, vcc_lo, 0x2000
	s_nop 0
	global_load_lds_dwordx4 v[242:243], off
	v_lshl_add_u64 v[242:243], s[56:57], 0, v[132:133]
	s_mov_b32 m0, s58
	s_nop 0
	global_load_lds_dwordx4 v[242:243], off
	s_mov_b32 m0, s59
	s_nop 0
	global_load_lds_dwordx4 v[244:245], off
	s_waitcnt vmcnt(8)
	s_waitcnt lgkmcnt(0)
	s_cmp_eq_u32 s100, 0
	s_cbranch_scc1 .Lmy_h2_3
	s_setprio 1
	s_barrier
.Lmy_h2_3:
	v_mfma_f32_16x16x32_bf16 v[62:65], v[144:147], v[194:197], v[62:65]
	v_mfma_f32_16x16x32_bf16 v[58:61], v[152:155], v[194:197], v[58:61]
	v_mfma_f32_16x16x32_bf16 v[46:49], v[144:147], v[202:205], v[46:49]
	v_mfma_f32_16x16x32_bf16 v[42:45], v[152:155], v[202:205], v[42:45]
	v_mfma_f32_16x16x32_bf16 v[30:33], v[144:147], v[210:213], v[30:33]
	v_mfma_f32_16x16x32_bf16 v[26:29], v[152:155], v[210:213], v[26:29]
	v_mfma_f32_16x16x32_bf16 v[14:17], v[144:147], v[218:221], v[14:17]
	v_mfma_f32_16x16x32_bf16 v[10:13], v[152:155], v[218:221], v[10:13]
	v_mfma_f32_16x16x32_bf16 v[62:65], v[148:151], v[198:201], v[62:65]
	v_mfma_f32_16x16x32_bf16 v[58:61], v[162:165], v[198:201], v[58:61]
	v_mfma_f32_16x16x32_bf16 v[46:49], v[148:151], v[206:209], v[46:49]
	v_mfma_f32_16x16x32_bf16 v[42:45], v[162:165], v[206:209], v[42:45]
	v_mfma_f32_16x16x32_bf16 v[30:33], v[148:151], v[214:217], v[30:33]
	v_mfma_f32_16x16x32_bf16 v[26:29], v[162:165], v[214:217], v[26:29]
	v_mfma_f32_16x16x32_bf16 v[14:17], v[148:151], v[238:241], v[14:17]
	v_mfma_f32_16x16x32_bf16 v[10:13], v[162:165], v[238:241], v[10:13]
	v_mfma_f32_16x16x32_bf16 v[54:57], v[166:169], v[194:197], v[54:57]
	v_mfma_f32_16x16x32_bf16 v[50:53], v[174:177], v[194:197], v[50:53]
	v_mfma_f32_16x16x32_bf16 v[38:41], v[166:169], v[202:205], v[38:41]
	v_mfma_f32_16x16x32_bf16 v[34:37], v[174:177], v[202:205], v[34:37]
	v_mfma_f32_16x16x32_bf16 v[22:25], v[166:169], v[210:213], v[22:25]
	v_mfma_f32_16x16x32_bf16 v[18:21], v[174:177], v[210:213], v[18:21]
	v_mfma_f32_16x16x32_bf16 v[6:9], v[166:169], v[218:221], v[6:9]
	v_mfma_f32_16x16x32_bf16 v[2:5], v[174:177], v[218:221], v[2:5]
	v_mfma_f32_16x16x32_bf16 v[54:57], v[170:173], v[198:201], v[54:57]
	v_mfma_f32_16x16x32_bf16 v[50:53], v[190:193], v[198:201], v[50:53]
	v_mfma_f32_16x16x32_bf16 v[38:41], v[170:173], v[206:209], v[38:41]
	v_mfma_f32_16x16x32_bf16 v[34:37], v[190:193], v[206:209], v[34:37]
	v_mfma_f32_16x16x32_bf16 v[22:25], v[170:173], v[214:217], v[22:25]
	v_mfma_f32_16x16x32_bf16 v[18:21], v[190:193], v[214:217], v[18:21]
	v_mfma_f32_16x16x32_bf16 v[6:9], v[170:173], v[238:241], v[6:9]
	v_mfma_f32_16x16x32_bf16 v[2:5], v[190:193], v[238:241], v[2:5]
	s_cmp_lg_u32 s100, 0
	s_cbranch_scc1 .Lmy_h2_4
	s_barrier
.Lmy_h2_4:
	s_setprio 0
	s_add_i32 s82, 0, 0x18000
	v_add_u32_e32 v161, s82, v159
	s_add_i32 s83, 0, 0x1c000
	ds_read_b128 v[144:147], v161
	ds_read_b128 v[148:151], v161 offset:1024
	ds_read_b128 v[152:155], v161 offset:2048
	ds_read_b128 v[162:165], v161 offset:3072
	v_add_u32_e32 v161, s83, v159
	ds_read_b128 v[166:169], v161
	ds_read_b128 v[170:173], v161 offset:1024
	ds_read_b128 v[174:177], v161 offset:2048
	ds_read_b128 v[190:193], v161 offset:3072
	s_add_u32 s56, s56, 0x80000
	s_addc_u32 s57, s57, 0
	s_mov_b32 m0, s60
	v_lshl_add_u64 v[246:247], s[56:57], 0, v[132:133]
	ds_read_b128 v[194:197], v160 offset:32768
	ds_read_b128 v[198:201], v160 offset:33792
	ds_read_b128 v[202:205], v160 offset:34816
	ds_read_b128 v[206:209], v160 offset:35840
	ds_read_b128 v[210:213], v160 offset:36864
	ds_read_b128 v[214:217], v160 offset:37888
	ds_read_b128 v[218:221], v160 offset:38912
	ds_read_b128 v[238:241], v160 offset:39936
	global_load_lds_dwordx4 v[246:247], off
	v_lshl_add_u64 v[246:247], s[56:57], 0, v[136:137]
	s_mov_b32 m0, s61
	s_nop 0
	global_load_lds_dwordx4 v[246:247], off
	s_waitcnt vmcnt(8)
	s_waitcnt lgkmcnt(0)
	s_cmp_eq_u32 s100, 0
	s_cbranch_scc1 .Lmy_h2_5
	s_setprio 1
	s_barrier

.Lmy_h2_6:
	s_setprio 0
	s_add_i32 s56, s82, s9
	v_lshl_add_u64 v[178:179], v[178:179], 0, s[16:17]
	s_mov_b32 m0, s56
	ds_read_b128 v[194:197], v160 offset:49152
	ds_read_b128 v[198:201], v160 offset:50176
	ds_read_b128 v[202:205], v160 offset:51200
	ds_read_b128 v[206:209], v160 offset:52224
	ds_read_b128 v[210:213], v160 offset:53248
	ds_read_b128 v[214:217], v160 offset:54272
	ds_read_b128 v[218:221], v160 offset:55296
	ds_read_b128 v[238:241], v160 offset:56320
	global_load_lds_dwordx4 v[178:179], off
	s_add_i32 m0, s56, 0x2000
	s_add_u32 s54, s54, 0x80080
	v_lshl_add_u64 v[178:179], v[222:223], 0, s[16:17]
	s_addc_u32 s55, s55, 0
	s_add_i32 s56, s83, s9
	global_load_lds_dwordx4 v[178:179], off
	v_lshl_add_u64 v[178:179], s[54:55], 0, v[134:135]
	s_mov_b32 m0, s56
	s_nop 0
	global_load_lds_dwordx4 v[178:179], off
	v_lshl_add_u64 v[178:179], s[54:55], 0, v[138:139]
	s_add_i32 m0, s56, 0x2000
	s_nop 0
	global_load_lds_dwordx4 v[178:179], off
	v_lshl_add_u64 v[178:179], v[242:243], 0, s[16:17]
	s_mov_b32 m0, s64
	s_nop 0
	global_load_lds_dwordx4 v[178:179], off
	v_lshl_add_u64 v[178:179], v[244:245], 0, s[16:17]
	s_mov_b32 m0, s69
	s_nop 0
	global_load_lds_dwordx4 v[178:179], off
	s_waitcnt vmcnt(8)
	s_waitcnt lgkmcnt(0)
	s_cmp_eq_u32 s100, 0
	s_cbranch_scc1 .Lmy_h2_7
	s_setprio 1
	s_barrier

.Lmy_h2_8:
	s_setprio 0
	s_add_i32 s76, s76, 2
	s_add_u32 s44, s44, 0x100
	s_addc_u32 s45, s45, 0
	s_add_u32 s74, s74, 0x100
	s_addc_u32 s75, s75, 0
	s_cmp_gt_u32 s76, 29
	s_cbranch_scc0 .LBB0_552
	s_and_b64 vcc, exec, s[30:31]
	s_cbranch_vccz .LBB0_555

.LBB0_715:
	s_andn2_b64 vcc, exec, s[38:39]
	s_mov_b64 s[38:39], -1
	s_cbranch_vccnz .LBB0_544
	s_andn2_b64 vcc, exec, s[26:27]
	s_cbranch_vccnz .LBB0_543
	s_branch .LBB0_543

.LBB0_812:
	s_add_u32 s14, s0, s54
	s_movk_i32 s24, 0x180
	s_addc_u32 s15, s1, 0
	s_load_dwordx2 s[22:23], s[14:15], 0x118
	v_mov_b32_e32 v14, v0
	s_andn2_b64 vcc, exec, s[10:11]
	v_readfirstlane_b32 s26, v14
	s_cbranch_vccnz .LBB0_832
	v_lshlrev_b32_e32 v2, 4, v14
	v_add_u32_e32 v3, 0x2000, v2
	v_ashrrev_i32_e32 v4, 31, v3
	v_lshrrev_b32_e32 v4, 22, v4
	v_add_u32_e32 v4, v3, v4
	v_ashrrev_i32_e32 v4, 10, v4
	v_mul_i32_i24_e32 v5, 0x400, v4
	v_sub_u32_e32 v3, v3, v5
	v_lshrrev_b32_e32 v5, 4, v3
	v_bitop3_b32 v3, v5, v3, 32 bitop3:0x6c
	v_ashrrev_i32_e32 v5, 31, v3
	v_lshrrev_b32_e32 v5, 26, v5
	v_add_u32_e32 v5, v3, v5
	v_lshlrev_b32_e32 v7, 3, v4
	v_ashrrev_i32_e32 v6, 6, v5
	v_and_b32_e32 v7, -16, v7
	v_lshlrev_b32_e32 v4, 5, v4
	v_add_u32_e32 v7, v6, v7
	v_and_b32_e32 v15, 32, v4
	v_and_b32_e32 v4, 0xc0, v5
	v_and_b32_e32 v6, 3, v6
	s_mov_b32 s18, 0x7fffffe0
	v_lshrrev_b32_e32 v8, 2, v7
	v_lshlrev_b32_e32 v9, 1, v7
	v_sub_u32_e32 v3, v3, v4
	v_and_or_b32 v6, v7, s18, v6
	v_and_b32_e32 v8, 4, v8
	v_and_b32_e32 v9, 24, v9
	v_ashrrev_i16_sdwa v3, v224, sext(v3) dst_sel:DWORD dst_unused:UNUSED_PAD src0_sel:DWORD src1_sel:BYTE_0
	v_or3_b32 v6, v6, v8, v9
	v_bfe_i32 v16, v3, 0, 16
	v_mul_lo_u32 v6, v6, s24
	v_add_u32_e32 v3, v15, v16
	v_mul_lo_u32 v17, v7, s24
	s_waitcnt vmcnt(0)
	v_add_lshl_u32 v132, v6, v3, 1
	v_add_lshl_u32 v134, v3, v17, 1
	v_bfe_i32 v3, v14, 27, 1
	v_lshrrev_b32_e32 v3, 22, v3
	v_add_u32_e32 v3, v2, v3
	v_and_b32_e32 v3, 0xfffffc00, v3
	v_sub_u32_e32 v2, v2, v3
	v_lshrrev_b32_e32 v3, 4, v2
	v_ashrrev_i32_e32 v5, 31, v14
	s_waitcnt lgkmcnt(0)
	s_add_u32 s9, s22, 0x37200000
	v_bitop3_b32 v2, v3, v2, 32 bitop3:0x6c
	v_lshrrev_b32_e32 v5, 26, v5
	s_mul_i32 s11, s12, 0x30000
	s_addc_u32 s21, s23, 0
	v_ashrrev_i32_e32 v3, 31, v2
	v_add_u32_e32 v5, v14, v5
	s_mul_hi_u32 s10, s12, 0x30000
	s_add_u32 s11, s22, s11
	v_lshrrev_b32_e32 v3, 26, v3
	v_ashrrev_i32_e32 v5, 6, v5
	s_addc_u32 s10, s23, s10
	v_add_u32_e32 v3, v2, v3
	v_lshlrev_b32_e32 v6, 3, v5
	s_add_u32 s42, s11, 0x16900000
	v_ashrrev_i32_e32 v4, 6, v3
	v_and_b32_e32 v6, -16, v6
	s_addc_u32 s43, s10, 0
	s_ashr_i32 s25, s24, 31
	v_add_u32_e32 v6, v4, v6
	v_and_b32_e32 v4, 3, v4
	s_lshl_b64 s[14:15], s[24:25], 9
	v_and_or_b32 v4, v6, s18, v4
	s_ashr_i32 s18, s6, 31
	s_mul_i32 s18, s14, s18
	s_mul_hi_u32 s19, s14, s6
	s_add_i32 s29, s19, s18
	s_lshr_b64 s[18:19], s[24:25], 23
	s_mul_i32 s19, s18, s6
	s_add_i32 s29, s29, s19
	s_ashr_i32 s19, s8, 31
	v_and_b32_e32 v3, 0xc0, v3
	s_mul_i32 s19, s14, s19
	s_mul_hi_u32 s31, s14, s8
	s_ashr_i32 s27, s26, 6
	v_lshrrev_b32_e32 v7, 2, v6
	v_lshlrev_b32_e32 v8, 1, v6
	v_sub_u32_e32 v2, v2, v3
	s_add_i32 s19, s31, s19
	s_mul_i32 s18, s18, s8
	s_ashr_i32 s28, s26, 8
	s_lshl_b64 s[10:11], s[24:25], 8
	s_lshl_b32 s44, s27, 10
	v_and_b32_e32 v7, 4, v7
	v_and_b32_e32 v8, 24, v8
	v_lshlrev_b32_e32 v5, 5, v5
	v_ashrrev_i16_sdwa v2, v224, sext(v2) dst_sel:DWORD dst_unused:UNUSED_PAD src0_sel:DWORD src1_sel:BYTE_0
	s_add_i32 s19, s19, s18
	s_mul_i32 s18, s14, s8
	v_or3_b32 v4, v4, v7, v8
	v_and_b32_e32 v18, 32, v5
	v_bfe_i32 v19, v2, 0, 16
	s_add_u32 s40, s42, s18
	v_mul_lo_u32 v4, v4, s24
	v_add_u32_e32 v2, v18, v19
	s_addc_u32 s41, s43, s19
	s_add_i32 s45, s44, 0
	v_add_lshl_u32 v136, v4, v2, 1
	s_add_i32 m0, s45, 0x10000
	s_mul_i32 s30, s14, s6
	global_load_lds_dwordx4 v136, s[40:41]
	s_add_i32 m0, s45, 0x12000
	s_add_u32 s18, s40, s10
	global_load_lds_dwordx4 v132, s[40:41]
	s_addc_u32 s19, s41, s11
	s_add_i32 m0, s45, 0x14000
	v_mul_lo_u32 v20, v6, s24
	global_load_lds_dwordx4 v136, s[18:19]
	s_add_i32 m0, s45, 0x16000
	s_add_u32 s34, s9, s30
	v_mov_b32_e32 v137, v181
	v_mov_b32_e32 v133, v181
	s_addc_u32 s35, s21, s29
	s_add_i32 s46, s45, 0x2000
	v_add_lshl_u32 v138, v2, v20, 1
	v_lshl_add_u64 v[6:7], s[18:19], 0, v[136:137]
	v_lshl_add_u64 v[8:9], s[18:19], 0, v[132:133]
	global_load_lds_dwordx4 v132, s[18:19]
	s_mov_b32 m0, s45
	s_add_u32 s18, s34, s10
	global_load_lds_dwordx4 v138, s[34:35]
	s_mov_b32 m0, s46
	s_addc_u32 s19, s35, s11
	s_add_i32 s47, s45, 0x4000
	global_load_lds_dwordx4 v134, s[34:35]
	s_mov_b32 m0, s47
	s_add_i32 s48, s45, 0x6000
	global_load_lds_dwordx4 v138, s[18:19]
	s_mov_b32 m0, s48
	v_mov_b32_e32 v139, v181
	global_load_lds_dwordx4 v134, s[18:19]
	v_mov_b32_e32 v135, v181
	s_cmp_eq_u32 s28, 1
	v_lshl_add_u64 v[2:3], s[40:41], 0, v[136:137]
	v_lshl_add_u64 v[4:5], s[40:41], 0, v[132:133]
	v_lshl_add_u64 v[10:11], s[34:35], 0, v[138:139]
	v_lshl_add_u64 v[12:13], s[34:35], 0, v[134:135]
	s_cselect_b64 s[18:19], -1, 0
	s_cmp_lg_u32 s28, 1
	s_cbranch_scc1 .LBB0_815
.LBB0_815:
	s_add_u32 s22, s22, 0x39600000
	s_addc_u32 s23, s23, 0
	s_add_i32 m0, s45, 0x18000
	v_lshl_add_u64 v[2:3], v[2:3], 0, s[16:17]
	s_waitcnt vmcnt(2)
	s_barrier
	global_load_lds_dwordx4 v[2:3], off
	v_lshl_add_u64 v[2:3], v[4:5], 0, s[16:17]
	s_add_i32 m0, s45, 0x1a000
	s_add_i32 s49, s45, 0x8000
	global_load_lds_dwordx4 v[2:3], off
	v_lshl_add_u64 v[2:3], v[10:11], 0, s[16:17]
	s_mov_b32 m0, s49
	s_add_i32 s50, s45, 0xa000
	global_load_lds_dwordx4 v[2:3], off
	v_lshl_add_u64 v[2:3], v[12:13], 0, s[16:17]
	s_mov_b32 m0, s50
	v_bfe_u32 v144, v14, 4, 2
	global_load_lds_dwordx4 v[2:3], off
	s_add_i32 m0, s45, 0x1c000
	v_lshl_add_u64 v[2:3], v[6:7], 0, s[16:17]
	global_load_lds_dwordx4 v[2:3], off
	v_lshl_add_u64 v[2:3], v[8:9], 0, s[16:17]
	s_add_i32 m0, s45, 0x1e000
	s_lshr_b32 s25, s25, 26
	global_load_lds_dwordx4 v[2:3], off
	v_and_b32_e32 v145, 15, v14
	s_add_i32 s25, s24, s25
	v_lshlrev_b32_e32 v2, 4, v144
	v_lshlrev_b32_e32 v3, 2, v14
	s_ashr_i32 s51, s25, 6
	v_lshl_or_b32 v2, v145, 6, v2
	s_lshl_b32 s25, s28, 13
	v_and_b32_e32 v3, 32, v3
	v_bitop3_b32 v4, v2, s25, v3 bitop3:0xde
	s_lshl_b32 s25, s27, 5
	s_and_b32 s56, s25, 0x60
	s_lshl_b32 s55, s28, 6
	s_lshl_b32 s25, s56, 7
	v_bitop3_b32 v146, v2, s25, v3 bitop3:0xde
	s_cmp_gt_i32 s24, 63
	v_add_u32_e32 v2, v20, v18
	s_waitcnt vmcnt(6)
	s_cselect_b64 s[24:25], -1, 0
	s_add_i32 s57, s51, -2
	v_add_lshl_u32 v180, v2, v19, 1
	v_add_u32_e32 v2, v17, v15
	s_cmpk_lt_u32 s26, 0x100
	v_lshl_add_u64 v[140:141], s[10:11], 0, v[180:181]
	v_add_lshl_u32 v180, v2, v16, 1
	s_cselect_b64 s[26:27], -1, 0
	v_lshl_add_u64 v[142:143], s[10:11], 0, v[180:181]
	s_mov_b32 s58, 0
	v_add_u32_e32 v147, 0, v4
	s_mov_b32 s61, s6
	s_mov_b64 s[28:29], s[34:35]
	s_barrier
	s_branch .LBB0_818

.LBB0_824:
	s_add_i32 s64, s40, 2
	s_add_u32 s69, s34, 0x80
	s_addc_u32 s41, s35, 0
	s_add_i32 s74, 0, 0x10000
	s_cmp_eq_u32 s57, s40
	s_cselect_b32 s41, s29, s41
	s_cselect_b32 s40, s28, s69
	v_add_u32_e32 v148, s74, v146
	s_cselect_b32 s71, s31, s63
	s_cselect_b32 s70, s30, s62
	s_add_i32 s69, 0, 0x14000
	ds_read_b128 v[154:157], v148
	ds_read_b128 v[158:161], v148 offset:1024
	ds_read_b128 v[162:165], v148 offset:2048
	ds_read_b128 v[166:169], v148 offset:3072
	v_add_u32_e32 v148, s69, v146
	ds_read_b128 v[170:173], v148
	ds_read_b128 v[174:177], v148 offset:1024
	ds_read_b128 v[190:193], v148 offset:2048
	ds_read_b128 v[194:197], v148 offset:3072
	v_lshl_add_u64 v[148:149], s[34:35], 0, v[140:141]
	s_add_i32 m0, s45, 0xc000
	ds_read_b128 v[198:201], v147
	ds_read_b128 v[202:205], v147 offset:1024
	ds_read_b128 v[206:209], v147 offset:2048
	ds_read_b128 v[210:213], v147 offset:3072
	ds_read_b128 v[214:217], v147 offset:4096
	ds_read_b128 v[218:221], v147 offset:5120
	ds_read_b128 v[238:241], v147 offset:6144
	ds_read_b128 v[242:245], v147 offset:7168
	global_load_lds_dwordx4 v[148:149], off
	v_lshl_add_u64 v[148:149], s[34:35], 0, v[142:143]
	s_add_i32 m0, s45, 0xe000
	s_nop 0
	global_load_lds_dwordx4 v[148:149], off
	s_waitcnt vmcnt(8)
	s_waitcnt lgkmcnt(0)
	s_cmp_eq_u32 s100, 0
	s_cbranch_scc1 .Lmy_h2_9
	s_setprio 1
	s_barrier
.Lmy_h2_9:
	v_mfma_f32_16x16x32_bf16 v[126:129], v[154:157], v[198:201], v[126:129]
	v_mfma_f32_16x16x32_bf16 v[122:125], v[162:165], v[198:201], v[122:125]
	v_mfma_f32_16x16x32_bf16 v[110:113], v[154:157], v[206:209], v[110:113]
	v_mfma_f32_16x16x32_bf16 v[106:109], v[162:165], v[206:209], v[106:109]
	v_mfma_f32_16x16x32_bf16 v[94:97], v[154:157], v[214:217], v[94:97]
	v_mfma_f32_16x16x32_bf16 v[90:93], v[162:165], v[214:217], v[90:93]
	v_mfma_f32_16x16x32_bf16 v[78:81], v[154:157], v[238:241], v[78:81]
	v_mfma_f32_16x16x32_bf16 v[74:77], v[162:165], v[238:241], v[74:77]
	v_mfma_f32_16x16x32_bf16 v[126:129], v[158:161], v[202:205], v[126:129]
	v_mfma_f32_16x16x32_bf16 v[122:125], v[166:169], v[202:205], v[122:125]
	v_mfma_f32_16x16x32_bf16 v[110:113], v[158:161], v[210:213], v[110:113]
	v_mfma_f32_16x16x32_bf16 v[106:109], v[166:169], v[210:213], v[106:109]
	v_mfma_f32_16x16x32_bf16 v[94:97], v[158:161], v[218:221], v[94:97]
	v_mfma_f32_16x16x32_bf16 v[90:93], v[166:169], v[218:221], v[90:93]
	v_mfma_f32_16x16x32_bf16 v[78:81], v[158:161], v[242:245], v[78:81]
	v_mfma_f32_16x16x32_bf16 v[74:77], v[166:169], v[242:245], v[74:77]
	v_mfma_f32_16x16x32_bf16 v[118:121], v[170:173], v[198:201], v[118:121]
	v_mfma_f32_16x16x32_bf16 v[114:117], v[190:193], v[198:201], v[114:117]
	v_mfma_f32_16x16x32_bf16 v[102:105], v[170:173], v[206:209], v[102:105]
	v_mfma_f32_16x16x32_bf16 v[98:101], v[190:193], v[206:209], v[98:101]
	v_mfma_f32_16x16x32_bf16 v[86:89], v[170:173], v[214:217], v[86:89]
	v_mfma_f32_16x16x32_bf16 v[82:85], v[190:193], v[214:217], v[82:85]
	v_mfma_f32_16x16x32_bf16 v[70:73], v[170:173], v[238:241], v[70:73]
	v_mfma_f32_16x16x32_bf16 v[66:69], v[190:193], v[238:241], v[66:69]
	v_mfma_f32_16x16x32_bf16 v[118:121], v[174:177], v[202:205], v[118:121]
	v_mfma_f32_16x16x32_bf16 v[114:117], v[194:197], v[202:205], v[114:117]
	v_mfma_f32_16x16x32_bf16 v[102:105], v[174:177], v[210:213], v[102:105]
	v_mfma_f32_16x16x32_bf16 v[98:101], v[194:197], v[210:213], v[98:101]
	v_mfma_f32_16x16x32_bf16 v[86:89], v[174:177], v[218:221], v[86:89]
	v_mfma_f32_16x16x32_bf16 v[82:85], v[194:197], v[218:221], v[82:85]
	v_mfma_f32_16x16x32_bf16 v[70:73], v[174:177], v[242:245], v[70:73]
	v_mfma_f32_16x16x32_bf16 v[66:69], v[194:197], v[242:245], v[66:69]
	s_cmp_lg_u32 s100, 0
	s_cbranch_scc1 .Lmy_h2_10
	s_barrier
.Lmy_h2_10:
	s_setprio 0
	s_add_i32 s74, s74, s44
	v_lshl_add_u64 v[148:149], s[70:71], 0, v[136:137]
	s_mov_b32 m0, s74
	ds_read_b128 v[198:201], v147 offset:16384
	ds_read_b128 v[202:205], v147 offset:17408
	ds_read_b128 v[206:209], v147 offset:18432
	ds_read_b128 v[210:213], v147 offset:19456
	ds_read_b128 v[214:217], v147 offset:20480
	ds_read_b128 v[218:221], v147 offset:21504
	ds_read_b128 v[238:241], v147 offset:22528
	ds_read_b128 v[242:245], v147 offset:23552
	global_load_lds_dwordx4 v[148:149], off
	s_add_i32 m0, s74, 0x2000
	v_lshl_add_u64 v[178:179], s[70:71], 0, v[132:133]
	s_add_u32 s70, s70, s10
	s_addc_u32 s71, s71, s11
	s_add_i32 s69, s69, s44
	global_load_lds_dwordx4 v[178:179], off
	v_lshl_add_u64 v[222:223], s[70:71], 0, v[136:137]
	s_mov_b32 m0, s69
	v_lshl_add_u64 v[246:247], s[70:71], 0, v[132:133]
	global_load_lds_dwordx4 v[222:223], off
	s_add_i32 m0, s69, 0x2000
	v_lshl_add_u64 v[248:249], s[40:41], 0, v[138:139]
	global_load_lds_dwordx4 v[246:247], off
	s_mov_b32 m0, s45
	v_lshl_add_u64 v[250:251], s[40:41], 0, v[134:135]
	global_load_lds_dwordx4 v[248:249], off
	s_mov_b32 m0, s46
	s_nop 0
	global_load_lds_dwordx4 v[250:251], off
	s_waitcnt vmcnt(8)
	s_waitcnt lgkmcnt(0)
	s_cmp_eq_u32 s100, 0
	s_cbranch_scc1 .Lmy_h2_11
	s_setprio 1
	s_barrier
.Lmy_h2_11:
	v_mfma_f32_16x16x32_bf16 v[62:65], v[154:157], v[198:201], v[62:65]
	v_mfma_f32_16x16x32_bf16 v[58:61], v[162:165], v[198:201], v[58:61]
	v_mfma_f32_16x16x32_bf16 v[46:49], v[154:157], v[206:209], v[46:49]
	v_mfma_f32_16x16x32_bf16 v[42:45], v[162:165], v[206:209], v[42:45]
	v_mfma_f32_16x16x32_bf16 v[30:33], v[154:157], v[214:217], v[30:33]
	v_mfma_f32_16x16x32_bf16 v[26:29], v[162:165], v[214:217], v[26:29]
	v_mfma_f32_16x16x32_bf16 v[14:17], v[154:157], v[238:241], v[14:17]
	v_mfma_f32_16x16x32_bf16 v[10:13], v[162:165], v[238:241], v[10:13]
	v_mfma_f32_16x16x32_bf16 v[62:65], v[158:161], v[202:205], v[62:65]
	v_mfma_f32_16x16x32_bf16 v[58:61], v[166:169], v[202:205], v[58:61]
	v_mfma_f32_16x16x32_bf16 v[46:49], v[158:161], v[210:213], v[46:49]
	v_mfma_f32_16x16x32_bf16 v[42:45], v[166:169], v[210:213], v[42:45]
	v_mfma_f32_16x16x32_bf16 v[30:33], v[158:161], v[218:221], v[30:33]
	v_mfma_f32_16x16x32_bf16 v[26:29], v[166:169], v[218:221], v[26:29]
	v_mfma_f32_16x16x32_bf16 v[14:17], v[158:161], v[242:245], v[14:17]
	v_mfma_f32_16x16x32_bf16 v[10:13], v[166:169], v[242:245], v[10:13]
	v_mfma_f32_16x16x32_bf16 v[54:57], v[170:173], v[198:201], v[54:57]
	v_mfma_f32_16x16x32_bf16 v[50:53], v[190:193], v[198:201], v[50:53]
	v_mfma_f32_16x16x32_bf16 v[38:41], v[170:173], v[206:209], v[38:41]
	v_mfma_f32_16x16x32_bf16 v[34:37], v[190:193], v[206:209], v[34:37]
	v_mfma_f32_16x16x32_bf16 v[22:25], v[170:173], v[214:217], v[22:25]
	v_mfma_f32_16x16x32_bf16 v[18:21], v[190:193], v[214:217], v[18:21]
	v_mfma_f32_16x16x32_bf16 v[6:9], v[170:173], v[238:241], v[6:9]
	v_mfma_f32_16x16x32_bf16 v[2:5], v[190:193], v[238:241], v[2:5]
	v_mfma_f32_16x16x32_bf16 v[54:57], v[174:177], v[202:205], v[54:57]
	v_mfma_f32_16x16x32_bf16 v[50:53], v[194:197], v[202:205], v[50:53]
	v_mfma_f32_16x16x32_bf16 v[38:41], v[174:177], v[210:213], v[38:41]
	v_mfma_f32_16x16x32_bf16 v[34:37], v[194:197], v[210:213], v[34:37]
	v_mfma_f32_16x16x32_bf16 v[22:25], v[174:177], v[218:221], v[22:25]
	v_mfma_f32_16x16x32_bf16 v[18:21], v[194:197], v[218:221], v[18:21]
	v_mfma_f32_16x16x32_bf16 v[6:9], v[174:177], v[242:245], v[6:9]
	v_mfma_f32_16x16x32_bf16 v[2:5], v[194:197], v[242:245], v[2:5]
	s_cmp_lg_u32 s100, 0
	s_cbranch_scc1 .Lmy_h2_12
	s_barrier
.Lmy_h2_12:
	s_setprio 0
	s_add_i32 s69, 0, 0x18000
	v_add_u32_e32 v151, s69, v146
	s_add_i32 s70, 0, 0x1c000
	ds_read_b128 v[154:157], v151
	ds_read_b128 v[158:161], v151 offset:1024
	ds_read_b128 v[162:165], v151 offset:2048
	ds_read_b128 v[166:169], v151 offset:3072
	v_add_u32_e32 v151, s70, v146
	ds_read_b128 v[170:173], v151
	ds_read_b128 v[174:177], v151 offset:1024
	ds_read_b128 v[190:193], v151 offset:2048
	ds_read_b128 v[194:197], v151 offset:3072
	s_add_u32 s40, s40, s10
	s_addc_u32 s41, s41, s11
	s_mov_b32 m0, s47
	v_lshl_add_u64 v[252:253], s[40:41], 0, v[138:139]
	ds_read_b128 v[198:201], v147 offset:32768
	ds_read_b128 v[202:205], v147 offset:33792
	ds_read_b128 v[206:209], v147 offset:34816
	ds_read_b128 v[210:213], v147 offset:35840
	ds_read_b128 v[214:217], v147 offset:36864
	ds_read_b128 v[218:221], v147 offset:37888
	ds_read_b128 v[238:241], v147 offset:38912
	ds_read_b128 v[242:245], v147 offset:39936
	global_load_lds_dwordx4 v[252:253], off
	v_lshl_add_u64 v[252:253], s[40:41], 0, v[134:135]
	s_mov_b32 m0, s48
	s_nop 0
	global_load_lds_dwordx4 v[252:253], off
	s_waitcnt vmcnt(8)
	s_waitcnt lgkmcnt(0)
	s_cmp_eq_u32 s100, 0
	s_cbranch_scc1 .Lmy_h2_13
	s_setprio 1
	s_barrier

.Lmy_h2_14:
	s_setprio 0
	s_add_i32 s40, s69, s44
	v_lshl_add_u64 v[148:149], v[148:149], 0, s[16:17]
	s_mov_b32 m0, s40
	ds_read_b128 v[198:201], v147 offset:49152
	ds_read_b128 v[202:205], v147 offset:50176
	ds_read_b128 v[206:209], v147 offset:51200
	ds_read_b128 v[210:213], v147 offset:52224
	ds_read_b128 v[214:217], v147 offset:53248
	ds_read_b128 v[218:221], v147 offset:54272
	ds_read_b128 v[238:241], v147 offset:55296
	ds_read_b128 v[242:245], v147 offset:56320
	global_load_lds_dwordx4 v[148:149], off
	v_lshl_add_u64 v[148:149], v[178:179], 0, s[16:17]
	s_add_i32 m0, s40, 0x2000
	s_add_i32 s40, s70, s44
	global_load_lds_dwordx4 v[148:149], off
	v_lshl_add_u64 v[148:149], v[222:223], 0, s[16:17]
	s_mov_b32 m0, s40
	s_nop 0
	global_load_lds_dwordx4 v[148:149], off
	v_lshl_add_u64 v[148:149], v[246:247], 0, s[16:17]
	s_add_i32 m0, s40, 0x2000
	s_nop 0
	global_load_lds_dwordx4 v[148:149], off
	v_lshl_add_u64 v[148:149], v[248:249], 0, s[16:17]
	s_mov_b32 m0, s49
	s_nop 0
	global_load_lds_dwordx4 v[148:149], off
	v_lshl_add_u64 v[148:149], v[250:251], 0, s[16:17]
	s_mov_b32 m0, s50
	s_nop 0
	global_load_lds_dwordx4 v[148:149], off
	s_waitcnt vmcnt(8)
	s_waitcnt lgkmcnt(0)
	s_cmp_eq_u32 s100, 0
	s_cbranch_scc1 .Lmy_h2_15
	s_setprio 1
	s_barrier

.Lmy_h2_16:
	s_setprio 0
	s_add_u32 s34, s34, 0x100
	s_addc_u32 s35, s35, 0
	s_add_u32 s62, s62, 0x100
	s_addc_u32 s63, s63, 0
	s_cmp_ge_i32 s64, s51
	s_mov_b32 s40, s64
	s_cbranch_scc0 .LBB0_824
	v_readlane_b32 s64, v255, 40
	s_mov_b32 s68, 0xff61b1e6
	s_mov_b32 s74, 0x24600000
	s_mov_b32 s69, 0xcf800000

.LBB0_828:
	v_mul_f32_e32 v155, 0x3dd2d3e8, v126
	v_fma_f32 v155, -v126, v155, s79
	v_mul_f32_e32 v155, v126, v155
	v_exp_f32_e32 v155, v155
	s_lshl_b32 s35, s8, 9
	v_mov_b32_e32 v151, v144
	v_mov_b32_e32 v149, v145
	v_add_f32_e32 v155, 1.0, v155
	v_rcp_f32_e32 v155, v155
	s_lshl_b32 s34, s61, 8
	s_sub_i32 s35, s55, s35
	v_mul_f32_e32 v126, v126, v155
	v_mul_f32_e32 v155, 0x3dd2d3e8, v127
	v_fma_f32 v155, -v127, v155, s79
	v_mul_f32_e32 v155, v127, v155
	v_exp_f32_e32 v155, v155
	s_add_i32 s40, s35, s34
	v_lshl_add_u32 v154, v151, 3, s56
	s_lshl_b32 s34, s8, 4
	v_add_f32_e32 v155, 1.0, v155
	v_rcp_f32_e32 v155, v155
	v_ashrrev_i32_e32 v148, 4, v154
	v_add_lshl_u32 v149, s40, v149, 4
	s_ashr_i32 s35, s34, 31
	v_mul_f32_e32 v127, v127, v155
	v_mul_f32_e32 v155, 0x3dd2d3e8, v128
	v_fma_f32 v155, -v128, v155, s79
	v_mul_f32_e32 v155, v128, v155
	v_exp_f32_e32 v155, v155
	s_lshl_b64 s[34:35], s[34:35], 1
	v_lshlrev_b32_e32 v151, 4, v151
	v_and_b32_e32 v180, 16, v151
	v_add_f32_e32 v155, 1.0, v155
	v_rcp_f32_e32 v155, v155
	s_nop 0
	v_mul_f32_e32 v128, v128, v155
	v_mul_f32_e32 v155, 0x3dd2d3e8, v129
	v_fma_f32 v155, -v129, v155, s79
	v_mul_f32_e32 v155, v129, v155
	v_exp_f32_e32 v155, v155
	s_nop 0
	v_add_f32_e32 v155, 1.0, v155
	v_rcp_f32_e32 v155, v155
	s_nop 0
	v_mul_f32_e32 v129, v129, v155
	v_mul_f32_e32 v155, 0x3dd2d3e8, v122
	v_fma_f32 v155, -v122, v155, s79
	v_mul_f32_e32 v155, v122, v155
	v_exp_f32_e32 v155, v155
	s_nop 0
	v_add_f32_e32 v155, 1.0, v155
	v_rcp_f32_e32 v155, v155
	s_nop 0
	v_mul_f32_e32 v122, v122, v155
	v_mul_f32_e32 v155, 0x3dd2d3e8, v123
	v_fma_f32 v155, -v123, v155, s79
	v_mul_f32_e32 v155, v123, v155
	v_exp_f32_e32 v155, v155
	s_nop 0
	v_add_f32_e32 v155, 1.0, v155
	v_rcp_f32_e32 v155, v155
	s_nop 0
	v_mul_f32_e32 v123, v123, v155
	v_mul_f32_e32 v155, 0x3dd2d3e8, v124
	v_fma_f32 v155, -v124, v155, s79
	v_mul_f32_e32 v155, v124, v155
	v_exp_f32_e32 v155, v155
	s_nop 0
	v_add_f32_e32 v155, 1.0, v155
	v_rcp_f32_e32 v155, v155
	s_nop 0
	v_mul_f32_e32 v155, v124, v155
	v_mul_f32_e32 v124, 0x3dd2d3e8, v125
	v_fma_f32 v124, -v125, v124, s79
	v_mul_f32_e32 v124, v125, v124
	v_exp_f32_e32 v124, v124
	s_nop 0
	v_add_f32_e32 v124, 1.0, v124
	v_rcp_f32_e32 v124, v124
	s_nop 0
	v_mul_f32_e32 v156, v125, v124
	v_cvt_pk_bf16_f32 v124, v126, v127
	v_cvt_pk_bf16_f32 v125, v128, v129
	v_cvt_pk_bf16_f32 v126, v122, v123
	v_add_u32_e32 v128, v148, v149
	v_mov_b64_e32 v[122:123], s[22:23]
	v_mad_i64_i32 v[128:129], s[40:41], v128, s80, v[122:123]
	v_lshl_add_u64 v[128:129], v[128:129], 0, s[34:35]
	v_lshl_add_u64 v[128:129], v[128:129], 0, v[180:181]
	v_cvt_pk_bf16_f32 v127, v155, v156
	global_store_dwordx4 v[128:129], v[124:127], off
	s_nop 1
	v_mul_f32_e32 v125, 0x3dd2d3e8, v118
	v_fma_f32 v125, -v118, v125, s79
	v_mul_f32_e32 v125, v118, v125
	v_exp_f32_e32 v125, v125
	v_add_u32_e32 v124, 0x80, v154
	v_ashrrev_i32_e32 v124, 4, v124
	v_add_f32_e32 v125, 1.0, v125
	v_rcp_f32_e32 v125, v125
	s_nop 0
	v_mul_f32_e32 v118, v118, v125
	v_mul_f32_e32 v125, 0x3dd2d3e8, v119
	v_fma_f32 v125, -v119, v125, s79
	v_mul_f32_e32 v125, v119, v125
	v_exp_f32_e32 v125, v125
	s_nop 0
	v_add_f32_e32 v125, 1.0, v125
	v_rcp_f32_e32 v125, v125
	s_nop 0
	v_mul_f32_e32 v119, v119, v125
	v_mul_f32_e32 v125, 0x3dd2d3e8, v120
	v_fma_f32 v125, -v120, v125, s79
	v_mul_f32_e32 v125, v120, v125
	v_exp_f32_e32 v125, v125
	s_nop 0
	v_add_f32_e32 v125, 1.0, v125
	v_rcp_f32_e32 v125, v125
	s_nop 0
	v_mul_f32_e32 v120, v120, v125
	v_mul_f32_e32 v125, 0x3dd2d3e8, v121
	v_fma_f32 v125, -v121, v125, s79
	v_mul_f32_e32 v125, v121, v125
	v_exp_f32_e32 v125, v125
	s_nop 0
	v_add_f32_e32 v125, 1.0, v125
	v_rcp_f32_e32 v125, v125
	s_nop 0
	v_mul_f32_e32 v121, v121, v125
	v_mul_f32_e32 v125, 0x3dd2d3e8, v114
	v_fma_f32 v125, -v114, v125, s79
	v_mul_f32_e32 v125, v114, v125
	v_exp_f32_e32 v125, v125
	s_nop 0
	v_add_f32_e32 v125, 1.0, v125
	v_rcp_f32_e32 v125, v125
	s_nop 0
	v_mul_f32_e32 v125, v114, v125
	v_mul_f32_e32 v114, 0x3dd2d3e8, v115
	v_fma_f32 v114, -v115, v114, s79
	v_mul_f32_e32 v114, v115, v114
	v_exp_f32_e32 v114, v114
	s_nop 0
	v_add_f32_e32 v114, 1.0, v114
	v_rcp_f32_e32 v114, v114
	s_nop 0
	v_mul_f32_e32 v126, v115, v114
	v_mul_f32_e32 v114, 0x3dd2d3e8, v116
	v_fma_f32 v114, -v116, v114, s79
	v_mul_f32_e32 v114, v116, v114
	v_exp_f32_e32 v114, v114
	s_nop 0
	v_add_f32_e32 v114, 1.0, v114
	v_rcp_f32_e32 v114, v114
	s_nop 0
	v_mul_f32_e32 v127, v116, v114
	v_mul_f32_e32 v114, 0x3dd2d3e8, v117
	v_fma_f32 v114, -v117, v114, s79
	v_mul_f32_e32 v114, v117, v114
	v_exp_f32_e32 v114, v114
	s_nop 0
	v_add_f32_e32 v114, 1.0, v114
	v_rcp_f32_e32 v114, v114
	s_nop 0
	v_mul_f32_e32 v117, v117, v114
	v_cvt_pk_bf16_f32 v114, v118, v119
	v_add_u32_e32 v118, v124, v149
	v_mad_i64_i32 v[118:119], s[40:41], v118, s80, v[122:123]
	v_lshl_add_u64 v[118:119], v[118:119], 0, s[34:35]
	v_lshl_add_u64 v[118:119], v[118:119], 0, v[180:181]
	v_cvt_pk_bf16_f32 v115, v120, v121
	v_cvt_pk_bf16_f32 v116, v125, v126
	v_cvt_pk_bf16_f32 v117, v127, v117
	global_store_dwordx4 v[118:119], v[114:117], off
	s_nop 1
	v_mul_f32_e32 v115, 0x3dd2d3e8, v110
	v_fma_f32 v115, -v110, v115, s79
	v_mul_f32_e32 v115, v110, v115
	v_exp_f32_e32 v115, v115
	v_add_u32_e32 v114, 0x100, v149
	v_add_f32_e32 v115, 1.0, v115
	v_rcp_f32_e32 v115, v115
	s_nop 0
	v_mul_f32_e32 v110, v110, v115
	v_mul_f32_e32 v115, 0x3dd2d3e8, v111
	v_fma_f32 v115, -v111, v115, s79
	v_mul_f32_e32 v115, v111, v115
	v_exp_f32_e32 v115, v115
	s_nop 0
	v_add_f32_e32 v115, 1.0, v115
	v_rcp_f32_e32 v115, v115
	s_nop 0
	v_mul_f32_e32 v111, v111, v115
	v_mul_f32_e32 v115, 0x3dd2d3e8, v112
	v_fma_f32 v115, -v112, v115, s79
	v_mul_f32_e32 v115, v112, v115
	v_exp_f32_e32 v115, v115
	s_nop 0
	v_add_f32_e32 v115, 1.0, v115
	v_rcp_f32_e32 v115, v115
	s_nop 0
	v_mul_f32_e32 v112, v112, v115
	v_mul_f32_e32 v115, 0x3dd2d3e8, v113
	v_fma_f32 v115, -v113, v115, s79
	v_mul_f32_e32 v115, v113, v115
	v_exp_f32_e32 v115, v115
	s_nop 0
	v_add_f32_e32 v115, 1.0, v115
	v_rcp_f32_e32 v115, v115
	s_nop 0
	v_mul_f32_e32 v113, v113, v115
	v_mul_f32_e32 v115, 0x3dd2d3e8, v106
	v_fma_f32 v115, -v106, v115, s79
	v_mul_f32_e32 v115, v106, v115
	v_exp_f32_e32 v115, v115
	s_nop 0
	v_add_f32_e32 v115, 1.0, v115
	v_rcp_f32_e32 v115, v115
	s_nop 0
	v_mul_f32_e32 v115, v106, v115
	v_mul_f32_e32 v106, 0x3dd2d3e8, v107
	v_fma_f32 v106, -v107, v106, s79
	v_mul_f32_e32 v106, v107, v106
	v_exp_f32_e32 v106, v106
	s_nop 0
	v_add_f32_e32 v106, 1.0, v106
	v_rcp_f32_e32 v106, v106
	s_nop 0
	v_mul_f32_e32 v116, v107, v106
	v_mul_f32_e32 v106, 0x3dd2d3e8, v108
	v_fma_f32 v106, -v108, v106, s79
	v_mul_f32_e32 v106, v108, v106
	v_exp_f32_e32 v106, v106
	s_nop 0
	v_add_f32_e32 v106, 1.0, v106
	v_rcp_f32_e32 v106, v106
	s_nop 0
	v_mul_f32_e32 v117, v108, v106
	v_mul_f32_e32 v106, 0x3dd2d3e8, v109
	v_fma_f32 v106, -v109, v106, s79
	v_mul_f32_e32 v106, v109, v106
	v_exp_f32_e32 v106, v106
	s_nop 0
	v_add_f32_e32 v106, 1.0, v106
	v_rcp_f32_e32 v106, v106
	s_nop 0
	v_mul_f32_e32 v109, v109, v106
	v_cvt_pk_bf16_f32 v106, v110, v111
	v_add_u32_e32 v110, v148, v114
	v_mad_i64_i32 v[110:111], s[40:41], v110, s80, v[122:123]
	v_lshl_add_u64 v[110:111], v[110:111], 0, s[34:35]
	v_lshl_add_u64 v[110:111], v[110:111], 0, v[180:181]
	v_cvt_pk_bf16_f32 v107, v112, v113
	v_cvt_pk_bf16_f32 v108, v115, v116
	v_cvt_pk_bf16_f32 v109, v117, v109
	global_store_dwordx4 v[110:111], v[106:109], off
	s_nop 1
	v_mul_f32_e32 v106, 0x3dd2d3e8, v102
	v_fma_f32 v106, -v102, v106, s79
	v_mul_f32_e32 v106, v102, v106
	v_exp_f32_e32 v106, v106
	s_nop 0
	v_add_f32_e32 v106, 1.0, v106
	v_rcp_f32_e32 v106, v106
	s_nop 0
	v_mul_f32_e32 v102, v102, v106
	v_mul_f32_e32 v106, 0x3dd2d3e8, v103
	v_fma_f32 v106, -v103, v106, s79
	v_mul_f32_e32 v106, v103, v106
	v_exp_f32_e32 v106, v106
	s_nop 0
	v_add_f32_e32 v106, 1.0, v106
	v_rcp_f32_e32 v106, v106
	s_nop 0
	v_mul_f32_e32 v103, v103, v106
	v_mul_f32_e32 v106, 0x3dd2d3e8, v104
	v_fma_f32 v106, -v104, v106, s79
	v_mul_f32_e32 v106, v104, v106
	v_exp_f32_e32 v106, v106
	s_nop 0
	v_add_f32_e32 v106, 1.0, v106
	v_rcp_f32_e32 v106, v106
	s_nop 0
	v_mul_f32_e32 v104, v104, v106
	v_mul_f32_e32 v106, 0x3dd2d3e8, v105
	v_fma_f32 v106, -v105, v106, s79
	v_mul_f32_e32 v106, v105, v106
	v_exp_f32_e32 v106, v106
	s_nop 0
	v_add_f32_e32 v106, 1.0, v106
	v_rcp_f32_e32 v106, v106
	s_nop 0
	v_mul_f32_e32 v105, v105, v106
	v_mul_f32_e32 v106, 0x3dd2d3e8, v98
	v_fma_f32 v106, -v98, v106, s79
	v_mul_f32_e32 v106, v98, v106
	v_exp_f32_e32 v106, v106
	s_nop 0
	v_add_f32_e32 v106, 1.0, v106
	v_rcp_f32_e32 v106, v106
	s_nop 0
	v_mul_f32_e32 v106, v98, v106
	v_mul_f32_e32 v98, 0x3dd2d3e8, v99
	v_fma_f32 v98, -v99, v98, s79
	v_mul_f32_e32 v98, v99, v98
	v_exp_f32_e32 v98, v98
	s_nop 0
	v_add_f32_e32 v98, 1.0, v98
	v_rcp_f32_e32 v98, v98
	s_nop 0
	v_mul_f32_e32 v107, v99, v98
	v_mul_f32_e32 v98, 0x3dd2d3e8, v100
	v_fma_f32 v98, -v100, v98, s79
	v_mul_f32_e32 v98, v100, v98
	v_exp_f32_e32 v98, v98
	s_nop 0
	v_add_f32_e32 v98, 1.0, v98
	v_rcp_f32_e32 v98, v98
	s_nop 0
	v_mul_f32_e32 v108, v100, v98
	v_mul_f32_e32 v98, 0x3dd2d3e8, v101
	v_fma_f32 v98, -v101, v98, s79
	v_mul_f32_e32 v98, v101, v98
	v_exp_f32_e32 v98, v98
	s_nop 0
	v_add_f32_e32 v98, 1.0, v98
	v_rcp_f32_e32 v98, v98
	s_nop 0
	v_mul_f32_e32 v101, v101, v98
	v_cvt_pk_bf16_f32 v98, v102, v103
	v_add_u32_e32 v102, v124, v114
	v_mad_i64_i32 v[102:103], s[40:41], v102, s80, v[122:123]
	v_lshl_add_u64 v[102:103], v[102:103], 0, s[34:35]
	v_lshl_add_u64 v[102:103], v[102:103], 0, v[180:181]
	v_cvt_pk_bf16_f32 v99, v104, v105
	v_cvt_pk_bf16_f32 v100, v106, v107
	v_cvt_pk_bf16_f32 v101, v108, v101
	global_store_dwordx4 v[102:103], v[98:101], off
	s_nop 1
	v_mul_f32_e32 v99, 0x3dd2d3e8, v94
	v_fma_f32 v99, -v94, v99, s79
	v_mul_f32_e32 v99, v94, v99
	v_exp_f32_e32 v99, v99
	v_add_u32_e32 v98, 0x200, v149
	v_add_f32_e32 v99, 1.0, v99
	v_rcp_f32_e32 v99, v99
	s_nop 0
	v_mul_f32_e32 v94, v94, v99
	v_mul_f32_e32 v99, 0x3dd2d3e8, v95
	v_fma_f32 v99, -v95, v99, s79
	v_mul_f32_e32 v99, v95, v99
	v_exp_f32_e32 v99, v99
	s_nop 0
	v_add_f32_e32 v99, 1.0, v99
	v_rcp_f32_e32 v99, v99
	s_nop 0
	v_mul_f32_e32 v95, v95, v99
	v_mul_f32_e32 v99, 0x3dd2d3e8, v96
	v_fma_f32 v99, -v96, v99, s79
	v_mul_f32_e32 v99, v96, v99
	v_exp_f32_e32 v99, v99
	s_nop 0
	v_add_f32_e32 v99, 1.0, v99
	v_rcp_f32_e32 v99, v99
	s_nop 0
	v_mul_f32_e32 v96, v96, v99
	v_mul_f32_e32 v99, 0x3dd2d3e8, v97
	v_fma_f32 v99, -v97, v99, s79
	v_mul_f32_e32 v99, v97, v99
	v_exp_f32_e32 v99, v99
	s_nop 0
	v_add_f32_e32 v99, 1.0, v99
	v_rcp_f32_e32 v99, v99
	s_nop 0
	v_mul_f32_e32 v97, v97, v99
	v_mul_f32_e32 v99, 0x3dd2d3e8, v90
	v_fma_f32 v99, -v90, v99, s79
	v_mul_f32_e32 v99, v90, v99
	v_exp_f32_e32 v99, v99
	s_nop 0
	v_add_f32_e32 v99, 1.0, v99
	v_rcp_f32_e32 v99, v99
	s_nop 0
	v_mul_f32_e32 v99, v90, v99
	v_mul_f32_e32 v90, 0x3dd2d3e8, v91
	v_fma_f32 v90, -v91, v90, s79
	v_mul_f32_e32 v90, v91, v90
	v_exp_f32_e32 v90, v90
	s_nop 0
	v_add_f32_e32 v90, 1.0, v90
	v_rcp_f32_e32 v90, v90
	s_nop 0
	v_mul_f32_e32 v100, v91, v90
	v_mul_f32_e32 v90, 0x3dd2d3e8, v92
	v_fma_f32 v90, -v92, v90, s79
	v_mul_f32_e32 v90, v92, v90
	v_exp_f32_e32 v90, v90
	s_nop 0
	v_add_f32_e32 v90, 1.0, v90
	v_rcp_f32_e32 v90, v90
	s_nop 0
	v_mul_f32_e32 v101, v92, v90
	v_mul_f32_e32 v90, 0x3dd2d3e8, v93
	v_fma_f32 v90, -v93, v90, s79
	v_mul_f32_e32 v90, v93, v90
	v_exp_f32_e32 v90, v90
	s_nop 0
	v_add_f32_e32 v90, 1.0, v90
	v_rcp_f32_e32 v90, v90
	s_nop 0
	v_mul_f32_e32 v93, v93, v90
	v_cvt_pk_bf16_f32 v90, v94, v95
	v_add_u32_e32 v94, v148, v98
	v_mad_i64_i32 v[94:95], s[40:41], v94, s80, v[122:123]
	v_lshl_add_u64 v[94:95], v[94:95], 0, s[34:35]
	v_lshl_add_u64 v[94:95], v[94:95], 0, v[180:181]
	v_cvt_pk_bf16_f32 v91, v96, v97
	v_cvt_pk_bf16_f32 v92, v99, v100
	v_cvt_pk_bf16_f32 v93, v101, v93
	global_store_dwordx4 v[94:95], v[90:93], off
	s_nop 1
	v_mul_f32_e32 v90, 0x3dd2d3e8, v86
	v_fma_f32 v90, -v86, v90, s79
	v_mul_f32_e32 v90, v86, v90
	v_exp_f32_e32 v90, v90
	s_nop 0
	v_add_f32_e32 v90, 1.0, v90
	v_rcp_f32_e32 v90, v90
	s_nop 0
	v_mul_f32_e32 v86, v86, v90
	v_mul_f32_e32 v90, 0x3dd2d3e8, v87
	v_fma_f32 v90, -v87, v90, s79
	v_mul_f32_e32 v90, v87, v90
	v_exp_f32_e32 v90, v90
	s_nop 0
	v_add_f32_e32 v90, 1.0, v90
	v_rcp_f32_e32 v90, v90
	s_nop 0
	v_mul_f32_e32 v87, v87, v90
	v_mul_f32_e32 v90, 0x3dd2d3e8, v88
	v_fma_f32 v90, -v88, v90, s79
	v_mul_f32_e32 v90, v88, v90
	v_exp_f32_e32 v90, v90
	s_nop 0
	v_add_f32_e32 v90, 1.0, v90
	v_rcp_f32_e32 v90, v90
	s_nop 0
	v_mul_f32_e32 v88, v88, v90
	v_mul_f32_e32 v90, 0x3dd2d3e8, v89
	v_fma_f32 v90, -v89, v90, s79
	v_mul_f32_e32 v90, v89, v90
	v_exp_f32_e32 v90, v90
	s_nop 0
	v_add_f32_e32 v90, 1.0, v90
	v_rcp_f32_e32 v90, v90
	s_nop 0
	v_mul_f32_e32 v89, v89, v90
	v_mul_f32_e32 v90, 0x3dd2d3e8, v82
	v_fma_f32 v90, -v82, v90, s79
	v_mul_f32_e32 v90, v82, v90
	v_exp_f32_e32 v90, v90
	s_nop 0
	v_add_f32_e32 v90, 1.0, v90
	v_rcp_f32_e32 v90, v90
	s_nop 0
	v_mul_f32_e32 v90, v82, v90
	v_mul_f32_e32 v82, 0x3dd2d3e8, v83
	v_fma_f32 v82, -v83, v82, s79
	v_mul_f32_e32 v82, v83, v82
	v_exp_f32_e32 v82, v82
	s_nop 0
	v_add_f32_e32 v82, 1.0, v82
	v_rcp_f32_e32 v82, v82
	s_nop 0
	v_mul_f32_e32 v91, v83, v82
	v_mul_f32_e32 v82, 0x3dd2d3e8, v84
	v_fma_f32 v82, -v84, v82, s79
	v_mul_f32_e32 v82, v84, v82
	v_exp_f32_e32 v82, v82
	s_nop 0
	v_add_f32_e32 v82, 1.0, v82
	v_rcp_f32_e32 v82, v82
	s_nop 0
	v_mul_f32_e32 v92, v84, v82
	v_mul_f32_e32 v82, 0x3dd2d3e8, v85
	v_fma_f32 v82, -v85, v82, s79
	v_mul_f32_e32 v82, v85, v82
	v_exp_f32_e32 v82, v82
	s_nop 0
	v_add_f32_e32 v82, 1.0, v82
	v_rcp_f32_e32 v82, v82
	s_nop 0
	v_mul_f32_e32 v85, v85, v82
	v_cvt_pk_bf16_f32 v82, v86, v87
	v_add_u32_e32 v86, v124, v98
	v_mad_i64_i32 v[86:87], s[40:41], v86, s80, v[122:123]
	v_lshl_add_u64 v[86:87], v[86:87], 0, s[34:35]
	v_lshl_add_u64 v[86:87], v[86:87], 0, v[180:181]
	v_cvt_pk_bf16_f32 v83, v88, v89
	v_cvt_pk_bf16_f32 v84, v90, v91
	v_cvt_pk_bf16_f32 v85, v92, v85
	global_store_dwordx4 v[86:87], v[82:85], off
	s_nop 1
	v_mul_f32_e32 v83, 0x3dd2d3e8, v78
	v_fma_f32 v83, -v78, v83, s79
	v_mul_f32_e32 v83, v78, v83
	v_exp_f32_e32 v83, v83
	v_add_u32_e32 v82, 0x300, v149
	v_add_f32_e32 v83, 1.0, v83
	v_rcp_f32_e32 v83, v83
	s_nop 0
	v_mul_f32_e32 v78, v78, v83
	v_mul_f32_e32 v83, 0x3dd2d3e8, v79
	v_fma_f32 v83, -v79, v83, s79
	v_mul_f32_e32 v83, v79, v83
	v_exp_f32_e32 v83, v83
	s_nop 0
	v_add_f32_e32 v83, 1.0, v83
	v_rcp_f32_e32 v83, v83
	s_nop 0
	v_mul_f32_e32 v79, v79, v83
	v_mul_f32_e32 v83, 0x3dd2d3e8, v80
	v_fma_f32 v83, -v80, v83, s79
	v_mul_f32_e32 v83, v80, v83
	v_exp_f32_e32 v83, v83
	s_nop 0
	v_add_f32_e32 v83, 1.0, v83
	v_rcp_f32_e32 v83, v83
	s_nop 0
	v_mul_f32_e32 v80, v80, v83
	v_mul_f32_e32 v83, 0x3dd2d3e8, v81
	v_fma_f32 v83, -v81, v83, s79
	v_mul_f32_e32 v83, v81, v83
	v_exp_f32_e32 v83, v83
	s_nop 0
	v_add_f32_e32 v83, 1.0, v83
	v_rcp_f32_e32 v83, v83
	s_nop 0
	v_mul_f32_e32 v81, v81, v83
	v_mul_f32_e32 v83, 0x3dd2d3e8, v74
	v_fma_f32 v83, -v74, v83, s79
	v_mul_f32_e32 v83, v74, v83
	v_exp_f32_e32 v83, v83
	s_nop 0
	v_add_f32_e32 v83, 1.0, v83
	v_rcp_f32_e32 v83, v83
	s_nop 0
	v_mul_f32_e32 v83, v74, v83
	v_mul_f32_e32 v74, 0x3dd2d3e8, v75
	v_fma_f32 v74, -v75, v74, s79
	v_mul_f32_e32 v74, v75, v74
	v_exp_f32_e32 v74, v74
	s_nop 0
	v_add_f32_e32 v74, 1.0, v74
	v_rcp_f32_e32 v74, v74
	s_nop 0
	v_mul_f32_e32 v84, v75, v74
	v_mul_f32_e32 v74, 0x3dd2d3e8, v76
	v_fma_f32 v74, -v76, v74, s79
	v_mul_f32_e32 v74, v76, v74
	v_exp_f32_e32 v74, v74
	s_nop 0
	v_add_f32_e32 v74, 1.0, v74
	v_rcp_f32_e32 v74, v74
	s_nop 0
	v_mul_f32_e32 v85, v76, v74
	v_mul_f32_e32 v74, 0x3dd2d3e8, v77
	v_fma_f32 v74, -v77, v74, s79
	v_mul_f32_e32 v74, v77, v74
	v_exp_f32_e32 v74, v74
	s_nop 0
	v_add_f32_e32 v74, 1.0, v74
	v_rcp_f32_e32 v74, v74
	s_nop 0
	v_mul_f32_e32 v77, v77, v74
	v_cvt_pk_bf16_f32 v74, v78, v79
	v_add_u32_e32 v78, v148, v82
	v_mad_i64_i32 v[78:79], s[40:41], v78, s80, v[122:123]
	v_lshl_add_u64 v[78:79], v[78:79], 0, s[34:35]
	v_lshl_add_u64 v[78:79], v[78:79], 0, v[180:181]
	v_cvt_pk_bf16_f32 v75, v80, v81
	v_cvt_pk_bf16_f32 v76, v83, v84
	v_cvt_pk_bf16_f32 v77, v85, v77
	global_store_dwordx4 v[78:79], v[74:77], off
	s_nop 1
	v_mul_f32_e32 v74, 0x3dd2d3e8, v70
	v_fma_f32 v74, -v70, v74, s79
	v_mul_f32_e32 v74, v70, v74
	v_exp_f32_e32 v74, v74
	s_nop 0
	v_add_f32_e32 v74, 1.0, v74
	v_rcp_f32_e32 v74, v74
	s_nop 0
	v_mul_f32_e32 v70, v70, v74
	v_mul_f32_e32 v74, 0x3dd2d3e8, v71
	v_fma_f32 v74, -v71, v74, s79
	v_mul_f32_e32 v74, v71, v74
	v_exp_f32_e32 v74, v74
	s_nop 0
	v_add_f32_e32 v74, 1.0, v74
	v_rcp_f32_e32 v74, v74
	s_nop 0
	v_mul_f32_e32 v71, v71, v74
	v_mul_f32_e32 v74, 0x3dd2d3e8, v72
	v_fma_f32 v74, -v72, v74, s79
	v_mul_f32_e32 v74, v72, v74
	v_exp_f32_e32 v74, v74
	s_nop 0
	v_add_f32_e32 v74, 1.0, v74
	v_rcp_f32_e32 v74, v74
	s_nop 0
	v_mul_f32_e32 v72, v72, v74
	v_mul_f32_e32 v74, 0x3dd2d3e8, v73
	v_fma_f32 v74, -v73, v74, s79
	v_mul_f32_e32 v74, v73, v74
	v_exp_f32_e32 v74, v74
	s_nop 0
	v_add_f32_e32 v74, 1.0, v74
	v_rcp_f32_e32 v74, v74
	s_nop 0
	v_mul_f32_e32 v73, v73, v74
	v_mul_f32_e32 v74, 0x3dd2d3e8, v66
	v_fma_f32 v74, -v66, v74, s79
	v_mul_f32_e32 v74, v66, v74
	v_exp_f32_e32 v74, v74
	s_nop 0
	v_add_f32_e32 v74, 1.0, v74
	v_rcp_f32_e32 v74, v74
	s_nop 0
	v_mul_f32_e32 v74, v66, v74
	v_mul_f32_e32 v66, 0x3dd2d3e8, v67
	v_fma_f32 v66, -v67, v66, s79
	v_mul_f32_e32 v66, v67, v66
	v_exp_f32_e32 v66, v66
	s_nop 0
	v_add_f32_e32 v66, 1.0, v66
	v_rcp_f32_e32 v66, v66
	s_nop 0
	v_mul_f32_e32 v75, v67, v66
	v_mul_f32_e32 v66, 0x3dd2d3e8, v68
	v_fma_f32 v66, -v68, v66, s79
	v_mul_f32_e32 v66, v68, v66
	v_exp_f32_e32 v66, v66
	s_nop 0
	v_add_f32_e32 v66, 1.0, v66
	v_rcp_f32_e32 v66, v66
	s_nop 0
	v_mul_f32_e32 v76, v68, v66
	v_mul_f32_e32 v66, 0x3dd2d3e8, v69
	v_fma_f32 v66, -v69, v66, s79
	v_mul_f32_e32 v66, v69, v66
	v_exp_f32_e32 v66, v66
	s_nop 0
	v_add_f32_e32 v66, 1.0, v66
	v_rcp_f32_e32 v66, v66
	s_nop 0
	v_mul_f32_e32 v69, v69, v66
	v_cvt_pk_bf16_f32 v66, v70, v71
	v_add_u32_e32 v70, v124, v82
	v_mad_i64_i32 v[70:71], s[40:41], v70, s80, v[122:123]
	v_lshl_add_u64 v[70:71], v[70:71], 0, s[34:35]
	v_lshl_add_u64 v[70:71], v[70:71], 0, v[180:181]
	v_cvt_pk_bf16_f32 v67, v72, v73
	v_cvt_pk_bf16_f32 v68, v74, v75
	v_cvt_pk_bf16_f32 v69, v76, v69
	global_store_dwordx4 v[70:71], v[66:69], off
	s_nop 1
	v_mul_f32_e32 v67, 0x3dd2d3e8, v62
	v_fma_f32 v67, -v62, v67, s79
	v_mul_f32_e32 v67, v62, v67
	v_exp_f32_e32 v67, v67
	v_add_u32_e32 v66, 0x800, v149
	v_add_f32_e32 v67, 1.0, v67
	v_rcp_f32_e32 v67, v67
	s_nop 0
	v_mul_f32_e32 v62, v62, v67
	v_mul_f32_e32 v67, 0x3dd2d3e8, v63
	v_fma_f32 v67, -v63, v67, s79
	v_mul_f32_e32 v67, v63, v67
	v_exp_f32_e32 v67, v67
	s_nop 0
	v_add_f32_e32 v67, 1.0, v67
	v_rcp_f32_e32 v67, v67
	s_nop 0
	v_mul_f32_e32 v63, v63, v67
	v_mul_f32_e32 v67, 0x3dd2d3e8, v64
	v_fma_f32 v67, -v64, v67, s79
	v_mul_f32_e32 v67, v64, v67
	v_exp_f32_e32 v67, v67
	s_nop 0
	v_add_f32_e32 v67, 1.0, v67
	v_rcp_f32_e32 v67, v67
	s_nop 0
	v_mul_f32_e32 v64, v64, v67
	v_mul_f32_e32 v67, 0x3dd2d3e8, v65
	v_fma_f32 v67, -v65, v67, s79
	v_mul_f32_e32 v67, v65, v67
	v_exp_f32_e32 v67, v67
	s_nop 0
	v_add_f32_e32 v67, 1.0, v67
	v_rcp_f32_e32 v67, v67
	s_nop 0
	v_mul_f32_e32 v65, v65, v67
	v_mul_f32_e32 v67, 0x3dd2d3e8, v58
	v_fma_f32 v67, -v58, v67, s79
	v_mul_f32_e32 v67, v58, v67
	v_exp_f32_e32 v67, v67
	s_nop 0
	v_add_f32_e32 v67, 1.0, v67
	v_rcp_f32_e32 v67, v67
	s_nop 0
	v_mul_f32_e32 v67, v58, v67
	v_mul_f32_e32 v58, 0x3dd2d3e8, v59
	v_fma_f32 v58, -v59, v58, s79
	v_mul_f32_e32 v58, v59, v58
	v_exp_f32_e32 v58, v58
	s_nop 0
	v_add_f32_e32 v58, 1.0, v58
	v_rcp_f32_e32 v58, v58
	s_nop 0
	v_mul_f32_e32 v68, v59, v58
	v_mul_f32_e32 v58, 0x3dd2d3e8, v60
	v_fma_f32 v58, -v60, v58, s79
	v_mul_f32_e32 v58, v60, v58
	v_exp_f32_e32 v58, v58
	s_nop 0
	v_add_f32_e32 v58, 1.0, v58
	v_rcp_f32_e32 v58, v58
	s_nop 0
	v_mul_f32_e32 v69, v60, v58
	v_mul_f32_e32 v58, 0x3dd2d3e8, v61
	v_fma_f32 v58, -v61, v58, s79
	v_mul_f32_e32 v58, v61, v58
	v_exp_f32_e32 v58, v58
	s_nop 0
	v_add_f32_e32 v58, 1.0, v58
	v_rcp_f32_e32 v58, v58
	s_nop 0
	v_mul_f32_e32 v61, v61, v58
	v_cvt_pk_bf16_f32 v58, v62, v63
	v_add_u32_e32 v62, v148, v66
	v_mad_i64_i32 v[62:63], s[40:41], v62, s80, v[122:123]
	v_lshl_add_u64 v[62:63], v[62:63], 0, s[34:35]
	v_lshl_add_u64 v[62:63], v[62:63], 0, v[180:181]
	v_cvt_pk_bf16_f32 v59, v64, v65
	v_cvt_pk_bf16_f32 v60, v67, v68
	v_cvt_pk_bf16_f32 v61, v69, v61
	global_store_dwordx4 v[62:63], v[58:61], off
	s_nop 1
	v_mul_f32_e32 v58, 0x3dd2d3e8, v54
	v_fma_f32 v58, -v54, v58, s79
	v_mul_f32_e32 v58, v54, v58
	v_exp_f32_e32 v58, v58
	s_nop 0
	v_add_f32_e32 v58, 1.0, v58
	v_rcp_f32_e32 v58, v58
	s_nop 0
	v_mul_f32_e32 v54, v54, v58
	v_mul_f32_e32 v58, 0x3dd2d3e8, v55
	v_fma_f32 v58, -v55, v58, s79
	v_mul_f32_e32 v58, v55, v58
	v_exp_f32_e32 v58, v58
	s_nop 0
	v_add_f32_e32 v58, 1.0, v58
	v_rcp_f32_e32 v58, v58
	s_nop 0
	v_mul_f32_e32 v55, v55, v58
	v_mul_f32_e32 v58, 0x3dd2d3e8, v56
	v_fma_f32 v58, -v56, v58, s79
	v_mul_f32_e32 v58, v56, v58
	v_exp_f32_e32 v58, v58
	s_nop 0
	v_add_f32_e32 v58, 1.0, v58
	v_rcp_f32_e32 v58, v58
	s_nop 0
	v_mul_f32_e32 v56, v56, v58
	v_mul_f32_e32 v58, 0x3dd2d3e8, v57
	v_fma_f32 v58, -v57, v58, s79
	v_mul_f32_e32 v58, v57, v58
	v_exp_f32_e32 v58, v58
	s_nop 0
	v_add_f32_e32 v58, 1.0, v58
	v_rcp_f32_e32 v58, v58
	s_nop 0
	v_mul_f32_e32 v57, v57, v58
	v_mul_f32_e32 v58, 0x3dd2d3e8, v50
	v_fma_f32 v58, -v50, v58, s79
	v_mul_f32_e32 v58, v50, v58
	v_exp_f32_e32 v58, v58
	s_nop 0
	v_add_f32_e32 v58, 1.0, v58
	v_rcp_f32_e32 v58, v58
	s_nop 0
	v_mul_f32_e32 v58, v50, v58
	v_mul_f32_e32 v50, 0x3dd2d3e8, v51
	v_fma_f32 v50, -v51, v50, s79
	v_mul_f32_e32 v50, v51, v50
	v_exp_f32_e32 v50, v50
	s_nop 0
	v_add_f32_e32 v50, 1.0, v50
	v_rcp_f32_e32 v50, v50
	s_nop 0
	v_mul_f32_e32 v59, v51, v50
	v_mul_f32_e32 v50, 0x3dd2d3e8, v52
	v_fma_f32 v50, -v52, v50, s79
	v_mul_f32_e32 v50, v52, v50
	v_exp_f32_e32 v50, v50
	s_nop 0
	v_add_f32_e32 v50, 1.0, v50
	v_rcp_f32_e32 v50, v50
	s_nop 0
	v_mul_f32_e32 v60, v52, v50
	v_mul_f32_e32 v50, 0x3dd2d3e8, v53
	v_fma_f32 v50, -v53, v50, s79
	v_mul_f32_e32 v50, v53, v50
	v_exp_f32_e32 v50, v50
	s_nop 0
	v_add_f32_e32 v50, 1.0, v50
	v_rcp_f32_e32 v50, v50
	s_nop 0
	v_mul_f32_e32 v53, v53, v50
	v_cvt_pk_bf16_f32 v50, v54, v55
	v_add_u32_e32 v54, v124, v66
	v_mad_i64_i32 v[54:55], s[40:41], v54, s80, v[122:123]
	v_lshl_add_u64 v[54:55], v[54:55], 0, s[34:35]
	v_lshl_add_u64 v[54:55], v[54:55], 0, v[180:181]
	v_cvt_pk_bf16_f32 v51, v56, v57
	v_cvt_pk_bf16_f32 v52, v58, v59
	v_cvt_pk_bf16_f32 v53, v60, v53
	global_store_dwordx4 v[54:55], v[50:53], off
	s_nop 1
	v_mul_f32_e32 v51, 0x3dd2d3e8, v46
	v_fma_f32 v51, -v46, v51, s79
	v_mul_f32_e32 v51, v46, v51
	v_exp_f32_e32 v51, v51
	v_add_u32_e32 v50, 0x900, v149
	v_add_f32_e32 v51, 1.0, v51
	v_rcp_f32_e32 v51, v51
	s_nop 0
	v_mul_f32_e32 v46, v46, v51
	v_mul_f32_e32 v51, 0x3dd2d3e8, v47
	v_fma_f32 v51, -v47, v51, s79
	v_mul_f32_e32 v51, v47, v51
	v_exp_f32_e32 v51, v51
	s_nop 0
	v_add_f32_e32 v51, 1.0, v51
	v_rcp_f32_e32 v51, v51
	s_nop 0
	v_mul_f32_e32 v47, v47, v51
	v_mul_f32_e32 v51, 0x3dd2d3e8, v48
	v_fma_f32 v51, -v48, v51, s79
	v_mul_f32_e32 v51, v48, v51
	v_exp_f32_e32 v51, v51
	s_nop 0
	v_add_f32_e32 v51, 1.0, v51
	v_rcp_f32_e32 v51, v51
	s_nop 0
	v_mul_f32_e32 v48, v48, v51
	v_mul_f32_e32 v51, 0x3dd2d3e8, v49
	v_fma_f32 v51, -v49, v51, s79
	v_mul_f32_e32 v51, v49, v51
	v_exp_f32_e32 v51, v51
	s_nop 0
	v_add_f32_e32 v51, 1.0, v51
	v_rcp_f32_e32 v51, v51
	s_nop 0
	v_mul_f32_e32 v49, v49, v51
	v_mul_f32_e32 v51, 0x3dd2d3e8, v42
	v_fma_f32 v51, -v42, v51, s79
	v_mul_f32_e32 v51, v42, v51
	v_exp_f32_e32 v51, v51
	s_nop 0
	v_add_f32_e32 v51, 1.0, v51
	v_rcp_f32_e32 v51, v51
	s_nop 0
	v_mul_f32_e32 v51, v42, v51
	v_mul_f32_e32 v42, 0x3dd2d3e8, v43
	v_fma_f32 v42, -v43, v42, s79
	v_mul_f32_e32 v42, v43, v42
	v_exp_f32_e32 v42, v42
	s_nop 0
	v_add_f32_e32 v42, 1.0, v42
	v_rcp_f32_e32 v42, v42
	s_nop 0
	v_mul_f32_e32 v52, v43, v42
	v_mul_f32_e32 v42, 0x3dd2d3e8, v44
	v_fma_f32 v42, -v44, v42, s79
	v_mul_f32_e32 v42, v44, v42
	v_exp_f32_e32 v42, v42
	s_nop 0
	v_add_f32_e32 v42, 1.0, v42
	v_rcp_f32_e32 v42, v42
	s_nop 0
	v_mul_f32_e32 v53, v44, v42
	v_mul_f32_e32 v42, 0x3dd2d3e8, v45
	v_fma_f32 v42, -v45, v42, s79
	v_mul_f32_e32 v42, v45, v42
	v_exp_f32_e32 v42, v42
	s_nop 0
	v_add_f32_e32 v42, 1.0, v42
	v_rcp_f32_e32 v42, v42
	s_nop 0
	v_mul_f32_e32 v45, v45, v42
	v_cvt_pk_bf16_f32 v42, v46, v47
	v_add_u32_e32 v46, v148, v50
	v_mad_i64_i32 v[46:47], s[40:41], v46, s80, v[122:123]
	v_lshl_add_u64 v[46:47], v[46:47], 0, s[34:35]
	v_lshl_add_u64 v[46:47], v[46:47], 0, v[180:181]
	v_cvt_pk_bf16_f32 v43, v48, v49
	v_cvt_pk_bf16_f32 v44, v51, v52
	v_cvt_pk_bf16_f32 v45, v53, v45
	global_store_dwordx4 v[46:47], v[42:45], off
	s_nop 1
	v_mul_f32_e32 v42, 0x3dd2d3e8, v38
	v_fma_f32 v42, -v38, v42, s79
	v_mul_f32_e32 v42, v38, v42
	v_exp_f32_e32 v42, v42
	s_nop 0
	v_add_f32_e32 v42, 1.0, v42
	v_rcp_f32_e32 v42, v42
	s_nop 0
	v_mul_f32_e32 v38, v38, v42
	v_mul_f32_e32 v42, 0x3dd2d3e8, v39
	v_fma_f32 v42, -v39, v42, s79
	v_mul_f32_e32 v42, v39, v42
	v_exp_f32_e32 v42, v42
	s_nop 0
	v_add_f32_e32 v42, 1.0, v42
	v_rcp_f32_e32 v42, v42
	s_nop 0
	v_mul_f32_e32 v39, v39, v42
	v_mul_f32_e32 v42, 0x3dd2d3e8, v40
	v_fma_f32 v42, -v40, v42, s79
	v_mul_f32_e32 v42, v40, v42
	v_exp_f32_e32 v42, v42
	s_nop 0
	v_add_f32_e32 v42, 1.0, v42
	v_rcp_f32_e32 v42, v42
	s_nop 0
	v_mul_f32_e32 v40, v40, v42
	v_mul_f32_e32 v42, 0x3dd2d3e8, v41
	v_fma_f32 v42, -v41, v42, s79
	v_mul_f32_e32 v42, v41, v42
	v_exp_f32_e32 v42, v42
	s_nop 0
	v_add_f32_e32 v42, 1.0, v42
	v_rcp_f32_e32 v42, v42
	s_nop 0
	v_mul_f32_e32 v41, v41, v42
	v_mul_f32_e32 v42, 0x3dd2d3e8, v34
	v_fma_f32 v42, -v34, v42, s79
	v_mul_f32_e32 v42, v34, v42
	v_exp_f32_e32 v42, v42
	s_nop 0
	v_add_f32_e32 v42, 1.0, v42
	v_rcp_f32_e32 v42, v42
	s_nop 0
	v_mul_f32_e32 v42, v34, v42
	v_mul_f32_e32 v34, 0x3dd2d3e8, v35
	v_fma_f32 v34, -v35, v34, s79
	v_mul_f32_e32 v34, v35, v34
	v_exp_f32_e32 v34, v34
	s_nop 0
	v_add_f32_e32 v34, 1.0, v34
	v_rcp_f32_e32 v34, v34
	s_nop 0
	v_mul_f32_e32 v43, v35, v34
	v_mul_f32_e32 v34, 0x3dd2d3e8, v36
	v_fma_f32 v34, -v36, v34, s79
	v_mul_f32_e32 v34, v36, v34
	v_exp_f32_e32 v34, v34
	s_nop 0
	v_add_f32_e32 v34, 1.0, v34
	v_rcp_f32_e32 v34, v34
	s_nop 0
	v_mul_f32_e32 v44, v36, v34
	v_mul_f32_e32 v34, 0x3dd2d3e8, v37
	v_fma_f32 v34, -v37, v34, s79
	v_mul_f32_e32 v34, v37, v34
	v_exp_f32_e32 v34, v34
	s_nop 0
	v_add_f32_e32 v34, 1.0, v34
	v_rcp_f32_e32 v34, v34
	s_nop 0
	v_mul_f32_e32 v37, v37, v34
	v_cvt_pk_bf16_f32 v34, v38, v39
	v_add_u32_e32 v38, v124, v50
	v_mad_i64_i32 v[38:39], s[40:41], v38, s80, v[122:123]
	v_lshl_add_u64 v[38:39], v[38:39], 0, s[34:35]
	v_lshl_add_u64 v[38:39], v[38:39], 0, v[180:181]
	v_cvt_pk_bf16_f32 v35, v40, v41
	v_cvt_pk_bf16_f32 v36, v42, v43
	v_cvt_pk_bf16_f32 v37, v44, v37
	global_store_dwordx4 v[38:39], v[34:37], off
	s_nop 1
	v_mul_f32_e32 v35, 0x3dd2d3e8, v30
	v_fma_f32 v35, -v30, v35, s79
	v_mul_f32_e32 v35, v30, v35
	v_exp_f32_e32 v35, v35
	v_add_u32_e32 v34, 0xa00, v149
	v_add_f32_e32 v35, 1.0, v35
	v_rcp_f32_e32 v35, v35
	s_nop 0
	v_mul_f32_e32 v30, v30, v35
	v_mul_f32_e32 v35, 0x3dd2d3e8, v31
	v_fma_f32 v35, -v31, v35, s79
	v_mul_f32_e32 v35, v31, v35
	v_exp_f32_e32 v35, v35
	s_nop 0
	v_add_f32_e32 v35, 1.0, v35
	v_rcp_f32_e32 v35, v35
	s_nop 0
	v_mul_f32_e32 v31, v31, v35
	v_mul_f32_e32 v35, 0x3dd2d3e8, v32
	v_fma_f32 v35, -v32, v35, s79
	v_mul_f32_e32 v35, v32, v35
	v_exp_f32_e32 v35, v35
	s_nop 0
	v_add_f32_e32 v35, 1.0, v35
	v_rcp_f32_e32 v35, v35
	s_nop 0
	v_mul_f32_e32 v32, v32, v35
	v_mul_f32_e32 v35, 0x3dd2d3e8, v33
	v_fma_f32 v35, -v33, v35, s79
	v_mul_f32_e32 v35, v33, v35
	v_exp_f32_e32 v35, v35
	s_nop 0
	v_add_f32_e32 v35, 1.0, v35
	v_rcp_f32_e32 v35, v35
	s_nop 0
	v_mul_f32_e32 v33, v33, v35
	v_mul_f32_e32 v35, 0x3dd2d3e8, v26
	v_fma_f32 v35, -v26, v35, s79
	v_mul_f32_e32 v35, v26, v35
	v_exp_f32_e32 v35, v35
	s_nop 0
	v_add_f32_e32 v35, 1.0, v35
	v_rcp_f32_e32 v35, v35
	s_nop 0
	v_mul_f32_e32 v35, v26, v35
	v_mul_f32_e32 v26, 0x3dd2d3e8, v27
	v_fma_f32 v26, -v27, v26, s79
	v_mul_f32_e32 v26, v27, v26
	v_exp_f32_e32 v26, v26
	s_nop 0
	v_add_f32_e32 v26, 1.0, v26
	v_rcp_f32_e32 v26, v26
	s_nop 0
	v_mul_f32_e32 v36, v27, v26
	v_mul_f32_e32 v26, 0x3dd2d3e8, v28
	v_fma_f32 v26, -v28, v26, s79
	v_mul_f32_e32 v26, v28, v26
	v_exp_f32_e32 v26, v26
	s_nop 0
	v_add_f32_e32 v26, 1.0, v26
	v_rcp_f32_e32 v26, v26
	s_nop 0
	v_mul_f32_e32 v37, v28, v26
	v_mul_f32_e32 v26, 0x3dd2d3e8, v29
	v_fma_f32 v26, -v29, v26, s79
	v_mul_f32_e32 v26, v29, v26
	v_exp_f32_e32 v26, v26
	s_nop 0
	v_add_f32_e32 v26, 1.0, v26
	v_rcp_f32_e32 v26, v26
	s_nop 0
	v_mul_f32_e32 v29, v29, v26
	v_cvt_pk_bf16_f32 v26, v30, v31
	v_add_u32_e32 v30, v148, v34
	v_mad_i64_i32 v[30:31], s[40:41], v30, s80, v[122:123]
	v_lshl_add_u64 v[30:31], v[30:31], 0, s[34:35]
	v_lshl_add_u64 v[30:31], v[30:31], 0, v[180:181]
	v_cvt_pk_bf16_f32 v27, v32, v33
	v_cvt_pk_bf16_f32 v28, v35, v36
	v_cvt_pk_bf16_f32 v29, v37, v29
	global_store_dwordx4 v[30:31], v[26:29], off
	s_nop 1
	v_mul_f32_e32 v26, 0x3dd2d3e8, v22
	v_fma_f32 v26, -v22, v26, s79
	v_mul_f32_e32 v26, v22, v26
	v_exp_f32_e32 v26, v26
	s_nop 0
	v_add_f32_e32 v26, 1.0, v26
	v_rcp_f32_e32 v26, v26
	s_nop 0
	v_mul_f32_e32 v22, v22, v26
	v_mul_f32_e32 v26, 0x3dd2d3e8, v23
	v_fma_f32 v26, -v23, v26, s79
	v_mul_f32_e32 v26, v23, v26
	v_exp_f32_e32 v26, v26
	s_nop 0
	v_add_f32_e32 v26, 1.0, v26
	v_rcp_f32_e32 v26, v26
	s_nop 0
	v_mul_f32_e32 v23, v23, v26
	v_mul_f32_e32 v26, 0x3dd2d3e8, v24
	v_fma_f32 v26, -v24, v26, s79
	v_mul_f32_e32 v26, v24, v26
	v_exp_f32_e32 v26, v26
	s_nop 0
	v_add_f32_e32 v26, 1.0, v26
	v_rcp_f32_e32 v26, v26
	s_nop 0
	v_mul_f32_e32 v24, v24, v26
	v_mul_f32_e32 v26, 0x3dd2d3e8, v25
	v_fma_f32 v26, -v25, v26, s79
	v_mul_f32_e32 v26, v25, v26
	v_exp_f32_e32 v26, v26
	s_nop 0
	v_add_f32_e32 v26, 1.0, v26
	v_rcp_f32_e32 v26, v26
	s_nop 0
	v_mul_f32_e32 v25, v25, v26
	v_mul_f32_e32 v26, 0x3dd2d3e8, v18
	v_fma_f32 v26, -v18, v26, s79
	v_mul_f32_e32 v26, v18, v26
	v_exp_f32_e32 v26, v26
	s_nop 0
	v_add_f32_e32 v26, 1.0, v26
	v_rcp_f32_e32 v26, v26
	s_nop 0
	v_mul_f32_e32 v26, v18, v26
	v_mul_f32_e32 v18, 0x3dd2d3e8, v19
	v_fma_f32 v18, -v19, v18, s79
	v_mul_f32_e32 v18, v19, v18
	v_exp_f32_e32 v18, v18
	s_nop 0
	v_add_f32_e32 v18, 1.0, v18
	v_rcp_f32_e32 v18, v18
	s_nop 0
	v_mul_f32_e32 v27, v19, v18
	v_mul_f32_e32 v18, 0x3dd2d3e8, v20
	v_fma_f32 v18, -v20, v18, s79
	v_mul_f32_e32 v18, v20, v18
	v_exp_f32_e32 v18, v18
	s_nop 0
	v_add_f32_e32 v18, 1.0, v18
	v_rcp_f32_e32 v18, v18
	s_nop 0
	v_mul_f32_e32 v28, v20, v18
	v_mul_f32_e32 v18, 0x3dd2d3e8, v21
	v_fma_f32 v18, -v21, v18, s79
	v_mul_f32_e32 v18, v21, v18
	v_exp_f32_e32 v18, v18
	s_nop 0
	v_add_f32_e32 v18, 1.0, v18
	v_rcp_f32_e32 v18, v18
	s_nop 0
	v_mul_f32_e32 v21, v21, v18
	v_cvt_pk_bf16_f32 v18, v22, v23
	v_add_u32_e32 v22, v124, v34
	v_mad_i64_i32 v[22:23], s[40:41], v22, s80, v[122:123]
	v_lshl_add_u64 v[22:23], v[22:23], 0, s[34:35]
	v_lshl_add_u64 v[22:23], v[22:23], 0, v[180:181]
	v_cvt_pk_bf16_f32 v19, v24, v25
	v_cvt_pk_bf16_f32 v20, v26, v27
	v_cvt_pk_bf16_f32 v21, v28, v21
	global_store_dwordx4 v[22:23], v[18:21], off
	s_nop 1
	v_mul_f32_e32 v19, 0x3dd2d3e8, v14
	v_fma_f32 v19, -v14, v19, s79
	v_mul_f32_e32 v19, v14, v19
	v_exp_f32_e32 v19, v19
	v_add_u32_e32 v18, 0xb00, v149
	v_add_f32_e32 v19, 1.0, v19
	v_rcp_f32_e32 v19, v19
	s_nop 0
	v_mul_f32_e32 v14, v14, v19
	v_mul_f32_e32 v19, 0x3dd2d3e8, v15
	v_fma_f32 v19, -v15, v19, s79
	v_mul_f32_e32 v19, v15, v19
	v_exp_f32_e32 v19, v19
	s_nop 0
	v_add_f32_e32 v19, 1.0, v19
	v_rcp_f32_e32 v19, v19
	s_nop 0
	v_mul_f32_e32 v15, v15, v19
	v_mul_f32_e32 v19, 0x3dd2d3e8, v16
	v_fma_f32 v19, -v16, v19, s79
	v_mul_f32_e32 v19, v16, v19
	v_exp_f32_e32 v19, v19
	s_nop 0
	v_add_f32_e32 v19, 1.0, v19
	v_rcp_f32_e32 v19, v19
	s_nop 0
	v_mul_f32_e32 v16, v16, v19
	v_mul_f32_e32 v19, 0x3dd2d3e8, v17
	v_fma_f32 v19, -v17, v19, s79
	v_mul_f32_e32 v19, v17, v19
	v_exp_f32_e32 v19, v19
	s_nop 0
	v_add_f32_e32 v19, 1.0, v19
	v_rcp_f32_e32 v19, v19
	s_nop 0
	v_mul_f32_e32 v17, v17, v19
	v_mul_f32_e32 v19, 0x3dd2d3e8, v10
	v_fma_f32 v19, -v10, v19, s79
	v_mul_f32_e32 v19, v10, v19
	v_exp_f32_e32 v19, v19
	s_nop 0
	v_add_f32_e32 v19, 1.0, v19
	v_rcp_f32_e32 v19, v19
	s_nop 0
	v_mul_f32_e32 v19, v10, v19
	v_mul_f32_e32 v10, 0x3dd2d3e8, v11
	v_fma_f32 v10, -v11, v10, s79
	v_mul_f32_e32 v10, v11, v10
	v_exp_f32_e32 v10, v10
	s_nop 0
	v_add_f32_e32 v10, 1.0, v10
	v_rcp_f32_e32 v10, v10
	s_nop 0
	v_mul_f32_e32 v20, v11, v10
	v_mul_f32_e32 v10, 0x3dd2d3e8, v12
	v_fma_f32 v10, -v12, v10, s79
	v_mul_f32_e32 v10, v12, v10
	v_exp_f32_e32 v10, v10
	s_nop 0
	v_add_f32_e32 v10, 1.0, v10
	v_rcp_f32_e32 v10, v10
	s_nop 0
	v_mul_f32_e32 v21, v12, v10
	v_mul_f32_e32 v10, 0x3dd2d3e8, v13
	v_fma_f32 v10, -v13, v10, s79
	v_mul_f32_e32 v10, v13, v10
	v_exp_f32_e32 v10, v10
	s_nop 0
	v_add_f32_e32 v10, 1.0, v10
	v_rcp_f32_e32 v10, v10
	s_nop 0
	v_mul_f32_e32 v13, v13, v10
	v_cvt_pk_bf16_f32 v10, v14, v15
	v_add_u32_e32 v14, v148, v18
	v_mad_i64_i32 v[14:15], s[40:41], v14, s80, v[122:123]
	v_lshl_add_u64 v[14:15], v[14:15], 0, s[34:35]
	v_lshl_add_u64 v[14:15], v[14:15], 0, v[180:181]
	v_cvt_pk_bf16_f32 v11, v16, v17
	v_cvt_pk_bf16_f32 v12, v19, v20
	v_cvt_pk_bf16_f32 v13, v21, v13
	global_store_dwordx4 v[14:15], v[10:13], off
	s_nop 1
	v_mul_f32_e32 v10, 0x3dd2d3e8, v6
	v_fma_f32 v10, -v6, v10, s79
	v_mul_f32_e32 v10, v6, v10
	v_exp_f32_e32 v10, v10
	s_nop 0
	v_add_f32_e32 v10, 1.0, v10
	v_rcp_f32_e32 v10, v10
	s_nop 0
	v_mul_f32_e32 v6, v6, v10
	v_mul_f32_e32 v10, 0x3dd2d3e8, v7
	v_fma_f32 v10, -v7, v10, s79
	v_mul_f32_e32 v10, v7, v10
	v_exp_f32_e32 v10, v10
	s_nop 0
	v_add_f32_e32 v10, 1.0, v10
	v_rcp_f32_e32 v10, v10
	s_nop 0
	v_mul_f32_e32 v7, v7, v10
	v_mul_f32_e32 v10, 0x3dd2d3e8, v8
	v_fma_f32 v10, -v8, v10, s79
	v_mul_f32_e32 v10, v8, v10
	v_exp_f32_e32 v10, v10
	s_nop 0
	v_add_f32_e32 v10, 1.0, v10
	v_rcp_f32_e32 v10, v10
	s_nop 0
	v_mul_f32_e32 v8, v8, v10
	v_mul_f32_e32 v10, 0x3dd2d3e8, v9
	v_fma_f32 v10, -v9, v10, s79
	v_mul_f32_e32 v10, v9, v10
	v_exp_f32_e32 v10, v10
	s_nop 0
	v_add_f32_e32 v10, 1.0, v10
	v_rcp_f32_e32 v10, v10
	s_nop 0
	v_mul_f32_e32 v9, v9, v10
	v_mul_f32_e32 v10, 0x3dd2d3e8, v2
	v_fma_f32 v10, -v2, v10, s79
	v_mul_f32_e32 v10, v2, v10
	v_exp_f32_e32 v10, v10
	s_nop 0
	v_add_f32_e32 v10, 1.0, v10
	v_rcp_f32_e32 v10, v10
	s_nop 0
	v_mul_f32_e32 v10, v2, v10
	v_mul_f32_e32 v2, 0x3dd2d3e8, v3
	v_fma_f32 v2, -v3, v2, s79
	v_mul_f32_e32 v2, v3, v2
	v_exp_f32_e32 v2, v2
	s_nop 0
	v_add_f32_e32 v2, 1.0, v2
	v_rcp_f32_e32 v2, v2
	s_nop 0
	v_mul_f32_e32 v11, v3, v2
	v_mul_f32_e32 v2, 0x3dd2d3e8, v4
	v_fma_f32 v2, -v4, v2, s79
	v_mul_f32_e32 v2, v4, v2
	v_exp_f32_e32 v2, v2
	s_nop 0
	v_add_f32_e32 v2, 1.0, v2
	v_rcp_f32_e32 v2, v2
	s_nop 0
	v_mul_f32_e32 v12, v4, v2
	v_mul_f32_e32 v2, 0x3dd2d3e8, v5
	v_fma_f32 v2, -v5, v2, s79
	v_mul_f32_e32 v2, v5, v2
	v_exp_f32_e32 v2, v2
	s_nop 0
	v_add_f32_e32 v2, 1.0, v2
	v_rcp_f32_e32 v2, v2
	s_nop 0
	v_mul_f32_e32 v5, v5, v2
	v_cvt_pk_bf16_f32 v2, v6, v7
	v_add_u32_e32 v6, v124, v18
	v_mad_i64_i32 v[6:7], s[40:41], v6, s80, v[122:123]
	v_lshl_add_u64 v[6:7], v[6:7], 0, s[34:35]
	v_lshl_add_u64 v[6:7], v[6:7], 0, v[180:181]
	v_cvt_pk_bf16_f32 v3, v8, v9
	v_cvt_pk_bf16_f32 v4, v10, v11
	v_cvt_pk_bf16_f32 v5, v12, v5
	global_store_dwordx4 v[6:7], v[2:5], off
	s_and_b64 vcc, exec, s[38:39]
	s_mov_b64 s[34:35], -1
	s_cbranch_vccnz .LBB0_817
	s_andn2_b64 vcc, exec, s[18:19]
	s_cbranch_vccnz .LBB0_816
	s_branch .LBB0_816

.LBB0_921:
	v_ashrrev_i32_e32 v3, 31, v15
	v_lshrrev_b32_e32 v3, 26, v3
	v_add_u32_e32 v3, v15, v3
	v_ashrrev_i32_e32 v10, 6, v3
	v_bfe_i32 v3, v15, 27, 1
	v_lshlrev_b32_e32 v2, 4, v15
	v_lshrrev_b32_e32 v3, 22, v3
	v_add_u32_e32 v3, v2, v3
	v_and_b32_e32 v3, 0xfffffc00, v3
	v_sub_u32_e32 v3, v2, v3
	v_lshrrev_b32_e32 v4, 4, v3
	v_bitop3_b32 v3, v4, v3, 32 bitop3:0x6c
	v_ashrrev_i32_e32 v5, 31, v3
	v_lshrrev_b32_e32 v5, 26, v5
	v_lshlrev_b32_e32 v4, 3, v10
	v_add_u32_e32 v5, v3, v5
	v_and_b32_e32 v4, -16, v4
	v_ashrrev_i32_e32 v12, 6, v5
	v_and_b32_e32 v5, 0xc0, v5
	v_readlane_b32 s8, v255, 41
	v_add_u32_e32 v4, v12, v4
	v_lshlrev_b32_e32 v6, 5, v10
	v_sub_u32_e32 v3, v3, v5
	s_mul_i32 s12, s8, 0x240000
	s_waitcnt lgkmcnt(0)
	s_add_u32 s10, s22, 0x39600000
	v_and_b32_e32 v11, 32, v6
	v_ashrrev_i16_sdwa v3, v224, sext(v3) dst_sel:DWORD dst_unused:UNUSED_PAD src0_sel:DWORD src1_sel:BYTE_0
	v_lshlrev_b32_e32 v5, 1, v4
	v_lshrrev_b32_e32 v6, 2, v4
	v_and_b32_e32 v7, 3, v12
	s_mov_b32 s21, 0x7fffe0
	s_addc_u32 s11, s23, 0
	s_lshl_b64 s[8:9], s[12:13], 1
	v_bfe_i32 v13, v3, 0, 16
	v_and_b32_e32 v5, 24, v5
	v_and_b32_e32 v6, 4, v6
	v_and_or_b32 v7, v4, s21, v7
	s_movk_i32 s12, 0x600
	v_add_u32_e32 v3, v11, v13
	v_or3_b32 v5, v7, v6, v5
	v_mul_lo_u32 v4, v4, s12
	s_waitcnt vmcnt(1)
	v_add_lshl_u32 v130, v3, v4, 1
	v_mul_u32_u24_e32 v4, 0x600, v5
	v_add_u32_e32 v2, 0x2000, v2
	v_add_lshl_u32 v180, v4, v3, 1
	v_ashrrev_i32_e32 v3, 31, v2
	v_lshrrev_b32_e32 v3, 22, v3
	v_add_u32_e32 v3, v2, v3
	v_ashrrev_i32_e32 v14, 10, v3
	v_mul_i32_i24_e32 v3, 0x400, v14
	v_sub_u32_e32 v2, v2, v3
	v_lshrrev_b32_e32 v3, 4, v2
	v_bitop3_b32 v2, v3, v2, 32 bitop3:0x6c
	v_ashrrev_i32_e32 v4, 31, v2
	v_lshrrev_b32_e32 v4, 26, v4
	s_add_u32 s8, s22, s8
	v_lshlrev_b32_e32 v3, 3, v14
	v_add_u32_e32 v4, v2, v4
	s_addc_u32 s9, s23, s9
	v_and_b32_e32 v3, -16, v3
	v_ashrrev_i32_e32 v17, 6, v4
	s_add_u32 s8, s8, 0x4d00000
	v_add_u32_e32 v3, v17, v3
	v_lshlrev_b32_e32 v5, 5, v14
	v_and_b32_e32 v4, 0xc0, v4
	v_and_b32_e32 v6, 3, v17
	s_addc_u32 s9, s9, 0
	v_and_b32_e32 v16, 32, v5
	v_sub_u32_e32 v2, v2, v4
	v_lshlrev_b32_e32 v4, 1, v3
	v_lshrrev_b32_e32 v5, 2, v3
	v_and_or_b32 v6, v3, s21, v6
	v_mul_lo_u32 v3, v3, s12
	s_add_i32 s12, s14, s15
	s_mul_hi_i32 s14, s12, 0x2aaaaaab
	s_lshr_b32 s15, s14, 31
	s_ashr_i32 s14, s14, 3
	v_ashrrev_i16_sdwa v2, v224, sext(v2) dst_sel:DWORD dst_unused:UNUSED_PAD src0_sel:DWORD src1_sel:BYTE_0
	s_add_i32 s14, s14, s15
	v_bfe_i32 v18, v2, 0, 16
	v_and_b32_e32 v4, 24, v4
	v_and_b32_e32 v5, 4, v5
	s_lshl_b32 s27, s14, 3
	v_add_u32_e32 v2, v16, v18
	v_or3_b32 v4, v6, v5, v4
	s_sub_i32 s15, 33, s27
	s_waitcnt vmcnt(0)
	v_add_lshl_u32 v132, v2, v3, 1
	v_mul_u32_u24_e32 v3, 0x600, v4
	s_min_u32 s28, s15, 8
	s_mul_i32 s14, s14, 48
	v_add_lshl_u32 v134, v3, v2, 1
	s_sub_i32 s29, s12, s14
	v_cvt_f32_ubyte0_e32 v3, s28
	v_cvt_f32_i32_e32 v2, s29
	v_rcp_iflag_f32_e32 v4, v3
	s_ashr_i32 s26, s24, 6
	s_ashr_i32 s12, s29, 30
	s_ashr_i32 s25, s24, 8
	v_mul_f32_e32 v4, v2, v4
	v_trunc_f32_e32 v4, v4
	v_fma_f32 v2, -v4, v3, v2
	v_cvt_i32_f32_e32 v4, v4
	s_lshl_b32 s21, s26, 10
	s_or_b32 s12, s12, 1
	v_cmp_ge_f32_e64 s[14:15], |v2|, v3
	s_and_b64 s[14:15], s[14:15], exec
	s_cselect_b32 s12, s12, 0
	v_readfirstlane_b32 s14, v4
	s_add_i32 s12, s14, s12
	s_mul_i32 s14, s12, s28
	s_sub_i32 s14, s29, s14
	s_sext_i32_i8 s14, s14
	s_add_i32 s56, s27, s14
	s_bfe_i64 s[14:15], s[12:13], 0x80000
	s_mul_hi_i32 s15, s14, 0xc0000
	s_mul_i32 s14, s14, 0xc0000
	s_add_u32 s34, s8, s14
	s_addc_u32 s35, s9, s15
	s_add_i32 s44, s21, 0
	s_add_i32 m0, s44, 0x10000
	s_mul_i32 s28, s56, 0xc0000
	global_load_lds_dwordx4 v180, s[34:35]
	s_add_i32 m0, s44, 0x12000
	s_add_u32 s14, s34, 0x60000
	global_load_lds_dwordx4 v134, s[34:35]
	s_addc_u32 s15, s35, 0
	s_add_i32 m0, s44, 0x14000
	s_mul_hi_i32 s27, s56, 0xc0000
	global_load_lds_dwordx4 v180, s[14:15]
	s_add_i32 m0, s44, 0x16000
	s_add_u32 s30, s10, s28
	s_addc_u32 s31, s11, s27
	s_add_i32 s45, s44, 0x2000
	global_load_lds_dwordx4 v134, s[14:15]
	s_mov_b32 m0, s44
	s_add_u32 s14, s30, 0x60000
	global_load_lds_dwordx4 v130, s[30:31]
	s_mov_b32 m0, s45
	s_addc_u32 s15, s31, 0
	s_add_i32 s46, s44, 0x4000
	global_load_lds_dwordx4 v132, s[30:31]
	s_mov_b32 m0, s46
	s_add_i32 s47, s44, 0x6000
	global_load_lds_dwordx4 v130, s[14:15]
	s_mov_b32 m0, s47
	v_mov_b32_e32 v135, v181
	global_load_lds_dwordx4 v132, s[14:15]
	v_mov_b32_e32 v131, v181
	v_mov_b32_e32 v133, v181
	s_cmp_eq_u32 s25, 1
	v_lshl_add_u64 v[8:9], s[34:35], 0, v[180:181]
	v_lshl_add_u64 v[6:7], s[34:35], 0, v[134:135]
	v_lshl_add_u64 v[2:3], s[30:31], 0, v[130:131]
	s_cselect_b64 s[14:15], -1, 0
	s_cmp_lg_u32 s25, 1
	v_lshl_add_u64 v[4:5], s[30:31], 0, v[132:133]
	s_cbranch_scc1 .LBB0_923
.LBB0_923:
	s_sext_i32_i8 s57, s12
	v_readlane_b32 s12, v255, 41
	s_mulk_i32 s12, 0x600
	s_lshl_b64 s[28:29], s[12:13], 2
	s_add_u32 s18, s18, s28
	s_addc_u32 s19, s19, s29
	v_bfe_u32 v149, v15, 4, 2
	s_add_u32 s22, s22, 0x24600000
	v_and_b32_e32 v148, 15, v15
	v_lshlrev_b32_e32 v19, 4, v149
	v_lshlrev_b32_e32 v15, 2, v15
	s_addc_u32 s23, s23, 0
	s_lshl_b32 s12, s25, 6
	v_lshl_or_b32 v19, v148, 6, v19
	s_lshl_b32 s25, s25, 13
	v_and_b32_e32 v15, 32, v15
	v_bitop3_b32 v20, v19, s25, v15 bitop3:0xde
	s_lshl_b32 s25, s26, 5
	s_and_b32 s48, s25, 0x60
	s_add_i32 m0, s44, 0x18000
	v_lshl_add_u64 v[8:9], v[8:9], 0, s[16:17]
	s_lshl_b32 s25, s48, 7
	s_waitcnt vmcnt(2)
	s_barrier
	global_load_lds_dwordx4 v[8:9], off
	v_lshl_add_u64 v[6:7], v[6:7], 0, s[16:17]
	s_add_i32 m0, s44, 0x1a000
	s_add_i32 s49, s44, 0x8000
	s_add_i32 s50, s44, 0xa000
	global_load_lds_dwordx4 v[6:7], off
	v_lshl_add_u64 v[2:3], v[2:3], 0, s[16:17]
	s_mov_b32 m0, s49
	s_add_u32 s26, s34, 0x60080
	global_load_lds_dwordx4 v[2:3], off
	v_lshl_add_u64 v[2:3], v[4:5], 0, s[16:17]
	s_mov_b32 m0, s50
	s_addc_u32 s27, s35, 0
	global_load_lds_dwordx4 v[2:3], off
	s_add_i32 m0, s44, 0x1c000
	v_lshl_add_u64 v[2:3], s[26:27], 0, v[180:181]
	global_load_lds_dwordx4 v[2:3], off
	v_lshl_add_u64 v[2:3], s[26:27], 0, v[134:135]
	s_add_i32 m0, s44, 0x1e000
	s_movk_i32 s29, 0x600
	global_load_lds_dwordx4 v[2:3], off
	v_lshrrev_b32_e32 v3, 1, v10
	v_mul_lo_u32 v2, v12, s29
	s_movk_i32 s28, 0x6000
	v_mad_u64_u32 v[2:3], s[26:27], v3, s28, v[2:3]
	v_or_b32_e32 v2, v2, v11
	v_add_lshl_u32 v2, v2, v13, 1
	v_mov_b32_e32 v3, v181
	s_mov_b64 s[36:37], 0x60080
	v_lshl_add_u64 v[136:137], v[2:3], 0, s[36:37]
	v_lshrrev_b32_e32 v3, 1, v14
	v_mul_lo_u32 v2, v17, s29
	v_mad_u64_u32 v[2:3], s[26:27], v3, s28, v[2:3]
	s_waitcnt vmcnt(6)
	v_or_b32_e32 v2, v2, v16
	s_cmpk_lt_u32 s24, 0x100
	v_add_lshl_u32 v2, v2, v18, 1
	v_mov_b32_e32 v3, v181
	v_bitop3_b32 v150, v19, s25, v15 bitop3:0xde
	s_cselect_b64 s[24:25], -1, 0
	v_lshl_add_u64 v[138:139], v[2:3], 0, s[36:37]
	s_mov_b32 s51, 0
	v_add_u32_e32 v151, 0, v20
	s_barrier
	s_branch .LBB0_926

.LBB0_937:
	s_add_u32 s34, s30, 0x100
	s_addc_u32 s35, s31, 0
	s_add_i32 s61, 0, 0x10000
	s_cmp_eq_u32 s60, 20
	s_cselect_b32 s43, s27, s35
	s_cselect_b32 s42, s26, s34
	s_cselect_b32 s41, s29, s59
	s_cselect_b32 s40, s28, s58
	s_add_i32 s62, 0, 0x14000
	v_add_u32_e32 v156, s61, v150
	v_add_u32_e32 v172, s62, v150
	ds_read_b128 v[140:143], v156
	ds_read_b128 v[144:147], v156 offset:1024
	ds_read_b128 v[152:155], v156 offset:2048
	ds_read_b128 v[156:159], v156 offset:3072
	ds_read_b128 v[160:163], v172
	ds_read_b128 v[164:167], v172 offset:1024
	ds_read_b128 v[168:171], v172 offset:2048
	ds_read_b128 v[172:175], v172 offset:3072
	v_lshl_add_u64 v[218:219], s[30:31], 0, v[136:137]
	s_add_i32 m0, s44, 0xc000
	ds_read_b128 v[176:179], v151
	ds_read_b128 v[190:193], v151 offset:1024
	ds_read_b128 v[194:197], v151 offset:2048
	ds_read_b128 v[198:201], v151 offset:3072
	ds_read_b128 v[202:205], v151 offset:4096
	ds_read_b128 v[206:209], v151 offset:5120
	ds_read_b128 v[210:213], v151 offset:6144
	ds_read_b128 v[214:217], v151 offset:7168
	global_load_lds_dwordx4 v[218:219], off
	v_lshl_add_u64 v[218:219], s[30:31], 0, v[138:139]
	s_add_i32 m0, s44, 0xe000
	s_nop 0
	global_load_lds_dwordx4 v[218:219], off
	s_waitcnt vmcnt(8)
	s_waitcnt lgkmcnt(0)
	s_cmp_eq_u32 s100, 0
	s_cbranch_scc1 .Lmy_h2_17
	s_setprio 1
	s_barrier
.Lmy_h2_17:
	v_mfma_f32_16x16x32_bf16 v[126:129], v[140:143], v[176:179], v[126:129]
	v_mfma_f32_16x16x32_bf16 v[122:125], v[152:155], v[176:179], v[122:125]
	v_mfma_f32_16x16x32_bf16 v[110:113], v[140:143], v[194:197], v[110:113]
	v_mfma_f32_16x16x32_bf16 v[106:109], v[152:155], v[194:197], v[106:109]
	v_mfma_f32_16x16x32_bf16 v[94:97], v[140:143], v[202:205], v[94:97]
	v_mfma_f32_16x16x32_bf16 v[90:93], v[152:155], v[202:205], v[90:93]
	v_mfma_f32_16x16x32_bf16 v[78:81], v[140:143], v[210:213], v[78:81]
	v_mfma_f32_16x16x32_bf16 v[74:77], v[152:155], v[210:213], v[74:77]
	v_mfma_f32_16x16x32_bf16 v[126:129], v[144:147], v[190:193], v[126:129]
	v_mfma_f32_16x16x32_bf16 v[122:125], v[156:159], v[190:193], v[122:125]
	v_mfma_f32_16x16x32_bf16 v[110:113], v[144:147], v[198:201], v[110:113]
	v_mfma_f32_16x16x32_bf16 v[106:109], v[156:159], v[198:201], v[106:109]
	v_mfma_f32_16x16x32_bf16 v[94:97], v[144:147], v[206:209], v[94:97]
	v_mfma_f32_16x16x32_bf16 v[90:93], v[156:159], v[206:209], v[90:93]
	v_mfma_f32_16x16x32_bf16 v[78:81], v[144:147], v[214:217], v[78:81]
	v_mfma_f32_16x16x32_bf16 v[74:77], v[156:159], v[214:217], v[74:77]
	v_mfma_f32_16x16x32_bf16 v[118:121], v[160:163], v[176:179], v[118:121]
	v_mfma_f32_16x16x32_bf16 v[114:117], v[168:171], v[176:179], v[114:117]
	v_mfma_f32_16x16x32_bf16 v[102:105], v[160:163], v[194:197], v[102:105]
	v_mfma_f32_16x16x32_bf16 v[98:101], v[168:171], v[194:197], v[98:101]
	v_mfma_f32_16x16x32_bf16 v[86:89], v[160:163], v[202:205], v[86:89]
	v_mfma_f32_16x16x32_bf16 v[82:85], v[168:171], v[202:205], v[82:85]
	v_mfma_f32_16x16x32_bf16 v[70:73], v[160:163], v[210:213], v[70:73]
	v_mfma_f32_16x16x32_bf16 v[66:69], v[168:171], v[210:213], v[66:69]
	v_mfma_f32_16x16x32_bf16 v[118:121], v[164:167], v[190:193], v[118:121]
	v_mfma_f32_16x16x32_bf16 v[114:117], v[172:175], v[190:193], v[114:117]
	v_mfma_f32_16x16x32_bf16 v[102:105], v[164:167], v[198:201], v[102:105]
	v_mfma_f32_16x16x32_bf16 v[98:101], v[172:175], v[198:201], v[98:101]
	v_mfma_f32_16x16x32_bf16 v[86:89], v[164:167], v[206:209], v[86:89]
	v_mfma_f32_16x16x32_bf16 v[82:85], v[172:175], v[206:209], v[82:85]
	v_mfma_f32_16x16x32_bf16 v[70:73], v[164:167], v[214:217], v[70:73]
	v_mfma_f32_16x16x32_bf16 v[66:69], v[172:175], v[214:217], v[66:69]
	s_cmp_lg_u32 s100, 0
	s_cbranch_scc1 .Lmy_h2_18
	s_barrier
.Lmy_h2_18:
	s_setprio 0
	s_add_i32 s30, s61, s21
	v_lshl_add_u64 v[218:219], s[40:41], 0, v[180:181]
	s_mov_b32 m0, s30
	ds_read_b128 v[176:179], v151 offset:16384
	ds_read_b128 v[190:193], v151 offset:17408
	ds_read_b128 v[194:197], v151 offset:18432
	ds_read_b128 v[198:201], v151 offset:19456
	ds_read_b128 v[202:205], v151 offset:20480
	ds_read_b128 v[206:209], v151 offset:21504
	ds_read_b128 v[210:213], v151 offset:22528
	ds_read_b128 v[214:217], v151 offset:23552
	global_load_lds_dwordx4 v[218:219], off
	s_add_i32 m0, s30, 0x2000
	s_add_u32 s30, s40, 0x60000
	v_lshl_add_u64 v[220:221], s[40:41], 0, v[134:135]
	s_addc_u32 s31, s41, 0
	s_add_i32 s61, s62, s21
	global_load_lds_dwordx4 v[220:221], off
	v_lshl_add_u64 v[222:223], s[30:31], 0, v[180:181]
	s_mov_b32 m0, s61
	v_lshl_add_u64 v[238:239], s[42:43], 0, v[132:133]
	global_load_lds_dwordx4 v[222:223], off
	v_lshl_add_u64 v[222:223], s[30:31], 0, v[134:135]
	s_add_i32 m0, s61, 0x2000
	s_nop 0
	global_load_lds_dwordx4 v[222:223], off
	v_lshl_add_u64 v[222:223], s[42:43], 0, v[130:131]
	s_mov_b32 m0, s44
	s_nop 0
	global_load_lds_dwordx4 v[222:223], off
	s_mov_b32 m0, s45
	s_nop 0
	global_load_lds_dwordx4 v[238:239], off
	s_waitcnt vmcnt(8)
	s_waitcnt lgkmcnt(0)
	s_cmp_eq_u32 s100, 0
	s_cbranch_scc1 .Lmy_h2_19
	s_setprio 1
	s_barrier
.Lmy_h2_19:
	v_mfma_f32_16x16x32_bf16 v[62:65], v[140:143], v[176:179], v[62:65]
	v_mfma_f32_16x16x32_bf16 v[58:61], v[152:155], v[176:179], v[58:61]
	v_mfma_f32_16x16x32_bf16 v[46:49], v[140:143], v[194:197], v[46:49]
	v_mfma_f32_16x16x32_bf16 v[42:45], v[152:155], v[194:197], v[42:45]
	v_mfma_f32_16x16x32_bf16 v[30:33], v[140:143], v[202:205], v[30:33]
	v_mfma_f32_16x16x32_bf16 v[26:29], v[152:155], v[202:205], v[26:29]
	v_mfma_f32_16x16x32_bf16 v[14:17], v[140:143], v[210:213], v[14:17]
	v_mfma_f32_16x16x32_bf16 v[10:13], v[152:155], v[210:213], v[10:13]
	v_mfma_f32_16x16x32_bf16 v[62:65], v[144:147], v[190:193], v[62:65]
	v_mfma_f32_16x16x32_bf16 v[58:61], v[156:159], v[190:193], v[58:61]
	v_mfma_f32_16x16x32_bf16 v[46:49], v[144:147], v[198:201], v[46:49]
	v_mfma_f32_16x16x32_bf16 v[42:45], v[156:159], v[198:201], v[42:45]
	v_mfma_f32_16x16x32_bf16 v[30:33], v[144:147], v[206:209], v[30:33]
	v_mfma_f32_16x16x32_bf16 v[26:29], v[156:159], v[206:209], v[26:29]
	v_mfma_f32_16x16x32_bf16 v[14:17], v[144:147], v[214:217], v[14:17]
	v_mfma_f32_16x16x32_bf16 v[10:13], v[156:159], v[214:217], v[10:13]
	v_mfma_f32_16x16x32_bf16 v[54:57], v[160:163], v[176:179], v[54:57]
	v_mfma_f32_16x16x32_bf16 v[50:53], v[168:171], v[176:179], v[50:53]
	v_mfma_f32_16x16x32_bf16 v[38:41], v[160:163], v[194:197], v[38:41]
	v_mfma_f32_16x16x32_bf16 v[34:37], v[168:171], v[194:197], v[34:37]
	v_mfma_f32_16x16x32_bf16 v[22:25], v[160:163], v[202:205], v[22:25]
	v_mfma_f32_16x16x32_bf16 v[18:21], v[168:171], v[202:205], v[18:21]
	v_mfma_f32_16x16x32_bf16 v[6:9], v[160:163], v[210:213], v[6:9]
	v_mfma_f32_16x16x32_bf16 v[2:5], v[168:171], v[210:213], v[2:5]
	v_mfma_f32_16x16x32_bf16 v[54:57], v[164:167], v[190:193], v[54:57]
	v_mfma_f32_16x16x32_bf16 v[50:53], v[172:175], v[190:193], v[50:53]
	v_mfma_f32_16x16x32_bf16 v[38:41], v[164:167], v[198:201], v[38:41]
	v_mfma_f32_16x16x32_bf16 v[34:37], v[172:175], v[198:201], v[34:37]
	v_mfma_f32_16x16x32_bf16 v[22:25], v[164:167], v[206:209], v[22:25]
	v_mfma_f32_16x16x32_bf16 v[18:21], v[172:175], v[206:209], v[18:21]
	v_mfma_f32_16x16x32_bf16 v[6:9], v[164:167], v[214:217], v[6:9]
	v_mfma_f32_16x16x32_bf16 v[2:5], v[172:175], v[214:217], v[2:5]
	s_cmp_lg_u32 s100, 0
	s_cbranch_scc1 .Lmy_h2_20
	s_barrier
.Lmy_h2_20:
	s_setprio 0
	s_add_i32 s61, 0, 0x18000
	s_add_i32 s62, 0, 0x1c000
	v_add_u32_e32 v156, s61, v150
	v_add_u32_e32 v172, s62, v150
	ds_read_b128 v[140:143], v156
	ds_read_b128 v[144:147], v156 offset:1024
	ds_read_b128 v[152:155], v156 offset:2048
	ds_read_b128 v[156:159], v156 offset:3072
	ds_read_b128 v[160:163], v172
	ds_read_b128 v[164:167], v172 offset:1024
	ds_read_b128 v[168:171], v172 offset:2048
	ds_read_b128 v[172:175], v172 offset:3072
	s_add_u32 s30, s42, 0x60000
	s_addc_u32 s31, s43, 0
	s_mov_b32 m0, s46
	v_lshl_add_u64 v[240:241], s[30:31], 0, v[130:131]
	ds_read_b128 v[176:179], v151 offset:32768
	ds_read_b128 v[190:193], v151 offset:33792
	ds_read_b128 v[194:197], v151 offset:34816
	ds_read_b128 v[198:201], v151 offset:35840
	ds_read_b128 v[202:205], v151 offset:36864
	ds_read_b128 v[206:209], v151 offset:37888
	ds_read_b128 v[210:213], v151 offset:38912
	ds_read_b128 v[214:217], v151 offset:39936
	global_load_lds_dwordx4 v[240:241], off
	v_lshl_add_u64 v[240:241], s[30:31], 0, v[132:133]
	s_mov_b32 m0, s47
	s_nop 0
	global_load_lds_dwordx4 v[240:241], off
	s_waitcnt vmcnt(8)
	s_waitcnt lgkmcnt(0)
	s_cmp_eq_u32 s100, 0
	s_cbranch_scc1 .Lmy_h2_21
	s_setprio 1
	s_barrier

.Lmy_h2_22:
	s_setprio 0
	s_add_i32 s30, s61, s21
	v_lshl_add_u64 v[218:219], v[218:219], 0, s[16:17]
	s_mov_b32 m0, s30
	ds_read_b128 v[176:179], v151 offset:49152
	ds_read_b128 v[190:193], v151 offset:50176
	ds_read_b128 v[194:197], v151 offset:51200
	ds_read_b128 v[198:201], v151 offset:52224
	ds_read_b128 v[202:205], v151 offset:53248
	ds_read_b128 v[206:209], v151 offset:54272
	ds_read_b128 v[210:213], v151 offset:55296
	ds_read_b128 v[214:217], v151 offset:56320
	global_load_lds_dwordx4 v[218:219], off
	s_add_i32 m0, s30, 0x2000
	s_add_u32 s30, s40, 0x60080
	v_lshl_add_u64 v[218:219], v[220:221], 0, s[16:17]
	s_addc_u32 s31, s41, 0
	s_add_i32 s40, s62, s21
	global_load_lds_dwordx4 v[218:219], off
	v_lshl_add_u64 v[218:219], s[30:31], 0, v[180:181]
	s_mov_b32 m0, s40
	s_nop 0
	global_load_lds_dwordx4 v[218:219], off
	v_lshl_add_u64 v[218:219], s[30:31], 0, v[134:135]
	s_add_i32 m0, s40, 0x2000
	s_nop 0
	global_load_lds_dwordx4 v[218:219], off
	v_lshl_add_u64 v[218:219], v[222:223], 0, s[16:17]
	s_mov_b32 m0, s49
	s_nop 0
	global_load_lds_dwordx4 v[218:219], off
	v_lshl_add_u64 v[218:219], v[238:239], 0, s[16:17]
	s_mov_b32 m0, s50
	s_nop 0
	global_load_lds_dwordx4 v[218:219], off
	s_waitcnt vmcnt(8)
	s_waitcnt lgkmcnt(0)
	s_cmp_eq_u32 s100, 0
	s_cbranch_scc1 .Lmy_h2_23
	s_setprio 1
	s_barrier

.Lmy_h2_24:
	s_setprio 0
	s_add_i32 s60, s60, 2
	s_add_u32 s58, s58, 0x100
	s_addc_u32 s59, s59, 0
	s_cmp_gt_u32 s60, 21
	s_mov_b64 s[30:31], s[34:35]
	s_cbranch_scc0 .LBB0_937
	s_and_b64 vcc, exec, s[24:25]
	s_cbranch_vccz .LBB0_940
.LBB0_940:
	s_lshl_b32 s30, s56, 8
	v_mov_b32_e32 v140, v148
	v_mov_b32_e32 v141, v149
	s_add_i32 s30, s30, s12
	v_mov_b64_e32 v[144:145], s[10:11]
	v_add_u32_e32 v146, s30, v140
	s_lshl_b32 s30, s57, 8
	s_or_b32 s30, s30, s48
	v_lshl_add_u32 v142, v141, 3, s30
	v_ashrrev_i32_e32 v143, 31, v142
	v_lshl_add_u64 v[140:141], v[142:143], 2, s[18:19]
	global_load_dwordx4 v[152:155], v[140:141], off offset:16
	global_load_dwordx4 v[156:159], v[140:141], off
	v_mad_i64_i32 v[160:161], s[30:31], v146, s80, v[144:145]
	v_lshlrev_b64 v[142:143], 1, v[142:143]
	v_lshl_add_u64 v[164:165], v[160:161], 0, v[142:143]
	global_load_dwordx4 v[160:163], v[164:165], off
	v_ashrrev_i32_e32 v147, 31, v146
	v_lshlrev_b64 v[166:167], 12, v[146:147]
	v_lshl_add_u64 v[166:167], s[22:23], 0, v[166:167]
	v_lshl_add_u64 v[166:167], v[166:167], 0, v[142:143]
	s_and_b64 vcc, exec, s[38:39]
	s_waitcnt vmcnt(0)
	v_pk_add_f32 v[124:125], v[124:125], v[154:155]
	v_pk_add_f32 v[128:129], v[128:129], v[158:159]
	v_pk_add_f32 v[126:127], v[126:127], v[156:157]
	v_pk_add_f32 v[122:123], v[122:123], v[152:153]
	v_mul_f32_e32 v125, 0xbfb8aa3b, v125
	v_mul_f32_e32 v126, 0xbfb8aa3b, v126
	v_mul_f32_e32 v127, 0xbfb8aa3b, v127
	v_mul_f32_e32 v128, 0xbfb8aa3b, v128
	v_mul_f32_e32 v129, 0xbfb8aa3b, v129
	v_mul_f32_e32 v122, 0xbfb8aa3b, v122
	v_mul_f32_e32 v123, 0xbfb8aa3b, v123
	v_mul_f32_e32 v124, 0xbfb8aa3b, v124
	v_exp_f32_e32 v125, v125
	v_exp_f32_e32 v126, v126
	v_exp_f32_e32 v127, v127
	v_exp_f32_e32 v128, v128
	v_exp_f32_e32 v129, v129
	v_exp_f32_e32 v122, v122
	v_exp_f32_e32 v123, v123
	v_exp_f32_e32 v124, v124
	v_add_f32_e32 v125, 1.0, v125
	v_add_f32_e32 v126, 1.0, v126
	v_add_f32_e32 v127, 1.0, v127
	v_add_f32_e32 v128, 1.0, v128
	v_add_f32_e32 v129, 1.0, v129
	v_add_f32_e32 v122, 1.0, v122
	v_add_f32_e32 v123, 1.0, v123
	v_add_f32_e32 v124, 1.0, v124
	v_rcp_f32_e32 v125, v125
	v_rcp_f32_e32 v126, v126
	v_rcp_f32_e32 v127, v127
	v_rcp_f32_e32 v128, v128
	v_rcp_f32_e32 v129, v129
	v_rcp_f32_e32 v122, v122
	v_rcp_f32_e32 v123, v123
	v_rcp_f32_e32 v124, v124
	v_and_b32_e32 v158, 0xffff0000, v163
	v_lshlrev_b32_e32 v147, 16, v160
	v_and_b32_e32 v152, 0xffff0000, v160
	v_lshlrev_b32_e32 v153, 16, v161
	v_and_b32_e32 v154, 0xffff0000, v161
	v_lshlrev_b32_e32 v155, 16, v162
	v_and_b32_e32 v156, 0xffff0000, v162
	v_lshlrev_b32_e32 v157, 16, v163
	v_mul_f32_e32 v125, v125, v158
	v_mul_f32_e32 v126, v126, v147
	v_mul_f32_e32 v127, v127, v152
	v_mul_f32_e32 v128, v128, v153
	v_mul_f32_e32 v129, v129, v154
	v_mul_f32_e32 v147, v122, v155
	v_mul_f32_e32 v152, v123, v156
	v_mul_f32_e32 v153, v124, v157
	v_cvt_pk_bf16_f32 v122, v126, v127
	v_cvt_pk_bf16_f32 v123, v128, v129
	v_cvt_pk_bf16_f32 v124, v147, v152
	v_cvt_pk_bf16_f32 v125, v153, v125
	global_store_dwordx4 v[166:167], v[122:125], off
	global_load_dwordx4 v[122:125], v[140:141], off offset:512
	global_load_dwordx4 v[126:129], v[140:141], off offset:528
	global_load_dwordx4 v[152:155], v[164:165], off offset:256
	v_add_u32_e32 v156, 16, v146
	v_ashrrev_i32_e32 v157, 31, v156
	s_waitcnt vmcnt(2)
	v_pk_add_f32 v[120:121], v[120:121], v[124:125]
	s_waitcnt vmcnt(1)
	v_pk_add_f32 v[116:117], v[116:117], v[128:129]
	v_pk_add_f32 v[118:119], v[118:119], v[122:123]
	v_pk_add_f32 v[114:115], v[114:115], v[126:127]
	v_mul_f32_e32 v117, 0xbfb8aa3b, v117
	v_mul_f32_e32 v118, 0xbfb8aa3b, v118
	v_mul_f32_e32 v119, 0xbfb8aa3b, v119
	v_mul_f32_e32 v120, 0xbfb8aa3b, v120
	v_mul_f32_e32 v121, 0xbfb8aa3b, v121
	v_mul_f32_e32 v114, 0xbfb8aa3b, v114
	v_mul_f32_e32 v115, 0xbfb8aa3b, v115
	v_mul_f32_e32 v116, 0xbfb8aa3b, v116
	v_exp_f32_e32 v117, v117
	v_exp_f32_e32 v118, v118
	v_exp_f32_e32 v119, v119
	v_exp_f32_e32 v120, v120
	v_exp_f32_e32 v121, v121
	v_exp_f32_e32 v114, v114
	v_exp_f32_e32 v115, v115
	v_exp_f32_e32 v116, v116
	v_add_f32_e32 v117, 1.0, v117
	v_add_f32_e32 v118, 1.0, v118
	v_add_f32_e32 v119, 1.0, v119
	v_add_f32_e32 v120, 1.0, v120
	v_add_f32_e32 v121, 1.0, v121
	v_add_f32_e32 v114, 1.0, v114
	v_add_f32_e32 v115, 1.0, v115
	v_add_f32_e32 v116, 1.0, v116
	v_rcp_f32_e32 v117, v117
	v_rcp_f32_e32 v118, v118
	v_rcp_f32_e32 v119, v119
	v_rcp_f32_e32 v120, v120
	v_rcp_f32_e32 v121, v121
	v_rcp_f32_e32 v114, v114
	v_rcp_f32_e32 v115, v115
	v_rcp_f32_e32 v116, v116
	s_waitcnt vmcnt(0)
	v_and_b32_e32 v129, 0xffff0000, v155
	v_lshlrev_b32_e32 v122, 16, v152
	v_and_b32_e32 v123, 0xffff0000, v152
	v_lshlrev_b32_e32 v124, 16, v153
	v_and_b32_e32 v125, 0xffff0000, v153
	v_lshlrev_b32_e32 v126, 16, v154
	v_and_b32_e32 v127, 0xffff0000, v154
	v_lshlrev_b32_e32 v128, 16, v155
	v_mul_f32_e32 v117, v117, v129
	v_mul_f32_e32 v118, v118, v122
	v_mul_f32_e32 v119, v119, v123
	v_mul_f32_e32 v120, v120, v124
	v_mul_f32_e32 v121, v121, v125
	v_mul_f32_e32 v122, v114, v126
	v_mul_f32_e32 v123, v115, v127
	v_mul_f32_e32 v124, v116, v128
	v_cvt_pk_bf16_f32 v114, v118, v119
	v_cvt_pk_bf16_f32 v115, v120, v121
	v_cvt_pk_bf16_f32 v116, v122, v123
	v_cvt_pk_bf16_f32 v117, v124, v117
	global_store_dwordx4 v[166:167], v[114:117], off offset:256
	global_load_dwordx4 v[114:117], v[140:141], off offset:16
	global_load_dwordx4 v[118:121], v[140:141], off
	v_mad_i64_i32 v[122:123], s[30:31], v156, s80, v[144:145]
	v_lshl_add_u64 v[126:127], v[122:123], 0, v[142:143]
	global_load_dwordx4 v[122:125], v[126:127], off
	v_lshlrev_b64 v[128:129], 12, v[156:157]
	v_lshl_add_u64 v[128:129], s[22:23], 0, v[128:129]
	v_lshl_add_u64 v[128:129], v[128:129], 0, v[142:143]
	s_waitcnt vmcnt(2)
	v_pk_add_f32 v[108:109], v[108:109], v[116:117]
	s_waitcnt vmcnt(1)
	v_pk_add_f32 v[112:113], v[112:113], v[120:121]
	v_pk_add_f32 v[110:111], v[110:111], v[118:119]
	v_pk_add_f32 v[106:107], v[106:107], v[114:115]
	v_mul_f32_e32 v109, 0xbfb8aa3b, v109
	v_mul_f32_e32 v110, 0xbfb8aa3b, v110
	v_mul_f32_e32 v111, 0xbfb8aa3b, v111
	v_mul_f32_e32 v112, 0xbfb8aa3b, v112
	v_mul_f32_e32 v113, 0xbfb8aa3b, v113
	v_mul_f32_e32 v106, 0xbfb8aa3b, v106
	v_mul_f32_e32 v107, 0xbfb8aa3b, v107
	v_mul_f32_e32 v108, 0xbfb8aa3b, v108
	v_exp_f32_e32 v109, v109
	v_exp_f32_e32 v110, v110
	v_exp_f32_e32 v111, v111
	v_exp_f32_e32 v112, v112
	v_exp_f32_e32 v113, v113
	v_exp_f32_e32 v106, v106
	v_exp_f32_e32 v107, v107
	v_exp_f32_e32 v108, v108
	v_add_f32_e32 v109, 1.0, v109
	v_add_f32_e32 v110, 1.0, v110
	v_add_f32_e32 v111, 1.0, v111
	v_add_f32_e32 v112, 1.0, v112
	v_add_f32_e32 v113, 1.0, v113
	v_add_f32_e32 v106, 1.0, v106
	v_add_f32_e32 v107, 1.0, v107
	v_add_f32_e32 v108, 1.0, v108
	v_rcp_f32_e32 v109, v109
	v_rcp_f32_e32 v110, v110
	v_rcp_f32_e32 v111, v111
	v_rcp_f32_e32 v112, v112
	v_rcp_f32_e32 v113, v113
	v_rcp_f32_e32 v106, v106
	v_rcp_f32_e32 v107, v107
	v_rcp_f32_e32 v108, v108
	s_waitcnt vmcnt(0)
	v_and_b32_e32 v121, 0xffff0000, v125
	v_lshlrev_b32_e32 v114, 16, v122
	v_and_b32_e32 v115, 0xffff0000, v122
	v_lshlrev_b32_e32 v116, 16, v123
	v_and_b32_e32 v117, 0xffff0000, v123
	v_lshlrev_b32_e32 v118, 16, v124
	v_and_b32_e32 v119, 0xffff0000, v124
	v_lshlrev_b32_e32 v120, 16, v125
	v_mul_f32_e32 v109, v109, v121
	v_mul_f32_e32 v110, v110, v114
	v_mul_f32_e32 v111, v111, v115
	v_mul_f32_e32 v112, v112, v116
	v_mul_f32_e32 v113, v113, v117
	v_mul_f32_e32 v114, v106, v118
	v_mul_f32_e32 v115, v107, v119
	v_mul_f32_e32 v116, v108, v120
	v_cvt_pk_bf16_f32 v106, v110, v111
	v_cvt_pk_bf16_f32 v107, v112, v113
	v_cvt_pk_bf16_f32 v108, v114, v115
	v_cvt_pk_bf16_f32 v109, v116, v109
	global_store_dwordx4 v[128:129], v[106:109], off
	global_load_dwordx4 v[106:109], v[140:141], off offset:512
	global_load_dwordx4 v[110:113], v[140:141], off offset:528
	global_load_dwordx4 v[114:117], v[126:127], off offset:256
	v_add_u32_e32 v118, 32, v146
	v_ashrrev_i32_e32 v119, 31, v118
	s_waitcnt vmcnt(2)
	v_pk_add_f32 v[104:105], v[104:105], v[108:109]
	s_waitcnt vmcnt(1)
	v_pk_add_f32 v[100:101], v[100:101], v[112:113]
	v_pk_add_f32 v[102:103], v[102:103], v[106:107]
	v_pk_add_f32 v[98:99], v[98:99], v[110:111]
	v_mul_f32_e32 v101, 0xbfb8aa3b, v101
	v_mul_f32_e32 v102, 0xbfb8aa3b, v102
	v_mul_f32_e32 v103, 0xbfb8aa3b, v103
	v_mul_f32_e32 v104, 0xbfb8aa3b, v104
	v_mul_f32_e32 v105, 0xbfb8aa3b, v105
	v_mul_f32_e32 v98, 0xbfb8aa3b, v98
	v_mul_f32_e32 v99, 0xbfb8aa3b, v99
	v_mul_f32_e32 v100, 0xbfb8aa3b, v100
	v_exp_f32_e32 v101, v101
	v_exp_f32_e32 v102, v102
	v_exp_f32_e32 v103, v103
	v_exp_f32_e32 v104, v104
	v_exp_f32_e32 v105, v105
	v_exp_f32_e32 v98, v98
	v_exp_f32_e32 v99, v99
	v_exp_f32_e32 v100, v100
	v_add_f32_e32 v101, 1.0, v101
	v_add_f32_e32 v102, 1.0, v102
	v_add_f32_e32 v103, 1.0, v103
	v_add_f32_e32 v104, 1.0, v104
	v_add_f32_e32 v105, 1.0, v105
	v_add_f32_e32 v98, 1.0, v98
	v_add_f32_e32 v99, 1.0, v99
	v_add_f32_e32 v100, 1.0, v100
	v_rcp_f32_e32 v101, v101
	v_rcp_f32_e32 v102, v102
	v_rcp_f32_e32 v103, v103
	v_rcp_f32_e32 v104, v104
	v_rcp_f32_e32 v105, v105
	v_rcp_f32_e32 v98, v98
	v_rcp_f32_e32 v99, v99
	v_rcp_f32_e32 v100, v100
	s_waitcnt vmcnt(0)
	v_and_b32_e32 v113, 0xffff0000, v117
	v_lshlrev_b32_e32 v106, 16, v114
	v_and_b32_e32 v107, 0xffff0000, v114
	v_lshlrev_b32_e32 v108, 16, v115
	v_and_b32_e32 v109, 0xffff0000, v115
	v_lshlrev_b32_e32 v110, 16, v116
	v_and_b32_e32 v111, 0xffff0000, v116
	v_lshlrev_b32_e32 v112, 16, v117
	v_mul_f32_e32 v101, v101, v113
	v_mul_f32_e32 v102, v102, v106
	v_mul_f32_e32 v103, v103, v107
	v_mul_f32_e32 v104, v104, v108
	v_mul_f32_e32 v105, v105, v109
	v_mul_f32_e32 v106, v98, v110
	v_mul_f32_e32 v107, v99, v111
	v_mul_f32_e32 v108, v100, v112
	v_cvt_pk_bf16_f32 v98, v102, v103
	v_cvt_pk_bf16_f32 v99, v104, v105
	v_cvt_pk_bf16_f32 v100, v106, v107
	v_cvt_pk_bf16_f32 v101, v108, v101
	global_store_dwordx4 v[128:129], v[98:101], off offset:256
	global_load_dwordx4 v[98:101], v[140:141], off offset:16
	global_load_dwordx4 v[102:105], v[140:141], off
	v_mad_i64_i32 v[106:107], s[30:31], v118, s80, v[144:145]
	v_lshl_add_u64 v[110:111], v[106:107], 0, v[142:143]
	global_load_dwordx4 v[106:109], v[110:111], off
	v_lshlrev_b64 v[112:113], 12, v[118:119]
	v_lshl_add_u64 v[112:113], s[22:23], 0, v[112:113]
	v_lshl_add_u64 v[112:113], v[112:113], 0, v[142:143]
	s_waitcnt vmcnt(2)
	v_pk_add_f32 v[92:93], v[92:93], v[100:101]
	s_waitcnt vmcnt(1)
	v_pk_add_f32 v[96:97], v[96:97], v[104:105]
	v_pk_add_f32 v[94:95], v[94:95], v[102:103]
	v_pk_add_f32 v[90:91], v[90:91], v[98:99]
	v_mul_f32_e32 v93, 0xbfb8aa3b, v93
	v_mul_f32_e32 v94, 0xbfb8aa3b, v94
	v_mul_f32_e32 v95, 0xbfb8aa3b, v95
	v_mul_f32_e32 v96, 0xbfb8aa3b, v96
	v_mul_f32_e32 v97, 0xbfb8aa3b, v97
	v_mul_f32_e32 v90, 0xbfb8aa3b, v90
	v_mul_f32_e32 v91, 0xbfb8aa3b, v91
	v_mul_f32_e32 v92, 0xbfb8aa3b, v92
	v_exp_f32_e32 v93, v93
	v_exp_f32_e32 v94, v94
	v_exp_f32_e32 v95, v95
	v_exp_f32_e32 v96, v96
	v_exp_f32_e32 v97, v97
	v_exp_f32_e32 v90, v90
	v_exp_f32_e32 v91, v91
	v_exp_f32_e32 v92, v92
	v_add_f32_e32 v93, 1.0, v93
	v_add_f32_e32 v94, 1.0, v94
	v_add_f32_e32 v95, 1.0, v95
	v_add_f32_e32 v96, 1.0, v96
	v_add_f32_e32 v97, 1.0, v97
	v_add_f32_e32 v90, 1.0, v90
	v_add_f32_e32 v91, 1.0, v91
	v_add_f32_e32 v92, 1.0, v92
	v_rcp_f32_e32 v93, v93
	v_rcp_f32_e32 v94, v94
	v_rcp_f32_e32 v95, v95
	v_rcp_f32_e32 v96, v96
	v_rcp_f32_e32 v97, v97
	v_rcp_f32_e32 v90, v90
	v_rcp_f32_e32 v91, v91
	v_rcp_f32_e32 v92, v92
	s_waitcnt vmcnt(0)
	v_and_b32_e32 v105, 0xffff0000, v109
	v_lshlrev_b32_e32 v98, 16, v106
	v_and_b32_e32 v99, 0xffff0000, v106
	v_lshlrev_b32_e32 v100, 16, v107
	v_and_b32_e32 v101, 0xffff0000, v107
	v_lshlrev_b32_e32 v102, 16, v108
	v_and_b32_e32 v103, 0xffff0000, v108
	v_lshlrev_b32_e32 v104, 16, v109
	v_mul_f32_e32 v93, v93, v105
	v_mul_f32_e32 v94, v94, v98
	v_mul_f32_e32 v95, v95, v99
	v_mul_f32_e32 v96, v96, v100
	v_mul_f32_e32 v97, v97, v101
	v_mul_f32_e32 v98, v90, v102
	v_mul_f32_e32 v99, v91, v103
	v_mul_f32_e32 v100, v92, v104
	v_cvt_pk_bf16_f32 v90, v94, v95
	v_cvt_pk_bf16_f32 v91, v96, v97
	v_cvt_pk_bf16_f32 v92, v98, v99
	v_cvt_pk_bf16_f32 v93, v100, v93
	global_store_dwordx4 v[112:113], v[90:93], off
	global_load_dwordx4 v[90:93], v[140:141], off offset:512
	global_load_dwordx4 v[94:97], v[140:141], off offset:528
	global_load_dwordx4 v[98:101], v[110:111], off offset:256
	v_add_u32_e32 v102, 48, v146
	v_ashrrev_i32_e32 v103, 31, v102
	s_waitcnt vmcnt(2)
	v_pk_add_f32 v[88:89], v[88:89], v[92:93]
	s_waitcnt vmcnt(1)
	v_pk_add_f32 v[84:85], v[84:85], v[96:97]
	v_pk_add_f32 v[86:87], v[86:87], v[90:91]
	v_pk_add_f32 v[82:83], v[82:83], v[94:95]
	v_mul_f32_e32 v85, 0xbfb8aa3b, v85
	v_mul_f32_e32 v86, 0xbfb8aa3b, v86
	v_mul_f32_e32 v87, 0xbfb8aa3b, v87
	v_mul_f32_e32 v88, 0xbfb8aa3b, v88
	v_mul_f32_e32 v89, 0xbfb8aa3b, v89
	v_mul_f32_e32 v82, 0xbfb8aa3b, v82
	v_mul_f32_e32 v83, 0xbfb8aa3b, v83
	v_mul_f32_e32 v84, 0xbfb8aa3b, v84
	v_exp_f32_e32 v85, v85
	v_exp_f32_e32 v86, v86
	v_exp_f32_e32 v87, v87
	v_exp_f32_e32 v88, v88
	v_exp_f32_e32 v89, v89
	v_exp_f32_e32 v82, v82
	v_exp_f32_e32 v83, v83
	v_exp_f32_e32 v84, v84
	v_add_f32_e32 v85, 1.0, v85
	v_add_f32_e32 v86, 1.0, v86
	v_add_f32_e32 v87, 1.0, v87
	v_add_f32_e32 v88, 1.0, v88
	v_add_f32_e32 v89, 1.0, v89
	v_add_f32_e32 v82, 1.0, v82
	v_add_f32_e32 v83, 1.0, v83
	v_add_f32_e32 v84, 1.0, v84
	v_rcp_f32_e32 v85, v85
	v_rcp_f32_e32 v86, v86
	v_rcp_f32_e32 v87, v87
	v_rcp_f32_e32 v88, v88
	v_rcp_f32_e32 v89, v89
	v_rcp_f32_e32 v82, v82
	v_rcp_f32_e32 v83, v83
	v_rcp_f32_e32 v84, v84
	s_waitcnt vmcnt(0)
	v_and_b32_e32 v97, 0xffff0000, v101
	v_lshlrev_b32_e32 v90, 16, v98
	v_and_b32_e32 v91, 0xffff0000, v98
	v_lshlrev_b32_e32 v92, 16, v99
	v_and_b32_e32 v93, 0xffff0000, v99
	v_lshlrev_b32_e32 v94, 16, v100
	v_and_b32_e32 v95, 0xffff0000, v100
	v_lshlrev_b32_e32 v96, 16, v101
	v_mul_f32_e32 v85, v85, v97
	v_mul_f32_e32 v86, v86, v90
	v_mul_f32_e32 v87, v87, v91
	v_mul_f32_e32 v88, v88, v92
	v_mul_f32_e32 v89, v89, v93
	v_mul_f32_e32 v90, v82, v94
	v_mul_f32_e32 v91, v83, v95
	v_mul_f32_e32 v92, v84, v96
	v_cvt_pk_bf16_f32 v82, v86, v87
	v_cvt_pk_bf16_f32 v83, v88, v89
	v_cvt_pk_bf16_f32 v84, v90, v91
	v_cvt_pk_bf16_f32 v85, v92, v85
	global_store_dwordx4 v[112:113], v[82:85], off offset:256
	global_load_dwordx4 v[82:85], v[140:141], off offset:16
	global_load_dwordx4 v[86:89], v[140:141], off
	v_mad_i64_i32 v[90:91], s[30:31], v102, s80, v[144:145]
	v_lshl_add_u64 v[94:95], v[90:91], 0, v[142:143]
	global_load_dwordx4 v[90:93], v[94:95], off
	v_lshlrev_b64 v[96:97], 12, v[102:103]
	v_lshl_add_u64 v[96:97], s[22:23], 0, v[96:97]
	v_lshl_add_u64 v[96:97], v[96:97], 0, v[142:143]
	s_waitcnt vmcnt(2)
	v_pk_add_f32 v[76:77], v[76:77], v[84:85]
	s_waitcnt vmcnt(1)
	v_pk_add_f32 v[80:81], v[80:81], v[88:89]
	v_pk_add_f32 v[78:79], v[78:79], v[86:87]
	v_pk_add_f32 v[74:75], v[74:75], v[82:83]
	v_mul_f32_e32 v77, 0xbfb8aa3b, v77
	v_mul_f32_e32 v78, 0xbfb8aa3b, v78
	v_mul_f32_e32 v79, 0xbfb8aa3b, v79
	v_mul_f32_e32 v80, 0xbfb8aa3b, v80
	v_mul_f32_e32 v81, 0xbfb8aa3b, v81
	v_mul_f32_e32 v74, 0xbfb8aa3b, v74
	v_mul_f32_e32 v75, 0xbfb8aa3b, v75
	v_mul_f32_e32 v76, 0xbfb8aa3b, v76
	v_exp_f32_e32 v77, v77
	v_exp_f32_e32 v78, v78
	v_exp_f32_e32 v79, v79
	v_exp_f32_e32 v80, v80
	v_exp_f32_e32 v81, v81
	v_exp_f32_e32 v74, v74
	v_exp_f32_e32 v75, v75
	v_exp_f32_e32 v76, v76
	v_add_f32_e32 v77, 1.0, v77
	v_add_f32_e32 v78, 1.0, v78
	v_add_f32_e32 v79, 1.0, v79
	v_add_f32_e32 v80, 1.0, v80
	v_add_f32_e32 v81, 1.0, v81
	v_add_f32_e32 v74, 1.0, v74
	v_add_f32_e32 v75, 1.0, v75
	v_add_f32_e32 v76, 1.0, v76
	v_rcp_f32_e32 v77, v77
	v_rcp_f32_e32 v78, v78
	v_rcp_f32_e32 v79, v79
	v_rcp_f32_e32 v80, v80
	v_rcp_f32_e32 v81, v81
	v_rcp_f32_e32 v74, v74
	v_rcp_f32_e32 v75, v75
	v_rcp_f32_e32 v76, v76
	s_waitcnt vmcnt(0)
	v_and_b32_e32 v89, 0xffff0000, v93
	v_lshlrev_b32_e32 v82, 16, v90
	v_and_b32_e32 v83, 0xffff0000, v90
	v_lshlrev_b32_e32 v84, 16, v91
	v_and_b32_e32 v85, 0xffff0000, v91
	v_lshlrev_b32_e32 v86, 16, v92
	v_and_b32_e32 v87, 0xffff0000, v92
	v_lshlrev_b32_e32 v88, 16, v93
	v_mul_f32_e32 v77, v77, v89
	v_mul_f32_e32 v78, v78, v82
	v_mul_f32_e32 v79, v79, v83
	v_mul_f32_e32 v80, v80, v84
	v_mul_f32_e32 v81, v81, v85
	v_mul_f32_e32 v82, v74, v86
	v_mul_f32_e32 v83, v75, v87
	v_mul_f32_e32 v84, v76, v88
	v_cvt_pk_bf16_f32 v74, v78, v79
	v_cvt_pk_bf16_f32 v75, v80, v81
	v_cvt_pk_bf16_f32 v76, v82, v83
	v_cvt_pk_bf16_f32 v77, v84, v77
	global_store_dwordx4 v[96:97], v[74:77], off
	global_load_dwordx4 v[74:77], v[140:141], off offset:512
	global_load_dwordx4 v[78:81], v[140:141], off offset:528
	global_load_dwordx4 v[82:85], v[94:95], off offset:256
	v_add_u32_e32 v86, 0x80, v146
	v_ashrrev_i32_e32 v87, 31, v86
	s_waitcnt vmcnt(2)
	v_pk_add_f32 v[72:73], v[72:73], v[76:77]
	s_waitcnt vmcnt(1)
	v_pk_add_f32 v[68:69], v[68:69], v[80:81]
	v_pk_add_f32 v[70:71], v[70:71], v[74:75]
	v_pk_add_f32 v[66:67], v[66:67], v[78:79]
	v_mul_f32_e32 v69, 0xbfb8aa3b, v69
	v_mul_f32_e32 v70, 0xbfb8aa3b, v70
	v_mul_f32_e32 v71, 0xbfb8aa3b, v71
	v_mul_f32_e32 v72, 0xbfb8aa3b, v72
	v_mul_f32_e32 v73, 0xbfb8aa3b, v73
	v_mul_f32_e32 v66, 0xbfb8aa3b, v66
	v_mul_f32_e32 v67, 0xbfb8aa3b, v67
	v_mul_f32_e32 v68, 0xbfb8aa3b, v68
	v_exp_f32_e32 v69, v69
	v_exp_f32_e32 v70, v70
	v_exp_f32_e32 v71, v71
	v_exp_f32_e32 v72, v72
	v_exp_f32_e32 v73, v73
	v_exp_f32_e32 v66, v66
	v_exp_f32_e32 v67, v67
	v_exp_f32_e32 v68, v68
	v_add_f32_e32 v69, 1.0, v69
	v_add_f32_e32 v70, 1.0, v70
	v_add_f32_e32 v71, 1.0, v71
	v_add_f32_e32 v72, 1.0, v72
	v_add_f32_e32 v73, 1.0, v73
	v_add_f32_e32 v66, 1.0, v66
	v_add_f32_e32 v67, 1.0, v67
	v_add_f32_e32 v68, 1.0, v68
	v_rcp_f32_e32 v69, v69
	v_rcp_f32_e32 v70, v70
	v_rcp_f32_e32 v71, v71
	v_rcp_f32_e32 v72, v72
	v_rcp_f32_e32 v73, v73
	v_rcp_f32_e32 v66, v66
	v_rcp_f32_e32 v67, v67
	v_rcp_f32_e32 v68, v68
	s_waitcnt vmcnt(0)
	v_and_b32_e32 v81, 0xffff0000, v85
	v_lshlrev_b32_e32 v74, 16, v82
	v_and_b32_e32 v75, 0xffff0000, v82
	v_lshlrev_b32_e32 v76, 16, v83
	v_and_b32_e32 v77, 0xffff0000, v83
	v_lshlrev_b32_e32 v78, 16, v84
	v_and_b32_e32 v79, 0xffff0000, v84
	v_lshlrev_b32_e32 v80, 16, v85
	v_mul_f32_e32 v69, v69, v81
	v_mul_f32_e32 v70, v70, v74
	v_mul_f32_e32 v71, v71, v75
	v_mul_f32_e32 v72, v72, v76
	v_mul_f32_e32 v73, v73, v77
	v_mul_f32_e32 v74, v66, v78
	v_mul_f32_e32 v75, v67, v79
	v_mul_f32_e32 v76, v68, v80
	v_cvt_pk_bf16_f32 v66, v70, v71
	v_cvt_pk_bf16_f32 v67, v72, v73
	v_cvt_pk_bf16_f32 v68, v74, v75
	v_cvt_pk_bf16_f32 v69, v76, v69
	global_store_dwordx4 v[96:97], v[66:69], off offset:256
	global_load_dwordx4 v[66:69], v[140:141], off offset:16
	global_load_dwordx4 v[70:73], v[140:141], off
	v_mad_i64_i32 v[74:75], s[30:31], v86, s80, v[144:145]
	v_lshl_add_u64 v[78:79], v[74:75], 0, v[142:143]
	global_load_dwordx4 v[74:77], v[78:79], off
	v_lshlrev_b64 v[80:81], 12, v[86:87]
	v_lshl_add_u64 v[80:81], s[22:23], 0, v[80:81]
	v_lshl_add_u64 v[80:81], v[80:81], 0, v[142:143]
	s_waitcnt vmcnt(2)
	v_pk_add_f32 v[60:61], v[60:61], v[68:69]
	s_waitcnt vmcnt(1)
	v_pk_add_f32 v[64:65], v[64:65], v[72:73]
	v_pk_add_f32 v[62:63], v[62:63], v[70:71]
	v_pk_add_f32 v[58:59], v[58:59], v[66:67]
	v_mul_f32_e32 v61, 0xbfb8aa3b, v61
	v_mul_f32_e32 v62, 0xbfb8aa3b, v62
	v_mul_f32_e32 v63, 0xbfb8aa3b, v63
	v_mul_f32_e32 v64, 0xbfb8aa3b, v64
	v_mul_f32_e32 v65, 0xbfb8aa3b, v65
	v_mul_f32_e32 v58, 0xbfb8aa3b, v58
	v_mul_f32_e32 v59, 0xbfb8aa3b, v59
	v_mul_f32_e32 v60, 0xbfb8aa3b, v60
	v_exp_f32_e32 v61, v61
	v_exp_f32_e32 v62, v62
	v_exp_f32_e32 v63, v63
	v_exp_f32_e32 v64, v64
	v_exp_f32_e32 v65, v65
	v_exp_f32_e32 v58, v58
	v_exp_f32_e32 v59, v59
	v_exp_f32_e32 v60, v60
	v_add_f32_e32 v61, 1.0, v61
	v_add_f32_e32 v62, 1.0, v62
	v_add_f32_e32 v63, 1.0, v63
	v_add_f32_e32 v64, 1.0, v64
	v_add_f32_e32 v65, 1.0, v65
	v_add_f32_e32 v58, 1.0, v58
	v_add_f32_e32 v59, 1.0, v59
	v_add_f32_e32 v60, 1.0, v60
	v_rcp_f32_e32 v61, v61
	v_rcp_f32_e32 v62, v62
	v_rcp_f32_e32 v63, v63
	v_rcp_f32_e32 v64, v64
	v_rcp_f32_e32 v65, v65
	v_rcp_f32_e32 v58, v58
	v_rcp_f32_e32 v59, v59
	v_rcp_f32_e32 v60, v60
	s_waitcnt vmcnt(0)
	v_and_b32_e32 v73, 0xffff0000, v77
	v_lshlrev_b32_e32 v66, 16, v74
	v_and_b32_e32 v67, 0xffff0000, v74
	v_lshlrev_b32_e32 v68, 16, v75
	v_and_b32_e32 v69, 0xffff0000, v75
	v_lshlrev_b32_e32 v70, 16, v76
	v_and_b32_e32 v71, 0xffff0000, v76
	v_lshlrev_b32_e32 v72, 16, v77
	v_mul_f32_e32 v61, v61, v73
	v_mul_f32_e32 v62, v62, v66
	v_mul_f32_e32 v63, v63, v67
	v_mul_f32_e32 v64, v64, v68
	v_mul_f32_e32 v65, v65, v69
	v_mul_f32_e32 v66, v58, v70
	v_mul_f32_e32 v67, v59, v71
	v_mul_f32_e32 v68, v60, v72
	v_cvt_pk_bf16_f32 v58, v62, v63
	v_cvt_pk_bf16_f32 v59, v64, v65
	v_cvt_pk_bf16_f32 v60, v66, v67
	v_cvt_pk_bf16_f32 v61, v68, v61
	global_store_dwordx4 v[80:81], v[58:61], off
	global_load_dwordx4 v[58:61], v[140:141], off offset:512
	global_load_dwordx4 v[62:65], v[140:141], off offset:528
	global_load_dwordx4 v[66:69], v[78:79], off offset:256
	v_add_u32_e32 v70, 0x90, v146
	v_ashrrev_i32_e32 v71, 31, v70
	s_waitcnt vmcnt(2)
	v_pk_add_f32 v[56:57], v[56:57], v[60:61]
	s_waitcnt vmcnt(1)
	v_pk_add_f32 v[52:53], v[52:53], v[64:65]
	v_pk_add_f32 v[54:55], v[54:55], v[58:59]
	v_pk_add_f32 v[50:51], v[50:51], v[62:63]
	v_mul_f32_e32 v53, 0xbfb8aa3b, v53
	v_mul_f32_e32 v54, 0xbfb8aa3b, v54
	v_mul_f32_e32 v55, 0xbfb8aa3b, v55
	v_mul_f32_e32 v56, 0xbfb8aa3b, v56
	v_mul_f32_e32 v57, 0xbfb8aa3b, v57
	v_mul_f32_e32 v50, 0xbfb8aa3b, v50
	v_mul_f32_e32 v51, 0xbfb8aa3b, v51
	v_mul_f32_e32 v52, 0xbfb8aa3b, v52
	v_exp_f32_e32 v53, v53
	v_exp_f32_e32 v54, v54
	v_exp_f32_e32 v55, v55
	v_exp_f32_e32 v56, v56
	v_exp_f32_e32 v57, v57
	v_exp_f32_e32 v50, v50
	v_exp_f32_e32 v51, v51
	v_exp_f32_e32 v52, v52
	v_add_f32_e32 v53, 1.0, v53
	v_add_f32_e32 v54, 1.0, v54
	v_add_f32_e32 v55, 1.0, v55
	v_add_f32_e32 v56, 1.0, v56
	v_add_f32_e32 v57, 1.0, v57
	v_add_f32_e32 v50, 1.0, v50
	v_add_f32_e32 v51, 1.0, v51
	v_add_f32_e32 v52, 1.0, v52
	v_rcp_f32_e32 v53, v53
	v_rcp_f32_e32 v54, v54
	v_rcp_f32_e32 v55, v55
	v_rcp_f32_e32 v56, v56
	v_rcp_f32_e32 v57, v57
	v_rcp_f32_e32 v50, v50
	v_rcp_f32_e32 v51, v51
	v_rcp_f32_e32 v52, v52
	s_waitcnt vmcnt(0)
	v_and_b32_e32 v65, 0xffff0000, v69
	v_lshlrev_b32_e32 v58, 16, v66
	v_and_b32_e32 v59, 0xffff0000, v66
	v_lshlrev_b32_e32 v60, 16, v67
	v_and_b32_e32 v61, 0xffff0000, v67
	v_lshlrev_b32_e32 v62, 16, v68
	v_and_b32_e32 v63, 0xffff0000, v68
	v_lshlrev_b32_e32 v64, 16, v69
	v_mul_f32_e32 v53, v53, v65
	v_mul_f32_e32 v54, v54, v58
	v_mul_f32_e32 v55, v55, v59
	v_mul_f32_e32 v56, v56, v60
	v_mul_f32_e32 v57, v57, v61
	v_mul_f32_e32 v58, v50, v62
	v_mul_f32_e32 v59, v51, v63
	v_mul_f32_e32 v60, v52, v64
	v_cvt_pk_bf16_f32 v50, v54, v55
	v_cvt_pk_bf16_f32 v51, v56, v57
	v_cvt_pk_bf16_f32 v52, v58, v59
	v_cvt_pk_bf16_f32 v53, v60, v53
	global_store_dwordx4 v[80:81], v[50:53], off offset:256
	global_load_dwordx4 v[50:53], v[140:141], off offset:16
	global_load_dwordx4 v[54:57], v[140:141], off
	v_mad_i64_i32 v[58:59], s[30:31], v70, s80, v[144:145]
	v_lshl_add_u64 v[62:63], v[58:59], 0, v[142:143]
	global_load_dwordx4 v[58:61], v[62:63], off
	v_lshlrev_b64 v[64:65], 12, v[70:71]
	v_lshl_add_u64 v[64:65], s[22:23], 0, v[64:65]
	v_lshl_add_u64 v[64:65], v[64:65], 0, v[142:143]
	s_waitcnt vmcnt(2)
	v_pk_add_f32 v[44:45], v[44:45], v[52:53]
	s_waitcnt vmcnt(1)
	v_pk_add_f32 v[48:49], v[48:49], v[56:57]
	v_pk_add_f32 v[46:47], v[46:47], v[54:55]
	v_pk_add_f32 v[42:43], v[42:43], v[50:51]
	v_mul_f32_e32 v45, 0xbfb8aa3b, v45
	v_mul_f32_e32 v46, 0xbfb8aa3b, v46
	v_mul_f32_e32 v47, 0xbfb8aa3b, v47
	v_mul_f32_e32 v48, 0xbfb8aa3b, v48
	v_mul_f32_e32 v49, 0xbfb8aa3b, v49
	v_mul_f32_e32 v42, 0xbfb8aa3b, v42
	v_mul_f32_e32 v43, 0xbfb8aa3b, v43
	v_mul_f32_e32 v44, 0xbfb8aa3b, v44
	v_exp_f32_e32 v45, v45
	v_exp_f32_e32 v46, v46
	v_exp_f32_e32 v47, v47
	v_exp_f32_e32 v48, v48
	v_exp_f32_e32 v49, v49
	v_exp_f32_e32 v42, v42
	v_exp_f32_e32 v43, v43
	v_exp_f32_e32 v44, v44
	v_add_f32_e32 v45, 1.0, v45
	v_add_f32_e32 v46, 1.0, v46
	v_add_f32_e32 v47, 1.0, v47
	v_add_f32_e32 v48, 1.0, v48
	v_add_f32_e32 v49, 1.0, v49
	v_add_f32_e32 v42, 1.0, v42
	v_add_f32_e32 v43, 1.0, v43
	v_add_f32_e32 v44, 1.0, v44
	v_rcp_f32_e32 v45, v45
	v_rcp_f32_e32 v46, v46
	v_rcp_f32_e32 v47, v47
	v_rcp_f32_e32 v48, v48
	v_rcp_f32_e32 v49, v49
	v_rcp_f32_e32 v42, v42
	v_rcp_f32_e32 v43, v43
	v_rcp_f32_e32 v44, v44
	s_waitcnt vmcnt(0)
	v_and_b32_e32 v57, 0xffff0000, v61
	v_lshlrev_b32_e32 v50, 16, v58
	v_and_b32_e32 v51, 0xffff0000, v58
	v_lshlrev_b32_e32 v52, 16, v59
	v_and_b32_e32 v53, 0xffff0000, v59
	v_lshlrev_b32_e32 v54, 16, v60
	v_and_b32_e32 v55, 0xffff0000, v60
	v_lshlrev_b32_e32 v56, 16, v61
	v_mul_f32_e32 v45, v45, v57
	v_mul_f32_e32 v46, v46, v50
	v_mul_f32_e32 v47, v47, v51
	v_mul_f32_e32 v48, v48, v52
	v_mul_f32_e32 v49, v49, v53
	v_mul_f32_e32 v50, v42, v54
	v_mul_f32_e32 v51, v43, v55
	v_mul_f32_e32 v52, v44, v56
	v_cvt_pk_bf16_f32 v42, v46, v47
	v_cvt_pk_bf16_f32 v43, v48, v49
	v_cvt_pk_bf16_f32 v44, v50, v51
	v_cvt_pk_bf16_f32 v45, v52, v45
	global_store_dwordx4 v[64:65], v[42:45], off
	global_load_dwordx4 v[42:45], v[140:141], off offset:512
	global_load_dwordx4 v[46:49], v[140:141], off offset:528
	global_load_dwordx4 v[50:53], v[62:63], off offset:256
	v_add_u32_e32 v54, 0xa0, v146
	v_ashrrev_i32_e32 v55, 31, v54
	s_waitcnt vmcnt(2)
	v_pk_add_f32 v[40:41], v[40:41], v[44:45]
	s_waitcnt vmcnt(1)
	v_pk_add_f32 v[36:37], v[36:37], v[48:49]
	v_pk_add_f32 v[38:39], v[38:39], v[42:43]
	v_pk_add_f32 v[34:35], v[34:35], v[46:47]
	v_mul_f32_e32 v37, 0xbfb8aa3b, v37
	v_mul_f32_e32 v38, 0xbfb8aa3b, v38
	v_mul_f32_e32 v39, 0xbfb8aa3b, v39
	v_mul_f32_e32 v40, 0xbfb8aa3b, v40
	v_mul_f32_e32 v41, 0xbfb8aa3b, v41
	v_mul_f32_e32 v34, 0xbfb8aa3b, v34
	v_mul_f32_e32 v35, 0xbfb8aa3b, v35
	v_mul_f32_e32 v36, 0xbfb8aa3b, v36
	v_exp_f32_e32 v37, v37
	v_exp_f32_e32 v38, v38
	v_exp_f32_e32 v39, v39
	v_exp_f32_e32 v40, v40
	v_exp_f32_e32 v41, v41
	v_exp_f32_e32 v34, v34
	v_exp_f32_e32 v35, v35
	v_exp_f32_e32 v36, v36
	v_add_f32_e32 v37, 1.0, v37
	v_add_f32_e32 v38, 1.0, v38
	v_add_f32_e32 v39, 1.0, v39
	v_add_f32_e32 v40, 1.0, v40
	v_add_f32_e32 v41, 1.0, v41
	v_add_f32_e32 v34, 1.0, v34
	v_add_f32_e32 v35, 1.0, v35
	v_add_f32_e32 v36, 1.0, v36
	v_rcp_f32_e32 v37, v37
	v_rcp_f32_e32 v38, v38
	v_rcp_f32_e32 v39, v39
	v_rcp_f32_e32 v40, v40
	v_rcp_f32_e32 v41, v41
	v_rcp_f32_e32 v34, v34
	v_rcp_f32_e32 v35, v35
	v_rcp_f32_e32 v36, v36
	s_waitcnt vmcnt(0)
	v_and_b32_e32 v49, 0xffff0000, v53
	v_lshlrev_b32_e32 v42, 16, v50
	v_and_b32_e32 v43, 0xffff0000, v50
	v_lshlrev_b32_e32 v44, 16, v51
	v_and_b32_e32 v45, 0xffff0000, v51
	v_lshlrev_b32_e32 v46, 16, v52
	v_and_b32_e32 v47, 0xffff0000, v52
	v_lshlrev_b32_e32 v48, 16, v53
	v_mul_f32_e32 v37, v37, v49
	v_mul_f32_e32 v38, v38, v42
	v_mul_f32_e32 v39, v39, v43
	v_mul_f32_e32 v40, v40, v44
	v_mul_f32_e32 v41, v41, v45
	v_mul_f32_e32 v42, v34, v46
	v_mul_f32_e32 v43, v35, v47
	v_mul_f32_e32 v44, v36, v48
	v_cvt_pk_bf16_f32 v34, v38, v39
	v_cvt_pk_bf16_f32 v35, v40, v41
	v_cvt_pk_bf16_f32 v36, v42, v43
	v_cvt_pk_bf16_f32 v37, v44, v37
	global_store_dwordx4 v[64:65], v[34:37], off offset:256
	global_load_dwordx4 v[34:37], v[140:141], off offset:16
	global_load_dwordx4 v[38:41], v[140:141], off
	v_mad_i64_i32 v[42:43], s[30:31], v54, s80, v[144:145]
	v_lshl_add_u64 v[46:47], v[42:43], 0, v[142:143]
	global_load_dwordx4 v[42:45], v[46:47], off
	v_lshlrev_b64 v[48:49], 12, v[54:55]
	v_lshl_add_u64 v[48:49], s[22:23], 0, v[48:49]
	v_lshl_add_u64 v[48:49], v[48:49], 0, v[142:143]
	s_waitcnt vmcnt(2)
	v_pk_add_f32 v[28:29], v[28:29], v[36:37]
	s_waitcnt vmcnt(1)
	v_pk_add_f32 v[32:33], v[32:33], v[40:41]
	v_pk_add_f32 v[30:31], v[30:31], v[38:39]
	v_pk_add_f32 v[26:27], v[26:27], v[34:35]
	v_mul_f32_e32 v29, 0xbfb8aa3b, v29
	v_mul_f32_e32 v30, 0xbfb8aa3b, v30
	v_mul_f32_e32 v31, 0xbfb8aa3b, v31
	v_mul_f32_e32 v32, 0xbfb8aa3b, v32
	v_mul_f32_e32 v33, 0xbfb8aa3b, v33
	v_mul_f32_e32 v26, 0xbfb8aa3b, v26
	v_mul_f32_e32 v27, 0xbfb8aa3b, v27
	v_mul_f32_e32 v28, 0xbfb8aa3b, v28
	v_exp_f32_e32 v29, v29
	v_exp_f32_e32 v30, v30
	v_exp_f32_e32 v31, v31
	v_exp_f32_e32 v32, v32
	v_exp_f32_e32 v33, v33
	v_exp_f32_e32 v26, v26
	v_exp_f32_e32 v27, v27
	v_exp_f32_e32 v28, v28
	v_add_f32_e32 v29, 1.0, v29
	v_add_f32_e32 v30, 1.0, v30
	v_add_f32_e32 v31, 1.0, v31
	v_add_f32_e32 v32, 1.0, v32
	v_add_f32_e32 v33, 1.0, v33
	v_add_f32_e32 v26, 1.0, v26
	v_add_f32_e32 v27, 1.0, v27
	v_add_f32_e32 v28, 1.0, v28
	v_rcp_f32_e32 v29, v29
	v_rcp_f32_e32 v30, v30
	v_rcp_f32_e32 v31, v31
	v_rcp_f32_e32 v32, v32
	v_rcp_f32_e32 v33, v33
	v_rcp_f32_e32 v26, v26
	v_rcp_f32_e32 v27, v27
	v_rcp_f32_e32 v28, v28
	s_waitcnt vmcnt(0)
	v_and_b32_e32 v41, 0xffff0000, v45
	v_lshlrev_b32_e32 v34, 16, v42
	v_and_b32_e32 v35, 0xffff0000, v42
	v_lshlrev_b32_e32 v36, 16, v43
	v_and_b32_e32 v37, 0xffff0000, v43
	v_lshlrev_b32_e32 v38, 16, v44
	v_and_b32_e32 v39, 0xffff0000, v44
	v_lshlrev_b32_e32 v40, 16, v45
	v_mul_f32_e32 v29, v29, v41
	v_mul_f32_e32 v30, v30, v34
	v_mul_f32_e32 v31, v31, v35
	v_mul_f32_e32 v32, v32, v36
	v_mul_f32_e32 v33, v33, v37
	v_mul_f32_e32 v34, v26, v38
	v_mul_f32_e32 v35, v27, v39
	v_mul_f32_e32 v36, v28, v40
	v_cvt_pk_bf16_f32 v26, v30, v31
	v_cvt_pk_bf16_f32 v27, v32, v33
	v_cvt_pk_bf16_f32 v28, v34, v35
	v_cvt_pk_bf16_f32 v29, v36, v29
	global_store_dwordx4 v[48:49], v[26:29], off
	global_load_dwordx4 v[26:29], v[140:141], off offset:512
	global_load_dwordx4 v[30:33], v[140:141], off offset:528
	global_load_dwordx4 v[34:37], v[46:47], off offset:256
	v_add_u32_e32 v38, 0xb0, v146
	v_ashrrev_i32_e32 v39, 31, v38
	s_waitcnt vmcnt(2)
	v_pk_add_f32 v[24:25], v[24:25], v[28:29]
	s_waitcnt vmcnt(1)
	v_pk_add_f32 v[20:21], v[20:21], v[32:33]
	v_pk_add_f32 v[22:23], v[22:23], v[26:27]
	v_pk_add_f32 v[18:19], v[18:19], v[30:31]
	v_mul_f32_e32 v21, 0xbfb8aa3b, v21
	v_mul_f32_e32 v22, 0xbfb8aa3b, v22
	v_mul_f32_e32 v23, 0xbfb8aa3b, v23
	v_mul_f32_e32 v24, 0xbfb8aa3b, v24
	v_mul_f32_e32 v25, 0xbfb8aa3b, v25
	v_mul_f32_e32 v18, 0xbfb8aa3b, v18
	v_mul_f32_e32 v19, 0xbfb8aa3b, v19
	v_mul_f32_e32 v20, 0xbfb8aa3b, v20
	v_exp_f32_e32 v21, v21
	v_exp_f32_e32 v22, v22
	v_exp_f32_e32 v23, v23
	v_exp_f32_e32 v24, v24
	v_exp_f32_e32 v25, v25
	v_exp_f32_e32 v18, v18
	v_exp_f32_e32 v19, v19
	v_exp_f32_e32 v20, v20
	v_add_f32_e32 v21, 1.0, v21
	v_add_f32_e32 v22, 1.0, v22
	v_add_f32_e32 v23, 1.0, v23
	v_add_f32_e32 v24, 1.0, v24
	v_add_f32_e32 v25, 1.0, v25
	v_add_f32_e32 v18, 1.0, v18
	v_add_f32_e32 v19, 1.0, v19
	v_add_f32_e32 v20, 1.0, v20
	v_rcp_f32_e32 v21, v21
	v_rcp_f32_e32 v22, v22
	v_rcp_f32_e32 v23, v23
	v_rcp_f32_e32 v24, v24
	v_rcp_f32_e32 v25, v25
	v_rcp_f32_e32 v18, v18
	v_rcp_f32_e32 v19, v19
	v_rcp_f32_e32 v20, v20
	s_waitcnt vmcnt(0)
	v_and_b32_e32 v33, 0xffff0000, v37
	v_lshlrev_b32_e32 v26, 16, v34
	v_and_b32_e32 v27, 0xffff0000, v34
	v_lshlrev_b32_e32 v28, 16, v35
	v_and_b32_e32 v29, 0xffff0000, v35
	v_lshlrev_b32_e32 v30, 16, v36
	v_and_b32_e32 v31, 0xffff0000, v36
	v_lshlrev_b32_e32 v32, 16, v37
	v_mul_f32_e32 v21, v21, v33
	v_mul_f32_e32 v22, v22, v26
	v_mul_f32_e32 v23, v23, v27
	v_mul_f32_e32 v24, v24, v28
	v_mul_f32_e32 v25, v25, v29
	v_mul_f32_e32 v26, v18, v30
	v_mul_f32_e32 v27, v19, v31
	v_mul_f32_e32 v28, v20, v32
	v_cvt_pk_bf16_f32 v18, v22, v23
	v_cvt_pk_bf16_f32 v19, v24, v25
	v_cvt_pk_bf16_f32 v20, v26, v27
	v_cvt_pk_bf16_f32 v21, v28, v21
	global_store_dwordx4 v[48:49], v[18:21], off offset:256
	global_load_dwordx4 v[18:21], v[140:141], off offset:16
	global_load_dwordx4 v[22:25], v[140:141], off
	v_mad_i64_i32 v[26:27], s[30:31], v38, s80, v[144:145]
	v_lshl_add_u64 v[30:31], v[26:27], 0, v[142:143]
	global_load_dwordx4 v[26:29], v[30:31], off
	v_lshlrev_b64 v[32:33], 12, v[38:39]
	v_lshl_add_u64 v[32:33], s[22:23], 0, v[32:33]
	v_lshl_add_u64 v[32:33], v[32:33], 0, v[142:143]
	s_mov_b64 s[30:31], -1
	s_waitcnt vmcnt(2)
	v_pk_add_f32 v[12:13], v[12:13], v[20:21]
	s_waitcnt vmcnt(1)
	v_pk_add_f32 v[16:17], v[16:17], v[24:25]
	v_pk_add_f32 v[14:15], v[14:15], v[22:23]
	v_pk_add_f32 v[10:11], v[10:11], v[18:19]
	v_mul_f32_e32 v13, 0xbfb8aa3b, v13
	v_mul_f32_e32 v14, 0xbfb8aa3b, v14
	v_mul_f32_e32 v15, 0xbfb8aa3b, v15
	v_mul_f32_e32 v16, 0xbfb8aa3b, v16
	v_mul_f32_e32 v17, 0xbfb8aa3b, v17
	v_mul_f32_e32 v10, 0xbfb8aa3b, v10
	v_mul_f32_e32 v11, 0xbfb8aa3b, v11
	v_mul_f32_e32 v12, 0xbfb8aa3b, v12
	v_exp_f32_e32 v13, v13
	v_exp_f32_e32 v14, v14
	v_exp_f32_e32 v15, v15
	v_exp_f32_e32 v16, v16
	v_exp_f32_e32 v17, v17
	v_exp_f32_e32 v10, v10
	v_exp_f32_e32 v11, v11
	v_exp_f32_e32 v12, v12
	v_add_f32_e32 v13, 1.0, v13
	v_add_f32_e32 v14, 1.0, v14
	v_add_f32_e32 v15, 1.0, v15
	v_add_f32_e32 v16, 1.0, v16
	v_add_f32_e32 v17, 1.0, v17
	v_add_f32_e32 v10, 1.0, v10
	v_add_f32_e32 v11, 1.0, v11
	v_add_f32_e32 v12, 1.0, v12
	v_rcp_f32_e32 v13, v13
	v_rcp_f32_e32 v14, v14
	v_rcp_f32_e32 v15, v15
	v_rcp_f32_e32 v16, v16
	v_rcp_f32_e32 v17, v17
	v_rcp_f32_e32 v10, v10
	v_rcp_f32_e32 v11, v11
	v_rcp_f32_e32 v12, v12
	s_waitcnt vmcnt(0)
	v_and_b32_e32 v25, 0xffff0000, v29
	v_lshlrev_b32_e32 v18, 16, v26
	v_and_b32_e32 v19, 0xffff0000, v26
	v_lshlrev_b32_e32 v20, 16, v27
	v_and_b32_e32 v21, 0xffff0000, v27
	v_lshlrev_b32_e32 v22, 16, v28
	v_and_b32_e32 v23, 0xffff0000, v28
	v_lshlrev_b32_e32 v24, 16, v29
	v_mul_f32_e32 v13, v13, v25
	v_mul_f32_e32 v14, v14, v18
	v_mul_f32_e32 v15, v15, v19
	v_mul_f32_e32 v16, v16, v20
	v_mul_f32_e32 v17, v17, v21
	v_mul_f32_e32 v18, v10, v22
	v_mul_f32_e32 v19, v11, v23
	v_mul_f32_e32 v20, v12, v24
	v_cvt_pk_bf16_f32 v10, v14, v15
	v_cvt_pk_bf16_f32 v11, v16, v17
	v_cvt_pk_bf16_f32 v12, v18, v19
	v_cvt_pk_bf16_f32 v13, v20, v13
	global_store_dwordx4 v[32:33], v[10:13], off
	global_load_dwordx4 v[10:13], v[140:141], off offset:512
	global_load_dwordx4 v[14:17], v[140:141], off offset:528
	global_load_dwordx4 v[18:21], v[30:31], off offset:256
	s_waitcnt vmcnt(2)
	v_pk_add_f32 v[8:9], v[8:9], v[12:13]
	s_waitcnt vmcnt(1)
	v_pk_add_f32 v[4:5], v[4:5], v[16:17]
	v_pk_add_f32 v[6:7], v[6:7], v[10:11]
	v_pk_add_f32 v[2:3], v[2:3], v[14:15]
	v_mul_f32_e32 v5, 0xbfb8aa3b, v5
	v_mul_f32_e32 v6, 0xbfb8aa3b, v6
	v_mul_f32_e32 v7, 0xbfb8aa3b, v7
	v_mul_f32_e32 v8, 0xbfb8aa3b, v8
	v_mul_f32_e32 v9, 0xbfb8aa3b, v9
	v_mul_f32_e32 v2, 0xbfb8aa3b, v2
	v_mul_f32_e32 v3, 0xbfb8aa3b, v3
	v_mul_f32_e32 v4, 0xbfb8aa3b, v4
	v_exp_f32_e32 v5, v5
	v_exp_f32_e32 v6, v6
	v_exp_f32_e32 v7, v7
	v_exp_f32_e32 v8, v8
	v_exp_f32_e32 v9, v9
	v_exp_f32_e32 v2, v2
	v_exp_f32_e32 v3, v3
	v_exp_f32_e32 v4, v4
	v_add_f32_e32 v5, 1.0, v5
	v_add_f32_e32 v6, 1.0, v6
	v_add_f32_e32 v7, 1.0, v7
	v_add_f32_e32 v8, 1.0, v8
	v_add_f32_e32 v9, 1.0, v9
	v_add_f32_e32 v2, 1.0, v2
	v_add_f32_e32 v3, 1.0, v3
	v_add_f32_e32 v4, 1.0, v4
	v_rcp_f32_e32 v5, v5
	v_rcp_f32_e32 v6, v6
	v_rcp_f32_e32 v7, v7
	v_rcp_f32_e32 v8, v8
	v_rcp_f32_e32 v9, v9
	v_rcp_f32_e32 v2, v2
	v_rcp_f32_e32 v3, v3
	v_rcp_f32_e32 v4, v4
	s_waitcnt vmcnt(0)
	v_and_b32_e32 v17, 0xffff0000, v21
	v_lshlrev_b32_e32 v10, 16, v18
	v_and_b32_e32 v11, 0xffff0000, v18
	v_lshlrev_b32_e32 v12, 16, v19
	v_and_b32_e32 v13, 0xffff0000, v19
	v_lshlrev_b32_e32 v14, 16, v20
	v_and_b32_e32 v15, 0xffff0000, v20
	v_lshlrev_b32_e32 v16, 16, v21
	v_mul_f32_e32 v5, v5, v17
	v_mul_f32_e32 v6, v6, v10
	v_mul_f32_e32 v7, v7, v11
	v_mul_f32_e32 v8, v8, v12
	v_mul_f32_e32 v9, v9, v13
	v_mul_f32_e32 v10, v2, v14
	v_mul_f32_e32 v11, v3, v15
	v_mul_f32_e32 v12, v4, v16
	v_cvt_pk_bf16_f32 v2, v6, v7
	v_cvt_pk_bf16_f32 v3, v8, v9
	v_cvt_pk_bf16_f32 v4, v10, v11
	v_cvt_pk_bf16_f32 v5, v12, v5
	global_store_dwordx4 v[32:33], v[2:5], off offset:256
	s_cbranch_vccnz .LBB0_925
	s_andn2_b64 vcc, exec, s[14:15]
	s_cbranch_vccnz .LBB0_924
	s_branch .LBB0_924

.LBB0_1005:
	v_readlane_b32 s3, v255, 41
	s_andn2_b64 vcc, exec, s[14:15]
	s_lshl_b32 s12, s3, 6
	s_cbranch_vccnz .LBB0_1222
	v_ashrrev_i32_e32 v3, 31, v10
	v_lshrrev_b32_e32 v3, 26, v3
	v_add_u32_e32 v3, v10, v3
	v_ashrrev_i32_e32 v11, 6, v3
	v_bfe_i32 v3, v10, 27, 1
	v_lshlrev_b32_e32 v2, 4, v10
	v_lshrrev_b32_e32 v3, 22, v3
	v_add_u32_e32 v3, v2, v3
	v_and_b32_e32 v3, 0xfffffc00, v3
	s_load_dwordx2 s[30:31], s[0:1], s69 offset:0x118
	v_sub_u32_e32 v3, v2, v3
	v_lshrrev_b32_e32 v4, 4, v3
	v_bitop3_b32 v3, v4, v3, 32 bitop3:0x6c
	v_ashrrev_i32_e32 v5, 31, v3
	v_lshrrev_b32_e32 v5, 26, v5
	v_readlane_b32 s3, v255, 41
	s_waitcnt lgkmcnt(0)
	s_add_u32 s7, s30, 0x1de00000
	v_add_u32_e32 v5, v3, v5
	s_mul_i32 s11, s3, 0xe00000
	s_addc_u32 s8, s31, 0
	v_lshlrev_b32_e32 v4, 3, v11
	v_ashrrev_i32_e32 v12, 6, v5
	v_and_b32_e32 v5, 0xc0, v5
	s_mul_hi_u32 s9, s3, 0xe00000
	s_add_u32 s11, s30, s11
	v_and_b32_e32 v4, -16, v4
	v_sub_u32_e32 v3, v3, v5
	s_addc_u32 s14, s31, s9
	v_add_u32_e32 v4, v12, v4
	v_ashrrev_i16_sdwa v3, v224, sext(v3) dst_sel:DWORD dst_unused:UNUSED_PAD src0_sel:DWORD src1_sel:BYTE_0
	s_add_u32 s9, s11, 0x100000
	v_lshlrev_b32_e32 v6, 5, v11
	v_bfe_i32 v13, v3, 0, 16
	v_lshlrev_b32_e32 v3, 1, v4
	v_lshrrev_b32_e32 v5, 2, v4
	v_and_b32_e32 v7, 3, v12
	s_mov_b32 s11, 0xfffe0
	v_and_b32_e32 v6, 32, v6
	v_and_b32_e32 v3, 24, v3
	v_and_b32_e32 v5, 4, v5
	v_and_or_b32 v7, v4, s11, v7
	v_or3_b32 v3, v7, v5, v3
	v_add_lshl_u32 v5, v6, v13, 1
	v_add_u32_e32 v2, 0x2000, v2
	v_lshl_add_u32 v180, v3, 12, v5
	v_ashrrev_i32_e32 v3, 31, v2
	v_lshrrev_b32_e32 v3, 22, v3
	v_add_u32_e32 v3, v2, v3
	v_ashrrev_i32_e32 v14, 10, v3
	v_mul_i32_i24_e32 v3, 0x400, v14
	v_sub_u32_e32 v2, v2, v3
	v_lshrrev_b32_e32 v3, 4, v2
	v_bitop3_b32 v2, v3, v2, 32 bitop3:0x6c
	s_waitcnt vmcnt(0)
	v_lshl_add_u32 v132, v4, 12, v5
	v_ashrrev_i32_e32 v4, 31, v2
	v_lshrrev_b32_e32 v4, 26, v4
	v_lshlrev_b32_e32 v3, 3, v14
	v_add_u32_e32 v4, v2, v4
	v_and_b32_e32 v3, -16, v3
	v_ashrrev_i32_e32 v15, 6, v4
	v_add_u32_e32 v3, v15, v3
	v_and_b32_e32 v6, 3, v15
	s_addc_u32 s21, s14, 0
	v_and_b32_e32 v4, 0xc0, v4
	v_and_or_b32 v6, v3, s11, v6
	s_ashr_i32 s42, s34, 6
	s_ashr_i32 s11, s10, 31
	s_ashr_i32 s37, s36, 31
	s_ashr_i32 s35, s34, 8
	v_sub_u32_e32 v2, v2, v4
	s_lshl_b32 s60, s42, 10
	s_lshl_b64 s[14:15], s[10:11], 20
	s_lshl_b64 s[18:19], s[36:37], 20
	v_ashrrev_i16_sdwa v2, v224, sext(v2) dst_sel:DWORD dst_unused:UNUSED_PAD src0_sel:DWORD src1_sel:BYTE_0
	s_add_u32 s40, s9, s18
	v_lshlrev_b32_e32 v5, 5, v14
	v_bfe_i32 v16, v2, 0, 16
	v_lshlrev_b32_e32 v2, 1, v3
	v_lshrrev_b32_e32 v4, 2, v3
	s_addc_u32 s41, s21, s19
	s_add_i32 s61, s60, 0
	v_and_b32_e32 v5, 32, v5
	v_and_b32_e32 v2, 24, v2
	v_and_b32_e32 v4, 4, v4
	s_add_i32 m0, s61, 0x10000
	v_or3_b32 v2, v6, v4, v2
	v_add_lshl_u32 v4, v5, v16, 1
	global_load_lds_dwordx4 v180, s[40:41]
	s_add_i32 m0, s61, 0x12000
	v_lshl_add_u32 v136, v2, 12, v4
	s_add_u32 s18, s40, 0x80000
	global_load_lds_dwordx4 v136, s[40:41]
	s_addc_u32 s19, s41, 0
	s_add_i32 m0, s61, 0x14000
	v_lshl_add_u32 v134, v3, 12, v4
	global_load_lds_dwordx4 v180, s[18:19]
	s_add_i32 m0, s61, 0x16000
	s_add_u32 s38, s7, s14
	s_addc_u32 s39, s8, s15
	s_add_i32 s62, s61, 0x2000
	global_load_lds_dwordx4 v136, s[18:19]
	s_mov_b32 m0, s61
	s_add_u32 s14, s38, 0x80000
	global_load_lds_dwordx4 v132, s[38:39]
	s_mov_b32 m0, s62
	s_addc_u32 s15, s39, 0
	s_add_i32 s63, s61, 0x4000
	global_load_lds_dwordx4 v134, s[38:39]
	s_mov_b32 m0, s63
	s_add_i32 s64, s61, 0x6000
	global_load_lds_dwordx4 v132, s[14:15]
	s_mov_b32 m0, s64
	v_mov_b32_e32 v137, v181
	global_load_lds_dwordx4 v134, s[14:15]
	v_mov_b32_e32 v133, v181
	v_mov_b32_e32 v135, v181
	s_cmp_eq_u32 s35, 1
	v_lshl_add_u64 v[8:9], s[40:41], 0, v[180:181]
	v_lshl_add_u64 v[6:7], s[40:41], 0, v[136:137]
	v_lshl_add_u64 v[2:3], s[38:39], 0, v[132:133]
	s_cselect_b64 s[14:15], -1, 0
	s_cmp_lg_u32 s35, 1
	v_lshl_add_u64 v[4:5], s[38:39], 0, v[134:135]
	s_cbranch_scc1 .LBB0_1008
.LBB0_1008:
	v_readlane_b32 s3, v255, 43
	s_mul_i32 s18, s3, 0x4200
	s_mov_b32 s19, s13
	s_lshl_b64 s[18:19], s[18:19], 3
	s_add_u32 s18, s30, s18
	s_addc_u32 s19, s31, s19
	s_add_u32 s18, s18, 0x10000
	s_addc_u32 s19, s19, 0
	s_add_u32 s22, s30, 0x20b00000
	s_addc_u32 s23, s31, 0
	s_add_u32 s24, s30, 0x22400000
	s_addc_u32 s25, s31, 0
	v_readlane_b32 s3, v255, 41
	s_add_u32 s26, s30, 0x23d00000
	s_mul_i32 s28, s3, 0x10800
	s_addc_u32 s27, s31, 0
	s_mul_hi_u32 s11, s3, 0x10800
	s_add_u32 s28, s30, s28
	s_addc_u32 s11, s31, s11
	s_add_u32 s28, s28, 0xb0000
	s_addc_u32 s29, s11, 0
	s_lshl_b64 s[44:45], s[12:13], 2
	s_add_u32 s11, s30, s44
	s_addc_u32 s31, s31, s45
	s_add_u32 s30, s11, 0xb000
	s_addc_u32 s31, s31, 0
	s_lshl_b32 s70, s35, 6
	s_lshl_b32 s11, s35, 13
	s_lshl_b32 s35, s42, 5
	s_and_b32 s71, s35, 0x60
	s_add_i32 m0, s61, 0x18000
	v_lshl_add_u64 v[8:9], v[8:9], 0, s[16:17]
	s_lshl_b32 s35, s71, 7
	s_waitcnt vmcnt(2)
	s_barrier
	global_load_lds_dwordx4 v[8:9], off
	v_lshl_add_u64 v[6:7], v[6:7], 0, s[16:17]
	s_add_i32 m0, s61, 0x1a000
	s_add_i32 s74, s61, 0x8000
	s_add_i32 s75, s61, 0xa000
	global_load_lds_dwordx4 v[6:7], off
	v_lshl_add_u64 v[2:3], v[2:3], 0, s[16:17]
	s_mov_b32 m0, s74
	s_add_u32 s42, s40, 0x80080
	global_load_lds_dwordx4 v[2:3], off
	v_lshl_add_u64 v[2:3], v[4:5], 0, s[16:17]
	s_mov_b32 m0, s75
	s_addc_u32 s43, s41, 0
	global_load_lds_dwordx4 v[2:3], off
	s_add_i32 m0, s61, 0x1c000
	v_lshl_add_u64 v[2:3], s[42:43], 0, v[180:181]
	global_load_lds_dwordx4 v[2:3], off
	v_lshl_add_u64 v[2:3], s[42:43], 0, v[136:137]
	s_add_i32 m0, s61, 0x1e000
	v_bfe_u32 v158, v10, 4, 2
	global_load_lds_dwordx4 v[2:3], off
	v_and_b32_e32 v131, 15, v10
	v_lshlrev_b32_e32 v2, 4, v158
	v_lshlrev_b32_e32 v3, 2, v10
	v_lshl_or_b32 v2, v131, 6, v2
	v_and_b32_e32 v3, 32, v3
	v_bitop3_b32 v4, v2, s11, v3 bitop3:0xde
	v_bitop3_b32 v159, v2, s35, v3 bitop3:0xde
	v_lshlrev_b32_e32 v2, 15, v11
	v_and_b32_e32 v2, 0xffff0000, v2
	v_lshl_add_u32 v2, v12, 12, v2
	v_and_b32_e32 v3, 1, v11
	v_lshl_or_b32 v2, v3, 6, v2
	v_lshl_add_u32 v138, v13, 1, v2
	v_lshlrev_b32_e32 v2, 15, v14
	v_and_b32_e32 v2, 0xffff0000, v2
	s_waitcnt vmcnt(6)
	v_lshl_add_u32 v2, v15, 12, v2
	v_and_b32_e32 v3, 1, v14
	s_cmpk_lt_u32 s34, 0x100
	v_lshl_or_b32 v2, v3, 6, v2
	s_cselect_b64 s[34:35], -1, 0
	s_ashr_i32 s76, s6, 31
	v_mov_b32_e32 v139, v181
	v_lshl_add_u32 v140, v16, 1, v2
	v_mov_b32_e32 v141, v181
	s_mov_b32 s82, 0
	v_add_u32_e32 v160, 0, v4
	s_barrier
	s_branch .LBB0_1011

.LBB0_1018:
	s_add_u32 s40, s38, 0xfff80080
	s_addc_u32 s41, s39, -1
	s_add_i32 s51, 0, 0x10000
	s_cmp_eq_u32 s49, 28
	s_cselect_b32 s43, s11, s41
	s_cselect_b32 s42, s37, s40
	s_cselect_b32 s41, s44, s47
	s_cselect_b32 s40, s45, s46
	s_add_i32 s83, 0, 0x14000
	v_add_u32_e32 v154, s51, v159
	v_add_u32_e32 v161, s83, v159
	ds_read_b128 v[142:145], v154
	ds_read_b128 v[146:149], v154 offset:1024
	ds_read_b128 v[150:153], v154 offset:2048
	ds_read_b128 v[154:157], v154 offset:3072
	ds_read_b128 v[162:165], v161
	ds_read_b128 v[166:169], v161 offset:1024
	ds_read_b128 v[170:173], v161 offset:2048
	ds_read_b128 v[174:177], v161 offset:3072
	v_lshl_add_u64 v[178:179], s[38:39], 0, v[138:139]
	s_add_i32 m0, s61, 0xc000
	ds_read_b128 v[190:193], v160
	ds_read_b128 v[194:197], v160 offset:1024
	ds_read_b128 v[198:201], v160 offset:2048
	ds_read_b128 v[202:205], v160 offset:3072
	ds_read_b128 v[206:209], v160 offset:4096
	ds_read_b128 v[210:213], v160 offset:5120
	ds_read_b128 v[214:217], v160 offset:6144
	ds_read_b128 v[218:221], v160 offset:7168
	global_load_lds_dwordx4 v[178:179], off
	v_lshl_add_u64 v[178:179], s[38:39], 0, v[140:141]
	s_add_i32 m0, s61, 0xe000
	s_nop 0
	global_load_lds_dwordx4 v[178:179], off
	s_waitcnt vmcnt(8)
	s_waitcnt lgkmcnt(0)
	s_cmp_eq_u32 s100, 0
	s_cbranch_scc1 .Lmy_h2_25
	s_setprio 1
	s_barrier
.Lmy_h2_25:
	v_mfma_f32_16x16x32_bf16 v[126:129], v[142:145], v[190:193], v[126:129]
	v_mfma_f32_16x16x32_bf16 v[122:125], v[150:153], v[190:193], v[122:125]
	v_mfma_f32_16x16x32_bf16 v[110:113], v[142:145], v[198:201], v[110:113]
	v_mfma_f32_16x16x32_bf16 v[106:109], v[150:153], v[198:201], v[106:109]
	v_mfma_f32_16x16x32_bf16 v[94:97], v[142:145], v[206:209], v[94:97]
	v_mfma_f32_16x16x32_bf16 v[90:93], v[150:153], v[206:209], v[90:93]
	v_mfma_f32_16x16x32_bf16 v[78:81], v[142:145], v[214:217], v[78:81]
	v_mfma_f32_16x16x32_bf16 v[74:77], v[150:153], v[214:217], v[74:77]
	v_mfma_f32_16x16x32_bf16 v[126:129], v[146:149], v[194:197], v[126:129]
	v_mfma_f32_16x16x32_bf16 v[122:125], v[154:157], v[194:197], v[122:125]
	v_mfma_f32_16x16x32_bf16 v[110:113], v[146:149], v[202:205], v[110:113]
	v_mfma_f32_16x16x32_bf16 v[106:109], v[154:157], v[202:205], v[106:109]
	v_mfma_f32_16x16x32_bf16 v[94:97], v[146:149], v[210:213], v[94:97]
	v_mfma_f32_16x16x32_bf16 v[90:93], v[154:157], v[210:213], v[90:93]
	v_mfma_f32_16x16x32_bf16 v[78:81], v[146:149], v[218:221], v[78:81]
	v_mfma_f32_16x16x32_bf16 v[74:77], v[154:157], v[218:221], v[74:77]
	v_mfma_f32_16x16x32_bf16 v[118:121], v[162:165], v[190:193], v[118:121]
	v_mfma_f32_16x16x32_bf16 v[114:117], v[170:173], v[190:193], v[114:117]
	v_mfma_f32_16x16x32_bf16 v[102:105], v[162:165], v[198:201], v[102:105]
	v_mfma_f32_16x16x32_bf16 v[98:101], v[170:173], v[198:201], v[98:101]
	v_mfma_f32_16x16x32_bf16 v[86:89], v[162:165], v[206:209], v[86:89]
	v_mfma_f32_16x16x32_bf16 v[82:85], v[170:173], v[206:209], v[82:85]
	v_mfma_f32_16x16x32_bf16 v[70:73], v[162:165], v[214:217], v[70:73]
	v_mfma_f32_16x16x32_bf16 v[66:69], v[170:173], v[214:217], v[66:69]
	v_mfma_f32_16x16x32_bf16 v[118:121], v[166:169], v[194:197], v[118:121]
	v_mfma_f32_16x16x32_bf16 v[114:117], v[174:177], v[194:197], v[114:117]
	v_mfma_f32_16x16x32_bf16 v[102:105], v[166:169], v[202:205], v[102:105]
	v_mfma_f32_16x16x32_bf16 v[98:101], v[174:177], v[202:205], v[98:101]
	v_mfma_f32_16x16x32_bf16 v[86:89], v[166:169], v[210:213], v[86:89]
	v_mfma_f32_16x16x32_bf16 v[82:85], v[174:177], v[210:213], v[82:85]
	v_mfma_f32_16x16x32_bf16 v[70:73], v[166:169], v[218:221], v[70:73]
	v_mfma_f32_16x16x32_bf16 v[66:69], v[174:177], v[218:221], v[66:69]
	s_cmp_lg_u32 s100, 0
	s_cbranch_scc1 .Lmy_h2_26
	s_barrier
.Lmy_h2_26:
	s_setprio 0
	s_add_i32 s51, s51, s60
	v_lshl_add_u64 v[178:179], s[40:41], 0, v[180:181]
	s_mov_b32 m0, s51
	ds_read_b128 v[190:193], v160 offset:16384
	ds_read_b128 v[194:197], v160 offset:17408
	ds_read_b128 v[198:201], v160 offset:18432
	ds_read_b128 v[202:205], v160 offset:19456
	ds_read_b128 v[206:209], v160 offset:20480
	ds_read_b128 v[210:213], v160 offset:21504
	ds_read_b128 v[214:217], v160 offset:22528
	ds_read_b128 v[218:221], v160 offset:23552
	global_load_lds_dwordx4 v[178:179], off
	s_add_i32 m0, s51, 0x2000
	s_add_u32 vcc_lo, s40, 0x80000
	v_lshl_add_u64 v[222:223], s[40:41], 0, v[136:137]
	s_addc_u32 vcc_hi, s41, 0
	s_add_i32 s51, s83, s60
	global_load_lds_dwordx4 v[222:223], off
	v_lshl_add_u64 v[238:239], vcc, 0, v[180:181]
	s_mov_b32 m0, s51
	v_lshl_add_u64 v[240:241], s[42:43], 0, v[134:135]
	global_load_lds_dwordx4 v[238:239], off
	v_lshl_add_u64 v[238:239], vcc, 0, v[136:137]
	s_add_i32 m0, s51, 0x2000
	s_nop 0
	global_load_lds_dwordx4 v[238:239], off
	v_lshl_add_u64 v[238:239], s[42:43], 0, v[132:133]
	s_mov_b32 m0, s61
	s_nop 0
	global_load_lds_dwordx4 v[238:239], off
	s_mov_b32 m0, s62
	s_nop 0
	global_load_lds_dwordx4 v[240:241], off
	s_waitcnt vmcnt(8)
	s_waitcnt lgkmcnt(0)
	s_cmp_eq_u32 s100, 0
	s_cbranch_scc1 .Lmy_h2_27
	s_setprio 1
	s_barrier
.Lmy_h2_27:
	v_mfma_f32_16x16x32_bf16 v[62:65], v[142:145], v[190:193], v[62:65]
	v_mfma_f32_16x16x32_bf16 v[58:61], v[150:153], v[190:193], v[58:61]
	v_mfma_f32_16x16x32_bf16 v[46:49], v[142:145], v[198:201], v[46:49]
	v_mfma_f32_16x16x32_bf16 v[42:45], v[150:153], v[198:201], v[42:45]
	v_mfma_f32_16x16x32_bf16 v[30:33], v[142:145], v[206:209], v[30:33]
	v_mfma_f32_16x16x32_bf16 v[26:29], v[150:153], v[206:209], v[26:29]
	v_mfma_f32_16x16x32_bf16 v[14:17], v[142:145], v[214:217], v[14:17]
	v_mfma_f32_16x16x32_bf16 v[10:13], v[150:153], v[214:217], v[10:13]
	v_mfma_f32_16x16x32_bf16 v[62:65], v[146:149], v[194:197], v[62:65]
	v_mfma_f32_16x16x32_bf16 v[58:61], v[154:157], v[194:197], v[58:61]
	v_mfma_f32_16x16x32_bf16 v[46:49], v[146:149], v[202:205], v[46:49]
	v_mfma_f32_16x16x32_bf16 v[42:45], v[154:157], v[202:205], v[42:45]
	v_mfma_f32_16x16x32_bf16 v[30:33], v[146:149], v[210:213], v[30:33]
	v_mfma_f32_16x16x32_bf16 v[26:29], v[154:157], v[210:213], v[26:29]
	v_mfma_f32_16x16x32_bf16 v[14:17], v[146:149], v[218:221], v[14:17]
	v_mfma_f32_16x16x32_bf16 v[10:13], v[154:157], v[218:221], v[10:13]
	v_mfma_f32_16x16x32_bf16 v[54:57], v[162:165], v[190:193], v[54:57]
	v_mfma_f32_16x16x32_bf16 v[50:53], v[170:173], v[190:193], v[50:53]
	v_mfma_f32_16x16x32_bf16 v[38:41], v[162:165], v[198:201], v[38:41]
	v_mfma_f32_16x16x32_bf16 v[34:37], v[170:173], v[198:201], v[34:37]
	v_mfma_f32_16x16x32_bf16 v[22:25], v[162:165], v[206:209], v[22:25]
	v_mfma_f32_16x16x32_bf16 v[18:21], v[170:173], v[206:209], v[18:21]
	v_mfma_f32_16x16x32_bf16 v[6:9], v[162:165], v[214:217], v[6:9]
	v_mfma_f32_16x16x32_bf16 v[2:5], v[170:173], v[214:217], v[2:5]
	v_mfma_f32_16x16x32_bf16 v[54:57], v[166:169], v[194:197], v[54:57]
	v_mfma_f32_16x16x32_bf16 v[50:53], v[174:177], v[194:197], v[50:53]
	v_mfma_f32_16x16x32_bf16 v[38:41], v[166:169], v[202:205], v[38:41]
	v_mfma_f32_16x16x32_bf16 v[34:37], v[174:177], v[202:205], v[34:37]
	v_mfma_f32_16x16x32_bf16 v[22:25], v[166:169], v[210:213], v[22:25]
	v_mfma_f32_16x16x32_bf16 v[18:21], v[174:177], v[210:213], v[18:21]
	v_mfma_f32_16x16x32_bf16 v[6:9], v[166:169], v[218:221], v[6:9]
	v_mfma_f32_16x16x32_bf16 v[2:5], v[174:177], v[218:221], v[2:5]
	s_cmp_lg_u32 s100, 0
	s_cbranch_scc1 .Lmy_h2_28
	s_barrier
.Lmy_h2_28:
	s_setprio 0
	s_add_i32 s51, 0, 0x18000
	s_add_i32 s83, 0, 0x1c000
	v_add_u32_e32 v154, s51, v159
	v_add_u32_e32 v161, s83, v159
	ds_read_b128 v[142:145], v154
	ds_read_b128 v[146:149], v154 offset:1024
	ds_read_b128 v[150:153], v154 offset:2048
	ds_read_b128 v[154:157], v154 offset:3072
	ds_read_b128 v[162:165], v161
	ds_read_b128 v[166:169], v161 offset:1024
	ds_read_b128 v[170:173], v161 offset:2048
	ds_read_b128 v[174:177], v161 offset:3072
	s_add_u32 s42, s42, 0x80000
	s_addc_u32 s43, s43, 0
	s_mov_b32 m0, s63
	v_lshl_add_u64 v[242:243], s[42:43], 0, v[132:133]
	ds_read_b128 v[190:193], v160 offset:32768
	ds_read_b128 v[194:197], v160 offset:33792
	ds_read_b128 v[198:201], v160 offset:34816
	ds_read_b128 v[202:205], v160 offset:35840
	ds_read_b128 v[206:209], v160 offset:36864
	ds_read_b128 v[210:213], v160 offset:37888
	ds_read_b128 v[214:217], v160 offset:38912
	ds_read_b128 v[218:221], v160 offset:39936
	global_load_lds_dwordx4 v[242:243], off
	v_lshl_add_u64 v[242:243], s[42:43], 0, v[134:135]
	s_mov_b32 m0, s64
	s_nop 0
	global_load_lds_dwordx4 v[242:243], off
	s_waitcnt vmcnt(8)
	s_waitcnt lgkmcnt(0)
	s_cmp_eq_u32 s100, 0
	s_cbranch_scc1 .Lmy_h2_29
	s_setprio 1
	s_barrier

.Lmy_h2_30:
	s_setprio 0
	s_add_i32 s42, s51, s60
	v_lshl_add_u64 v[178:179], v[178:179], 0, s[16:17]
	s_mov_b32 m0, s42
	ds_read_b128 v[190:193], v160 offset:49152
	ds_read_b128 v[194:197], v160 offset:50176
	ds_read_b128 v[198:201], v160 offset:51200
	ds_read_b128 v[202:205], v160 offset:52224
	ds_read_b128 v[206:209], v160 offset:53248
	ds_read_b128 v[210:213], v160 offset:54272
	ds_read_b128 v[214:217], v160 offset:55296
	ds_read_b128 v[218:221], v160 offset:56320
	global_load_lds_dwordx4 v[178:179], off
	s_add_i32 m0, s42, 0x2000
	s_add_u32 s40, s40, 0x80080
	v_lshl_add_u64 v[178:179], v[222:223], 0, s[16:17]
	s_addc_u32 s41, s41, 0
	s_add_i32 s42, s83, s60
	global_load_lds_dwordx4 v[178:179], off
	v_lshl_add_u64 v[178:179], s[40:41], 0, v[180:181]
	s_mov_b32 m0, s42
	s_nop 0
	global_load_lds_dwordx4 v[178:179], off
	v_lshl_add_u64 v[178:179], s[40:41], 0, v[136:137]
	s_add_i32 m0, s42, 0x2000
	s_nop 0
	global_load_lds_dwordx4 v[178:179], off
	v_lshl_add_u64 v[178:179], v[238:239], 0, s[16:17]
	s_mov_b32 m0, s74
	s_nop 0
	global_load_lds_dwordx4 v[178:179], off
	v_lshl_add_u64 v[178:179], v[240:241], 0, s[16:17]
	s_mov_b32 m0, s75
	s_nop 0
	global_load_lds_dwordx4 v[178:179], off
	s_waitcnt vmcnt(8)
	s_waitcnt lgkmcnt(0)
	s_cmp_eq_u32 s100, 0
	s_cbranch_scc1 .Lmy_h2_31
	s_setprio 1
	s_barrier

.Lmy_h2_32:
	s_setprio 0
	s_add_i32 s49, s49, 2
	s_add_u32 s38, s38, 0x100
	s_addc_u32 s39, s39, 0
	s_add_u32 s46, s46, 0x100
	s_addc_u32 s47, s47, 0
	s_cmp_gt_u32 s49, 29
	s_cbranch_scc0 .LBB0_1018
	s_and_b64 vcc, exec, s[34:35]
	s_cbranch_vccz .LBB0_1021

.LBB0_1218:
	s_andn2_b64 vcc, exec, s[54:55]
	s_mov_b64 s[10:11], -1
	s_cbranch_vccnz .LBB0_1010
	s_andn2_b64 vcc, exec, s[14:15]
	s_cbranch_vccnz .LBB0_1009
	s_branch .LBB0_1009

.LBB0_1222:
	s_add_u32 s8, s0, s69
	s_addc_u32 s9, s1, 0
	s_load_dwordx2 s[28:29], s[8:9], 0x118
	v_readlane_b32 s2, v255, 43
	s_cmp_lg_u32 s2, 0
	s_mov_b32 s66, 0x3f22f983
	s_cbranch_scc1 .LBB0_1327
	s_add_i32 s6, s6, s33
	v_readlane_b32 s7, v255, 17
	s_sub_i32 s7, s6, s7
	s_ashr_i32 s8, s7, 31
	s_abs_i32 s7, s7
	v_readlane_b32 s9, v255, 20
	s_mul_hi_u32 s9, s7, s9
	v_readlane_b32 s10, v255, 21
	s_mul_i32 s9, s9, s10
	s_sub_i32 s7, s7, s9
	s_sub_i32 s9, s7, s10
	s_cmp_ge_u32 s7, s10
	s_cselect_b32 s7, s9, s7
	s_sub_i32 s9, s7, s10
	s_cmp_ge_u32 s7, s10
	s_cselect_b32 s7, s9, s7
	s_xor_b32 s7, s7, s8
	v_mov_b32_e32 v16, v0
	s_sub_i32 s7, s7, s8
	s_cmp_gt_i32 s7, 15
	v_readfirstlane_b32 s30, v16
	s_cbranch_scc1 .LBB0_1237
	v_lshlrev_b32_e32 v2, 4, v16
	s_waitcnt lgkmcnt(0)
	v_add_u32_e32 v3, 0x2000, v2
	v_ashrrev_i32_e32 v4, 31, v3
	v_lshrrev_b32_e32 v4, 22, v4
	v_add_u32_e32 v4, v3, v4
	v_ashrrev_i32_e32 v10, 10, v4
	v_mul_i32_i24_e32 v5, 0x400, v10
	v_sub_u32_e32 v3, v3, v5
	v_lshrrev_b32_e32 v5, 4, v3
	v_bitop3_b32 v3, v5, v3, 32 bitop3:0x6c
	v_ashrrev_i32_e32 v5, 31, v3
	v_lshrrev_b32_e32 v5, 26, v5
	v_add_u32_e32 v5, v3, v5
	v_ashrrev_i32_e32 v11, 6, v5
	v_and_b32_e32 v5, 0xc0, v5
	v_sub_u32_e32 v3, v3, v5
	v_lshlrev_b32_e32 v4, 5, v10
	v_ashrrev_i16_sdwa v3, v224, sext(v3) dst_sel:DWORD dst_unused:UNUSED_PAD src0_sel:DWORD src1_sel:BYTE_0
	v_and_b32_e32 v4, 32, v4
	v_bfe_i32 v12, v3, 0, 16
	v_add_u32_e32 v3, v4, v12
	v_lshlrev_b32_e32 v4, 3, v10
	v_and_b32_e32 v4, 0xffff0, v4
	v_add_lshl_u32 v4, v11, v4, 12
	s_waitcnt vmcnt(0)
	v_lshl_add_u32 v132, v3, 1, v4
	v_bfe_i32 v4, v16, 27, 1
	v_lshrrev_b32_e32 v4, 22, v4
	v_add_u32_e32 v4, v2, v4
	v_and_b32_e32 v4, 0xfffffc00, v4
	v_sub_u32_e32 v2, v2, v4
	v_lshrrev_b32_e32 v4, 4, v2
	v_bitop3_b32 v2, v4, v2, 32 bitop3:0x6c
	s_add_u32 s8, s28, 0x1ff00000
	v_ashrrev_i32_e32 v4, 31, v2
	s_addc_u32 s9, s29, 0
	v_ashrrev_i32_e32 v3, 31, v16
	v_lshrrev_b32_e32 v4, 26, v4
	s_add_u32 s21, s28, 0x15800000
	v_lshrrev_b32_e32 v3, 26, v3
	v_add_u32_e32 v4, v2, v4
	s_addc_u32 s42, s29, 0
	v_add_u32_e32 v3, v16, v3
	v_ashrrev_i32_e32 v14, 6, v4
	v_and_b32_e32 v4, 0xc0, v4
	s_add_u32 s18, s0, s69
	v_ashrrev_i32_e32 v13, 6, v3
	v_sub_u32_e32 v2, v2, v4
	s_addc_u32 s19, s1, 0
	s_ashr_i32 s10, s7, 2
	v_lshlrev_b32_e32 v3, 5, v13
	v_ashrrev_i16_sdwa v2, v224, sext(v2) dst_sel:DWORD dst_unused:UNUSED_PAD src0_sel:DWORD src1_sel:BYTE_0
	s_ashr_i32 s31, s30, 6
	s_and_b32 s44, s7, 3
	v_and_b32_e32 v3, 32, v3
	v_bfe_i32 v15, v2, 0, 16
	s_ashr_i32 s11, s10, 31
	s_ashr_i32 s34, s30, 8
	s_lshl_b32 s43, s31, 10
	v_add_u32_e32 v2, v3, v15
	v_lshlrev_b32_e32 v3, 3, v13
	s_lshl_b32 s24, s44, 20
	s_lshl_b64 s[14:15], s[10:11], 20
	v_and_b32_e32 v3, 0xffff0, v3
	s_add_u32 s14, s21, s14
	v_add_lshl_u32 v3, v14, v3, 12
	s_addc_u32 s15, s42, s15
	s_add_i32 s11, s43, 0
	v_lshl_add_u32 v134, v2, 1, v3
	s_add_i32 m0, s11, 0x10000
	s_load_dwordx2 s[18:19], s[18:19], 0x110
	global_load_lds_dwordx4 v134, s[14:15]
	s_add_i32 m0, s11, 0x12000
	s_add_u32 s22, s14, 0x80000
	global_load_lds_dwordx4 v132, s[14:15]
	s_addc_u32 s23, s15, 0
	s_add_i32 m0, s11, 0x14000
	v_mov_b32_e32 v135, v181
	global_load_lds_dwordx4 v134, s[22:23]
	s_add_i32 m0, s11, 0x16000
	v_mov_b32_e32 v133, v181
	global_load_lds_dwordx4 v132, s[22:23]
	s_add_u32 s22, s8, s24
	s_addc_u32 s23, s9, 0
	s_add_i32 s45, s11, 0x2000
	s_mov_b32 m0, s11
	s_add_u32 s24, s22, 0x80000
	global_load_lds_dwordx4 v134, s[22:23]
	s_mov_b32 m0, s45
	s_addc_u32 s25, s23, 0
	s_add_i32 s46, s11, 0x4000
	global_load_lds_dwordx4 v132, s[22:23]
	s_mov_b32 m0, s46
	s_add_i32 s47, s11, 0x6000
	global_load_lds_dwordx4 v134, s[24:25]
	s_mov_b32 m0, s47
	s_cmp_eq_u32 s34, 1
	global_load_lds_dwordx4 v132, s[24:25]
	v_lshl_add_u64 v[8:9], s[14:15], 0, v[134:135]
	v_lshl_add_u64 v[6:7], s[14:15], 0, v[132:133]
	v_lshl_add_u64 v[2:3], s[22:23], 0, v[134:135]
	s_cselect_b64 s[24:25], -1, 0
	s_cmp_lg_u32 s34, 1
	v_lshl_add_u64 v[4:5], s[22:23], 0, v[132:133]
	s_cbranch_scc1 .LBB0_1226
.LBB0_1226:
	s_add_u32 s26, s28, 0xe0000
	s_addc_u32 s27, s29, 0
	s_add_u32 s28, s28, 0x20300000
	s_addc_u32 s29, s29, 0
	v_bfe_u32 v152, v16, 4, 2
	s_lshl_b32 s31, s31, 5
	v_and_b32_e32 v131, 15, v16
	v_lshlrev_b32_e32 v17, 4, v152
	v_lshlrev_b32_e32 v16, 2, v16
	s_and_b32 s49, s31, 0x60
	s_add_i32 m0, s11, 0x18000
	v_lshl_add_u64 v[8:9], v[8:9], 0, s[16:17]
	s_lshl_b32 s48, s34, 6
	v_lshl_or_b32 v17, v131, 6, v17
	s_lshl_b32 s34, s34, 13
	v_and_b32_e32 v16, 32, v16
	s_lshl_b32 s31, s49, 7
	s_waitcnt vmcnt(2)
	s_barrier
	global_load_lds_dwordx4 v[8:9], off
	v_lshl_add_u64 v[6:7], v[6:7], 0, s[16:17]
	s_add_i32 m0, s11, 0x1a000
	s_add_i32 s50, s11, 0x8000
	s_add_i32 s51, s11, 0xa000
	v_bitop3_b32 v18, v17, s34, v16 bitop3:0xde
	global_load_lds_dwordx4 v[6:7], off
	v_lshl_add_u64 v[2:3], v[2:3], 0, s[16:17]
	s_mov_b32 m0, s50
	s_add_u32 s34, s14, 0x80080
	global_load_lds_dwordx4 v[2:3], off
	v_lshl_add_u64 v[2:3], v[4:5], 0, s[16:17]
	s_mov_b32 m0, s51
	s_addc_u32 s35, s15, 0
	global_load_lds_dwordx4 v[2:3], off
	s_add_i32 m0, s11, 0x1c000
	v_lshl_add_u64 v[2:3], s[34:35], 0, v[134:135]
	global_load_lds_dwordx4 v[2:3], off
	v_lshl_add_u64 v[2:3], s[34:35], 0, v[132:133]
	s_add_i32 m0, s11, 0x1e000
	s_cmpk_lt_u32 s30, 0x100
	global_load_lds_dwordx4 v[2:3], off
	v_lshlrev_b32_e32 v2, 15, v13
	v_and_b32_e32 v2, 0xffff0000, v2
	v_lshl_add_u32 v2, v14, 12, v2
	v_and_b32_e32 v3, 1, v13
	v_lshl_or_b32 v2, v3, 6, v2
	v_lshl_add_u32 v136, v15, 1, v2
	v_lshlrev_b32_e32 v2, 15, v10
	v_and_b32_e32 v2, 0xffff0000, v2
	s_waitcnt vmcnt(6)
	v_lshl_add_u32 v2, v11, 12, v2
	v_and_b32_e32 v3, 1, v10
	v_lshl_or_b32 v2, v3, 6, v2
	v_bitop3_b32 v153, v17, s31, v16 bitop3:0xde
	s_cselect_b64 s[30:31], -1, 0
	v_mov_b32_e32 v137, v181
	v_lshl_add_u32 v138, v12, 1, v2
	v_mov_b32_e32 v139, v181
	s_mov_b32 s54, 0
	v_add_u32_e32 v154, 0, v18
	s_barrier
	s_branch .LBB0_1229

.LBB0_1230:
	s_add_u32 s38, s36, 0xfff80080
	s_addc_u32 s39, s37, -1
	s_add_i32 s64, 0, 0x10000
	s_cmp_eq_u32 s63, 28
	s_cselect_b32 s41, s57, s39
	s_cselect_b32 s40, s58, s38
	v_add_u32_e32 v155, s64, v153
	s_cselect_b32 s39, s59, s62
	s_cselect_b32 s38, s60, s61
	s_add_i32 s74, 0, 0x14000
	ds_read_b128 v[140:143], v155
	ds_read_b128 v[144:147], v155 offset:1024
	ds_read_b128 v[148:151], v155 offset:2048
	ds_read_b128 v[156:159], v155 offset:3072
	v_add_u32_e32 v155, s74, v153
	ds_read_b128 v[160:163], v155
	ds_read_b128 v[164:167], v155 offset:1024
	ds_read_b128 v[168:171], v155 offset:2048
	ds_read_b128 v[172:175], v155 offset:3072
	v_lshl_add_u64 v[218:219], s[36:37], 0, v[136:137]
	s_add_i32 m0, s11, 0xc000
	ds_read_b128 v[176:179], v154
	ds_read_b128 v[190:193], v154 offset:1024
	ds_read_b128 v[194:197], v154 offset:2048
	ds_read_b128 v[198:201], v154 offset:3072
	ds_read_b128 v[202:205], v154 offset:4096
	ds_read_b128 v[206:209], v154 offset:5120
	ds_read_b128 v[210:213], v154 offset:6144
	ds_read_b128 v[214:217], v154 offset:7168
	global_load_lds_dwordx4 v[218:219], off
	v_lshl_add_u64 v[218:219], s[36:37], 0, v[138:139]
	s_add_i32 m0, s11, 0xe000
	s_nop 0
	global_load_lds_dwordx4 v[218:219], off
	s_waitcnt vmcnt(8)
	s_waitcnt lgkmcnt(0)
	s_cmp_eq_u32 s100, 0
	s_cbranch_scc1 .Lmy_h2_33
	s_setprio 1
	s_barrier
.Lmy_h2_33:
	v_mfma_f32_16x16x32_bf16 v[126:129], v[140:143], v[176:179], v[126:129]
	v_mfma_f32_16x16x32_bf16 v[122:125], v[148:151], v[176:179], v[122:125]
	v_mfma_f32_16x16x32_bf16 v[110:113], v[140:143], v[194:197], v[110:113]
	v_mfma_f32_16x16x32_bf16 v[106:109], v[148:151], v[194:197], v[106:109]
	v_mfma_f32_16x16x32_bf16 v[94:97], v[140:143], v[202:205], v[94:97]
	v_mfma_f32_16x16x32_bf16 v[90:93], v[148:151], v[202:205], v[90:93]
	v_mfma_f32_16x16x32_bf16 v[78:81], v[140:143], v[210:213], v[78:81]
	v_mfma_f32_16x16x32_bf16 v[74:77], v[148:151], v[210:213], v[74:77]
	v_mfma_f32_16x16x32_bf16 v[126:129], v[144:147], v[190:193], v[126:129]
	v_mfma_f32_16x16x32_bf16 v[122:125], v[156:159], v[190:193], v[122:125]
	v_mfma_f32_16x16x32_bf16 v[110:113], v[144:147], v[198:201], v[110:113]
	v_mfma_f32_16x16x32_bf16 v[106:109], v[156:159], v[198:201], v[106:109]
	v_mfma_f32_16x16x32_bf16 v[94:97], v[144:147], v[206:209], v[94:97]
	v_mfma_f32_16x16x32_bf16 v[90:93], v[156:159], v[206:209], v[90:93]
	v_mfma_f32_16x16x32_bf16 v[78:81], v[144:147], v[214:217], v[78:81]
	v_mfma_f32_16x16x32_bf16 v[74:77], v[156:159], v[214:217], v[74:77]
	v_mfma_f32_16x16x32_bf16 v[118:121], v[160:163], v[176:179], v[118:121]
	v_mfma_f32_16x16x32_bf16 v[114:117], v[168:171], v[176:179], v[114:117]
	v_mfma_f32_16x16x32_bf16 v[102:105], v[160:163], v[194:197], v[102:105]
	v_mfma_f32_16x16x32_bf16 v[98:101], v[168:171], v[194:197], v[98:101]
	v_mfma_f32_16x16x32_bf16 v[86:89], v[160:163], v[202:205], v[86:89]
	v_mfma_f32_16x16x32_bf16 v[82:85], v[168:171], v[202:205], v[82:85]
	v_mfma_f32_16x16x32_bf16 v[70:73], v[160:163], v[210:213], v[70:73]
	v_mfma_f32_16x16x32_bf16 v[66:69], v[168:171], v[210:213], v[66:69]
	v_mfma_f32_16x16x32_bf16 v[118:121], v[164:167], v[190:193], v[118:121]
	v_mfma_f32_16x16x32_bf16 v[114:117], v[172:175], v[190:193], v[114:117]
	v_mfma_f32_16x16x32_bf16 v[102:105], v[164:167], v[198:201], v[102:105]
	v_mfma_f32_16x16x32_bf16 v[98:101], v[172:175], v[198:201], v[98:101]
	v_mfma_f32_16x16x32_bf16 v[86:89], v[164:167], v[206:209], v[86:89]
	v_mfma_f32_16x16x32_bf16 v[82:85], v[172:175], v[206:209], v[82:85]
	v_mfma_f32_16x16x32_bf16 v[70:73], v[164:167], v[214:217], v[70:73]
	v_mfma_f32_16x16x32_bf16 v[66:69], v[172:175], v[214:217], v[66:69]
	s_cmp_lg_u32 s100, 0
	s_cbranch_scc1 .Lmy_h2_34
	s_barrier
.Lmy_h2_34:
	s_setprio 0
	s_add_i32 s64, s64, s43
	v_lshl_add_u64 v[218:219], s[38:39], 0, v[134:135]
	s_mov_b32 m0, s64
	ds_read_b128 v[176:179], v154 offset:16384
	ds_read_b128 v[190:193], v154 offset:17408
	ds_read_b128 v[194:197], v154 offset:18432
	ds_read_b128 v[198:201], v154 offset:19456
	ds_read_b128 v[202:205], v154 offset:20480
	ds_read_b128 v[206:209], v154 offset:21504
	ds_read_b128 v[210:213], v154 offset:22528
	ds_read_b128 v[214:217], v154 offset:23552
	global_load_lds_dwordx4 v[218:219], off
	s_add_i32 m0, s64, 0x2000
	s_add_u32 s70, s38, 0x80000
	v_lshl_add_u64 v[220:221], s[38:39], 0, v[132:133]
	s_addc_u32 s71, s39, 0
	s_add_i32 s64, s74, s43
	global_load_lds_dwordx4 v[220:221], off
	v_lshl_add_u64 v[222:223], s[70:71], 0, v[134:135]
	s_mov_b32 m0, s64
	v_lshl_add_u64 v[238:239], s[40:41], 0, v[132:133]
	global_load_lds_dwordx4 v[222:223], off
	v_lshl_add_u64 v[222:223], s[70:71], 0, v[132:133]
	s_add_i32 m0, s64, 0x2000
	s_nop 0
	global_load_lds_dwordx4 v[222:223], off
	v_lshl_add_u64 v[222:223], s[40:41], 0, v[134:135]
	s_mov_b32 m0, s11
	s_nop 0
	global_load_lds_dwordx4 v[222:223], off
	s_mov_b32 m0, s45
	s_nop 0
	global_load_lds_dwordx4 v[238:239], off
	s_waitcnt vmcnt(8)
	s_waitcnt lgkmcnt(0)
	s_cmp_eq_u32 s100, 0
	s_cbranch_scc1 .Lmy_h2_35
	s_setprio 1
	s_barrier
.Lmy_h2_35:
	v_mfma_f32_16x16x32_bf16 v[62:65], v[140:143], v[176:179], v[62:65]
	v_mfma_f32_16x16x32_bf16 v[58:61], v[148:151], v[176:179], v[58:61]
	v_mfma_f32_16x16x32_bf16 v[46:49], v[140:143], v[194:197], v[46:49]
	v_mfma_f32_16x16x32_bf16 v[42:45], v[148:151], v[194:197], v[42:45]
	v_mfma_f32_16x16x32_bf16 v[30:33], v[140:143], v[202:205], v[30:33]
	v_mfma_f32_16x16x32_bf16 v[26:29], v[148:151], v[202:205], v[26:29]
	v_mfma_f32_16x16x32_bf16 v[14:17], v[140:143], v[210:213], v[14:17]
	v_mfma_f32_16x16x32_bf16 v[10:13], v[148:151], v[210:213], v[10:13]
	v_mfma_f32_16x16x32_bf16 v[62:65], v[144:147], v[190:193], v[62:65]
	v_mfma_f32_16x16x32_bf16 v[58:61], v[156:159], v[190:193], v[58:61]
	v_mfma_f32_16x16x32_bf16 v[46:49], v[144:147], v[198:201], v[46:49]
	v_mfma_f32_16x16x32_bf16 v[42:45], v[156:159], v[198:201], v[42:45]
	v_mfma_f32_16x16x32_bf16 v[30:33], v[144:147], v[206:209], v[30:33]
	v_mfma_f32_16x16x32_bf16 v[26:29], v[156:159], v[206:209], v[26:29]
	v_mfma_f32_16x16x32_bf16 v[14:17], v[144:147], v[214:217], v[14:17]
	v_mfma_f32_16x16x32_bf16 v[10:13], v[156:159], v[214:217], v[10:13]
	v_mfma_f32_16x16x32_bf16 v[54:57], v[160:163], v[176:179], v[54:57]
	v_mfma_f32_16x16x32_bf16 v[50:53], v[168:171], v[176:179], v[50:53]
	v_mfma_f32_16x16x32_bf16 v[38:41], v[160:163], v[194:197], v[38:41]
	v_mfma_f32_16x16x32_bf16 v[34:37], v[168:171], v[194:197], v[34:37]
	v_mfma_f32_16x16x32_bf16 v[22:25], v[160:163], v[202:205], v[22:25]
	v_mfma_f32_16x16x32_bf16 v[18:21], v[168:171], v[202:205], v[18:21]
	v_mfma_f32_16x16x32_bf16 v[6:9], v[160:163], v[210:213], v[6:9]
	v_mfma_f32_16x16x32_bf16 v[2:5], v[168:171], v[210:213], v[2:5]
	v_mfma_f32_16x16x32_bf16 v[54:57], v[164:167], v[190:193], v[54:57]
	v_mfma_f32_16x16x32_bf16 v[50:53], v[172:175], v[190:193], v[50:53]
	v_mfma_f32_16x16x32_bf16 v[38:41], v[164:167], v[198:201], v[38:41]
	v_mfma_f32_16x16x32_bf16 v[34:37], v[172:175], v[198:201], v[34:37]
	v_mfma_f32_16x16x32_bf16 v[22:25], v[164:167], v[206:209], v[22:25]
	v_mfma_f32_16x16x32_bf16 v[18:21], v[172:175], v[206:209], v[18:21]
	v_mfma_f32_16x16x32_bf16 v[6:9], v[164:167], v[214:217], v[6:9]
	v_mfma_f32_16x16x32_bf16 v[2:5], v[172:175], v[214:217], v[2:5]
	s_cmp_lg_u32 s100, 0
	s_cbranch_scc1 .Lmy_h2_36
	s_barrier
.Lmy_h2_36:
	s_setprio 0
	s_add_i32 s64, 0, 0x18000
	v_add_u32_e32 v155, s64, v153
	s_add_i32 s70, 0, 0x1c000
	ds_read_b128 v[140:143], v155
	ds_read_b128 v[144:147], v155 offset:1024
	ds_read_b128 v[148:151], v155 offset:2048
	ds_read_b128 v[156:159], v155 offset:3072
	v_add_u32_e32 v155, s70, v153
	ds_read_b128 v[160:163], v155
	ds_read_b128 v[164:167], v155 offset:1024
	ds_read_b128 v[168:171], v155 offset:2048
	ds_read_b128 v[172:175], v155 offset:3072
	s_add_u32 s40, s40, 0x80000
	s_addc_u32 s41, s41, 0
	s_mov_b32 m0, s46
	v_lshl_add_u64 v[240:241], s[40:41], 0, v[134:135]
	ds_read_b128 v[176:179], v154 offset:32768
	ds_read_b128 v[190:193], v154 offset:33792
	ds_read_b128 v[194:197], v154 offset:34816
	ds_read_b128 v[198:201], v154 offset:35840
	ds_read_b128 v[202:205], v154 offset:36864
	ds_read_b128 v[206:209], v154 offset:37888
	ds_read_b128 v[210:213], v154 offset:38912
	ds_read_b128 v[214:217], v154 offset:39936
	global_load_lds_dwordx4 v[240:241], off
	v_lshl_add_u64 v[240:241], s[40:41], 0, v[132:133]
	s_mov_b32 m0, s47
	s_nop 0
	global_load_lds_dwordx4 v[240:241], off
	s_waitcnt vmcnt(8)
	s_waitcnt lgkmcnt(0)
	s_cmp_eq_u32 s100, 0
	s_cbranch_scc1 .Lmy_h2_37
	s_setprio 1
	s_barrier

.Lmy_h2_38:
	s_setprio 0
	s_add_i32 s40, s64, s43
	v_lshl_add_u64 v[218:219], v[218:219], 0, s[16:17]
	s_mov_b32 m0, s40
	ds_read_b128 v[176:179], v154 offset:49152
	ds_read_b128 v[190:193], v154 offset:50176
	ds_read_b128 v[194:197], v154 offset:51200
	ds_read_b128 v[198:201], v154 offset:52224
	ds_read_b128 v[202:205], v154 offset:53248
	ds_read_b128 v[206:209], v154 offset:54272
	ds_read_b128 v[210:213], v154 offset:55296
	ds_read_b128 v[214:217], v154 offset:56320
	global_load_lds_dwordx4 v[218:219], off
	s_add_i32 m0, s40, 0x2000
	s_add_u32 s38, s38, 0x80080
	v_lshl_add_u64 v[218:219], v[220:221], 0, s[16:17]
	s_addc_u32 s39, s39, 0
	s_add_i32 s40, s70, s43
	global_load_lds_dwordx4 v[218:219], off
	v_lshl_add_u64 v[218:219], s[38:39], 0, v[134:135]
	s_mov_b32 m0, s40
	s_nop 0
	global_load_lds_dwordx4 v[218:219], off
	v_lshl_add_u64 v[218:219], s[38:39], 0, v[132:133]
	s_add_i32 m0, s40, 0x2000
	s_nop 0
	global_load_lds_dwordx4 v[218:219], off
	v_lshl_add_u64 v[218:219], v[222:223], 0, s[16:17]
	s_mov_b32 m0, s50
	s_nop 0
	global_load_lds_dwordx4 v[218:219], off
	v_lshl_add_u64 v[218:219], v[238:239], 0, s[16:17]
	s_mov_b32 m0, s51
	s_nop 0
	global_load_lds_dwordx4 v[218:219], off
	s_waitcnt vmcnt(8)
	s_waitcnt lgkmcnt(0)
	s_cmp_eq_u32 s100, 0
	s_cbranch_scc1 .Lmy_h2_39
	s_setprio 1
	s_barrier

.Lmy_h2_40:
	s_setprio 0
	s_add_i32 s63, s63, 2
	s_add_u32 s36, s36, 0x100
	s_addc_u32 s37, s37, 0
	s_add_u32 s61, s61, 0x100
	s_addc_u32 s62, s62, 0
	s_cmp_gt_u32 s63, 29
	s_cbranch_scc0 .LBB0_1230
	s_and_b64 vcc, exec, s[30:31]
	s_cbranch_vccz .LBB0_1233
.LBB0_1233:
	v_mov_b32_e32 v140, v131
	v_mov_b32_e32 v141, v152
	s_lshl_b32 s36, s56, 8
	s_lshl_b32 s37, s55, 8
	s_add_i32 s36, s36, s48
	v_add_u32_e32 v140, s36, v140
	s_or_b32 s36, s37, s49
	v_lshl_add_u32 v149, v141, 2, s36
	v_ashrrev_i32_e32 v141, 31, v140
	v_lshl_add_u64 v[142:143], v[140:141], 3, s[26:27]
	global_load_dwordx2 v[144:145], v[142:143], off
	v_and_b32_e32 v155, 0x3fc, v149
	s_movk_i32 s36, 0x200
	v_and_b32_e32 v156, 0x1fc, v149
	v_add_u32_e32 v158, 16, v149
	v_and_b32_e32 v159, 0x3fc, v158
	v_add_u32_e32 v162, 0x80, v149
	v_and_b32_e32 v163, 0x3fc, v162
	v_readlane_b32 s64, v255, 40
	s_mov_b32 s68, 0xff61b1e6
	s_mov_b32 s74, 0x24600000
	s_waitcnt vmcnt(0)
	v_ffbh_u32_e32 v141, v145
	v_min_u32_e32 v141, 32, v141
	v_lshlrev_b64 v[144:145], v141, v[144:145]
	v_min_u32_e32 v144, 1, v144
	v_or_b32_e32 v144, v145, v144
	v_cvt_f32_u32_e32 v144, v144
	v_sub_u32_e32 v141, 32, v141
	v_ldexp_f32 v141, v144, v141
	v_mul_f32_e32 v141, 0x30800000, v141
	v_fmamk_f32 v141, v141, 0x3a000000, v1
	v_cmp_gt_f32_e32 vcc, s65, v141
	v_mul_f32_e32 v144, 0x4b800000, v141
	s_nop 0
	v_cndmask_b32_e32 v141, v141, v144, vcc
	v_rsq_f32_e32 v141, v141
	s_nop 0
	v_mul_f32_e32 v144, 0x45800000, v141
	v_cndmask_b32_e32 v148, v141, v144, vcc
	v_and_b32_e32 v141, 0xfffffc00, v149
	v_pk_mul_f32 v[146:147], v[128:129], v[148:149] op_sel_hi:[1,0]
	v_cmp_gt_u32_e32 vcc, s36, v155
	v_add_u32_e32 v128, v141, v140
	v_ashrrev_i32_e32 v129, 31, v128
	v_cndmask_b32_e32 v180, v230, v231, vcc
	v_pk_mul_f32 v[144:145], v[126:127], v[148:149] op_sel_hi:[1,0]
	v_lshl_add_u64 v[126:127], s[18:19], 0, v[180:181]
	v_lshlrev_b64 v[128:129], 11, v[128:129]
	v_lshl_add_u64 v[150:151], v[126:127], 0, v[128:129]
	v_lshlrev_b32_e32 v180, 2, v156
	v_lshl_add_u64 v[150:151], v[150:151], 0, v[180:181]
	global_store_dwordx4 v[150:151], v[144:147], off
	v_cmp_gt_u32_e32 vcc, s36, v159
	v_pk_mul_f32 v[160:161], v[120:121], v[148:149] op_sel_hi:[1,0]
	v_cvt_pk_bf16_f32 v144, v144, v145
	v_cvt_pk_bf16_f32 v145, v146, v147
	v_lshl_add_u64 v[146:147], s[28:29], 0, v[128:129]
	v_lshlrev_b32_e32 v128, 1, v155
	v_mov_b32_e32 v129, v181
	v_lshl_add_u64 v[146:147], v[146:147], 0, v[128:129]
	v_and_b32_e32 v155, 0xfffffc00, v158
	global_store_dwordx2 v[146:147], v[144:145], off
	v_pk_mul_f32 v[146:147], v[124:125], v[148:149] op_sel_hi:[1,0]
	v_add_u32_e32 v124, v155, v140
	v_pk_mul_f32 v[144:145], v[122:123], v[148:149] op_sel_hi:[1,0]
	v_cndmask_b32_e32 v122, v230, v231, vcc
	v_mov_b32_e32 v123, v181
	v_ashrrev_i32_e32 v125, 31, v124
	v_lshl_add_u64 v[122:123], s[18:19], 0, v[122:123]
	v_lshlrev_b64 v[150:151], 11, v[124:125]
	v_and_b32_e32 v124, 0x1fc, v158
	v_lshl_add_u64 v[156:157], v[122:123], 0, v[150:151]
	v_lshlrev_b32_e32 v124, 2, v124
	v_mov_b32_e32 v125, v181
	v_lshl_add_u64 v[156:157], v[156:157], 0, v[124:125]
	global_store_dwordx4 v[156:157], v[144:147], off
	v_cvt_pk_bf16_f32 v156, v144, v145
	v_cvt_pk_bf16_f32 v157, v146, v147
	v_cmp_gt_u32_e32 vcc, s36, v163
	v_pk_mul_f32 v[116:117], v[116:117], v[148:149] op_sel_hi:[1,0]
	v_lshl_add_u64 v[146:147], s[28:29], 0, v[150:151]
	v_lshlrev_b32_e32 v144, 1, v159
	v_mov_b32_e32 v145, v181
	v_lshl_add_u64 v[146:147], v[146:147], 0, v[144:145]
	global_store_dwordx2 v[146:147], v[156:157], off
	v_and_b32_e32 v156, 0xfffffc00, v162
	v_add_u32_e32 v120, v156, v140
	v_pk_mul_f32 v[158:159], v[118:119], v[148:149] op_sel_hi:[1,0]
	v_cndmask_b32_e32 v118, v230, v231, vcc
	v_mov_b32_e32 v119, v181
	v_ashrrev_i32_e32 v121, 31, v120
	v_lshl_add_u64 v[118:119], s[18:19], 0, v[118:119]
	v_lshlrev_b64 v[146:147], 11, v[120:121]
	v_and_b32_e32 v120, 0x1fc, v162
	v_lshl_add_u64 v[150:151], v[118:119], 0, v[146:147]
	v_lshlrev_b32_e32 v120, 2, v120
	v_mov_b32_e32 v121, v181
	v_lshl_add_u64 v[150:151], v[150:151], 0, v[120:121]
	global_store_dwordx4 v[150:151], v[158:161], off
	v_cvt_pk_bf16_f32 v150, v158, v159
	v_add_u32_e32 v162, 0x90, v149
	v_and_b32_e32 v157, 0xfffffc00, v162
	v_lshl_add_u64 v[158:159], s[28:29], 0, v[146:147]
	v_lshlrev_b32_e32 v146, 1, v163
	v_mov_b32_e32 v147, v181
	v_lshl_add_u64 v[158:159], v[158:159], 0, v[146:147]
	v_and_b32_e32 v163, 0x3fc, v162
	v_cvt_pk_bf16_f32 v151, v160, v161
	global_store_dwordx2 v[158:159], v[150:151], off
	v_cmp_gt_u32_e32 vcc, s36, v163
	v_add_u32_e32 v150, v157, v140
	v_pk_mul_f32 v[114:115], v[114:115], v[148:149] op_sel_hi:[1,0]
	v_cndmask_b32_e32 v148, v230, v231, vcc
	v_mov_b32_e32 v149, v181
	v_ashrrev_i32_e32 v151, 31, v150
	v_lshl_add_u64 v[148:149], s[18:19], 0, v[148:149]
	v_lshlrev_b64 v[158:159], 11, v[150:151]
	v_and_b32_e32 v150, 0x1fc, v162
	v_lshl_add_u64 v[160:161], v[148:149], 0, v[158:159]
	v_lshlrev_b32_e32 v150, 2, v150
	v_mov_b32_e32 v151, v181
	v_lshl_add_u64 v[160:161], v[160:161], 0, v[150:151]
	global_store_dwordx4 v[160:161], v[114:117], off
	v_cvt_pk_bf16_f32 v160, v114, v115
	v_cvt_pk_bf16_f32 v161, v116, v117
	v_add_u32_e32 v162, 16, v140
	s_mov_b64 s[36:37], -1
	v_lshl_add_u64 v[116:117], s[28:29], 0, v[158:159]
	v_lshlrev_b32_e32 v114, 1, v163
	v_mov_b32_e32 v115, v181
	v_lshl_add_u64 v[116:117], v[116:117], 0, v[114:115]
	global_store_dwordx2 v[116:117], v[160:161], off
	global_load_dwordx2 v[116:117], v[142:143], off offset:128
	s_waitcnt vmcnt(0)
	v_ffbh_u32_e32 v158, v117
	v_min_u32_e32 v158, 32, v158
	v_lshlrev_b64 v[116:117], v158, v[116:117]
	v_min_u32_e32 v116, 1, v116
	v_or_b32_e32 v116, v117, v116
	v_cvt_f32_u32_e32 v116, v116
	v_sub_u32_e32 v117, 32, v158
	v_add_u32_e32 v158, v141, v162
	v_ashrrev_i32_e32 v159, 31, v158
	v_ldexp_f32 v116, v116, v117
	v_mul_f32_e32 v116, 0x30800000, v116
	v_fmamk_f32 v116, v116, 0x3a000000, v1
	v_cmp_gt_f32_e32 vcc, s65, v116
	v_mul_f32_e32 v117, 0x4b800000, v116
	v_lshlrev_b64 v[158:159], 11, v[158:159]
	v_cndmask_b32_e32 v116, v116, v117, vcc
	v_rsq_f32_e32 v116, v116
	v_lshl_add_u64 v[160:161], v[126:127], 0, v[158:159]
	v_lshl_add_u64 v[160:161], v[160:161], 0, v[180:181]
	v_mul_f32_e32 v117, 0x45800000, v116
	v_cndmask_b32_e32 v116, v116, v117, vcc
	v_pk_mul_f32 v[112:113], v[112:113], v[116:117] op_sel_hi:[1,0]
	v_pk_mul_f32 v[110:111], v[110:111], v[116:117] op_sel_hi:[1,0]
	global_store_dwordx4 v[160:161], v[110:113], off
	v_pk_mul_f32 v[108:109], v[108:109], v[116:117] op_sel_hi:[1,0]
	v_pk_mul_f32 v[106:107], v[106:107], v[116:117] op_sel_hi:[1,0]
	v_cvt_pk_bf16_f32 v110, v110, v111
	v_cvt_pk_bf16_f32 v111, v112, v113
	v_lshl_add_u64 v[112:113], s[28:29], 0, v[158:159]
	v_lshl_add_u64 v[112:113], v[112:113], 0, v[128:129]
	global_store_dwordx2 v[112:113], v[110:111], off
	v_add_u32_e32 v110, v155, v162
	v_ashrrev_i32_e32 v111, 31, v110
	v_lshlrev_b64 v[110:111], 11, v[110:111]
	v_lshl_add_u64 v[112:113], v[122:123], 0, v[110:111]
	v_lshl_add_u64 v[112:113], v[112:113], 0, v[124:125]
	global_store_dwordx4 v[112:113], v[106:109], off
	v_pk_mul_f32 v[104:105], v[104:105], v[116:117] op_sel_hi:[1,0]
	v_pk_mul_f32 v[102:103], v[102:103], v[116:117] op_sel_hi:[1,0]
	v_cvt_pk_bf16_f32 v106, v106, v107
	v_cvt_pk_bf16_f32 v107, v108, v109
	v_lshl_add_u64 v[108:109], s[28:29], 0, v[110:111]
	v_lshl_add_u64 v[108:109], v[108:109], 0, v[144:145]
	global_store_dwordx2 v[108:109], v[106:107], off
	v_add_u32_e32 v106, v156, v162
	v_ashrrev_i32_e32 v107, 31, v106
	v_lshlrev_b64 v[106:107], 11, v[106:107]
	v_lshl_add_u64 v[108:109], v[118:119], 0, v[106:107]
	v_lshl_add_u64 v[108:109], v[108:109], 0, v[120:121]
	global_store_dwordx4 v[108:109], v[102:105], off
	v_pk_mul_f32 v[100:101], v[100:101], v[116:117] op_sel_hi:[1,0]
	v_pk_mul_f32 v[98:99], v[98:99], v[116:117] op_sel_hi:[1,0]
	v_cvt_pk_bf16_f32 v102, v102, v103
	v_cvt_pk_bf16_f32 v103, v104, v105
	v_lshl_add_u64 v[104:105], s[28:29], 0, v[106:107]
	v_lshl_add_u64 v[104:105], v[104:105], 0, v[146:147]
	global_store_dwordx2 v[104:105], v[102:103], off
	v_add_u32_e32 v102, v157, v162
	v_ashrrev_i32_e32 v103, 31, v102
	v_lshlrev_b64 v[102:103], 11, v[102:103]
	v_lshl_add_u64 v[104:105], v[148:149], 0, v[102:103]
	v_lshl_add_u64 v[104:105], v[104:105], 0, v[150:151]
	global_store_dwordx4 v[104:105], v[98:101], off
	v_add_u32_e32 v104, 32, v140
	s_nop 0
	v_cvt_pk_bf16_f32 v98, v98, v99
	v_cvt_pk_bf16_f32 v99, v100, v101
	v_lshl_add_u64 v[100:101], s[28:29], 0, v[102:103]
	v_lshl_add_u64 v[100:101], v[100:101], 0, v[114:115]
	global_store_dwordx2 v[100:101], v[98:99], off
	global_load_dwordx2 v[98:99], v[142:143], off offset:256
	s_waitcnt vmcnt(0)
	v_ffbh_u32_e32 v100, v99
	v_min_u32_e32 v100, 32, v100
	v_lshlrev_b64 v[98:99], v100, v[98:99]
	v_min_u32_e32 v98, 1, v98
	v_or_b32_e32 v98, v99, v98
	v_cvt_f32_u32_e32 v98, v98
	v_sub_u32_e32 v99, 32, v100
	v_add_u32_e32 v100, v141, v104
	v_ashrrev_i32_e32 v101, 31, v100
	v_ldexp_f32 v98, v98, v99
	v_mul_f32_e32 v98, 0x30800000, v98
	v_fmamk_f32 v98, v98, 0x3a000000, v1
	v_cmp_gt_f32_e32 vcc, s65, v98
	v_mul_f32_e32 v99, 0x4b800000, v98
	v_lshlrev_b64 v[100:101], 11, v[100:101]
	v_cndmask_b32_e32 v98, v98, v99, vcc
	v_rsq_f32_e32 v98, v98
	v_lshl_add_u64 v[102:103], v[126:127], 0, v[100:101]
	v_lshl_add_u64 v[102:103], v[102:103], 0, v[180:181]
	v_mul_f32_e32 v99, 0x45800000, v98
	v_cndmask_b32_e32 v98, v98, v99, vcc
	v_pk_mul_f32 v[96:97], v[96:97], v[98:99] op_sel_hi:[1,0]
	v_pk_mul_f32 v[94:95], v[94:95], v[98:99] op_sel_hi:[1,0]
	global_store_dwordx4 v[102:103], v[94:97], off
	v_pk_mul_f32 v[92:93], v[92:93], v[98:99] op_sel_hi:[1,0]
	v_pk_mul_f32 v[90:91], v[90:91], v[98:99] op_sel_hi:[1,0]
	v_cvt_pk_bf16_f32 v94, v94, v95
	v_cvt_pk_bf16_f32 v95, v96, v97
	v_lshl_add_u64 v[96:97], s[28:29], 0, v[100:101]
	v_lshl_add_u64 v[96:97], v[96:97], 0, v[128:129]
	global_store_dwordx2 v[96:97], v[94:95], off
	v_add_u32_e32 v94, v155, v104
	v_ashrrev_i32_e32 v95, 31, v94
	v_lshlrev_b64 v[94:95], 11, v[94:95]
	v_lshl_add_u64 v[96:97], v[122:123], 0, v[94:95]
	v_lshl_add_u64 v[96:97], v[96:97], 0, v[124:125]
	global_store_dwordx4 v[96:97], v[90:93], off
	v_pk_mul_f32 v[88:89], v[88:89], v[98:99] op_sel_hi:[1,0]
	v_pk_mul_f32 v[86:87], v[86:87], v[98:99] op_sel_hi:[1,0]
	v_cvt_pk_bf16_f32 v90, v90, v91
	v_cvt_pk_bf16_f32 v91, v92, v93
	v_lshl_add_u64 v[92:93], s[28:29], 0, v[94:95]
	v_lshl_add_u64 v[92:93], v[92:93], 0, v[144:145]
	global_store_dwordx2 v[92:93], v[90:91], off
	v_add_u32_e32 v90, v156, v104
	v_ashrrev_i32_e32 v91, 31, v90
	v_lshlrev_b64 v[90:91], 11, v[90:91]
	v_lshl_add_u64 v[92:93], v[118:119], 0, v[90:91]
	v_lshl_add_u64 v[92:93], v[92:93], 0, v[120:121]
	global_store_dwordx4 v[92:93], v[86:89], off
	v_pk_mul_f32 v[84:85], v[84:85], v[98:99] op_sel_hi:[1,0]
	v_pk_mul_f32 v[82:83], v[82:83], v[98:99] op_sel_hi:[1,0]
	v_cvt_pk_bf16_f32 v86, v86, v87
	v_cvt_pk_bf16_f32 v87, v88, v89
	v_lshl_add_u64 v[88:89], s[28:29], 0, v[90:91]
	v_lshl_add_u64 v[88:89], v[88:89], 0, v[146:147]
	global_store_dwordx2 v[88:89], v[86:87], off
	v_add_u32_e32 v86, v157, v104
	v_ashrrev_i32_e32 v87, 31, v86
	v_lshlrev_b64 v[86:87], 11, v[86:87]
	v_lshl_add_u64 v[88:89], v[148:149], 0, v[86:87]
	v_lshl_add_u64 v[88:89], v[88:89], 0, v[150:151]
	global_store_dwordx4 v[88:89], v[82:85], off
	v_add_u32_e32 v88, 48, v140
	s_nop 0
	v_cvt_pk_bf16_f32 v82, v82, v83
	v_cvt_pk_bf16_f32 v83, v84, v85
	v_lshl_add_u64 v[84:85], s[28:29], 0, v[86:87]
	v_lshl_add_u64 v[84:85], v[84:85], 0, v[114:115]
	global_store_dwordx2 v[84:85], v[82:83], off
	global_load_dwordx2 v[82:83], v[142:143], off offset:384
	s_waitcnt vmcnt(0)
	v_ffbh_u32_e32 v84, v83
	v_min_u32_e32 v84, 32, v84
	v_lshlrev_b64 v[82:83], v84, v[82:83]
	v_min_u32_e32 v82, 1, v82
	v_or_b32_e32 v82, v83, v82
	v_cvt_f32_u32_e32 v82, v82
	v_sub_u32_e32 v83, 32, v84
	v_add_u32_e32 v84, v141, v88
	v_ashrrev_i32_e32 v85, 31, v84
	v_ldexp_f32 v82, v82, v83
	v_mul_f32_e32 v82, 0x30800000, v82
	v_fmamk_f32 v82, v82, 0x3a000000, v1
	v_cmp_gt_f32_e32 vcc, s65, v82
	v_mul_f32_e32 v83, 0x4b800000, v82
	v_lshlrev_b64 v[84:85], 11, v[84:85]
	v_cndmask_b32_e32 v82, v82, v83, vcc
	v_rsq_f32_e32 v82, v82
	v_lshl_add_u64 v[86:87], v[126:127], 0, v[84:85]
	v_lshl_add_u64 v[86:87], v[86:87], 0, v[180:181]
	v_mul_f32_e32 v83, 0x45800000, v82
	v_cndmask_b32_e32 v82, v82, v83, vcc
	v_pk_mul_f32 v[80:81], v[80:81], v[82:83] op_sel_hi:[1,0]
	v_pk_mul_f32 v[78:79], v[78:79], v[82:83] op_sel_hi:[1,0]
	global_store_dwordx4 v[86:87], v[78:81], off
	v_pk_mul_f32 v[76:77], v[76:77], v[82:83] op_sel_hi:[1,0]
	v_pk_mul_f32 v[74:75], v[74:75], v[82:83] op_sel_hi:[1,0]
	v_cvt_pk_bf16_f32 v78, v78, v79
	v_cvt_pk_bf16_f32 v79, v80, v81
	v_lshl_add_u64 v[80:81], s[28:29], 0, v[84:85]
	v_lshl_add_u64 v[80:81], v[80:81], 0, v[128:129]
	global_store_dwordx2 v[80:81], v[78:79], off
	v_add_u32_e32 v78, v155, v88
	v_ashrrev_i32_e32 v79, 31, v78
	v_lshlrev_b64 v[78:79], 11, v[78:79]
	v_lshl_add_u64 v[80:81], v[122:123], 0, v[78:79]
	v_lshl_add_u64 v[80:81], v[80:81], 0, v[124:125]
	global_store_dwordx4 v[80:81], v[74:77], off
	v_pk_mul_f32 v[72:73], v[72:73], v[82:83] op_sel_hi:[1,0]
	v_pk_mul_f32 v[70:71], v[70:71], v[82:83] op_sel_hi:[1,0]
	v_cvt_pk_bf16_f32 v74, v74, v75
	v_cvt_pk_bf16_f32 v75, v76, v77
	v_lshl_add_u64 v[76:77], s[28:29], 0, v[78:79]
	v_lshl_add_u64 v[76:77], v[76:77], 0, v[144:145]
	global_store_dwordx2 v[76:77], v[74:75], off
	v_add_u32_e32 v74, v156, v88
	v_ashrrev_i32_e32 v75, 31, v74
	v_lshlrev_b64 v[74:75], 11, v[74:75]
	v_lshl_add_u64 v[76:77], v[118:119], 0, v[74:75]
	v_lshl_add_u64 v[76:77], v[76:77], 0, v[120:121]
	global_store_dwordx4 v[76:77], v[70:73], off
	v_pk_mul_f32 v[68:69], v[68:69], v[82:83] op_sel_hi:[1,0]
	v_pk_mul_f32 v[66:67], v[66:67], v[82:83] op_sel_hi:[1,0]
	v_cvt_pk_bf16_f32 v70, v70, v71
	v_cvt_pk_bf16_f32 v71, v72, v73
	v_lshl_add_u64 v[72:73], s[28:29], 0, v[74:75]
	v_lshl_add_u64 v[72:73], v[72:73], 0, v[146:147]
	global_store_dwordx2 v[72:73], v[70:71], off
	v_add_u32_e32 v70, v157, v88
	v_ashrrev_i32_e32 v71, 31, v70
	v_lshlrev_b64 v[70:71], 11, v[70:71]
	v_lshl_add_u64 v[72:73], v[148:149], 0, v[70:71]
	v_lshl_add_u64 v[72:73], v[72:73], 0, v[150:151]
	global_store_dwordx4 v[72:73], v[66:69], off
	v_add_u32_e32 v72, 0x80, v140
	s_nop 0
	v_cvt_pk_bf16_f32 v66, v66, v67
	v_cvt_pk_bf16_f32 v67, v68, v69
	v_lshl_add_u64 v[68:69], s[28:29], 0, v[70:71]
	v_lshl_add_u64 v[68:69], v[68:69], 0, v[114:115]
	global_store_dwordx2 v[68:69], v[66:67], off
	global_load_dwordx2 v[66:67], v[142:143], off offset:1024
	s_waitcnt vmcnt(0)
	v_ffbh_u32_e32 v68, v67
	v_min_u32_e32 v68, 32, v68
	v_lshlrev_b64 v[66:67], v68, v[66:67]
	v_min_u32_e32 v66, 1, v66
	v_or_b32_e32 v66, v67, v66
	v_cvt_f32_u32_e32 v66, v66
	v_sub_u32_e32 v67, 32, v68
	v_add_u32_e32 v68, v141, v72
	v_ashrrev_i32_e32 v69, 31, v68
	v_ldexp_f32 v66, v66, v67
	v_mul_f32_e32 v66, 0x30800000, v66
	v_fmamk_f32 v66, v66, 0x3a000000, v1
	v_cmp_gt_f32_e32 vcc, s65, v66
	v_mul_f32_e32 v67, 0x4b800000, v66
	v_lshlrev_b64 v[68:69], 11, v[68:69]
	v_cndmask_b32_e32 v66, v66, v67, vcc
	v_rsq_f32_e32 v66, v66
	v_lshl_add_u64 v[70:71], v[126:127], 0, v[68:69]
	v_lshl_add_u64 v[70:71], v[70:71], 0, v[180:181]
	v_mul_f32_e32 v67, 0x45800000, v66
	v_cndmask_b32_e32 v66, v66, v67, vcc
	v_pk_mul_f32 v[64:65], v[64:65], v[66:67] op_sel_hi:[1,0]
	v_pk_mul_f32 v[62:63], v[62:63], v[66:67] op_sel_hi:[1,0]
	global_store_dwordx4 v[70:71], v[62:65], off
	v_pk_mul_f32 v[60:61], v[60:61], v[66:67] op_sel_hi:[1,0]
	v_pk_mul_f32 v[58:59], v[58:59], v[66:67] op_sel_hi:[1,0]
	v_cvt_pk_bf16_f32 v62, v62, v63
	v_cvt_pk_bf16_f32 v63, v64, v65
	v_lshl_add_u64 v[64:65], s[28:29], 0, v[68:69]
	v_lshl_add_u64 v[64:65], v[64:65], 0, v[128:129]
	global_store_dwordx2 v[64:65], v[62:63], off
	v_add_u32_e32 v62, v155, v72
	v_ashrrev_i32_e32 v63, 31, v62
	v_lshlrev_b64 v[62:63], 11, v[62:63]
	v_lshl_add_u64 v[64:65], v[122:123], 0, v[62:63]
	v_lshl_add_u64 v[64:65], v[64:65], 0, v[124:125]
	global_store_dwordx4 v[64:65], v[58:61], off
	v_pk_mul_f32 v[56:57], v[56:57], v[66:67] op_sel_hi:[1,0]
	v_pk_mul_f32 v[54:55], v[54:55], v[66:67] op_sel_hi:[1,0]
	v_cvt_pk_bf16_f32 v58, v58, v59
	v_cvt_pk_bf16_f32 v59, v60, v61
	v_lshl_add_u64 v[60:61], s[28:29], 0, v[62:63]
	v_lshl_add_u64 v[60:61], v[60:61], 0, v[144:145]
	global_store_dwordx2 v[60:61], v[58:59], off
	v_add_u32_e32 v58, v156, v72
	v_ashrrev_i32_e32 v59, 31, v58
	v_lshlrev_b64 v[58:59], 11, v[58:59]
	v_lshl_add_u64 v[60:61], v[118:119], 0, v[58:59]
	v_lshl_add_u64 v[60:61], v[60:61], 0, v[120:121]
	global_store_dwordx4 v[60:61], v[54:57], off
	v_pk_mul_f32 v[52:53], v[52:53], v[66:67] op_sel_hi:[1,0]
	v_pk_mul_f32 v[50:51], v[50:51], v[66:67] op_sel_hi:[1,0]
	v_cvt_pk_bf16_f32 v54, v54, v55
	v_cvt_pk_bf16_f32 v55, v56, v57
	v_lshl_add_u64 v[56:57], s[28:29], 0, v[58:59]
	v_lshl_add_u64 v[56:57], v[56:57], 0, v[146:147]
	global_store_dwordx2 v[56:57], v[54:55], off
	v_add_u32_e32 v54, v157, v72
	v_ashrrev_i32_e32 v55, 31, v54
	v_lshlrev_b64 v[54:55], 11, v[54:55]
	v_lshl_add_u64 v[56:57], v[148:149], 0, v[54:55]
	v_lshl_add_u64 v[56:57], v[56:57], 0, v[150:151]
	global_store_dwordx4 v[56:57], v[50:53], off
	v_add_u32_e32 v56, 0x90, v140
	s_nop 0
	v_cvt_pk_bf16_f32 v50, v50, v51
	v_cvt_pk_bf16_f32 v51, v52, v53
	v_lshl_add_u64 v[52:53], s[28:29], 0, v[54:55]
	v_lshl_add_u64 v[52:53], v[52:53], 0, v[114:115]
	global_store_dwordx2 v[52:53], v[50:51], off
	global_load_dwordx2 v[50:51], v[142:143], off offset:1152
	s_waitcnt vmcnt(0)
	v_ffbh_u32_e32 v52, v51
	v_min_u32_e32 v52, 32, v52
	v_lshlrev_b64 v[50:51], v52, v[50:51]
	v_min_u32_e32 v50, 1, v50
	v_or_b32_e32 v50, v51, v50
	v_cvt_f32_u32_e32 v50, v50
	v_sub_u32_e32 v51, 32, v52
	v_add_u32_e32 v52, v141, v56
	v_ashrrev_i32_e32 v53, 31, v52
	v_ldexp_f32 v50, v50, v51
	v_mul_f32_e32 v50, 0x30800000, v50
	v_fmamk_f32 v50, v50, 0x3a000000, v1
	v_cmp_gt_f32_e32 vcc, s65, v50
	v_mul_f32_e32 v51, 0x4b800000, v50
	v_lshlrev_b64 v[52:53], 11, v[52:53]
	v_cndmask_b32_e32 v50, v50, v51, vcc
	v_rsq_f32_e32 v50, v50
	v_lshl_add_u64 v[54:55], v[126:127], 0, v[52:53]
	v_lshl_add_u64 v[54:55], v[54:55], 0, v[180:181]
	v_mul_f32_e32 v51, 0x45800000, v50
	v_cndmask_b32_e32 v50, v50, v51, vcc
	v_pk_mul_f32 v[48:49], v[48:49], v[50:51] op_sel_hi:[1,0]
	v_pk_mul_f32 v[46:47], v[46:47], v[50:51] op_sel_hi:[1,0]
	global_store_dwordx4 v[54:55], v[46:49], off
	v_pk_mul_f32 v[44:45], v[44:45], v[50:51] op_sel_hi:[1,0]
	v_pk_mul_f32 v[42:43], v[42:43], v[50:51] op_sel_hi:[1,0]
	v_cvt_pk_bf16_f32 v46, v46, v47
	v_cvt_pk_bf16_f32 v47, v48, v49
	v_lshl_add_u64 v[48:49], s[28:29], 0, v[52:53]
	v_lshl_add_u64 v[48:49], v[48:49], 0, v[128:129]
	global_store_dwordx2 v[48:49], v[46:47], off
	v_add_u32_e32 v46, v155, v56
	v_ashrrev_i32_e32 v47, 31, v46
	v_lshlrev_b64 v[46:47], 11, v[46:47]
	v_lshl_add_u64 v[48:49], v[122:123], 0, v[46:47]
	v_lshl_add_u64 v[48:49], v[48:49], 0, v[124:125]
	global_store_dwordx4 v[48:49], v[42:45], off
	v_pk_mul_f32 v[40:41], v[40:41], v[50:51] op_sel_hi:[1,0]
	v_pk_mul_f32 v[38:39], v[38:39], v[50:51] op_sel_hi:[1,0]
	v_cvt_pk_bf16_f32 v42, v42, v43
	v_cvt_pk_bf16_f32 v43, v44, v45
	v_lshl_add_u64 v[44:45], s[28:29], 0, v[46:47]
	v_lshl_add_u64 v[44:45], v[44:45], 0, v[144:145]
	global_store_dwordx2 v[44:45], v[42:43], off
	v_add_u32_e32 v42, v156, v56
	v_ashrrev_i32_e32 v43, 31, v42
	v_lshlrev_b64 v[42:43], 11, v[42:43]
	v_lshl_add_u64 v[44:45], v[118:119], 0, v[42:43]
	v_lshl_add_u64 v[44:45], v[44:45], 0, v[120:121]
	global_store_dwordx4 v[44:45], v[38:41], off
	v_pk_mul_f32 v[36:37], v[36:37], v[50:51] op_sel_hi:[1,0]
	v_pk_mul_f32 v[34:35], v[34:35], v[50:51] op_sel_hi:[1,0]
	v_cvt_pk_bf16_f32 v38, v38, v39
	v_cvt_pk_bf16_f32 v39, v40, v41
	v_lshl_add_u64 v[40:41], s[28:29], 0, v[42:43]
	v_lshl_add_u64 v[40:41], v[40:41], 0, v[146:147]
	global_store_dwordx2 v[40:41], v[38:39], off
	v_add_u32_e32 v38, v157, v56
	v_ashrrev_i32_e32 v39, 31, v38
	v_lshlrev_b64 v[38:39], 11, v[38:39]
	v_lshl_add_u64 v[40:41], v[148:149], 0, v[38:39]
	v_lshl_add_u64 v[40:41], v[40:41], 0, v[150:151]
	global_store_dwordx4 v[40:41], v[34:37], off
	v_add_u32_e32 v40, 0xa0, v140
	s_nop 0
	v_cvt_pk_bf16_f32 v34, v34, v35
	v_cvt_pk_bf16_f32 v35, v36, v37
	v_lshl_add_u64 v[36:37], s[28:29], 0, v[38:39]
	v_lshl_add_u64 v[36:37], v[36:37], 0, v[114:115]
	global_store_dwordx2 v[36:37], v[34:35], off
	global_load_dwordx2 v[34:35], v[142:143], off offset:1280
	s_waitcnt vmcnt(0)
	v_ffbh_u32_e32 v36, v35
	v_min_u32_e32 v36, 32, v36
	v_lshlrev_b64 v[34:35], v36, v[34:35]
	v_min_u32_e32 v34, 1, v34
	v_or_b32_e32 v34, v35, v34
	v_cvt_f32_u32_e32 v34, v34
	v_sub_u32_e32 v35, 32, v36
	v_add_u32_e32 v36, v141, v40
	v_ashrrev_i32_e32 v37, 31, v36
	v_ldexp_f32 v34, v34, v35
	v_mul_f32_e32 v34, 0x30800000, v34
	v_fmamk_f32 v34, v34, 0x3a000000, v1
	v_cmp_gt_f32_e32 vcc, s65, v34
	v_mul_f32_e32 v35, 0x4b800000, v34
	v_lshlrev_b64 v[36:37], 11, v[36:37]
	v_cndmask_b32_e32 v34, v34, v35, vcc
	v_rsq_f32_e32 v34, v34
	v_lshl_add_u64 v[38:39], v[126:127], 0, v[36:37]
	v_lshl_add_u64 v[38:39], v[38:39], 0, v[180:181]
	v_mul_f32_e32 v35, 0x45800000, v34
	v_cndmask_b32_e32 v34, v34, v35, vcc
	v_pk_mul_f32 v[32:33], v[32:33], v[34:35] op_sel_hi:[1,0]
	v_pk_mul_f32 v[30:31], v[30:31], v[34:35] op_sel_hi:[1,0]
	global_store_dwordx4 v[38:39], v[30:33], off
	v_pk_mul_f32 v[28:29], v[28:29], v[34:35] op_sel_hi:[1,0]
	v_pk_mul_f32 v[26:27], v[26:27], v[34:35] op_sel_hi:[1,0]
	v_cvt_pk_bf16_f32 v30, v30, v31
	v_cvt_pk_bf16_f32 v31, v32, v33
	v_lshl_add_u64 v[32:33], s[28:29], 0, v[36:37]
	v_lshl_add_u64 v[32:33], v[32:33], 0, v[128:129]
	global_store_dwordx2 v[32:33], v[30:31], off
	v_add_u32_e32 v30, v155, v40
	v_ashrrev_i32_e32 v31, 31, v30
	v_lshlrev_b64 v[30:31], 11, v[30:31]
	v_lshl_add_u64 v[32:33], v[122:123], 0, v[30:31]
	v_lshl_add_u64 v[32:33], v[32:33], 0, v[124:125]
	global_store_dwordx4 v[32:33], v[26:29], off
	v_pk_mul_f32 v[24:25], v[24:25], v[34:35] op_sel_hi:[1,0]
	v_pk_mul_f32 v[22:23], v[22:23], v[34:35] op_sel_hi:[1,0]
	v_cvt_pk_bf16_f32 v26, v26, v27
	v_cvt_pk_bf16_f32 v27, v28, v29
	v_lshl_add_u64 v[28:29], s[28:29], 0, v[30:31]
	v_lshl_add_u64 v[28:29], v[28:29], 0, v[144:145]
	global_store_dwordx2 v[28:29], v[26:27], off
	v_add_u32_e32 v26, v156, v40
	v_ashrrev_i32_e32 v27, 31, v26
	v_lshlrev_b64 v[26:27], 11, v[26:27]
	v_lshl_add_u64 v[28:29], v[118:119], 0, v[26:27]
	v_lshl_add_u64 v[28:29], v[28:29], 0, v[120:121]
	global_store_dwordx4 v[28:29], v[22:25], off
	v_pk_mul_f32 v[20:21], v[20:21], v[34:35] op_sel_hi:[1,0]
	v_pk_mul_f32 v[18:19], v[18:19], v[34:35] op_sel_hi:[1,0]
	v_cvt_pk_bf16_f32 v22, v22, v23
	v_cvt_pk_bf16_f32 v23, v24, v25
	v_lshl_add_u64 v[24:25], s[28:29], 0, v[26:27]
	v_lshl_add_u64 v[24:25], v[24:25], 0, v[146:147]
	global_store_dwordx2 v[24:25], v[22:23], off
	v_add_u32_e32 v22, v157, v40
	v_ashrrev_i32_e32 v23, 31, v22
	v_lshlrev_b64 v[22:23], 11, v[22:23]
	v_lshl_add_u64 v[24:25], v[148:149], 0, v[22:23]
	v_lshl_add_u64 v[24:25], v[24:25], 0, v[150:151]
	global_store_dwordx4 v[24:25], v[18:21], off
	v_add_u32_e32 v24, 0xb0, v140
	s_nop 0
	v_cvt_pk_bf16_f32 v18, v18, v19
	v_cvt_pk_bf16_f32 v19, v20, v21
	v_lshl_add_u64 v[20:21], s[28:29], 0, v[22:23]
	v_lshl_add_u64 v[20:21], v[20:21], 0, v[114:115]
	global_store_dwordx2 v[20:21], v[18:19], off
	global_load_dwordx2 v[18:19], v[142:143], off offset:1408
	s_waitcnt vmcnt(0)
	v_ffbh_u32_e32 v20, v19
	v_min_u32_e32 v20, 32, v20
	v_lshlrev_b64 v[18:19], v20, v[18:19]
	v_min_u32_e32 v18, 1, v18
	v_or_b32_e32 v18, v19, v18
	v_cvt_f32_u32_e32 v18, v18
	v_sub_u32_e32 v19, 32, v20
	v_add_u32_e32 v20, v141, v24
	v_ashrrev_i32_e32 v21, 31, v20
	v_ldexp_f32 v18, v18, v19
	v_mul_f32_e32 v18, 0x30800000, v18
	v_fmamk_f32 v18, v18, 0x3a000000, v1
	v_cmp_gt_f32_e32 vcc, s65, v18
	v_mul_f32_e32 v19, 0x4b800000, v18
	v_lshlrev_b64 v[20:21], 11, v[20:21]
	v_cndmask_b32_e32 v18, v18, v19, vcc
	v_rsq_f32_e32 v18, v18
	v_lshl_add_u64 v[22:23], v[126:127], 0, v[20:21]
	v_lshl_add_u64 v[22:23], v[22:23], 0, v[180:181]
	v_mul_f32_e32 v19, 0x45800000, v18
	v_cndmask_b32_e32 v18, v18, v19, vcc
	v_pk_mul_f32 v[16:17], v[16:17], v[18:19] op_sel_hi:[1,0]
	v_pk_mul_f32 v[14:15], v[14:15], v[18:19] op_sel_hi:[1,0]
	global_store_dwordx4 v[22:23], v[14:17], off
	v_pk_mul_f32 v[12:13], v[12:13], v[18:19] op_sel_hi:[1,0]
	v_pk_mul_f32 v[10:11], v[10:11], v[18:19] op_sel_hi:[1,0]
	v_cvt_pk_bf16_f32 v14, v14, v15
	v_cvt_pk_bf16_f32 v15, v16, v17
	v_lshl_add_u64 v[16:17], s[28:29], 0, v[20:21]
	v_lshl_add_u64 v[16:17], v[16:17], 0, v[128:129]
	global_store_dwordx2 v[16:17], v[14:15], off
	v_add_u32_e32 v14, v155, v24
	v_ashrrev_i32_e32 v15, 31, v14
	v_lshlrev_b64 v[14:15], 11, v[14:15]
	v_lshl_add_u64 v[16:17], v[122:123], 0, v[14:15]
	v_lshl_add_u64 v[16:17], v[16:17], 0, v[124:125]
	global_store_dwordx4 v[16:17], v[10:13], off
	v_pk_mul_f32 v[8:9], v[8:9], v[18:19] op_sel_hi:[1,0]
	v_pk_mul_f32 v[6:7], v[6:7], v[18:19] op_sel_hi:[1,0]
	v_cvt_pk_bf16_f32 v10, v10, v11
	v_cvt_pk_bf16_f32 v11, v12, v13
	v_lshl_add_u64 v[12:13], s[28:29], 0, v[14:15]
	v_lshl_add_u64 v[12:13], v[12:13], 0, v[144:145]
	global_store_dwordx2 v[12:13], v[10:11], off
	v_add_u32_e32 v10, v156, v24
	v_ashrrev_i32_e32 v11, 31, v10
	v_lshlrev_b64 v[10:11], 11, v[10:11]
	v_lshl_add_u64 v[12:13], v[118:119], 0, v[10:11]
	v_lshl_add_u64 v[12:13], v[12:13], 0, v[120:121]
	global_store_dwordx4 v[12:13], v[6:9], off
	v_pk_mul_f32 v[4:5], v[4:5], v[18:19] op_sel_hi:[1,0]
	v_pk_mul_f32 v[2:3], v[2:3], v[18:19] op_sel_hi:[1,0]
	v_cvt_pk_bf16_f32 v6, v6, v7
	v_cvt_pk_bf16_f32 v7, v8, v9
	v_lshl_add_u64 v[8:9], s[28:29], 0, v[10:11]
	v_lshl_add_u64 v[8:9], v[8:9], 0, v[146:147]
	global_store_dwordx2 v[8:9], v[6:7], off
	v_add_u32_e32 v6, v157, v24
	v_ashrrev_i32_e32 v7, 31, v6
	v_lshlrev_b64 v[6:7], 11, v[6:7]
	v_lshl_add_u64 v[8:9], v[148:149], 0, v[6:7]
	v_lshl_add_u64 v[8:9], v[8:9], 0, v[150:151]
	global_store_dwordx4 v[8:9], v[2:5], off
	s_andn2_b64 vcc, exec, s[34:35]
	s_nop 0
	v_cvt_pk_bf16_f32 v2, v2, v3
	v_cvt_pk_bf16_f32 v3, v4, v5
	v_lshl_add_u64 v[4:5], s[28:29], 0, v[6:7]
	v_lshl_add_u64 v[4:5], v[4:5], 0, v[114:115]
	global_store_dwordx2 v[4:5], v[2:3], off
	s_cbranch_vccnz .LBB0_1228
	s_andn2_b64 vcc, exec, s[24:25]
	s_cbranch_vccnz .LBB0_1227
	s_branch .LBB0_1227

.LBB0_1571:
	v_ashrrev_i32_e32 v4, 31, v2
	v_lshrrev_b32_e32 v4, 26, v4
	v_add_u32_e32 v4, v2, v4
	v_ashrrev_i32_e32 v146, 6, v4
	v_bfe_i32 v4, v2, 27, 1
	v_lshlrev_b32_e32 v3, 4, v2
	v_lshrrev_b32_e32 v4, 22, v4
	v_add_u32_e32 v4, v3, v4
	v_and_b32_e32 v4, 0xfffffc00, v4
	v_sub_u32_e32 v4, v3, v4
	v_lshrrev_b32_e32 v5, 4, v4
	v_bitop3_b32 v4, v5, v4, 32 bitop3:0x6c
	v_ashrrev_i32_e32 v6, 31, v4
	v_lshrrev_b32_e32 v6, 26, v6
	v_add_u32_e32 v6, v4, v6
	v_lshlrev_b32_e32 v5, 3, v146
	v_ashrrev_i32_e32 v147, 6, v6
	v_and_b32_e32 v6, 0xc0, v6
	v_and_b32_e32 v5, -16, v5
	v_sub_u32_e32 v4, v4, v6
	v_add_u32_e32 v5, v147, v5
	v_ashrrev_i16_sdwa v4, v224, sext(v4) dst_sel:DWORD dst_unused:UNUSED_PAD src0_sel:DWORD src1_sel:BYTE_0
	v_lshlrev_b32_e32 v7, 5, v146
	v_bfe_i32 v153, v4, 0, 16
	v_lshlrev_b32_e32 v4, 1, v5
	v_lshrrev_b32_e32 v6, 2, v5
	v_and_b32_e32 v8, 3, v147
	s_mov_b32 s8, 0xfffe0
	v_and_b32_e32 v7, 32, v7
	v_and_b32_e32 v4, 24, v4
	v_and_b32_e32 v6, 4, v6
	v_and_or_b32 v8, v5, s8, v8
	v_or3_b32 v4, v8, v6, v4
	v_add_lshl_u32 v6, v7, v153, 1
	v_add_u32_e32 v3, 0x2000, v3
	s_waitcnt vmcnt(0)
	v_lshl_add_u32 v134, v4, 12, v6
	v_ashrrev_i32_e32 v4, 31, v3
	v_lshrrev_b32_e32 v4, 22, v4
	v_add_u32_e32 v4, v3, v4
	v_ashrrev_i32_e32 v154, 10, v4
	v_mul_i32_i24_e32 v4, 0x400, v154
	v_sub_u32_e32 v3, v3, v4
	v_lshrrev_b32_e32 v4, 4, v3
	v_bitop3_b32 v3, v4, v3, 32 bitop3:0x6c
	v_lshl_add_u32 v132, v5, 12, v6
	v_ashrrev_i32_e32 v5, 31, v3
	v_lshrrev_b32_e32 v5, 26, v5
	v_lshlrev_b32_e32 v4, 3, v154
	v_add_u32_e32 v5, v3, v5
	v_and_b32_e32 v4, -16, v4
	v_ashrrev_i32_e32 v155, 6, v5
	v_add_u32_e32 v4, v155, v4
	v_and_b32_e32 v7, 3, v155
	s_ashr_i32 s12, s30, 6
	s_ashr_i32 s28, s30, 8
	v_and_b32_e32 v5, 0xc0, v5
	v_and_or_b32 v7, v4, s8, v7
	s_lshl_b32 s8, s12, 10
	s_lshl_b32 s12, s12, 5
	v_sub_u32_e32 v3, v3, v5
	s_lshl_b32 s9, s28, 6
	s_and_b32 s21, s12, 0x60
	v_ashrrev_i16_sdwa v3, v224, sext(v3) dst_sel:DWORD dst_unused:UNUSED_PAD src0_sel:DWORD src1_sel:BYTE_0
	s_add_u32 s54, s26, 0x24600000
	v_lshlrev_b32_e32 v6, 5, v154
	v_bfe_i32 v156, v3, 0, 16
	v_lshlrev_b32_e32 v3, 1, v4
	v_lshrrev_b32_e32 v5, 2, v4
	s_addc_u32 s55, s27, 0
	s_lshl_b32 s12, s44, 8
	v_and_b32_e32 v6, 32, v6
	v_and_b32_e32 v3, 24, v3
	v_and_b32_e32 v5, 4, v5
	v_and_b32_e32 v150, 15, v2
	s_add_i32 s12, s12, s9
	v_bfe_u32 v131, v2, 4, 2
	v_or3_b32 v3, v7, v5, v3
	v_add_lshl_u32 v5, v6, v156, 1
	v_or_b32_e32 v2, s12, v150
	v_lshl_add_u32 v138, v3, 12, v5
	v_ashrrev_i32_e32 v3, 31, v2
	v_lshlrev_b64 v[2:3], 12, v[2:3]
	s_lshl_b32 s26, s38, 8
	v_lshl_add_u64 v[2:3], s[14:15], 0, v[2:3]
	s_ashr_i32 s27, s26, 31
	v_lshl_add_u64 v[2:3], s[26:27], 1, v[2:3]
	s_lshl_b32 s12, s21, 1
	v_lshl_add_u64 v[2:3], v[2:3], 0, s[12:13]
	v_lshlrev_b32_e32 v180, 4, v131
	v_lshl_add_u64 v[2:3], v[2:3], 0, v[180:181]
	s_mov_b32 s26, 0x10000
	v_lshl_add_u32 v136, v4, 12, v5
	v_add_co_u32_e32 v4, vcc, s26, v2
	s_mov_b32 s26, 0x20000
	s_nop 0
	v_addc_co_u32_e32 v5, vcc, 0, v3, vcc
	global_load_dwordx4 v[64:67], v[2:3], off
	global_load_dwordx4 v[60:63], v[2:3], off offset:256
	global_load_dwordx4 v[56:59], v[4:5], off
	global_load_dwordx4 v[52:55], v[4:5], off offset:256
	v_add_co_u32_e32 v4, vcc, s26, v2
	s_mov_b32 s26, 0x30000
	s_nop 0
	v_addc_co_u32_e32 v5, vcc, 0, v3, vcc
	global_load_dwordx4 v[48:51], v[4:5], off
	global_load_dwordx4 v[44:47], v[4:5], off offset:256
	v_add_co_u32_e32 v4, vcc, s26, v2
	s_mov_b32 s26, 0x80000
	s_nop 0
	v_addc_co_u32_e32 v5, vcc, 0, v3, vcc
	global_load_dwordx4 v[40:43], v[4:5], off
	global_load_dwordx4 v[36:39], v[4:5], off offset:256
	v_add_co_u32_e32 v4, vcc, s26, v2
	s_mov_b32 s26, 0x90000
	s_nop 0
	v_addc_co_u32_e32 v5, vcc, 0, v3, vcc
	global_load_dwordx4 v[32:35], v[4:5], off
	global_load_dwordx4 v[28:31], v[4:5], off offset:256
	v_add_co_u32_e32 v4, vcc, s26, v2
	s_mov_b32 s26, 0xa0000
	s_nop 0
	v_addc_co_u32_e32 v5, vcc, 0, v3, vcc
	global_load_dwordx4 v[24:27], v[4:5], off
	global_load_dwordx4 v[18:21], v[4:5], off offset:256
	v_add_co_u32_e32 v4, vcc, s26, v2
	s_mov_b32 s26, 0xb0000
	s_nop 0
	v_addc_co_u32_e32 v5, vcc, 0, v3, vcc
	s_ashr_i32 s45, s44, 31
	s_ashr_i32 s39, s38, 31
	v_add_co_u32_e32 v14, vcc, s26, v2
	s_lshl_b64 s[26:27], s[44:45], 20
	s_lshl_b64 s[34:35], s[38:39], 20
	s_add_u32 s46, s18, s34
	s_addc_u32 s47, s19, s35
	s_add_i32 s56, s8, 0
	v_addc_co_u32_e32 v15, vcc, 0, v3, vcc
	s_add_i32 m0, s56, 0x10000
	global_load_dwordx4 v[10:13], v[4:5], off
	global_load_dwordx4 v[6:9], v[4:5], off offset:256
	s_nop 0
	global_load_dwordx4 v[2:5], v[14:15], off
	s_nop 0
	global_load_dwordx4 v[14:17], v[14:15], off offset:256
	v_mov_b32_e32 v135, v181
	global_load_lds_dwordx4 v134, s[46:47]
	s_add_i32 m0, s56, 0x12000
	s_add_u32 s34, s46, 0x80000
	global_load_lds_dwordx4 v138, s[46:47]
	s_addc_u32 s35, s47, 0
	s_add_i32 m0, s56, 0x14000
	v_mov_b32_e32 v139, v181
	global_load_lds_dwordx4 v134, s[34:35]
	s_add_i32 m0, s56, 0x16000
	s_add_u32 s48, s54, s26
	s_addc_u32 s49, s55, s27
	s_add_i32 s57, s56, 0x2000
	global_load_lds_dwordx4 v138, s[34:35]
	s_mov_b32 m0, s56
	s_add_u32 s26, s48, 0x80000
	global_load_lds_dwordx4 v132, s[48:49]
	s_mov_b32 m0, s57
	s_addc_u32 s27, s49, 0
	s_add_i32 s58, s56, 0x4000
	global_load_lds_dwordx4 v136, s[48:49]
	s_mov_b32 m0, s58
	s_add_i32 s59, s56, 0x6000
	global_load_lds_dwordx4 v132, s[26:27]
	s_mov_b32 m0, s59
	v_mov_b32_e32 v133, v181
	global_load_lds_dwordx4 v136, s[26:27]
	v_mov_b32_e32 v137, v181
	s_cmp_eq_u32 s28, 1
	v_lshl_add_u64 v[144:145], s[46:47], 0, v[134:135]
	v_lshl_add_u64 v[142:143], s[46:47], 0, v[138:139]
	v_lshl_add_u64 v[68:69], s[48:49], 0, v[132:133]
	s_cselect_b64 s[26:27], -1, 0
	s_cmp_lg_u32 s28, 1
	v_lshl_add_u64 v[140:141], s[48:49], 0, v[136:137]
	s_cbranch_scc1 .LBB0_1573
.LBB0_1573:
	s_waitcnt vmcnt(0)
	v_lshlrev_b32_e32 v90, 16, v48
	v_and_b32_e32 v91, 0xffff0000, v48
	v_lshlrev_b32_e32 v92, 16, v49
	v_and_b32_e32 v93, 0xffff0000, v49
	v_lshlrev_b32_e32 v94, 16, v46
	v_and_b32_e32 v95, 0xffff0000, v46
	v_lshlrev_b32_e32 v96, 16, v47
	v_and_b32_e32 v97, 0xffff0000, v47
	v_lshlrev_b32_e32 v46, 16, v28
	v_and_b32_e32 v47, 0xffff0000, v28
	v_lshlrev_b32_e32 v48, 16, v29
	v_and_b32_e32 v49, 0xffff0000, v29
	s_add_i32 m0, s56, 0x18000
	v_lshl_add_u64 v[28:29], v[144:145], 0, s[16:17]
	s_lshl_b32 s31, s28, 13
	s_lshl_b32 s34, s21, 7
	s_waitcnt vmcnt(2)
	s_barrier
	global_load_lds_dwordx4 v[28:29], off
	v_lshl_add_u64 v[28:29], v[142:143], 0, s[16:17]
	s_add_i32 m0, s56, 0x1a000
	s_add_i32 s60, s56, 0x8000
	s_add_i32 s61, s56, 0xa000
	global_load_lds_dwordx4 v[28:29], off
	v_lshl_add_u64 v[28:29], v[68:69], 0, s[16:17]
	s_mov_b32 m0, s60
	s_add_u32 s28, s46, 0x80080
	global_load_lds_dwordx4 v[28:29], off
	v_lshl_add_u64 v[28:29], v[140:141], 0, s[16:17]
	s_mov_b32 m0, s61
	s_addc_u32 s29, s47, 0
	global_load_lds_dwordx4 v[28:29], off
	s_add_i32 m0, s56, 0x1c000
	v_lshl_add_u64 v[28:29], s[28:29], 0, v[134:135]
	global_load_lds_dwordx4 v[28:29], off
	v_lshl_add_u64 v[28:29], s[28:29], 0, v[138:139]
	s_add_i32 m0, s56, 0x1e000
	v_or_b32_e32 v151, s9, v150
	global_load_lds_dwordx4 v[28:29], off
	v_lshlrev_b32_e32 v140, 6, v151
	s_movk_i32 s28, 0x3c0
	v_lshlrev_b32_e32 v141, 2, v151
	v_and_or_b32 v140, v140, s28, v180
	v_and_b32_e32 v141, 32, v141
	v_bitop3_b32 v144, v140, s31, v141 bitop3:0xde
	v_lshlrev_b32_e32 v141, 2, v150
	v_lshl_or_b32 v140, v150, 6, v180
	v_and_b32_e32 v141, 32, v141
	v_bitop3_b32 v152, v140, s34, v141 bitop3:0xde
	v_lshlrev_b32_e32 v140, 15, v146
	v_lshlrev_b32_e32 v142, 15, v154
	v_and_b32_e32 v140, 0xffff0000, v140
	v_and_b32_e32 v142, 0xffff0000, v142
	s_waitcnt vmcnt(6)
	v_lshl_add_u32 v140, v147, 12, v140
	v_and_b32_e32 v141, 1, v146
	v_lshl_add_u32 v142, v155, 12, v142
	v_and_b32_e32 v143, 1, v154
	v_lshlrev_b32_e32 v157, 3, v131
	s_cmpk_lt_u32 s30, 0x100
	v_lshl_or_b32 v140, v141, 6, v140
	v_lshl_or_b32 v142, v143, 6, v142
	v_lshlrev_b32_e32 v126, 16, v64
	v_and_b32_e32 v127, 0xffff0000, v64
	v_lshlrev_b32_e32 v128, 16, v65
	v_and_b32_e32 v129, 0xffff0000, v65
	v_lshlrev_b32_e32 v114, 16, v66
	v_and_b32_e32 v115, 0xffff0000, v66
	v_lshlrev_b32_e32 v116, 16, v67
	v_and_b32_e32 v117, 0xffff0000, v67
	v_lshlrev_b32_e32 v118, 16, v60
	v_and_b32_e32 v119, 0xffff0000, v60
	v_lshlrev_b32_e32 v120, 16, v61
	v_and_b32_e32 v121, 0xffff0000, v61
	v_lshlrev_b32_e32 v122, 16, v62
	v_and_b32_e32 v123, 0xffff0000, v62
	v_lshlrev_b32_e32 v124, 16, v63
	v_and_b32_e32 v125, 0xffff0000, v63
	v_lshlrev_b32_e32 v106, 16, v56
	v_and_b32_e32 v107, 0xffff0000, v56
	v_lshlrev_b32_e32 v108, 16, v57
	v_and_b32_e32 v109, 0xffff0000, v57
	v_lshlrev_b32_e32 v98, 16, v58
	v_and_b32_e32 v99, 0xffff0000, v58
	v_lshlrev_b32_e32 v100, 16, v59
	v_and_b32_e32 v101, 0xffff0000, v59
	v_lshlrev_b32_e32 v102, 16, v52
	v_and_b32_e32 v103, 0xffff0000, v52
	v_lshlrev_b32_e32 v104, 16, v53
	v_and_b32_e32 v105, 0xffff0000, v53
	v_lshlrev_b32_e32 v110, 16, v54
	v_and_b32_e32 v111, 0xffff0000, v54
	v_lshlrev_b32_e32 v112, 16, v55
	v_and_b32_e32 v113, 0xffff0000, v55
	v_lshlrev_b32_e32 v82, 16, v50
	v_and_b32_e32 v83, 0xffff0000, v50
	v_lshlrev_b32_e32 v84, 16, v51
	v_and_b32_e32 v85, 0xffff0000, v51
	v_lshlrev_b32_e32 v86, 16, v44
	v_and_b32_e32 v87, 0xffff0000, v44
	v_lshlrev_b32_e32 v88, 16, v45
	v_and_b32_e32 v89, 0xffff0000, v45
	v_lshlrev_b32_e32 v74, 16, v40
	v_and_b32_e32 v75, 0xffff0000, v40
	v_lshlrev_b32_e32 v76, 16, v41
	v_and_b32_e32 v77, 0xffff0000, v41
	v_lshlrev_b32_e32 v54, 16, v42
	v_and_b32_e32 v55, 0xffff0000, v42
	v_lshlrev_b32_e32 v56, 16, v43
	v_and_b32_e32 v57, 0xffff0000, v43
	v_lshlrev_b32_e32 v70, 16, v36
	v_and_b32_e32 v71, 0xffff0000, v36
	v_lshlrev_b32_e32 v72, 16, v37
	v_and_b32_e32 v73, 0xffff0000, v37
	v_lshlrev_b32_e32 v78, 16, v38
	v_and_b32_e32 v79, 0xffff0000, v38
	v_lshlrev_b32_e32 v80, 16, v39
	v_and_b32_e32 v81, 0xffff0000, v39
	v_lshlrev_b32_e32 v50, 16, v32
	v_and_b32_e32 v51, 0xffff0000, v32
	v_lshlrev_b32_e32 v52, 16, v33
	v_and_b32_e32 v53, 0xffff0000, v33
	v_lshlrev_b32_e32 v38, 16, v34
	v_and_b32_e32 v39, 0xffff0000, v34
	v_lshlrev_b32_e32 v40, 16, v35
	v_and_b32_e32 v41, 0xffff0000, v35
	v_lshlrev_b32_e32 v58, 16, v30
	v_and_b32_e32 v59, 0xffff0000, v30
	v_lshlrev_b32_e32 v60, 16, v31
	v_and_b32_e32 v61, 0xffff0000, v31
	v_lshlrev_b32_e32 v22, 16, v24
	v_and_b32_e32 v23, 0xffff0000, v24
	v_lshlrev_b32_e32 v24, 16, v25
	v_and_b32_e32 v25, 0xffff0000, v25
	v_lshlrev_b32_e32 v42, 16, v26
	v_and_b32_e32 v43, 0xffff0000, v26
	v_lshlrev_b32_e32 v44, 16, v27
	v_and_b32_e32 v45, 0xffff0000, v27
	v_lshlrev_b32_e32 v62, 16, v18
	v_and_b32_e32 v63, 0xffff0000, v18
	v_lshlrev_b32_e32 v64, 16, v19
	v_and_b32_e32 v65, 0xffff0000, v19
	v_lshlrev_b32_e32 v66, 16, v20
	v_and_b32_e32 v67, 0xffff0000, v20
	v_lshlrev_b32_e32 v68, 16, v21
	v_and_b32_e32 v69, 0xffff0000, v21
	v_lshlrev_b32_e32 v30, 16, v10
	v_and_b32_e32 v31, 0xffff0000, v10
	v_lshlrev_b32_e32 v32, 16, v11
	v_and_b32_e32 v33, 0xffff0000, v11
	v_lshlrev_b32_e32 v18, 16, v12
	v_and_b32_e32 v19, 0xffff0000, v12
	v_lshlrev_b32_e32 v20, 16, v13
	v_and_b32_e32 v21, 0xffff0000, v13
	v_lshlrev_b32_e32 v26, 16, v6
	v_and_b32_e32 v27, 0xffff0000, v6
	v_lshlrev_b32_e32 v28, 16, v7
	v_and_b32_e32 v29, 0xffff0000, v7
	v_lshlrev_b32_e32 v34, 16, v8
	v_and_b32_e32 v35, 0xffff0000, v8
	v_lshlrev_b32_e32 v36, 16, v9
	v_and_b32_e32 v37, 0xffff0000, v9
	v_lshlrev_b32_e32 v10, 16, v2
	v_and_b32_e32 v11, 0xffff0000, v2
	v_lshlrev_b32_e32 v12, 16, v3
	v_and_b32_e32 v13, 0xffff0000, v3
	v_lshlrev_b32_e32 v2, 16, v4
	v_and_b32_e32 v3, 0xffff0000, v4
	v_lshlrev_b32_e32 v4, 16, v5
	v_and_b32_e32 v5, 0xffff0000, v5
	v_lshlrev_b32_e32 v6, 16, v14
	v_and_b32_e32 v7, 0xffff0000, v14
	v_lshlrev_b32_e32 v8, 16, v15
	v_and_b32_e32 v9, 0xffff0000, v15
	v_lshlrev_b32_e32 v14, 16, v16
	v_and_b32_e32 v15, 0xffff0000, v16
	v_lshlrev_b32_e32 v16, 16, v17
	v_and_b32_e32 v17, 0xffff0000, v17
	s_cselect_b64 s[28:29], -1, 0
	s_ashr_i32 s62, s7, 31
	v_lshl_add_u32 v140, v153, 1, v140
	v_mov_b32_e32 v141, v181
	v_lshl_add_u32 v142, v156, 1, v142
	v_mov_b32_e32 v143, v181
	s_mov_b32 s63, 0
	v_add_u32_e32 v153, 0, v144
	v_lshlrev_b32_e32 v180, 1, v157
	s_barrier
	s_branch .LBB0_1576

.LBB0_1583:
	s_add_u32 s46, s48, 0xfff80080
	s_addc_u32 s47, s49, -1
	s_add_i32 s68, 0, 0x10000
	s_cmp_eq_u32 s67, 28
	s_cselect_b32 s51, s35, s47
	s_cselect_b32 s50, s39, s46
	s_cselect_b32 s47, s31, s66
	s_cselect_b32 s46, s45, s64
	s_add_i32 s70, 0, 0x14000
	v_add_u32_e32 v162, s68, v152
	v_add_u32_e32 v178, s70, v152
	ds_read_b128 v[144:147], v162
	ds_read_b128 v[154:157], v162 offset:1024
	ds_read_b128 v[158:161], v162 offset:2048
	ds_read_b128 v[162:165], v162 offset:3072
	ds_read_b128 v[166:169], v178
	ds_read_b128 v[170:173], v178 offset:1024
	ds_read_b128 v[174:177], v178 offset:2048
	ds_read_b128 v[190:193], v178 offset:3072
	v_lshl_add_u64 v[178:179], s[48:49], 0, v[140:141]
	s_add_i32 m0, s56, 0xc000
	ds_read_b128 v[194:197], v153
	ds_read_b128 v[198:201], v153 offset:1024
	ds_read_b128 v[202:205], v153 offset:2048
	ds_read_b128 v[206:209], v153 offset:3072
	ds_read_b128 v[210:213], v153 offset:4096
	ds_read_b128 v[214:217], v153 offset:5120
	ds_read_b128 v[218:221], v153 offset:6144
	ds_read_b128 v[238:241], v153 offset:7168
	global_load_lds_dwordx4 v[178:179], off
	v_lshl_add_u64 v[178:179], s[48:49], 0, v[142:143]
	s_add_i32 m0, s56, 0xe000
	s_nop 0
	global_load_lds_dwordx4 v[178:179], off
	s_waitcnt vmcnt(8)
	s_waitcnt lgkmcnt(0)
	s_cmp_eq_u32 s100, 0
	s_cbranch_scc1 .Lmy_h2_41
	s_setprio 1
	s_barrier
.Lmy_h2_41:
	v_mfma_f32_16x16x32_bf16 v[126:129], v[144:147], v[194:197], v[126:129]
	v_mfma_f32_16x16x32_bf16 v[114:117], v[158:161], v[194:197], v[114:117]
	v_mfma_f32_16x16x32_bf16 v[106:109], v[144:147], v[202:205], v[106:109]
	v_mfma_f32_16x16x32_bf16 v[98:101], v[158:161], v[202:205], v[98:101]
	v_mfma_f32_16x16x32_bf16 v[90:93], v[144:147], v[210:213], v[90:93]
	v_mfma_f32_16x16x32_bf16 v[82:85], v[158:161], v[210:213], v[82:85]
	v_mfma_f32_16x16x32_bf16 v[74:77], v[144:147], v[218:221], v[74:77]
	v_mfma_f32_16x16x32_bf16 v[54:57], v[158:161], v[218:221], v[54:57]
	v_mfma_f32_16x16x32_bf16 v[126:129], v[154:157], v[198:201], v[126:129]
	v_mfma_f32_16x16x32_bf16 v[114:117], v[162:165], v[198:201], v[114:117]
	v_mfma_f32_16x16x32_bf16 v[106:109], v[154:157], v[206:209], v[106:109]
	v_mfma_f32_16x16x32_bf16 v[98:101], v[162:165], v[206:209], v[98:101]
	v_mfma_f32_16x16x32_bf16 v[90:93], v[154:157], v[214:217], v[90:93]
	v_mfma_f32_16x16x32_bf16 v[82:85], v[162:165], v[214:217], v[82:85]
	v_mfma_f32_16x16x32_bf16 v[74:77], v[154:157], v[238:241], v[74:77]
	v_mfma_f32_16x16x32_bf16 v[54:57], v[162:165], v[238:241], v[54:57]
	v_mfma_f32_16x16x32_bf16 v[118:121], v[166:169], v[194:197], v[118:121]
	v_mfma_f32_16x16x32_bf16 v[122:125], v[174:177], v[194:197], v[122:125]
	v_mfma_f32_16x16x32_bf16 v[102:105], v[166:169], v[202:205], v[102:105]
	v_mfma_f32_16x16x32_bf16 v[110:113], v[174:177], v[202:205], v[110:113]
	v_mfma_f32_16x16x32_bf16 v[86:89], v[166:169], v[210:213], v[86:89]
	v_mfma_f32_16x16x32_bf16 v[94:97], v[174:177], v[210:213], v[94:97]
	v_mfma_f32_16x16x32_bf16 v[70:73], v[166:169], v[218:221], v[70:73]
	v_mfma_f32_16x16x32_bf16 v[78:81], v[174:177], v[218:221], v[78:81]
	v_mfma_f32_16x16x32_bf16 v[118:121], v[170:173], v[198:201], v[118:121]
	v_mfma_f32_16x16x32_bf16 v[122:125], v[190:193], v[198:201], v[122:125]
	v_mfma_f32_16x16x32_bf16 v[102:105], v[170:173], v[206:209], v[102:105]
	v_mfma_f32_16x16x32_bf16 v[110:113], v[190:193], v[206:209], v[110:113]
	v_mfma_f32_16x16x32_bf16 v[86:89], v[170:173], v[214:217], v[86:89]
	v_mfma_f32_16x16x32_bf16 v[94:97], v[190:193], v[214:217], v[94:97]
	v_mfma_f32_16x16x32_bf16 v[70:73], v[170:173], v[238:241], v[70:73]
	v_mfma_f32_16x16x32_bf16 v[78:81], v[190:193], v[238:241], v[78:81]
	s_cmp_lg_u32 s100, 0
	s_cbranch_scc1 .Lmy_h2_42
	s_barrier
.Lmy_h2_42:
	s_setprio 0
	s_add_i32 s68, s68, s8
	v_lshl_add_u64 v[178:179], s[46:47], 0, v[134:135]
	s_mov_b32 m0, s68
	ds_read_b128 v[194:197], v153 offset:16384
	ds_read_b128 v[198:201], v153 offset:17408
	ds_read_b128 v[202:205], v153 offset:18432
	ds_read_b128 v[206:209], v153 offset:19456
	ds_read_b128 v[210:213], v153 offset:20480
	ds_read_b128 v[214:217], v153 offset:21504
	ds_read_b128 v[218:221], v153 offset:22528
	ds_read_b128 v[238:241], v153 offset:23552
	global_load_lds_dwordx4 v[178:179], off
	s_add_i32 m0, s68, 0x2000
	s_add_u32 s68, s46, 0x80000
	v_lshl_add_u64 v[222:223], s[46:47], 0, v[138:139]
	s_addc_u32 s69, s47, 0
	s_add_i32 s70, s70, s8
	global_load_lds_dwordx4 v[222:223], off
	v_lshl_add_u64 v[242:243], s[68:69], 0, v[134:135]
	s_mov_b32 m0, s70
	v_lshl_add_u64 v[244:245], s[50:51], 0, v[136:137]
	global_load_lds_dwordx4 v[242:243], off
	v_lshl_add_u64 v[242:243], s[68:69], 0, v[138:139]
	s_add_i32 m0, s70, 0x2000
	s_nop 0
	global_load_lds_dwordx4 v[242:243], off
	v_lshl_add_u64 v[242:243], s[50:51], 0, v[132:133]
	s_mov_b32 m0, s56
	s_nop 0
	global_load_lds_dwordx4 v[242:243], off
	s_mov_b32 m0, s57
	s_nop 0
	global_load_lds_dwordx4 v[244:245], off
	s_waitcnt vmcnt(8)
	s_waitcnt lgkmcnt(0)
	s_cmp_eq_u32 s100, 0
	s_cbranch_scc1 .Lmy_h2_43
	s_setprio 1
	s_barrier
.Lmy_h2_43:
	v_mfma_f32_16x16x32_bf16 v[50:53], v[144:147], v[194:197], v[50:53]
	v_mfma_f32_16x16x32_bf16 v[38:41], v[158:161], v[194:197], v[38:41]
	v_mfma_f32_16x16x32_bf16 v[22:25], v[144:147], v[202:205], v[22:25]
	v_mfma_f32_16x16x32_bf16 v[42:45], v[158:161], v[202:205], v[42:45]
	v_mfma_f32_16x16x32_bf16 v[30:33], v[144:147], v[210:213], v[30:33]
	v_mfma_f32_16x16x32_bf16 v[18:21], v[158:161], v[210:213], v[18:21]
	v_mfma_f32_16x16x32_bf16 v[10:13], v[144:147], v[218:221], v[10:13]
	v_mfma_f32_16x16x32_bf16 v[2:5], v[158:161], v[218:221], v[2:5]
	v_mfma_f32_16x16x32_bf16 v[50:53], v[154:157], v[198:201], v[50:53]
	v_mfma_f32_16x16x32_bf16 v[38:41], v[162:165], v[198:201], v[38:41]
	v_mfma_f32_16x16x32_bf16 v[22:25], v[154:157], v[206:209], v[22:25]
	v_mfma_f32_16x16x32_bf16 v[42:45], v[162:165], v[206:209], v[42:45]
	v_mfma_f32_16x16x32_bf16 v[30:33], v[154:157], v[214:217], v[30:33]
	v_mfma_f32_16x16x32_bf16 v[18:21], v[162:165], v[214:217], v[18:21]
	v_mfma_f32_16x16x32_bf16 v[10:13], v[154:157], v[238:241], v[10:13]
	v_mfma_f32_16x16x32_bf16 v[2:5], v[162:165], v[238:241], v[2:5]
	v_mfma_f32_16x16x32_bf16 v[46:49], v[166:169], v[194:197], v[46:49]
	v_mfma_f32_16x16x32_bf16 v[58:61], v[174:177], v[194:197], v[58:61]
	v_mfma_f32_16x16x32_bf16 v[62:65], v[166:169], v[202:205], v[62:65]
	v_mfma_f32_16x16x32_bf16 v[66:69], v[174:177], v[202:205], v[66:69]
	v_mfma_f32_16x16x32_bf16 v[26:29], v[166:169], v[210:213], v[26:29]
	v_mfma_f32_16x16x32_bf16 v[34:37], v[174:177], v[210:213], v[34:37]
	v_mfma_f32_16x16x32_bf16 v[6:9], v[166:169], v[218:221], v[6:9]
	v_mfma_f32_16x16x32_bf16 v[14:17], v[174:177], v[218:221], v[14:17]
	v_mfma_f32_16x16x32_bf16 v[46:49], v[170:173], v[198:201], v[46:49]
	v_mfma_f32_16x16x32_bf16 v[58:61], v[190:193], v[198:201], v[58:61]
	v_mfma_f32_16x16x32_bf16 v[62:65], v[170:173], v[206:209], v[62:65]
	v_mfma_f32_16x16x32_bf16 v[66:69], v[190:193], v[206:209], v[66:69]
	v_mfma_f32_16x16x32_bf16 v[26:29], v[170:173], v[214:217], v[26:29]
	v_mfma_f32_16x16x32_bf16 v[34:37], v[190:193], v[214:217], v[34:37]
	v_mfma_f32_16x16x32_bf16 v[6:9], v[170:173], v[238:241], v[6:9]
	v_mfma_f32_16x16x32_bf16 v[14:17], v[190:193], v[238:241], v[14:17]
	s_cmp_lg_u32 s100, 0
	s_cbranch_scc1 .Lmy_h2_44
	s_barrier
.Lmy_h2_44:
	s_setprio 0
	s_add_i32 s68, 0, 0x18000
	s_add_i32 s69, 0, 0x1c000
	v_add_u32_e32 v162, s68, v152
	v_add_u32_e32 v190, s69, v152
	ds_read_b128 v[144:147], v162
	ds_read_b128 v[154:157], v162 offset:1024
	ds_read_b128 v[158:161], v162 offset:2048
	ds_read_b128 v[162:165], v162 offset:3072
	ds_read_b128 v[166:169], v190
	ds_read_b128 v[170:173], v190 offset:1024
	ds_read_b128 v[174:177], v190 offset:2048
	ds_read_b128 v[190:193], v190 offset:3072
	s_add_u32 s50, s50, 0x80000
	s_addc_u32 s51, s51, 0
	s_mov_b32 m0, s58
	v_lshl_add_u64 v[246:247], s[50:51], 0, v[132:133]
	ds_read_b128 v[194:197], v153 offset:32768
	ds_read_b128 v[198:201], v153 offset:33792
	ds_read_b128 v[202:205], v153 offset:34816
	ds_read_b128 v[206:209], v153 offset:35840
	ds_read_b128 v[210:213], v153 offset:36864
	ds_read_b128 v[214:217], v153 offset:37888
	ds_read_b128 v[218:221], v153 offset:38912
	ds_read_b128 v[238:241], v153 offset:39936
	global_load_lds_dwordx4 v[246:247], off
	v_lshl_add_u64 v[246:247], s[50:51], 0, v[136:137]
	s_mov_b32 m0, s59
	s_nop 0
	global_load_lds_dwordx4 v[246:247], off
	s_waitcnt vmcnt(8)
	s_waitcnt lgkmcnt(0)
	s_cmp_eq_u32 s100, 0
	s_cbranch_scc1 .Lmy_h2_45
	s_setprio 1
	s_barrier

.Lmy_h2_46:
	s_setprio 0
	s_add_i32 s50, s68, s8
	v_lshl_add_u64 v[178:179], v[178:179], 0, s[16:17]
	s_mov_b32 m0, s50
	ds_read_b128 v[194:197], v153 offset:49152
	ds_read_b128 v[198:201], v153 offset:50176
	ds_read_b128 v[202:205], v153 offset:51200
	ds_read_b128 v[206:209], v153 offset:52224
	ds_read_b128 v[210:213], v153 offset:53248
	ds_read_b128 v[214:217], v153 offset:54272
	ds_read_b128 v[218:221], v153 offset:55296
	ds_read_b128 v[238:241], v153 offset:56320
	global_load_lds_dwordx4 v[178:179], off
	s_add_i32 m0, s50, 0x2000
	s_add_u32 s46, s46, 0x80080
	v_lshl_add_u64 v[178:179], v[222:223], 0, s[16:17]
	s_addc_u32 s47, s47, 0
	s_add_i32 s50, s69, s8
	global_load_lds_dwordx4 v[178:179], off
	v_lshl_add_u64 v[178:179], s[46:47], 0, v[134:135]
	s_mov_b32 m0, s50
	s_nop 0
	global_load_lds_dwordx4 v[178:179], off
	v_lshl_add_u64 v[178:179], s[46:47], 0, v[138:139]
	s_add_i32 m0, s50, 0x2000
	s_nop 0
	global_load_lds_dwordx4 v[178:179], off
	v_lshl_add_u64 v[178:179], v[242:243], 0, s[16:17]
	s_mov_b32 m0, s60
	s_nop 0
	global_load_lds_dwordx4 v[178:179], off
	v_lshl_add_u64 v[178:179], v[244:245], 0, s[16:17]
	s_mov_b32 m0, s61
	s_nop 0
	global_load_lds_dwordx4 v[178:179], off
	s_waitcnt vmcnt(8)
	s_waitcnt lgkmcnt(0)
	s_cmp_eq_u32 s100, 0
	s_cbranch_scc1 .Lmy_h2_47
	s_setprio 1
	s_barrier

.Lmy_h2_48:
	s_setprio 0
	s_add_i32 s67, s67, 2
	s_add_u32 s48, s48, 0x100
	s_addc_u32 s49, s49, 0
	s_add_u32 s64, s64, 0x100
	s_addc_u32 s66, s66, 0
	s_cmp_gt_u32 s67, 29
	s_cbranch_scc0 .LBB0_1583
	s_and_b64 vcc, exec, s[28:29]
	s_cbranch_vccz .LBB0_1586

.LBB0_1602:
	s_or_b64 exec, exec, s[38:39]
	s_andn2_b64 vcc, exec, s[36:37]
	s_mov_b64 s[36:37], -1
	s_cbranch_vccnz .LBB0_1575
	v_lshl_add_u32 v2, s34, 8, v151
	s_waitcnt lgkmcnt(0)
	v_ashrrev_i32_e32 v3, 31, v2
	v_lshlrev_b64 v[2:3], 12, v[2:3]
	s_lshl_b32 s36, s30, 8
	v_lshl_add_u64 v[2:3], s[14:15], 0, v[2:3]
	s_ashr_i32 s37, s36, 31
	v_lshl_add_u64 v[2:3], s[36:37], 1, v[2:3]
	v_lshl_add_u64 v[2:3], v[2:3], 0, s[12:13]
	v_lshl_add_u64 v[2:3], v[2:3], 0, v[180:181]
	s_mov_b32 s31, 0x10000
	v_add_co_u32_e32 v4, vcc, s31, v2
	s_mov_b32 s31, 0x20000
	s_nop 0
	v_addc_co_u32_e32 v5, vcc, 0, v3, vcc
	global_load_dwordx4 v[62:65], v[2:3], off
	global_load_dwordx4 v[54:57], v[2:3], off offset:256
	global_load_dwordx4 v[58:61], v[4:5], off
	global_load_dwordx4 v[46:49], v[4:5], off offset:256
	v_add_co_u32_e32 v4, vcc, s31, v2
	s_mov_b32 s31, 0x30000
	s_nop 0
	v_addc_co_u32_e32 v5, vcc, 0, v3, vcc
	global_load_dwordx4 v[50:53], v[4:5], off
	global_load_dwordx4 v[38:41], v[4:5], off offset:256
	v_add_co_u32_e32 v4, vcc, s31, v2
	s_mov_b32 s31, 0x80000
	s_nop 0
	v_addc_co_u32_e32 v5, vcc, 0, v3, vcc
	global_load_dwordx4 v[42:45], v[4:5], off
	global_load_dwordx4 v[30:33], v[4:5], off offset:256
	v_add_co_u32_e32 v4, vcc, s31, v2
	s_mov_b32 s31, 0x90000
	s_nop 0
	v_addc_co_u32_e32 v5, vcc, 0, v3, vcc
	global_load_dwordx4 v[34:37], v[4:5], off
	global_load_dwordx4 v[22:25], v[4:5], off offset:256
	v_add_co_u32_e32 v4, vcc, s31, v2
	s_nop 1
	v_addc_co_u32_e32 v5, vcc, 0, v3, vcc
	global_load_dwordx4 v[26:29], v[4:5], off
	global_load_dwordx4 v[18:21], v[4:5], off offset:256
	v_add_co_u32_e32 v4, vcc, 0xa0000, v2
	s_nop 1
	v_addc_co_u32_e32 v5, vcc, 0, v3, vcc
	v_add_co_u32_e32 v14, vcc, 0xb0000, v2
	global_load_dwordx4 v[10:13], v[4:5], off
	global_load_dwordx4 v[6:9], v[4:5], off offset:256
	v_addc_co_u32_e32 v15, vcc, 0, v3, vcc
	global_load_dwordx4 v[2:5], v[14:15], off
	s_nop 0
	global_load_dwordx4 v[14:17], v[14:15], off offset:256
	s_andn2_b64 vcc, exec, s[26:27]
	s_cbranch_vccnz .LBB0_1574
	s_branch .LBB0_1574

.LBB0_1672:
	s_waitcnt lgkmcnt(0)
	v_readlane_b32 s15, v255, 43
	s_lshl_b32 s6, s15, 6
	s_mov_b32 s7, s13
	v_writelane_b32 v255, s6, 53
	s_mul_i32 s12, s15, 0x4200
	s_andn2_b64 vcc, exec, s[2:3]
	v_writelane_b32 v255, s7, 54
	s_cbranch_vccnz .LBB0_1753
	s_waitcnt lgkmcnt(0)
	v_ashrrev_i32_e32 v3, 31, v16
	v_lshrrev_b32_e32 v3, 26, v3
	v_add_u32_e32 v3, v16, v3
	v_ashrrev_i32_e32 v10, 6, v3
	v_bfe_i32 v3, v16, 27, 1
	v_lshlrev_b32_e32 v2, 4, v16
	v_lshrrev_b32_e32 v3, 22, v3
	v_add_u32_e32 v3, v2, v3
	s_load_dwordx4 s[36:39], s[0:1], s8 offset:0x110
	v_and_b32_e32 v3, 0xfffffc00, v3
	v_sub_u32_e32 v3, v2, v3
	v_lshrrev_b32_e32 v4, 4, v3
	v_bitop3_b32 v3, v4, v3, 32 bitop3:0x6c
	v_ashrrev_i32_e32 v5, 31, v3
	s_waitcnt lgkmcnt(0)
	s_add_u32 s29, s38, 0x1de00000
	v_lshrrev_b32_e32 v5, 26, v5
	s_mul_i32 s3, s15, 0x2b00000
	s_addc_u32 s64, s39, 0
	v_add_u32_e32 v5, v3, v5
	s_mul_hi_u32 s2, s15, 0x2b00000
	s_add_u32 s3, s38, s3
	v_lshlrev_b32_e32 v4, 3, v10
	v_ashrrev_i32_e32 v11, 6, v5
	v_and_b32_e32 v5, 0xc0, v5
	s_addc_u32 s2, s39, s2
	v_and_b32_e32 v4, -16, v4
	v_sub_u32_e32 v3, v3, v5
	s_add_u32 s76, s3, 0x5600000
	v_add_u32_e32 v4, v11, v4
	v_ashrrev_i16_sdwa v3, v224, sext(v3) dst_sel:DWORD dst_unused:UNUSED_PAD src0_sel:DWORD src1_sel:BYTE_0
	s_addc_u32 s22, s2, 0
	v_lshlrev_b32_e32 v6, 5, v10
	v_bfe_i32 v12, v3, 0, 16
	v_lshlrev_b32_e32 v3, 1, v4
	v_lshrrev_b32_e32 v5, 2, v4
	v_and_b32_e32 v7, 3, v11
	s_mov_b32 s2, 0xfffe0
	v_and_b32_e32 v6, 32, v6
	v_and_b32_e32 v3, 24, v3
	v_and_b32_e32 v5, 4, v5
	v_and_or_b32 v7, v4, s2, v7
	v_or3_b32 v3, v7, v5, v3
	v_add_lshl_u32 v5, v6, v12, 1
	v_add_u32_e32 v2, 0x2000, v2
	v_lshl_add_u32 v180, v3, 12, v5
	v_ashrrev_i32_e32 v3, 31, v2
	v_lshrrev_b32_e32 v3, 22, v3
	v_add_u32_e32 v3, v2, v3
	v_ashrrev_i32_e32 v13, 10, v3
	v_mul_i32_i24_e32 v3, 0x400, v13
	v_sub_u32_e32 v2, v2, v3
	v_lshrrev_b32_e32 v3, 4, v2
	v_bitop3_b32 v2, v3, v2, 32 bitop3:0x6c
	v_lshl_add_u32 v192, v4, 12, v5
	v_ashrrev_i32_e32 v4, 31, v2
	v_lshrrev_b32_e32 v4, 26, v4
	v_lshlrev_b32_e32 v3, 3, v13
	v_add_u32_e32 v4, v2, v4
	v_and_b32_e32 v3, -16, v3
	v_ashrrev_i32_e32 v14, 6, v4
	v_add_u32_e32 v3, v14, v3
	v_and_b32_e32 v4, 0xc0, v4
	v_and_b32_e32 v6, 3, v14
	s_ashr_i32 s14, s10, 6
	s_ashr_i32 s45, s44, 31
	s_ashr_i32 s27, s26, 31
	v_sub_u32_e32 v2, v2, v4
	v_and_or_b32 v6, v3, s2, v6
	s_ashr_i32 s11, s10, 8
	s_lshl_b32 s23, s14, 10
	s_lshl_b64 s[2:3], s[44:45], 20
	s_lshl_b64 s[6:7], s[26:27], 20
	v_ashrrev_i16_sdwa v2, v224, sext(v2) dst_sel:DWORD dst_unused:UNUSED_PAD src0_sel:DWORD src1_sel:BYTE_0
	s_add_u32 s46, s76, s6
	v_lshlrev_b32_e32 v5, 5, v13
	v_bfe_i32 v15, v2, 0, 16
	v_lshlrev_b32_e32 v2, 1, v3
	v_lshrrev_b32_e32 v4, 2, v3
	s_addc_u32 s47, s22, s7
	s_add_i32 s6, s23, 0
	v_and_b32_e32 v5, 32, v5
	v_and_b32_e32 v2, 24, v2
	v_and_b32_e32 v4, 4, v4
	s_add_i32 m0, s6, 0x10000
	v_or3_b32 v2, v6, v4, v2
	v_add_lshl_u32 v4, v5, v15, 1
	global_load_lds_dwordx4 v180, s[46:47]
	s_add_i32 m0, s6, 0x12000
	v_lshl_add_u32 v196, v2, 12, v4
	s_add_u32 s18, s46, 0x80000
	global_load_lds_dwordx4 v196, s[46:47]
	s_addc_u32 s19, s47, 0
	s_add_i32 m0, s6, 0x14000
	v_lshl_add_u32 v194, v3, 12, v4
	global_load_lds_dwordx4 v180, s[18:19]
	s_add_i32 m0, s6, 0x16000
	s_add_u32 s48, s29, s2
	s_addc_u32 s49, s64, s3
	s_add_i32 s9, s6, 0x2000
	global_load_lds_dwordx4 v196, s[18:19]
	s_mov_b32 m0, s6
	s_add_u32 s2, s48, 0x80000
	global_load_lds_dwordx4 v192, s[48:49]
	s_mov_b32 m0, s9
	s_addc_u32 s3, s49, 0
	s_add_i32 s21, s6, 0x4000
	global_load_lds_dwordx4 v194, s[48:49]
	s_mov_b32 m0, s21
	s_add_i32 s7, s6, 0x6000
	global_load_lds_dwordx4 v192, s[2:3]
	s_mov_b32 m0, s7
	v_writelane_b32 v255, s97, 55
	global_load_lds_dwordx4 v194, s[2:3]
	s_load_dwordx2 s[2:3], s[0:1], s8 offset:0x38
	s_load_dwordx4 s[40:43], s[0:1], s8 offset:0xf8
	v_writelane_b32 v255, s96, 56
	v_mov_b32_e32 v197, v181
	v_mov_b32_e32 v193, v181
	v_mov_b32_e32 v195, v181
	s_cmp_eq_u32 s11, 1
	v_writelane_b32 v255, s70, 57
	v_lshl_add_u64 v[8:9], s[46:47], 0, v[180:181]
	v_lshl_add_u64 v[6:7], s[46:47], 0, v[196:197]
	v_lshl_add_u64 v[2:3], s[48:49], 0, v[192:193]
	s_cselect_b64 s[56:57], -1, 0
	s_cmp_lg_u32 s11, 1
	v_lshl_add_u64 v[4:5], s[48:49], 0, v[194:195]
	s_mov_b32 s8, s15
	s_cbranch_scc1 .LBB0_1675
.LBB0_1675:
	s_lshl_b32 s18, s8, 3
	s_mul_hi_u32 s15, s8, 0x560000
	s_mul_i32 s27, s8, 0x560000
	s_mul_hi_u32 s30, s8, 0x10200
	s_mul_i32 s31, s8, 0x10200
	s_mul_hi_u32 s34, s8, 0x5600
	s_mul_i32 s35, s8, 0x5600
	v_writelane_b32 v255, s18, 44
	s_lshl_b32 s8, s8, 7
	s_lshl_b64 s[18:19], s[12:13], 3
	s_add_u32 s45, s38, s18
	s_addc_u32 s50, s39, s19
	s_add_u32 s58, s38, 0x31900000
	s_addc_u32 s59, s39, 0
	s_waitcnt lgkmcnt(0)
	s_add_u32 s60, s2, s27
	s_addc_u32 s61, s3, s15
	s_add_u32 s27, s40, s31
	s_addc_u32 s40, s41, s30
	s_add_u32 s41, s42, s35
	s_addc_u32 s42, s43, s34
	v_readlane_b32 s2, v255, 53
	s_add_u32 s62, s38, 0x3b000000
	v_readlane_b32 s3, v255, 54
	s_addc_u32 s63, s39, 0
	s_lshl_b64 s[2:3], s[2:3], 2
	s_add_u32 s2, s38, s2
	s_addc_u32 s3, s39, s3
	s_add_u32 s2, s2, 0x8000
	s_addc_u32 s3, s3, 0
	v_writelane_b32 v255, s2, 58
	v_and_b32_e32 v17, 63, v16
	v_and_b32_e32 v191, 15, v16
	v_bfe_u32 v238, v16, 4, 2
	v_and_b32_e32 v18, 48, v16
	v_lshlrev_b32_e32 v16, 2, v16
	v_writelane_b32 v255, s3, 59
	s_lshl_b32 s2, s11, 13
	v_lshl_or_b32 v18, v191, 6, v18
	v_and_b32_e32 v16, 32, v16
	v_bitop3_b32 v19, v18, s2, v16 bitop3:0xde
	s_lshl_b32 s2, s14, 5
	s_and_b32 s35, s2, 0x60
	s_add_i32 m0, s6, 0x18000
	v_lshl_add_u64 v[8:9], v[8:9], 0, s[16:17]
	s_lshl_b32 s34, s11, 6
	s_lshl_b32 s3, s35, 7
	s_waitcnt vmcnt(2)
	s_barrier
	global_load_lds_dwordx4 v[8:9], off
	v_lshl_add_u64 v[6:7], v[6:7], 0, s[16:17]
	s_add_i32 m0, s6, 0x1a000
	s_add_i32 s54, s6, 0x8000
	s_add_i32 s55, s6, 0xa000
	global_load_lds_dwordx4 v[6:7], off
	v_lshl_add_u64 v[2:3], v[2:3], 0, s[16:17]
	s_mov_b32 m0, s54
	s_add_u32 s18, s46, 0x80080
	global_load_lds_dwordx4 v[2:3], off
	v_lshl_add_u64 v[2:3], v[4:5], 0, s[16:17]
	s_mov_b32 m0, s55
	s_addc_u32 s19, s47, 0
	global_load_lds_dwordx4 v[2:3], off
	s_add_i32 m0, s6, 0x1c000
	v_lshl_add_u64 v[2:3], s[18:19], 0, v[180:181]
	global_load_lds_dwordx4 v[2:3], off
	v_lshl_add_u64 v[2:3], s[18:19], 0, v[196:197]
	s_add_i32 m0, s6, 0x1e000
	s_ashr_i32 s18, s10, 7
	global_load_lds_dwordx4 v[2:3], off
	v_bitop3_b32 v239, s3, v18, v16 bitop3:0xf6
	s_lshl_b32 s51, s18, 9
	s_ashr_i32 s3, s2, 31
	s_lshl_b32 s68, s14, 8
	s_cmpk_lt_u32 s10, 0x100
	s_cselect_b64 s[30:31], -1, 0
	s_lshl_b32 s14, s11, 1
	s_add_i32 s14, s14, 0x7ffff2
	s_cmp_gt_i32 s11, 0
	v_writelane_b32 v255, s14, 50
	s_cselect_b64 s[14:15], -1, 0
	s_lshl_b32 s66, s11, 10
	v_writelane_b32 v255, s14, 41
	s_cmpk_gt_u32 s10, 0xff
	s_mul_i32 s43, s18, 0x5600
	v_writelane_b32 v255, s15, 42
	s_cselect_b64 s[14:15], -1, 0
	s_cmp_gt_i32 s11, -1
	s_cselect_b64 s[70:71], -1, 0
	s_ashr_i32 s83, s28, 31
	s_mul_hi_i32 s19, s18, 0x5600
	s_add_u32 s11, s27, s43
	s_addc_u32 s19, s40, s19
	s_cmp_lt_i32 s18, 3
	s_cselect_b32 s18, s19, s42
	s_cselect_b32 s11, s11, s41
	s_lshl_b32 s10, s10, 2
	s_and_b32 s19, s10, 0x100
	s_add_u32 s10, s11, s19
	s_addc_u32 s11, s18, 0
	v_lshlrev_b32_e32 v2, 2, v17
	v_mov_b32_e32 v3, v181
	v_writelane_b32 v255, s70, 15
	v_lshl_add_u64 v[198:199], s[10:11], 0, v[2:3]
	s_add_i32 s10, s51, 0
	v_writelane_b32 v255, s71, 16
	s_add_i32 s70, s10, s19
	s_add_i32 s70, s70, 0x21000
	s_lshl_b64 s[2:3], s[2:3], 3
	s_add_u32 s2, s45, s2
	s_addc_u32 s3, s50, s3
	v_lshl_add_u64 v[2:3], s[2:3], 0, v[2:3]
	s_mov_b64 s[2:3], 0x20800
	v_lshl_add_u64 v[200:201], v[2:3], 0, s[2:3]
	s_add_u32 s74, s38, 0x3b300000
	v_lshlrev_b32_e32 v2, 15, v10
	s_addc_u32 s75, s39, 0
	s_add_i32 s2, s66, 0
	v_and_b32_e32 v2, 0xffff0000, v2
	s_add_i32 s2, s2, 0x20000
	v_lshl_add_u32 v2, v11, 12, v2
	v_and_b32_e32 v3, 1, v10
	s_add_u32 s96, s36, 0x5160000
	v_lshl_or_b32 v2, v3, 6, v2
	s_addc_u32 s97, s37, 0
	v_lshl_add_u32 v202, v12, 1, v2
	v_lshlrev_b32_e32 v2, 15, v13
	s_add_u32 s66, s36, 0x5e0c000
	v_and_b32_e32 v2, 0xffff0000, v2
	s_waitcnt vmcnt(6)
	v_writelane_b32 v255, s2, 46
	s_addc_u32 s67, s37, 0
	v_lshl_add_u32 v2, v14, 12, v2
	v_and_b32_e32 v3, 1, v13
	s_xor_b64 s[2:3], s[14:15], -1
	v_lshl_or_b32 v2, v3, 6, v2
	s_add_i32 s71, s68, 0
	v_writelane_b32 v255, s2, 48
	s_mov_b32 s82, 0
	v_mov_b32_e32 v203, v181
	v_lshl_add_u32 v204, v15, 1, v2
	v_mov_b32_e32 v205, v181
	s_add_i32 s71, s71, 0x21800
	v_add_u32_e32 v240, 0, v19
	v_writelane_b32 v255, s3, 49
	s_barrier
	s_branch .LBB0_1678

.LBB0_1685:
	s_add_u32 s42, s40, 0xfff80080
	s_addc_u32 s43, s41, -1
	s_and_b64 s[26:27], s[26:27], exec
	s_cselect_b32 s43, s19, s43
	s_cselect_b32 s42, s45, s42
	s_cselect_b32 s27, s50, s39
	s_cselect_b32 s26, s51, s37
	s_add_i32 s47, 0, 0x10000
	s_add_i32 s69, 0, 0x14000
	v_add_u32_e32 v146, s47, v239
	v_add_u32_e32 v162, s69, v239
	ds_read_b128 v[114:117], v146
	ds_read_b128 v[118:121], v146 offset:1024
	ds_read_b128 v[122:125], v146 offset:2048
	ds_read_b128 v[146:149], v146 offset:3072
	ds_read_b128 v[150:153], v162
	ds_read_b128 v[154:157], v162 offset:1024
	ds_read_b128 v[158:161], v162 offset:2048
	ds_read_b128 v[162:165], v162 offset:3072
	v_lshl_add_u64 v[178:179], s[40:41], 0, v[202:203]
	s_add_i32 m0, s6, 0xc000
	ds_read_b128 v[166:169], v240
	ds_read_b128 v[170:173], v240 offset:1024
	ds_read_b128 v[174:177], v240 offset:2048
	ds_read_b128 v[206:209], v240 offset:3072
	ds_read_b128 v[210:213], v240 offset:4096
	ds_read_b128 v[214:217], v240 offset:5120
	ds_read_b128 v[218:221], v240 offset:6144
	ds_read_b128 v[242:245], v240 offset:7168
	global_load_lds_dwordx4 v[178:179], off
	v_lshl_add_u64 v[178:179], s[40:41], 0, v[204:205]
	s_add_i32 m0, s6, 0xe000
	s_nop 0
	global_load_lds_dwordx4 v[178:179], off
	s_waitcnt vmcnt(8)
	s_waitcnt lgkmcnt(0)
	s_cmp_eq_u32 s100, 0
	s_cbranch_scc1 .Lmy_h2_49
	s_setprio 1
	s_barrier
.Lmy_h2_49:
	v_mfma_f32_16x16x32_bf16 v[142:145], v[114:117], v[166:169], v[142:145]
	v_mfma_f32_16x16x32_bf16 v[62:65], v[122:125], v[166:169], v[62:65]
	v_mfma_f32_16x16x32_bf16 v[134:137], v[114:117], v[174:177], v[134:137]
	v_mfma_f32_16x16x32_bf16 v[54:57], v[122:125], v[174:177], v[54:57]
	v_mfma_f32_16x16x32_bf16 v[126:129], v[114:117], v[210:213], v[126:129]
	v_mfma_f32_16x16x32_bf16 v[46:49], v[122:125], v[210:213], v[46:49]
	v_mfma_f32_16x16x32_bf16 v[102:105], v[114:117], v[218:221], v[102:105]
	v_mfma_f32_16x16x32_bf16 v[38:41], v[122:125], v[218:221], v[38:41]
	v_mfma_f32_16x16x32_bf16 v[142:145], v[118:121], v[170:173], v[142:145]
	v_mfma_f32_16x16x32_bf16 v[62:65], v[146:149], v[170:173], v[62:65]
	v_mfma_f32_16x16x32_bf16 v[134:137], v[118:121], v[206:209], v[134:137]
	v_mfma_f32_16x16x32_bf16 v[54:57], v[146:149], v[206:209], v[54:57]
	v_mfma_f32_16x16x32_bf16 v[126:129], v[118:121], v[214:217], v[126:129]
	v_mfma_f32_16x16x32_bf16 v[46:49], v[146:149], v[214:217], v[46:49]
	v_mfma_f32_16x16x32_bf16 v[102:105], v[118:121], v[242:245], v[102:105]
	v_mfma_f32_16x16x32_bf16 v[38:41], v[146:149], v[242:245], v[38:41]
	v_mfma_f32_16x16x32_bf16 v[138:141], v[150:153], v[166:169], v[138:141]
	v_mfma_f32_16x16x32_bf16 v[58:61], v[158:161], v[166:169], v[58:61]
	v_mfma_f32_16x16x32_bf16 v[130:133], v[150:153], v[174:177], v[130:133]
	v_mfma_f32_16x16x32_bf16 v[50:53], v[158:161], v[174:177], v[50:53]
	v_mfma_f32_16x16x32_bf16 v[106:109], v[150:153], v[210:213], v[106:109]
	v_mfma_f32_16x16x32_bf16 v[42:45], v[158:161], v[210:213], v[42:45]
	v_mfma_f32_16x16x32_bf16 v[98:101], v[150:153], v[218:221], v[98:101]
	v_mfma_f32_16x16x32_bf16 v[34:37], v[158:161], v[218:221], v[34:37]
	v_mfma_f32_16x16x32_bf16 v[138:141], v[154:157], v[170:173], v[138:141]
	v_mfma_f32_16x16x32_bf16 v[58:61], v[162:165], v[170:173], v[58:61]
	v_mfma_f32_16x16x32_bf16 v[130:133], v[154:157], v[206:209], v[130:133]
	v_mfma_f32_16x16x32_bf16 v[50:53], v[162:165], v[206:209], v[50:53]
	v_mfma_f32_16x16x32_bf16 v[106:109], v[154:157], v[214:217], v[106:109]
	v_mfma_f32_16x16x32_bf16 v[42:45], v[162:165], v[214:217], v[42:45]
	v_mfma_f32_16x16x32_bf16 v[98:101], v[154:157], v[242:245], v[98:101]
	v_mfma_f32_16x16x32_bf16 v[34:37], v[162:165], v[242:245], v[34:37]
	s_cmp_lg_u32 s100, 0
	s_cbranch_scc1 .Lmy_h2_50
	s_barrier
.Lmy_h2_50:
	s_setprio 0
	s_add_i32 s47, s47, s23
	v_lshl_add_u64 v[178:179], s[26:27], 0, v[180:181]
	s_mov_b32 m0, s47
	ds_read_b128 v[166:169], v240 offset:16384
	ds_read_b128 v[170:173], v240 offset:17408
	ds_read_b128 v[174:177], v240 offset:18432
	ds_read_b128 v[206:209], v240 offset:19456
	ds_read_b128 v[210:213], v240 offset:20480
	ds_read_b128 v[214:217], v240 offset:21504
	ds_read_b128 v[218:221], v240 offset:22528
	ds_read_b128 v[242:245], v240 offset:23552
	global_load_lds_dwordx4 v[178:179], off
	s_add_i32 m0, s47, 0x2000
	s_add_u32 s48, s26, 0x80000
	v_lshl_add_u64 v[222:223], s[26:27], 0, v[196:197]
	s_addc_u32 s49, s27, 0
	s_add_i32 s47, s69, s23
	global_load_lds_dwordx4 v[222:223], off
	v_lshl_add_u64 v[246:247], s[48:49], 0, v[180:181]
	s_mov_b32 m0, s47
	v_lshl_add_u64 v[248:249], s[42:43], 0, v[194:195]
	global_load_lds_dwordx4 v[246:247], off
	v_lshl_add_u64 v[246:247], s[48:49], 0, v[196:197]
	s_add_i32 m0, s47, 0x2000
	s_nop 0
	global_load_lds_dwordx4 v[246:247], off
	v_lshl_add_u64 v[246:247], s[42:43], 0, v[192:193]
	s_mov_b32 m0, s6
	s_nop 0
	global_load_lds_dwordx4 v[246:247], off
	s_mov_b32 m0, s9
	s_nop 0
	global_load_lds_dwordx4 v[248:249], off
	s_waitcnt vmcnt(8)
	s_waitcnt lgkmcnt(0)
	s_cmp_eq_u32 s100, 0
	s_cbranch_scc1 .Lmy_h2_51
	s_setprio 1
	s_barrier
.Lmy_h2_51:
	v_mfma_f32_16x16x32_bf16 v[94:97], v[114:117], v[166:169], v[94:97]
	v_mfma_f32_16x16x32_bf16 v[30:33], v[122:125], v[166:169], v[30:33]
	v_mfma_f32_16x16x32_bf16 v[86:89], v[114:117], v[174:177], v[86:89]
	v_mfma_f32_16x16x32_bf16 v[22:25], v[122:125], v[174:177], v[22:25]
	v_mfma_f32_16x16x32_bf16 v[78:81], v[114:117], v[210:213], v[78:81]
	v_mfma_f32_16x16x32_bf16 v[14:17], v[122:125], v[210:213], v[14:17]
	v_mfma_f32_16x16x32_bf16 v[70:73], v[114:117], v[218:221], v[70:73]
	v_mfma_f32_16x16x32_bf16 v[6:9], v[122:125], v[218:221], v[6:9]
	v_mfma_f32_16x16x32_bf16 v[94:97], v[118:121], v[170:173], v[94:97]
	v_mfma_f32_16x16x32_bf16 v[30:33], v[146:149], v[170:173], v[30:33]
	v_mfma_f32_16x16x32_bf16 v[86:89], v[118:121], v[206:209], v[86:89]
	v_mfma_f32_16x16x32_bf16 v[22:25], v[146:149], v[206:209], v[22:25]
	v_mfma_f32_16x16x32_bf16 v[78:81], v[118:121], v[214:217], v[78:81]
	v_mfma_f32_16x16x32_bf16 v[14:17], v[146:149], v[214:217], v[14:17]
	v_mfma_f32_16x16x32_bf16 v[70:73], v[118:121], v[242:245], v[70:73]
	v_mfma_f32_16x16x32_bf16 v[6:9], v[146:149], v[242:245], v[6:9]
	v_mfma_f32_16x16x32_bf16 v[90:93], v[150:153], v[166:169], v[90:93]
	v_mfma_f32_16x16x32_bf16 v[26:29], v[158:161], v[166:169], v[26:29]
	v_mfma_f32_16x16x32_bf16 v[82:85], v[150:153], v[174:177], v[82:85]
	v_mfma_f32_16x16x32_bf16 v[18:21], v[158:161], v[174:177], v[18:21]
	v_mfma_f32_16x16x32_bf16 v[74:77], v[150:153], v[210:213], v[74:77]
	v_mfma_f32_16x16x32_bf16 v[10:13], v[158:161], v[210:213], v[10:13]
	v_mfma_f32_16x16x32_bf16 v[66:69], v[150:153], v[218:221], v[66:69]
	v_mfma_f32_16x16x32_bf16 v[2:5], v[158:161], v[218:221], v[2:5]
	v_mfma_f32_16x16x32_bf16 v[90:93], v[154:157], v[170:173], v[90:93]
	v_mfma_f32_16x16x32_bf16 v[26:29], v[162:165], v[170:173], v[26:29]
	v_mfma_f32_16x16x32_bf16 v[82:85], v[154:157], v[206:209], v[82:85]
	v_mfma_f32_16x16x32_bf16 v[18:21], v[162:165], v[206:209], v[18:21]
	v_mfma_f32_16x16x32_bf16 v[74:77], v[154:157], v[214:217], v[74:77]
	v_mfma_f32_16x16x32_bf16 v[10:13], v[162:165], v[214:217], v[10:13]
	v_mfma_f32_16x16x32_bf16 v[66:69], v[154:157], v[242:245], v[66:69]
	v_mfma_f32_16x16x32_bf16 v[2:5], v[162:165], v[242:245], v[2:5]
	s_cmp_lg_u32 s100, 0
	s_cbranch_scc1 .Lmy_h2_52
	s_barrier
.Lmy_h2_52:
	s_setprio 0
	s_add_i32 s47, 0, 0x18000
	s_add_i32 s48, 0, 0x1c000
	v_add_u32_e32 v146, s47, v239
	v_add_u32_e32 v162, s48, v239
	ds_read_b128 v[114:117], v146
	ds_read_b128 v[118:121], v146 offset:1024
	ds_read_b128 v[122:125], v146 offset:2048
	ds_read_b128 v[146:149], v146 offset:3072
	ds_read_b128 v[150:153], v162
	ds_read_b128 v[154:157], v162 offset:1024
	ds_read_b128 v[158:161], v162 offset:2048
	ds_read_b128 v[162:165], v162 offset:3072
	s_add_u32 s42, s42, 0x80000
	s_addc_u32 s43, s43, 0
	s_mov_b32 m0, s21
	v_lshl_add_u64 v[250:251], s[42:43], 0, v[192:193]
	ds_read_b128 v[166:169], v240 offset:32768
	ds_read_b128 v[170:173], v240 offset:33792
	ds_read_b128 v[174:177], v240 offset:34816
	ds_read_b128 v[206:209], v240 offset:35840
	ds_read_b128 v[210:213], v240 offset:36864
	ds_read_b128 v[214:217], v240 offset:37888
	ds_read_b128 v[218:221], v240 offset:38912
	ds_read_b128 v[242:245], v240 offset:39936
	global_load_lds_dwordx4 v[250:251], off
	v_lshl_add_u64 v[250:251], s[42:43], 0, v[194:195]
	s_mov_b32 m0, s7
	s_nop 0
	global_load_lds_dwordx4 v[250:251], off
	s_waitcnt vmcnt(8)
	s_waitcnt lgkmcnt(0)
	s_cmp_eq_u32 s100, 0
	s_cbranch_scc1 .Lmy_h2_53
	s_setprio 1
	s_barrier

.Lmy_h2_54:
	s_setprio 0
	s_add_i32 s42, s47, s23
	v_lshl_add_u64 v[178:179], v[178:179], 0, s[16:17]
	s_mov_b32 m0, s42
	ds_read_b128 v[166:169], v240 offset:49152
	ds_read_b128 v[170:173], v240 offset:50176
	ds_read_b128 v[174:177], v240 offset:51200
	ds_read_b128 v[206:209], v240 offset:52224
	ds_read_b128 v[210:213], v240 offset:53248
	ds_read_b128 v[214:217], v240 offset:54272
	ds_read_b128 v[218:221], v240 offset:55296
	ds_read_b128 v[242:245], v240 offset:56320
	global_load_lds_dwordx4 v[178:179], off
	s_add_i32 m0, s42, 0x2000
	s_add_u32 s26, s26, 0x80080
	v_lshl_add_u64 v[178:179], v[222:223], 0, s[16:17]
	s_addc_u32 s27, s27, 0
	s_add_i32 s42, s48, s23
	global_load_lds_dwordx4 v[178:179], off
	v_lshl_add_u64 v[178:179], s[26:27], 0, v[180:181]
	s_mov_b32 m0, s42
	s_nop 0
	global_load_lds_dwordx4 v[178:179], off
	v_lshl_add_u64 v[178:179], s[26:27], 0, v[196:197]
	s_add_i32 m0, s42, 0x2000
	s_nop 0
	global_load_lds_dwordx4 v[178:179], off
	v_lshl_add_u64 v[178:179], v[246:247], 0, s[16:17]
	s_mov_b32 m0, s54
	s_nop 0
	global_load_lds_dwordx4 v[178:179], off
	v_lshl_add_u64 v[178:179], v[248:249], 0, s[16:17]
	s_mov_b32 m0, s55
	s_nop 0
	global_load_lds_dwordx4 v[178:179], off
	s_waitcnt vmcnt(8)
	s_waitcnt lgkmcnt(0)
	s_cmp_eq_u32 s100, 0
	s_cbranch_scc1 .Lmy_h2_55
	s_setprio 1
	s_barrier

.Lmy_h2_56:
	s_setprio 0
	s_add_i32 s46, s46, 2
	s_add_u32 s40, s40, 0x100
	s_addc_u32 s41, s41, 0
	s_add_u32 s37, s37, 0x100
	s_addc_u32 s39, s39, 0
	s_cmp_gt_u32 s46, 29
	s_cbranch_scc1 .LBB0_1688

.LBB0_1688:
	s_and_b64 vcc, exec, s[30:31]
	s_cbranch_vccz .LBB0_1690
.LBB0_1690:
	v_mov_b32_e32 v114, v238
	v_mov_b32_e32 v209, v191
	s_mov_b64 s[26:27], -1
	v_add_u32_e32 v110, s34, v209
	v_add_u32_e32 v241, s38, v110
	v_lshl_add_u32 v110, v110, 3, 0
	v_add_u32_e32 v115, 0x21800, v110
	ds_read2_b64 v[110:113], v115 offset1:16
	v_lshl_add_u32 v242, v114, 3, s35
	v_add_u32_e32 v206, s36, v242
	s_cmp_lg_u32 s44, 32
	s_mov_b32 s69, 0xcf800000
	s_waitcnt lgkmcnt(0)
	v_ffbh_u32_e32 v116, v111
	v_min_u32_e32 v116, 32, v116
	v_lshlrev_b64 v[110:111], v116, v[110:111]
	v_min_u32_e32 v110, 1, v110
	v_or_b32_e32 v110, v111, v110
	v_cvt_f32_u32_e32 v110, v110
	v_sub_u32_e32 v111, 32, v116
	v_ldexp_f32 v110, v110, v111
	v_mul_f32_e32 v110, 0x30800000, v110
	v_fmamk_f32 v110, v110, 0x3a000000, v1
	v_cmp_gt_f32_e32 vcc, s65, v110
	v_mul_f32_e32 v111, 0x4b800000, v110
	s_nop 0
	v_cndmask_b32_e32 v110, v110, v111, vcc
	v_rsq_f32_e32 v110, v110
	s_nop 0
	v_mul_f32_e32 v111, 0x45800000, v110
	v_cndmask_b32_e32 v222, v110, v111, vcc
	v_ffbh_u32_e32 v110, v113
	v_min_u32_e32 v116, 32, v110
	v_lshlrev_b64 v[110:111], v116, v[112:113]
	v_min_u32_e32 v110, 1, v110
	v_or_b32_e32 v110, v111, v110
	v_cvt_f32_u32_e32 v110, v110
	v_sub_u32_e32 v111, 32, v116
	v_ldexp_f32 v110, v110, v111
	v_mul_f32_e32 v110, 0x30800000, v110
	v_fmamk_f32 v110, v110, 0x3a000000, v1
	v_cmp_gt_f32_e32 vcc, s65, v110
	v_mul_f32_e32 v111, 0x4b800000, v110
	s_nop 0
	v_cndmask_b32_e32 v110, v110, v111, vcc
	v_rsq_f32_e32 v110, v110
	s_nop 0
	v_mul_f32_e32 v111, 0x45800000, v110
	v_cndmask_b32_e32 v220, v110, v111, vcc
	ds_read2_b64 v[110:113], v115 offset0:32 offset1:48
	s_waitcnt lgkmcnt(0)
	v_ffbh_u32_e32 v116, v111
	v_min_u32_e32 v116, 32, v116
	v_lshlrev_b64 v[110:111], v116, v[110:111]
	v_min_u32_e32 v110, 1, v110
	v_or_b32_e32 v110, v111, v110
	v_cvt_f32_u32_e32 v110, v110
	v_sub_u32_e32 v111, 32, v116
	v_ldexp_f32 v110, v110, v111
	v_mul_f32_e32 v110, 0x30800000, v110
	v_fmamk_f32 v110, v110, 0x3a000000, v1
	v_cmp_gt_f32_e32 vcc, s65, v110
	v_mul_f32_e32 v111, 0x4b800000, v110
	s_nop 0
	v_cndmask_b32_e32 v110, v110, v111, vcc
	v_rsq_f32_e32 v110, v110
	s_nop 0
	v_mul_f32_e32 v111, 0x45800000, v110
	v_cndmask_b32_e32 v218, v110, v111, vcc
	v_ffbh_u32_e32 v110, v113
	v_min_u32_e32 v116, 32, v110
	v_lshlrev_b64 v[110:111], v116, v[112:113]
	v_min_u32_e32 v110, 1, v110
	v_or_b32_e32 v110, v111, v110
	v_cvt_f32_u32_e32 v110, v110
	v_sub_u32_e32 v111, 32, v116
	v_ldexp_f32 v110, v110, v111
	v_mul_f32_e32 v110, 0x30800000, v110
	v_fmamk_f32 v110, v110, 0x3a000000, v1
	v_cmp_gt_f32_e32 vcc, s65, v110
	v_mul_f32_e32 v111, 0x4b800000, v110
	s_nop 0
	v_cndmask_b32_e32 v110, v110, v111, vcc
	v_rsq_f32_e32 v110, v110
	s_nop 0
	v_mul_f32_e32 v111, 0x45800000, v110
	v_cndmask_b32_e32 v216, v110, v111, vcc
	ds_read2_b64 v[110:113], v115 offset0:128 offset1:144
	s_waitcnt lgkmcnt(0)
	v_ffbh_u32_e32 v116, v111
	v_min_u32_e32 v116, 32, v116
	v_lshlrev_b64 v[110:111], v116, v[110:111]
	v_min_u32_e32 v110, 1, v110
	v_or_b32_e32 v110, v111, v110
	v_cvt_f32_u32_e32 v110, v110
	v_sub_u32_e32 v111, 32, v116
	v_ldexp_f32 v110, v110, v111
	v_mul_f32_e32 v110, 0x30800000, v110
	v_fmamk_f32 v110, v110, 0x3a000000, v1
	v_cmp_gt_f32_e32 vcc, s65, v110
	v_mul_f32_e32 v111, 0x4b800000, v110
	s_nop 0
	v_cndmask_b32_e32 v110, v110, v111, vcc
	v_rsq_f32_e32 v110, v110
	s_nop 0
	v_mul_f32_e32 v111, 0x45800000, v110
	v_cndmask_b32_e32 v214, v110, v111, vcc
	v_ffbh_u32_e32 v110, v113
	v_min_u32_e32 v116, 32, v110
	v_lshlrev_b64 v[110:111], v116, v[112:113]
	v_min_u32_e32 v110, 1, v110
	v_or_b32_e32 v110, v111, v110
	v_cvt_f32_u32_e32 v110, v110
	v_sub_u32_e32 v111, 32, v116
	v_ldexp_f32 v110, v110, v111
	v_mul_f32_e32 v110, 0x30800000, v110
	v_fmamk_f32 v110, v110, 0x3a000000, v1
	v_cmp_gt_f32_e32 vcc, s65, v110
	v_mul_f32_e32 v111, 0x4b800000, v110
	s_nop 0
	v_cndmask_b32_e32 v110, v110, v111, vcc
	v_rsq_f32_e32 v110, v110
	s_nop 0
	v_mul_f32_e32 v111, 0x45800000, v110
	v_cndmask_b32_e32 v212, v110, v111, vcc
	ds_read2_b64 v[110:113], v115 offset0:160 offset1:176
	s_waitcnt lgkmcnt(0)
	v_ffbh_u32_e32 v115, v111
	v_min_u32_e32 v115, 32, v115
	v_lshlrev_b64 v[110:111], v115, v[110:111]
	v_min_u32_e32 v110, 1, v110
	v_or_b32_e32 v110, v111, v110
	v_cvt_f32_u32_e32 v110, v110
	v_sub_u32_e32 v111, 32, v115
	v_ldexp_f32 v110, v110, v111
	v_mul_f32_e32 v110, 0x30800000, v110
	v_fmamk_f32 v110, v110, 0x3a000000, v1
	v_cmp_gt_f32_e32 vcc, s65, v110
	v_mul_f32_e32 v111, 0x4b800000, v110
	s_nop 0
	v_cndmask_b32_e32 v110, v110, v111, vcc
	v_rsq_f32_e32 v110, v110
	s_nop 0
	v_mul_f32_e32 v111, 0x45800000, v110
	v_cndmask_b32_e32 v210, v110, v111, vcc
	v_ffbh_u32_e32 v110, v113
	v_min_u32_e32 v115, 32, v110
	v_lshlrev_b64 v[110:111], v115, v[112:113]
	v_min_u32_e32 v110, 1, v110
	v_or_b32_e32 v110, v111, v110
	v_cvt_f32_u32_e32 v110, v110
	v_sub_u32_e32 v111, 32, v115
	v_ldexp_f32 v110, v110, v111
	v_mul_f32_e32 v110, 0x30800000, v110
	v_fmamk_f32 v110, v110, 0x3a000000, v1
	v_cmp_gt_f32_e32 vcc, s65, v110
	v_mul_f32_e32 v111, 0x4b800000, v110
	s_nop 0
	v_cndmask_b32_e32 v110, v110, v111, vcc
	v_rsq_f32_e32 v110, v110
	s_nop 0
	v_mul_f32_e32 v111, 0x45800000, v110
	v_cndmask_b32_e32 v208, v110, v111, vcc
	s_cbranch_scc0 .LBB0_1713
	v_cmp_lt_i32_e32 vcc, 13, v209
	v_lshlrev_b32_e32 v211, 2, v242
	s_and_saveexec_b64 s[26:27], vcc
	s_cbranch_execz .LBB0_1693
	v_readlane_b32 s19, v255, 50
	v_pk_mul_f32 v[112:113], v[104:105], v[216:217] op_sel_hi:[1,0]
	v_pk_mul_f32 v[110:111], v[102:103], v[216:217] op_sel_hi:[1,0]
	v_add_lshl_u32 v114, s19, v209, 9
	s_add_i32 s19, 0, 0x20000
	v_add3_u32 v115, s19, v114, v211
	ds_write_b128 v115, v[110:113]
	v_pk_mul_f32 v[112:113], v[40:41], v[216:217] op_sel_hi:[1,0]
	v_pk_mul_f32 v[110:111], v[38:39], v[216:217] op_sel_hi:[1,0]
	v_readlane_b32 s19, v255, 34
	ds_write_b128 v115, v[110:113] offset:16
	v_pk_mul_f32 v[112:113], v[72:73], v[208:209] op_sel_hi:[1,0]
	v_pk_mul_f32 v[110:111], v[70:71], v[208:209] op_sel_hi:[1,0]
	v_add3_u32 v114, s19, v114, v211
	ds_write_b128 v114, v[110:113]
	v_pk_mul_f32 v[112:113], v[8:9], v[208:209] op_sel_hi:[1,0]
	v_pk_mul_f32 v[110:111], v[6:7], v[208:209] op_sel_hi:[1,0]
	ds_write_b128 v115, v[110:113] offset:2064

.LBB0_1750:
	s_andn2_b64 vcc, exec, s[56:57]
	s_cbranch_vccnz .LBB0_1676
	s_branch .LBB0_1676

.LBB0_1753:
	s_load_dwordx2 s[26:27], s[24:25], 0x118
	v_sub_co_u32_e64 v150, s[2:3], s15, 1
	s_andn2_b64 vcc, exec, s[2:3]
	s_cbranch_vccnz .LBB0_1858
	s_add_i32 s6, s28, s33
	v_readlane_b32 s2, v255, 19
	s_sub_i32 s2, s6, s2
	s_ashr_i32 s3, s2, 31
	s_abs_i32 s2, s2
	v_readlane_b32 s7, v255, 20
	s_mul_hi_u32 s7, s2, s7
	v_readlane_b32 s8, v255, 21
	s_mul_i32 s7, s7, s8
	s_sub_i32 s2, s2, s7
	s_sub_i32 s7, s2, s8
	s_cmp_ge_u32 s2, s8
	s_cselect_b32 s2, s7, s2
	s_sub_i32 s7, s2, s8
	s_cmp_ge_u32 s2, s8
	s_cselect_b32 s2, s7, s2
	s_xor_b32 s2, s2, s3
	v_mov_b32_e32 v16, v0
	s_sub_i32 s7, s2, s3
	s_cmp_gt_i32 s7, 47
	v_readfirstlane_b32 s34, v16
	s_cbranch_scc1 .LBB0_1768
	v_lshlrev_b32_e32 v2, 4, v16
	s_waitcnt lgkmcnt(0)
	v_add_u32_e32 v3, 0x2000, v2
	v_ashrrev_i32_e32 v4, 31, v3
	v_lshrrev_b32_e32 v4, 22, v4
	v_add_u32_e32 v4, v3, v4
	v_ashrrev_i32_e32 v10, 10, v4
	v_mul_i32_i24_e32 v5, 0x400, v10
	v_sub_u32_e32 v3, v3, v5
	v_lshrrev_b32_e32 v5, 4, v3
	v_bitop3_b32 v3, v5, v3, 32 bitop3:0x6c
	v_ashrrev_i32_e32 v5, 31, v3
	v_lshrrev_b32_e32 v5, 26, v5
	v_add_u32_e32 v5, v3, v5
	v_ashrrev_i32_e32 v11, 6, v5
	v_and_b32_e32 v5, 0xc0, v5
	v_sub_u32_e32 v3, v3, v5
	v_lshlrev_b32_e32 v4, 5, v10
	v_ashrrev_i16_sdwa v3, v224, sext(v3) dst_sel:DWORD dst_unused:UNUSED_PAD src0_sel:DWORD src1_sel:BYTE_0
	v_and_b32_e32 v4, 32, v4
	v_bfe_i32 v12, v3, 0, 16
	v_add_u32_e32 v3, v4, v12
	v_lshlrev_b32_e32 v4, 3, v10
	v_and_b32_e32 v4, 0xffff0, v4
	v_add_lshl_u32 v4, v11, v4, 12
	v_lshl_add_u32 v130, v3, 1, v4
	v_bfe_i32 v4, v16, 27, 1
	v_lshrrev_b32_e32 v4, 22, v4
	v_add_u32_e32 v4, v2, v4
	v_and_b32_e32 v4, 0xfffffc00, v4
	v_sub_u32_e32 v2, v2, v4
	v_lshrrev_b32_e32 v4, 4, v2
	v_bitop3_b32 v2, v4, v2, 32 bitop3:0x6c
	v_ashrrev_i32_e32 v4, 31, v2
	s_add_u32 s8, s26, 0x1ff00000
	v_ashrrev_i32_e32 v3, 31, v16
	v_lshrrev_b32_e32 v4, 26, v4
	s_addc_u32 s9, s27, 0
	v_lshrrev_b32_e32 v3, 26, v3
	v_add_u32_e32 v4, v2, v4
	s_add_u32 s21, s26, 0x15800000
	v_add_u32_e32 v3, v16, v3
	v_ashrrev_i32_e32 v14, 6, v4
	v_and_b32_e32 v4, 0xc0, v4
	s_addc_u32 s42, s27, 0
	s_add_i32 s2, s7, 16
	v_ashrrev_i32_e32 v13, 6, v3
	v_sub_u32_e32 v2, v2, v4
	s_ashr_i32 s2, s2, 2
	v_lshlrev_b32_e32 v3, 5, v13
	v_ashrrev_i16_sdwa v2, v224, sext(v2) dst_sel:DWORD dst_unused:UNUSED_PAD src0_sel:DWORD src1_sel:BYTE_0
	s_ashr_i32 s35, s34, 6
	s_and_b32 s44, s7, 3
	v_and_b32_e32 v3, 32, v3
	v_bfe_i32 v15, v2, 0, 16
	s_ashr_i32 s3, s2, 31
	s_ashr_i32 s36, s34, 8
	s_lshl_b32 s43, s35, 10
	v_add_u32_e32 v2, v3, v15
	v_lshlrev_b32_e32 v3, 3, v13
	s_lshl_b32 s18, s44, 20
	s_lshl_b64 s[10:11], s[2:3], 20
	v_and_b32_e32 v3, 0xffff0, v3
	s_add_u32 s10, s21, s10
	v_add_lshl_u32 v3, v14, v3, 12
	s_addc_u32 s11, s42, s11
	s_add_i32 s3, s43, 0
	v_lshl_add_u32 v132, v2, 1, v3
	s_add_i32 m0, s3, 0x10000
	v_mov_b32_e32 v133, v181
	global_load_lds_dwordx4 v132, s[10:11]
	s_add_i32 m0, s3, 0x12000
	s_add_u32 s14, s10, 0x80000
	global_load_lds_dwordx4 v130, s[10:11]
	s_addc_u32 s15, s11, 0
	s_add_i32 m0, s3, 0x14000
	v_mov_b32_e32 v131, v181
	global_load_lds_dwordx4 v132, s[14:15]
	s_add_i32 m0, s3, 0x16000
	s_add_u32 s18, s8, s18
	s_addc_u32 s19, s9, 0
	s_add_i32 s45, s3, 0x2000
	global_load_lds_dwordx4 v130, s[14:15]
	s_mov_b32 m0, s3
	s_add_u32 s14, s18, 0x80000
	global_load_lds_dwordx4 v132, s[18:19]
	s_mov_b32 m0, s45
	s_addc_u32 s15, s19, 0
	s_add_i32 s46, s3, 0x4000
	global_load_lds_dwordx4 v130, s[18:19]
	s_mov_b32 m0, s46
	s_add_i32 s47, s3, 0x6000
	global_load_lds_dwordx4 v132, s[14:15]
	s_mov_b32 m0, s47
	s_cmp_eq_u32 s36, 1
	global_load_lds_dwordx4 v130, s[14:15]
	s_load_dwordx2 s[14:15], s[24:25], 0x110
	v_lshl_add_u64 v[8:9], s[10:11], 0, v[132:133]
	v_lshl_add_u64 v[6:7], s[10:11], 0, v[130:131]
	v_lshl_add_u64 v[2:3], s[18:19], 0, v[132:133]
	s_cselect_b64 s[22:23], -1, 0
	s_cmp_lg_u32 s36, 1
	v_lshl_add_u64 v[4:5], s[18:19], 0, v[130:131]
	s_cbranch_scc1 .LBB0_1757
.LBB0_1757:
	s_add_u32 s28, s26, 0xe0000
	s_addc_u32 s29, s27, 0
	v_bfe_u32 v152, v16, 4, 2
	s_add_u32 s30, s26, 0x20300000
	v_and_b32_e32 v151, 15, v16
	v_lshlrev_b32_e32 v17, 4, v152
	v_lshlrev_b32_e32 v16, 2, v16
	s_addc_u32 s31, s27, 0
	v_lshl_or_b32 v17, v151, 6, v17
	s_lshl_b32 s26, s36, 13
	v_and_b32_e32 v16, 32, v16
	v_bitop3_b32 v18, v17, s26, v16 bitop3:0xde
	s_lshl_b32 s26, s35, 5
	s_and_b32 s49, s26, 0x60
	s_add_i32 m0, s3, 0x18000
	v_lshl_add_u64 v[8:9], v[8:9], 0, s[16:17]
	s_lshl_b32 s48, s36, 6
	s_lshl_b32 s26, s49, 7
	s_waitcnt vmcnt(2)
	s_barrier
	global_load_lds_dwordx4 v[8:9], off
	v_lshl_add_u64 v[6:7], v[6:7], 0, s[16:17]
	s_add_i32 m0, s3, 0x1a000
	s_add_i32 s50, s3, 0x8000
	s_add_i32 s51, s3, 0xa000
	v_bitop3_b32 v153, v17, s26, v16 bitop3:0xde
	global_load_lds_dwordx4 v[6:7], off
	v_lshl_add_u64 v[2:3], v[2:3], 0, s[16:17]
	s_mov_b32 m0, s50
	s_add_u32 s26, s10, 0x80080
	global_load_lds_dwordx4 v[2:3], off
	v_lshl_add_u64 v[2:3], v[4:5], 0, s[16:17]
	s_mov_b32 m0, s51
	s_addc_u32 s27, s11, 0
	global_load_lds_dwordx4 v[2:3], off
	s_add_i32 m0, s3, 0x1c000
	v_lshl_add_u64 v[2:3], s[26:27], 0, v[132:133]
	global_load_lds_dwordx4 v[2:3], off
	v_lshl_add_u64 v[2:3], s[26:27], 0, v[130:131]
	s_add_i32 m0, s3, 0x1e000
	s_cmpk_lt_u32 s34, 0x100
	global_load_lds_dwordx4 v[2:3], off
	v_lshlrev_b32_e32 v2, 15, v13
	v_and_b32_e32 v2, 0xffff0000, v2
	v_lshl_add_u32 v2, v14, 12, v2
	v_and_b32_e32 v3, 1, v13
	v_lshl_or_b32 v2, v3, 6, v2
	v_lshl_add_u32 v134, v15, 1, v2
	v_lshlrev_b32_e32 v2, 15, v10
	v_and_b32_e32 v2, 0xffff0000, v2
	s_waitcnt vmcnt(6)
	v_lshl_add_u32 v2, v11, 12, v2
	v_and_b32_e32 v3, 1, v10
	v_lshl_or_b32 v2, v3, 6, v2
	s_cselect_b64 s[34:35], -1, 0
	v_mov_b32_e32 v135, v181
	v_lshl_add_u32 v136, v12, 1, v2
	v_mov_b32_e32 v137, v181
	s_mov_b32 s54, 0
	v_add_u32_e32 v154, 0, v18
	s_barrier
	s_branch .LBB0_1760

.LBB0_1761:
	s_add_u32 s26, s38, 0xfff80080
	s_addc_u32 s27, s39, -1
	s_add_i32 s64, 0, 0x10000
	s_cmp_eq_u32 s63, 28
	s_cselect_b32 s41, s57, s27
	s_cselect_b32 s40, s58, s26
	v_add_u32_e32 v155, s64, v153
	s_cselect_b32 s27, s59, s62
	s_cselect_b32 s26, s60, s61
	s_add_i32 s68, 0, 0x14000
	ds_read_b128 v[138:141], v155
	ds_read_b128 v[142:145], v155 offset:1024
	ds_read_b128 v[146:149], v155 offset:2048
	ds_read_b128 v[156:159], v155 offset:3072
	v_add_u32_e32 v155, s68, v153
	ds_read_b128 v[160:163], v155
	ds_read_b128 v[164:167], v155 offset:1024
	ds_read_b128 v[168:171], v155 offset:2048
	ds_read_b128 v[172:175], v155 offset:3072
	v_lshl_add_u64 v[220:221], s[38:39], 0, v[134:135]
	s_add_i32 m0, s3, 0xc000
	ds_read_b128 v[176:179], v154
	ds_read_b128 v[192:195], v154 offset:1024
	ds_read_b128 v[196:199], v154 offset:2048
	ds_read_b128 v[200:203], v154 offset:3072
	ds_read_b128 v[204:207], v154 offset:4096
	ds_read_b128 v[208:211], v154 offset:5120
	ds_read_b128 v[212:215], v154 offset:6144
	ds_read_b128 v[216:219], v154 offset:7168
	global_load_lds_dwordx4 v[220:221], off
	v_lshl_add_u64 v[220:221], s[38:39], 0, v[136:137]
	s_add_i32 m0, s3, 0xe000
	s_nop 0
	global_load_lds_dwordx4 v[220:221], off
	s_waitcnt vmcnt(8)
	s_waitcnt lgkmcnt(0)
	s_cmp_eq_u32 s100, 0
	s_cbranch_scc1 .Lmy_h2_57
	s_setprio 1
	s_barrier
.Lmy_h2_57:
	v_mfma_f32_16x16x32_bf16 v[126:129], v[138:141], v[176:179], v[126:129]
	v_mfma_f32_16x16x32_bf16 v[122:125], v[146:149], v[176:179], v[122:125]
	v_mfma_f32_16x16x32_bf16 v[110:113], v[138:141], v[196:199], v[110:113]
	v_mfma_f32_16x16x32_bf16 v[106:109], v[146:149], v[196:199], v[106:109]
	v_mfma_f32_16x16x32_bf16 v[94:97], v[138:141], v[204:207], v[94:97]
	v_mfma_f32_16x16x32_bf16 v[90:93], v[146:149], v[204:207], v[90:93]
	v_mfma_f32_16x16x32_bf16 v[78:81], v[138:141], v[212:215], v[78:81]
	v_mfma_f32_16x16x32_bf16 v[74:77], v[146:149], v[212:215], v[74:77]
	v_mfma_f32_16x16x32_bf16 v[126:129], v[142:145], v[192:195], v[126:129]
	v_mfma_f32_16x16x32_bf16 v[122:125], v[156:159], v[192:195], v[122:125]
	v_mfma_f32_16x16x32_bf16 v[110:113], v[142:145], v[200:203], v[110:113]
	v_mfma_f32_16x16x32_bf16 v[106:109], v[156:159], v[200:203], v[106:109]
	v_mfma_f32_16x16x32_bf16 v[94:97], v[142:145], v[208:211], v[94:97]
	v_mfma_f32_16x16x32_bf16 v[90:93], v[156:159], v[208:211], v[90:93]
	v_mfma_f32_16x16x32_bf16 v[78:81], v[142:145], v[216:219], v[78:81]
	v_mfma_f32_16x16x32_bf16 v[74:77], v[156:159], v[216:219], v[74:77]
	v_mfma_f32_16x16x32_bf16 v[118:121], v[160:163], v[176:179], v[118:121]
	v_mfma_f32_16x16x32_bf16 v[114:117], v[168:171], v[176:179], v[114:117]
	v_mfma_f32_16x16x32_bf16 v[102:105], v[160:163], v[196:199], v[102:105]
	v_mfma_f32_16x16x32_bf16 v[98:101], v[168:171], v[196:199], v[98:101]
	v_mfma_f32_16x16x32_bf16 v[86:89], v[160:163], v[204:207], v[86:89]
	v_mfma_f32_16x16x32_bf16 v[82:85], v[168:171], v[204:207], v[82:85]
	v_mfma_f32_16x16x32_bf16 v[70:73], v[160:163], v[212:215], v[70:73]
	v_mfma_f32_16x16x32_bf16 v[66:69], v[168:171], v[212:215], v[66:69]
	v_mfma_f32_16x16x32_bf16 v[118:121], v[164:167], v[192:195], v[118:121]
	v_mfma_f32_16x16x32_bf16 v[114:117], v[172:175], v[192:195], v[114:117]
	v_mfma_f32_16x16x32_bf16 v[102:105], v[164:167], v[200:203], v[102:105]
	v_mfma_f32_16x16x32_bf16 v[98:101], v[172:175], v[200:203], v[98:101]
	v_mfma_f32_16x16x32_bf16 v[86:89], v[164:167], v[208:211], v[86:89]
	v_mfma_f32_16x16x32_bf16 v[82:85], v[172:175], v[208:211], v[82:85]
	v_mfma_f32_16x16x32_bf16 v[70:73], v[164:167], v[216:219], v[70:73]
	v_mfma_f32_16x16x32_bf16 v[66:69], v[172:175], v[216:219], v[66:69]
	s_cmp_lg_u32 s100, 0
	s_cbranch_scc1 .Lmy_h2_58
	s_barrier
.Lmy_h2_58:
	s_setprio 0
	s_add_i32 s64, s64, s43
	v_lshl_add_u64 v[220:221], s[26:27], 0, v[132:133]
	s_mov_b32 m0, s64
	ds_read_b128 v[176:179], v154 offset:16384
	ds_read_b128 v[192:195], v154 offset:17408
	ds_read_b128 v[196:199], v154 offset:18432
	ds_read_b128 v[200:203], v154 offset:19456
	ds_read_b128 v[204:207], v154 offset:20480
	ds_read_b128 v[208:211], v154 offset:21504
	ds_read_b128 v[212:215], v154 offset:22528
	ds_read_b128 v[216:219], v154 offset:23552
	global_load_lds_dwordx4 v[220:221], off
	s_add_i32 m0, s64, 0x2000
	s_add_u32 s66, s26, 0x80000
	v_lshl_add_u64 v[222:223], s[26:27], 0, v[130:131]
	s_addc_u32 s67, s27, 0
	s_add_i32 s64, s68, s43
	global_load_lds_dwordx4 v[222:223], off
	v_lshl_add_u64 v[238:239], s[66:67], 0, v[132:133]
	s_mov_b32 m0, s64
	v_lshl_add_u64 v[240:241], s[40:41], 0, v[130:131]
	global_load_lds_dwordx4 v[238:239], off
	v_lshl_add_u64 v[238:239], s[66:67], 0, v[130:131]
	s_add_i32 m0, s64, 0x2000
	s_nop 0
	global_load_lds_dwordx4 v[238:239], off
	v_lshl_add_u64 v[238:239], s[40:41], 0, v[132:133]
	s_mov_b32 m0, s3
	s_nop 0
	global_load_lds_dwordx4 v[238:239], off
	s_mov_b32 m0, s45
	s_nop 0
	global_load_lds_dwordx4 v[240:241], off
	s_waitcnt vmcnt(8)
	s_waitcnt lgkmcnt(0)
	s_cmp_eq_u32 s100, 0
	s_cbranch_scc1 .Lmy_h2_59
	s_setprio 1
	s_barrier
.Lmy_h2_59:
	v_mfma_f32_16x16x32_bf16 v[62:65], v[138:141], v[176:179], v[62:65]
	v_mfma_f32_16x16x32_bf16 v[58:61], v[146:149], v[176:179], v[58:61]
	v_mfma_f32_16x16x32_bf16 v[46:49], v[138:141], v[196:199], v[46:49]
	v_mfma_f32_16x16x32_bf16 v[42:45], v[146:149], v[196:199], v[42:45]
	v_mfma_f32_16x16x32_bf16 v[30:33], v[138:141], v[204:207], v[30:33]
	v_mfma_f32_16x16x32_bf16 v[26:29], v[146:149], v[204:207], v[26:29]
	v_mfma_f32_16x16x32_bf16 v[14:17], v[138:141], v[212:215], v[14:17]
	v_mfma_f32_16x16x32_bf16 v[10:13], v[146:149], v[212:215], v[10:13]
	v_mfma_f32_16x16x32_bf16 v[62:65], v[142:145], v[192:195], v[62:65]
	v_mfma_f32_16x16x32_bf16 v[58:61], v[156:159], v[192:195], v[58:61]
	v_mfma_f32_16x16x32_bf16 v[46:49], v[142:145], v[200:203], v[46:49]
	v_mfma_f32_16x16x32_bf16 v[42:45], v[156:159], v[200:203], v[42:45]
	v_mfma_f32_16x16x32_bf16 v[30:33], v[142:145], v[208:211], v[30:33]
	v_mfma_f32_16x16x32_bf16 v[26:29], v[156:159], v[208:211], v[26:29]
	v_mfma_f32_16x16x32_bf16 v[14:17], v[142:145], v[216:219], v[14:17]
	v_mfma_f32_16x16x32_bf16 v[10:13], v[156:159], v[216:219], v[10:13]
	v_mfma_f32_16x16x32_bf16 v[54:57], v[160:163], v[176:179], v[54:57]
	v_mfma_f32_16x16x32_bf16 v[50:53], v[168:171], v[176:179], v[50:53]
	v_mfma_f32_16x16x32_bf16 v[38:41], v[160:163], v[196:199], v[38:41]
	v_mfma_f32_16x16x32_bf16 v[34:37], v[168:171], v[196:199], v[34:37]
	v_mfma_f32_16x16x32_bf16 v[22:25], v[160:163], v[204:207], v[22:25]
	v_mfma_f32_16x16x32_bf16 v[18:21], v[168:171], v[204:207], v[18:21]
	v_mfma_f32_16x16x32_bf16 v[6:9], v[160:163], v[212:215], v[6:9]
	v_mfma_f32_16x16x32_bf16 v[2:5], v[168:171], v[212:215], v[2:5]
	v_mfma_f32_16x16x32_bf16 v[54:57], v[164:167], v[192:195], v[54:57]
	v_mfma_f32_16x16x32_bf16 v[50:53], v[172:175], v[192:195], v[50:53]
	v_mfma_f32_16x16x32_bf16 v[38:41], v[164:167], v[200:203], v[38:41]
	v_mfma_f32_16x16x32_bf16 v[34:37], v[172:175], v[200:203], v[34:37]
	v_mfma_f32_16x16x32_bf16 v[22:25], v[164:167], v[208:211], v[22:25]
	v_mfma_f32_16x16x32_bf16 v[18:21], v[172:175], v[208:211], v[18:21]
	v_mfma_f32_16x16x32_bf16 v[6:9], v[164:167], v[216:219], v[6:9]
	v_mfma_f32_16x16x32_bf16 v[2:5], v[172:175], v[216:219], v[2:5]
	s_cmp_lg_u32 s100, 0
	s_cbranch_scc1 .Lmy_h2_60
	s_barrier
.Lmy_h2_60:
	s_setprio 0
	s_add_i32 s64, 0, 0x18000
	v_add_u32_e32 v155, s64, v153
	s_add_i32 s66, 0, 0x1c000
	ds_read_b128 v[138:141], v155
	ds_read_b128 v[142:145], v155 offset:1024
	ds_read_b128 v[146:149], v155 offset:2048
	ds_read_b128 v[156:159], v155 offset:3072
	v_add_u32_e32 v155, s66, v153
	ds_read_b128 v[160:163], v155
	ds_read_b128 v[164:167], v155 offset:1024
	ds_read_b128 v[168:171], v155 offset:2048
	ds_read_b128 v[172:175], v155 offset:3072
	s_add_u32 s40, s40, 0x80000
	s_addc_u32 s41, s41, 0
	s_mov_b32 m0, s46
	v_lshl_add_u64 v[242:243], s[40:41], 0, v[132:133]
	ds_read_b128 v[176:179], v154 offset:32768
	ds_read_b128 v[192:195], v154 offset:33792
	ds_read_b128 v[196:199], v154 offset:34816
	ds_read_b128 v[200:203], v154 offset:35840
	ds_read_b128 v[204:207], v154 offset:36864
	ds_read_b128 v[208:211], v154 offset:37888
	ds_read_b128 v[212:215], v154 offset:38912
	ds_read_b128 v[216:219], v154 offset:39936
	global_load_lds_dwordx4 v[242:243], off
	v_lshl_add_u64 v[242:243], s[40:41], 0, v[130:131]
	s_mov_b32 m0, s47
	s_nop 0
	global_load_lds_dwordx4 v[242:243], off
	s_waitcnt vmcnt(8)
	s_waitcnt lgkmcnt(0)
	s_cmp_eq_u32 s100, 0
	s_cbranch_scc1 .Lmy_h2_61
	s_setprio 1
	s_barrier

.Lmy_h2_62:
	s_setprio 0
	s_add_i32 s40, s64, s43
	v_lshl_add_u64 v[220:221], v[220:221], 0, s[16:17]
	s_mov_b32 m0, s40
	ds_read_b128 v[176:179], v154 offset:49152
	ds_read_b128 v[192:195], v154 offset:50176
	ds_read_b128 v[196:199], v154 offset:51200
	ds_read_b128 v[200:203], v154 offset:52224
	ds_read_b128 v[204:207], v154 offset:53248
	ds_read_b128 v[208:211], v154 offset:54272
	ds_read_b128 v[212:215], v154 offset:55296
	ds_read_b128 v[216:219], v154 offset:56320
	global_load_lds_dwordx4 v[220:221], off
	s_add_i32 m0, s40, 0x2000
	s_add_u32 s26, s26, 0x80080
	v_lshl_add_u64 v[220:221], v[222:223], 0, s[16:17]
	s_addc_u32 s27, s27, 0
	s_add_i32 s40, s66, s43
	global_load_lds_dwordx4 v[220:221], off
	v_lshl_add_u64 v[220:221], s[26:27], 0, v[132:133]
	s_mov_b32 m0, s40
	s_nop 0
	global_load_lds_dwordx4 v[220:221], off
	v_lshl_add_u64 v[220:221], s[26:27], 0, v[130:131]
	s_add_i32 m0, s40, 0x2000
	s_nop 0
	global_load_lds_dwordx4 v[220:221], off
	v_lshl_add_u64 v[220:221], v[238:239], 0, s[16:17]
	s_mov_b32 m0, s50
	s_nop 0
	global_load_lds_dwordx4 v[220:221], off
	v_lshl_add_u64 v[220:221], v[240:241], 0, s[16:17]
	s_mov_b32 m0, s51
	s_nop 0
	global_load_lds_dwordx4 v[220:221], off
	s_waitcnt vmcnt(8)
	s_waitcnt lgkmcnt(0)
	s_cmp_eq_u32 s100, 0
	s_cbranch_scc1 .Lmy_h2_63
	s_setprio 1
	s_barrier

.Lmy_h2_64:
	s_setprio 0
	s_add_i32 s63, s63, 2
	s_add_u32 s38, s38, 0x100
	s_addc_u32 s39, s39, 0
	s_add_u32 s61, s61, 0x100
	s_addc_u32 s62, s62, 0
	s_cmp_gt_u32 s63, 29
	s_cbranch_scc0 .LBB0_1761
	s_and_b64 vcc, exec, s[34:35]
	s_cbranch_vccz .LBB0_1764
.LBB0_1764:
	v_mov_b32_e32 v138, v151
	v_mov_b32_e32 v139, v152
	s_lshl_b32 s26, s56, 8
	s_lshl_b32 s27, s55, 8
	s_add_i32 s26, s26, s48
	v_add_u32_e32 v138, s26, v138
	s_or_b32 s26, s27, s49
	v_lshl_add_u32 v147, v139, 2, s26
	v_ashrrev_i32_e32 v139, 31, v138
	v_lshl_add_u64 v[140:141], v[138:139], 3, s[28:29]
	global_load_dwordx2 v[142:143], v[140:141], off
	v_and_b32_e32 v155, 0x3fc, v147
	s_movk_i32 s26, 0x200
	v_and_b32_e32 v156, 0x1fc, v147
	v_add_u32_e32 v158, 16, v147
	v_and_b32_e32 v159, 0x3fc, v158
	v_add_u32_e32 v162, 0x80, v147
	v_and_b32_e32 v163, 0x3fc, v162
	s_mov_b64 s[38:39], -1
	s_mov_b32 s68, 0x2f800000
	s_mov_b32 s64, 0x3f22f983
	s_mov_b32 s66, 0xbfc90fda
	s_waitcnt vmcnt(0)
	v_ffbh_u32_e32 v139, v143
	v_min_u32_e32 v139, 32, v139
	v_lshlrev_b64 v[142:143], v139, v[142:143]
	v_min_u32_e32 v142, 1, v142
	v_or_b32_e32 v142, v143, v142
	v_cvt_f32_u32_e32 v142, v142
	v_sub_u32_e32 v139, 32, v139
	v_ldexp_f32 v139, v142, v139
	v_mul_f32_e32 v139, 0x30800000, v139
	v_fmamk_f32 v139, v139, 0x3a000000, v1
	v_cmp_gt_f32_e32 vcc, s65, v139
	v_mul_f32_e32 v142, 0x4b800000, v139
	s_nop 0
	v_cndmask_b32_e32 v139, v139, v142, vcc
	v_rsq_f32_e32 v139, v139
	s_nop 0
	v_mul_f32_e32 v142, 0x45800000, v139
	v_cndmask_b32_e32 v146, v139, v142, vcc
	v_and_b32_e32 v139, 0xfffffc00, v147
	v_pk_mul_f32 v[144:145], v[128:129], v[146:147] op_sel_hi:[1,0]
	v_cmp_gt_u32_e32 vcc, s26, v155
	v_add_u32_e32 v128, v139, v138
	v_ashrrev_i32_e32 v129, 31, v128
	v_cndmask_b32_e32 v180, v230, v231, vcc
	v_pk_mul_f32 v[142:143], v[126:127], v[146:147] op_sel_hi:[1,0]
	v_lshl_add_u64 v[126:127], s[14:15], 0, v[180:181]
	v_lshlrev_b64 v[128:129], 11, v[128:129]
	v_lshl_add_u64 v[148:149], v[126:127], 0, v[128:129]
	v_lshlrev_b32_e32 v180, 2, v156
	v_lshl_add_u64 v[148:149], v[148:149], 0, v[180:181]
	global_store_dwordx4 v[148:149], v[142:145], off
	v_cmp_gt_u32_e32 vcc, s26, v159
	v_pk_mul_f32 v[160:161], v[120:121], v[146:147] op_sel_hi:[1,0]
	v_cvt_pk_bf16_f32 v142, v142, v143
	v_cvt_pk_bf16_f32 v143, v144, v145
	v_lshl_add_u64 v[144:145], s[30:31], 0, v[128:129]
	v_lshlrev_b32_e32 v128, 1, v155
	v_mov_b32_e32 v129, v181
	v_lshl_add_u64 v[144:145], v[144:145], 0, v[128:129]
	v_and_b32_e32 v155, 0xfffffc00, v158
	global_store_dwordx2 v[144:145], v[142:143], off
	v_pk_mul_f32 v[144:145], v[124:125], v[146:147] op_sel_hi:[1,0]
	v_add_u32_e32 v124, v155, v138
	v_pk_mul_f32 v[142:143], v[122:123], v[146:147] op_sel_hi:[1,0]
	v_cndmask_b32_e32 v122, v230, v231, vcc
	v_mov_b32_e32 v123, v181
	v_ashrrev_i32_e32 v125, 31, v124
	v_lshl_add_u64 v[122:123], s[14:15], 0, v[122:123]
	v_lshlrev_b64 v[148:149], 11, v[124:125]
	v_and_b32_e32 v124, 0x1fc, v158
	v_lshl_add_u64 v[156:157], v[122:123], 0, v[148:149]
	v_lshlrev_b32_e32 v124, 2, v124
	v_mov_b32_e32 v125, v181
	v_lshl_add_u64 v[156:157], v[156:157], 0, v[124:125]
	global_store_dwordx4 v[156:157], v[142:145], off
	v_cvt_pk_bf16_f32 v156, v142, v143
	v_cvt_pk_bf16_f32 v157, v144, v145
	v_cmp_gt_u32_e32 vcc, s26, v163
	v_pk_mul_f32 v[116:117], v[116:117], v[146:147] op_sel_hi:[1,0]
	v_lshl_add_u64 v[144:145], s[30:31], 0, v[148:149]
	v_lshlrev_b32_e32 v142, 1, v159
	v_mov_b32_e32 v143, v181
	v_lshl_add_u64 v[144:145], v[144:145], 0, v[142:143]
	global_store_dwordx2 v[144:145], v[156:157], off
	v_and_b32_e32 v156, 0xfffffc00, v162
	v_add_u32_e32 v120, v156, v138
	v_pk_mul_f32 v[158:159], v[118:119], v[146:147] op_sel_hi:[1,0]
	v_cndmask_b32_e32 v118, v230, v231, vcc
	v_mov_b32_e32 v119, v181
	v_ashrrev_i32_e32 v121, 31, v120
	v_lshl_add_u64 v[118:119], s[14:15], 0, v[118:119]
	v_lshlrev_b64 v[144:145], 11, v[120:121]
	v_and_b32_e32 v120, 0x1fc, v162
	v_lshl_add_u64 v[148:149], v[118:119], 0, v[144:145]
	v_lshlrev_b32_e32 v120, 2, v120
	v_mov_b32_e32 v121, v181
	v_lshl_add_u64 v[148:149], v[148:149], 0, v[120:121]
	global_store_dwordx4 v[148:149], v[158:161], off
	v_cvt_pk_bf16_f32 v148, v158, v159
	v_add_u32_e32 v162, 0x90, v147
	v_and_b32_e32 v157, 0xfffffc00, v162
	v_lshl_add_u64 v[158:159], s[30:31], 0, v[144:145]
	v_lshlrev_b32_e32 v144, 1, v163
	v_mov_b32_e32 v145, v181
	v_lshl_add_u64 v[158:159], v[158:159], 0, v[144:145]
	v_and_b32_e32 v163, 0x3fc, v162
	v_cvt_pk_bf16_f32 v149, v160, v161
	global_store_dwordx2 v[158:159], v[148:149], off
	v_cmp_gt_u32_e32 vcc, s26, v163
	v_add_u32_e32 v148, v157, v138
	v_pk_mul_f32 v[114:115], v[114:115], v[146:147] op_sel_hi:[1,0]
	v_cndmask_b32_e32 v146, v230, v231, vcc
	v_mov_b32_e32 v147, v181
	v_ashrrev_i32_e32 v149, 31, v148
	v_lshl_add_u64 v[146:147], s[14:15], 0, v[146:147]
	v_lshlrev_b64 v[158:159], 11, v[148:149]
	v_and_b32_e32 v148, 0x1fc, v162
	v_lshl_add_u64 v[160:161], v[146:147], 0, v[158:159]
	v_lshlrev_b32_e32 v148, 2, v148
	v_mov_b32_e32 v149, v181
	v_lshl_add_u64 v[160:161], v[160:161], 0, v[148:149]
	global_store_dwordx4 v[160:161], v[114:117], off
	v_cvt_pk_bf16_f32 v160, v114, v115
	v_cvt_pk_bf16_f32 v161, v116, v117
	v_add_u32_e32 v162, 16, v138
	s_nop 0
	v_lshl_add_u64 v[116:117], s[30:31], 0, v[158:159]
	v_lshlrev_b32_e32 v114, 1, v163
	v_mov_b32_e32 v115, v181
	v_lshl_add_u64 v[116:117], v[116:117], 0, v[114:115]
	global_store_dwordx2 v[116:117], v[160:161], off
	global_load_dwordx2 v[116:117], v[140:141], off offset:128
	s_waitcnt vmcnt(0)
	v_ffbh_u32_e32 v158, v117
	v_min_u32_e32 v158, 32, v158
	v_lshlrev_b64 v[116:117], v158, v[116:117]
	v_min_u32_e32 v116, 1, v116
	v_or_b32_e32 v116, v117, v116
	v_cvt_f32_u32_e32 v116, v116
	v_sub_u32_e32 v117, 32, v158
	v_add_u32_e32 v158, v139, v162
	v_ashrrev_i32_e32 v159, 31, v158
	v_ldexp_f32 v116, v116, v117
	v_mul_f32_e32 v116, 0x30800000, v116
	v_fmamk_f32 v116, v116, 0x3a000000, v1
	v_cmp_gt_f32_e32 vcc, s65, v116
	v_mul_f32_e32 v117, 0x4b800000, v116
	v_lshlrev_b64 v[158:159], 11, v[158:159]
	v_cndmask_b32_e32 v116, v116, v117, vcc
	v_rsq_f32_e32 v116, v116
	v_lshl_add_u64 v[160:161], v[126:127], 0, v[158:159]
	v_lshl_add_u64 v[160:161], v[160:161], 0, v[180:181]
	v_mul_f32_e32 v117, 0x45800000, v116
	v_cndmask_b32_e32 v116, v116, v117, vcc
	v_pk_mul_f32 v[112:113], v[112:113], v[116:117] op_sel_hi:[1,0]
	v_pk_mul_f32 v[110:111], v[110:111], v[116:117] op_sel_hi:[1,0]
	global_store_dwordx4 v[160:161], v[110:113], off
	v_pk_mul_f32 v[108:109], v[108:109], v[116:117] op_sel_hi:[1,0]
	v_pk_mul_f32 v[106:107], v[106:107], v[116:117] op_sel_hi:[1,0]
	v_cvt_pk_bf16_f32 v110, v110, v111
	v_cvt_pk_bf16_f32 v111, v112, v113
	v_lshl_add_u64 v[112:113], s[30:31], 0, v[158:159]
	v_lshl_add_u64 v[112:113], v[112:113], 0, v[128:129]
	global_store_dwordx2 v[112:113], v[110:111], off
	v_add_u32_e32 v110, v155, v162
	v_ashrrev_i32_e32 v111, 31, v110
	v_lshlrev_b64 v[110:111], 11, v[110:111]
	v_lshl_add_u64 v[112:113], v[122:123], 0, v[110:111]
	v_lshl_add_u64 v[112:113], v[112:113], 0, v[124:125]
	global_store_dwordx4 v[112:113], v[106:109], off
	v_pk_mul_f32 v[104:105], v[104:105], v[116:117] op_sel_hi:[1,0]
	v_pk_mul_f32 v[102:103], v[102:103], v[116:117] op_sel_hi:[1,0]
	v_cvt_pk_bf16_f32 v106, v106, v107
	v_cvt_pk_bf16_f32 v107, v108, v109
	v_lshl_add_u64 v[108:109], s[30:31], 0, v[110:111]
	v_lshl_add_u64 v[108:109], v[108:109], 0, v[142:143]
	global_store_dwordx2 v[108:109], v[106:107], off
	v_add_u32_e32 v106, v156, v162
	v_ashrrev_i32_e32 v107, 31, v106
	v_lshlrev_b64 v[106:107], 11, v[106:107]
	v_lshl_add_u64 v[108:109], v[118:119], 0, v[106:107]
	v_lshl_add_u64 v[108:109], v[108:109], 0, v[120:121]
	global_store_dwordx4 v[108:109], v[102:105], off
	v_pk_mul_f32 v[100:101], v[100:101], v[116:117] op_sel_hi:[1,0]
	v_pk_mul_f32 v[98:99], v[98:99], v[116:117] op_sel_hi:[1,0]
	v_cvt_pk_bf16_f32 v102, v102, v103
	v_cvt_pk_bf16_f32 v103, v104, v105
	v_lshl_add_u64 v[104:105], s[30:31], 0, v[106:107]
	v_lshl_add_u64 v[104:105], v[104:105], 0, v[144:145]
	global_store_dwordx2 v[104:105], v[102:103], off
	v_add_u32_e32 v102, v157, v162
	v_ashrrev_i32_e32 v103, 31, v102
	v_lshlrev_b64 v[102:103], 11, v[102:103]
	v_lshl_add_u64 v[104:105], v[146:147], 0, v[102:103]
	v_lshl_add_u64 v[104:105], v[104:105], 0, v[148:149]
	global_store_dwordx4 v[104:105], v[98:101], off
	v_add_u32_e32 v104, 32, v138
	s_nop 0
	v_cvt_pk_bf16_f32 v98, v98, v99
	v_cvt_pk_bf16_f32 v99, v100, v101
	v_lshl_add_u64 v[100:101], s[30:31], 0, v[102:103]
	v_lshl_add_u64 v[100:101], v[100:101], 0, v[114:115]
	global_store_dwordx2 v[100:101], v[98:99], off
	global_load_dwordx2 v[98:99], v[140:141], off offset:256
	s_waitcnt vmcnt(0)
	v_ffbh_u32_e32 v100, v99
	v_min_u32_e32 v100, 32, v100
	v_lshlrev_b64 v[98:99], v100, v[98:99]
	v_min_u32_e32 v98, 1, v98
	v_or_b32_e32 v98, v99, v98
	v_cvt_f32_u32_e32 v98, v98
	v_sub_u32_e32 v99, 32, v100
	v_add_u32_e32 v100, v139, v104
	v_ashrrev_i32_e32 v101, 31, v100
	v_ldexp_f32 v98, v98, v99
	v_mul_f32_e32 v98, 0x30800000, v98
	v_fmamk_f32 v98, v98, 0x3a000000, v1
	v_cmp_gt_f32_e32 vcc, s65, v98
	v_mul_f32_e32 v99, 0x4b800000, v98
	v_lshlrev_b64 v[100:101], 11, v[100:101]
	v_cndmask_b32_e32 v98, v98, v99, vcc
	v_rsq_f32_e32 v98, v98
	v_lshl_add_u64 v[102:103], v[126:127], 0, v[100:101]
	v_lshl_add_u64 v[102:103], v[102:103], 0, v[180:181]
	v_mul_f32_e32 v99, 0x45800000, v98
	v_cndmask_b32_e32 v98, v98, v99, vcc
	v_pk_mul_f32 v[96:97], v[96:97], v[98:99] op_sel_hi:[1,0]
	v_pk_mul_f32 v[94:95], v[94:95], v[98:99] op_sel_hi:[1,0]
	global_store_dwordx4 v[102:103], v[94:97], off
	v_pk_mul_f32 v[92:93], v[92:93], v[98:99] op_sel_hi:[1,0]
	v_pk_mul_f32 v[90:91], v[90:91], v[98:99] op_sel_hi:[1,0]
	v_cvt_pk_bf16_f32 v94, v94, v95
	v_cvt_pk_bf16_f32 v95, v96, v97
	v_lshl_add_u64 v[96:97], s[30:31], 0, v[100:101]
	v_lshl_add_u64 v[96:97], v[96:97], 0, v[128:129]
	global_store_dwordx2 v[96:97], v[94:95], off
	v_add_u32_e32 v94, v155, v104
	v_ashrrev_i32_e32 v95, 31, v94
	v_lshlrev_b64 v[94:95], 11, v[94:95]
	v_lshl_add_u64 v[96:97], v[122:123], 0, v[94:95]
	v_lshl_add_u64 v[96:97], v[96:97], 0, v[124:125]
	global_store_dwordx4 v[96:97], v[90:93], off
	v_pk_mul_f32 v[88:89], v[88:89], v[98:99] op_sel_hi:[1,0]
	v_pk_mul_f32 v[86:87], v[86:87], v[98:99] op_sel_hi:[1,0]
	v_cvt_pk_bf16_f32 v90, v90, v91
	v_cvt_pk_bf16_f32 v91, v92, v93
	v_lshl_add_u64 v[92:93], s[30:31], 0, v[94:95]
	v_lshl_add_u64 v[92:93], v[92:93], 0, v[142:143]
	global_store_dwordx2 v[92:93], v[90:91], off
	v_add_u32_e32 v90, v156, v104
	v_ashrrev_i32_e32 v91, 31, v90
	v_lshlrev_b64 v[90:91], 11, v[90:91]
	v_lshl_add_u64 v[92:93], v[118:119], 0, v[90:91]
	v_lshl_add_u64 v[92:93], v[92:93], 0, v[120:121]
	global_store_dwordx4 v[92:93], v[86:89], off
	v_pk_mul_f32 v[84:85], v[84:85], v[98:99] op_sel_hi:[1,0]
	v_pk_mul_f32 v[82:83], v[82:83], v[98:99] op_sel_hi:[1,0]
	v_cvt_pk_bf16_f32 v86, v86, v87
	v_cvt_pk_bf16_f32 v87, v88, v89
	v_lshl_add_u64 v[88:89], s[30:31], 0, v[90:91]
	v_lshl_add_u64 v[88:89], v[88:89], 0, v[144:145]
	global_store_dwordx2 v[88:89], v[86:87], off
	v_add_u32_e32 v86, v157, v104
	v_ashrrev_i32_e32 v87, 31, v86
	v_lshlrev_b64 v[86:87], 11, v[86:87]
	v_lshl_add_u64 v[88:89], v[146:147], 0, v[86:87]
	v_lshl_add_u64 v[88:89], v[88:89], 0, v[148:149]
	global_store_dwordx4 v[88:89], v[82:85], off
	v_add_u32_e32 v88, 48, v138
	s_nop 0
	v_cvt_pk_bf16_f32 v82, v82, v83
	v_cvt_pk_bf16_f32 v83, v84, v85
	v_lshl_add_u64 v[84:85], s[30:31], 0, v[86:87]
	v_lshl_add_u64 v[84:85], v[84:85], 0, v[114:115]
	global_store_dwordx2 v[84:85], v[82:83], off
	global_load_dwordx2 v[82:83], v[140:141], off offset:384
	s_waitcnt vmcnt(0)
	v_ffbh_u32_e32 v84, v83
	v_min_u32_e32 v84, 32, v84
	v_lshlrev_b64 v[82:83], v84, v[82:83]
	v_min_u32_e32 v82, 1, v82
	v_or_b32_e32 v82, v83, v82
	v_cvt_f32_u32_e32 v82, v82
	v_sub_u32_e32 v83, 32, v84
	v_add_u32_e32 v84, v139, v88
	v_ashrrev_i32_e32 v85, 31, v84
	v_ldexp_f32 v82, v82, v83
	v_mul_f32_e32 v82, 0x30800000, v82
	v_fmamk_f32 v82, v82, 0x3a000000, v1
	v_cmp_gt_f32_e32 vcc, s65, v82
	v_mul_f32_e32 v83, 0x4b800000, v82
	v_lshlrev_b64 v[84:85], 11, v[84:85]
	v_cndmask_b32_e32 v82, v82, v83, vcc
	v_rsq_f32_e32 v82, v82
	v_lshl_add_u64 v[86:87], v[126:127], 0, v[84:85]
	v_lshl_add_u64 v[86:87], v[86:87], 0, v[180:181]
	v_mul_f32_e32 v83, 0x45800000, v82
	v_cndmask_b32_e32 v82, v82, v83, vcc
	v_pk_mul_f32 v[80:81], v[80:81], v[82:83] op_sel_hi:[1,0]
	v_pk_mul_f32 v[78:79], v[78:79], v[82:83] op_sel_hi:[1,0]
	global_store_dwordx4 v[86:87], v[78:81], off
	v_pk_mul_f32 v[76:77], v[76:77], v[82:83] op_sel_hi:[1,0]
	v_pk_mul_f32 v[74:75], v[74:75], v[82:83] op_sel_hi:[1,0]
	v_cvt_pk_bf16_f32 v78, v78, v79
	v_cvt_pk_bf16_f32 v79, v80, v81
	v_lshl_add_u64 v[80:81], s[30:31], 0, v[84:85]
	v_lshl_add_u64 v[80:81], v[80:81], 0, v[128:129]
	global_store_dwordx2 v[80:81], v[78:79], off
	v_add_u32_e32 v78, v155, v88
	v_ashrrev_i32_e32 v79, 31, v78
	v_lshlrev_b64 v[78:79], 11, v[78:79]
	v_lshl_add_u64 v[80:81], v[122:123], 0, v[78:79]
	v_lshl_add_u64 v[80:81], v[80:81], 0, v[124:125]
	global_store_dwordx4 v[80:81], v[74:77], off
	v_pk_mul_f32 v[72:73], v[72:73], v[82:83] op_sel_hi:[1,0]
	v_pk_mul_f32 v[70:71], v[70:71], v[82:83] op_sel_hi:[1,0]
	v_cvt_pk_bf16_f32 v74, v74, v75
	v_cvt_pk_bf16_f32 v75, v76, v77
	v_lshl_add_u64 v[76:77], s[30:31], 0, v[78:79]
	v_lshl_add_u64 v[76:77], v[76:77], 0, v[142:143]
	global_store_dwordx2 v[76:77], v[74:75], off
	v_add_u32_e32 v74, v156, v88
	v_ashrrev_i32_e32 v75, 31, v74
	v_lshlrev_b64 v[74:75], 11, v[74:75]
	v_lshl_add_u64 v[76:77], v[118:119], 0, v[74:75]
	v_lshl_add_u64 v[76:77], v[76:77], 0, v[120:121]
	global_store_dwordx4 v[76:77], v[70:73], off
	v_pk_mul_f32 v[68:69], v[68:69], v[82:83] op_sel_hi:[1,0]
	v_pk_mul_f32 v[66:67], v[66:67], v[82:83] op_sel_hi:[1,0]
	v_cvt_pk_bf16_f32 v70, v70, v71
	v_cvt_pk_bf16_f32 v71, v72, v73
	v_lshl_add_u64 v[72:73], s[30:31], 0, v[74:75]
	v_lshl_add_u64 v[72:73], v[72:73], 0, v[144:145]
	global_store_dwordx2 v[72:73], v[70:71], off
	v_add_u32_e32 v70, v157, v88
	v_ashrrev_i32_e32 v71, 31, v70
	v_lshlrev_b64 v[70:71], 11, v[70:71]
	v_lshl_add_u64 v[72:73], v[146:147], 0, v[70:71]
	v_lshl_add_u64 v[72:73], v[72:73], 0, v[148:149]
	global_store_dwordx4 v[72:73], v[66:69], off
	v_add_u32_e32 v72, 0x80, v138
	s_nop 0
	v_cvt_pk_bf16_f32 v66, v66, v67
	v_cvt_pk_bf16_f32 v67, v68, v69
	v_lshl_add_u64 v[68:69], s[30:31], 0, v[70:71]
	v_lshl_add_u64 v[68:69], v[68:69], 0, v[114:115]
	global_store_dwordx2 v[68:69], v[66:67], off
	global_load_dwordx2 v[66:67], v[140:141], off offset:1024
	s_waitcnt vmcnt(0)
	v_ffbh_u32_e32 v68, v67
	v_min_u32_e32 v68, 32, v68
	v_lshlrev_b64 v[66:67], v68, v[66:67]
	v_min_u32_e32 v66, 1, v66
	v_or_b32_e32 v66, v67, v66
	v_cvt_f32_u32_e32 v66, v66
	v_sub_u32_e32 v67, 32, v68
	v_add_u32_e32 v68, v139, v72
	v_ashrrev_i32_e32 v69, 31, v68
	v_ldexp_f32 v66, v66, v67
	v_mul_f32_e32 v66, 0x30800000, v66
	v_fmamk_f32 v66, v66, 0x3a000000, v1
	v_cmp_gt_f32_e32 vcc, s65, v66
	v_mul_f32_e32 v67, 0x4b800000, v66
	v_lshlrev_b64 v[68:69], 11, v[68:69]
	v_cndmask_b32_e32 v66, v66, v67, vcc
	v_rsq_f32_e32 v66, v66
	v_lshl_add_u64 v[70:71], v[126:127], 0, v[68:69]
	v_lshl_add_u64 v[70:71], v[70:71], 0, v[180:181]
	v_mul_f32_e32 v67, 0x45800000, v66
	v_cndmask_b32_e32 v66, v66, v67, vcc
	v_pk_mul_f32 v[64:65], v[64:65], v[66:67] op_sel_hi:[1,0]
	v_pk_mul_f32 v[62:63], v[62:63], v[66:67] op_sel_hi:[1,0]
	global_store_dwordx4 v[70:71], v[62:65], off
	v_pk_mul_f32 v[60:61], v[60:61], v[66:67] op_sel_hi:[1,0]
	v_pk_mul_f32 v[58:59], v[58:59], v[66:67] op_sel_hi:[1,0]
	v_cvt_pk_bf16_f32 v62, v62, v63
	v_cvt_pk_bf16_f32 v63, v64, v65
	v_lshl_add_u64 v[64:65], s[30:31], 0, v[68:69]
	v_lshl_add_u64 v[64:65], v[64:65], 0, v[128:129]
	global_store_dwordx2 v[64:65], v[62:63], off
	v_add_u32_e32 v62, v155, v72
	v_ashrrev_i32_e32 v63, 31, v62
	v_lshlrev_b64 v[62:63], 11, v[62:63]
	v_lshl_add_u64 v[64:65], v[122:123], 0, v[62:63]
	v_lshl_add_u64 v[64:65], v[64:65], 0, v[124:125]
	global_store_dwordx4 v[64:65], v[58:61], off
	v_pk_mul_f32 v[56:57], v[56:57], v[66:67] op_sel_hi:[1,0]
	v_pk_mul_f32 v[54:55], v[54:55], v[66:67] op_sel_hi:[1,0]
	v_cvt_pk_bf16_f32 v58, v58, v59
	v_cvt_pk_bf16_f32 v59, v60, v61
	v_lshl_add_u64 v[60:61], s[30:31], 0, v[62:63]
	v_lshl_add_u64 v[60:61], v[60:61], 0, v[142:143]
	global_store_dwordx2 v[60:61], v[58:59], off
	v_add_u32_e32 v58, v156, v72
	v_ashrrev_i32_e32 v59, 31, v58
	v_lshlrev_b64 v[58:59], 11, v[58:59]
	v_lshl_add_u64 v[60:61], v[118:119], 0, v[58:59]
	v_lshl_add_u64 v[60:61], v[60:61], 0, v[120:121]
	global_store_dwordx4 v[60:61], v[54:57], off
	v_pk_mul_f32 v[52:53], v[52:53], v[66:67] op_sel_hi:[1,0]
	v_pk_mul_f32 v[50:51], v[50:51], v[66:67] op_sel_hi:[1,0]
	v_cvt_pk_bf16_f32 v54, v54, v55
	v_cvt_pk_bf16_f32 v55, v56, v57
	v_lshl_add_u64 v[56:57], s[30:31], 0, v[58:59]
	v_lshl_add_u64 v[56:57], v[56:57], 0, v[144:145]
	global_store_dwordx2 v[56:57], v[54:55], off
	v_add_u32_e32 v54, v157, v72
	v_ashrrev_i32_e32 v55, 31, v54
	v_lshlrev_b64 v[54:55], 11, v[54:55]
	v_lshl_add_u64 v[56:57], v[146:147], 0, v[54:55]
	v_lshl_add_u64 v[56:57], v[56:57], 0, v[148:149]
	global_store_dwordx4 v[56:57], v[50:53], off
	v_add_u32_e32 v56, 0x90, v138
	s_nop 0
	v_cvt_pk_bf16_f32 v50, v50, v51
	v_cvt_pk_bf16_f32 v51, v52, v53
	v_lshl_add_u64 v[52:53], s[30:31], 0, v[54:55]
	v_lshl_add_u64 v[52:53], v[52:53], 0, v[114:115]
	global_store_dwordx2 v[52:53], v[50:51], off
	global_load_dwordx2 v[50:51], v[140:141], off offset:1152
	s_waitcnt vmcnt(0)
	v_ffbh_u32_e32 v52, v51
	v_min_u32_e32 v52, 32, v52
	v_lshlrev_b64 v[50:51], v52, v[50:51]
	v_min_u32_e32 v50, 1, v50
	v_or_b32_e32 v50, v51, v50
	v_cvt_f32_u32_e32 v50, v50
	v_sub_u32_e32 v51, 32, v52
	v_add_u32_e32 v52, v139, v56
	v_ashrrev_i32_e32 v53, 31, v52
	v_ldexp_f32 v50, v50, v51
	v_mul_f32_e32 v50, 0x30800000, v50
	v_fmamk_f32 v50, v50, 0x3a000000, v1
	v_cmp_gt_f32_e32 vcc, s65, v50
	v_mul_f32_e32 v51, 0x4b800000, v50
	v_lshlrev_b64 v[52:53], 11, v[52:53]
	v_cndmask_b32_e32 v50, v50, v51, vcc
	v_rsq_f32_e32 v50, v50
	v_lshl_add_u64 v[54:55], v[126:127], 0, v[52:53]
	v_lshl_add_u64 v[54:55], v[54:55], 0, v[180:181]
	v_mul_f32_e32 v51, 0x45800000, v50
	v_cndmask_b32_e32 v50, v50, v51, vcc
	v_pk_mul_f32 v[48:49], v[48:49], v[50:51] op_sel_hi:[1,0]
	v_pk_mul_f32 v[46:47], v[46:47], v[50:51] op_sel_hi:[1,0]
	global_store_dwordx4 v[54:55], v[46:49], off
	v_pk_mul_f32 v[44:45], v[44:45], v[50:51] op_sel_hi:[1,0]
	v_pk_mul_f32 v[42:43], v[42:43], v[50:51] op_sel_hi:[1,0]
	v_cvt_pk_bf16_f32 v46, v46, v47
	v_cvt_pk_bf16_f32 v47, v48, v49
	v_lshl_add_u64 v[48:49], s[30:31], 0, v[52:53]
	v_lshl_add_u64 v[48:49], v[48:49], 0, v[128:129]
	global_store_dwordx2 v[48:49], v[46:47], off
	v_add_u32_e32 v46, v155, v56
	v_ashrrev_i32_e32 v47, 31, v46
	v_lshlrev_b64 v[46:47], 11, v[46:47]
	v_lshl_add_u64 v[48:49], v[122:123], 0, v[46:47]
	v_lshl_add_u64 v[48:49], v[48:49], 0, v[124:125]
	global_store_dwordx4 v[48:49], v[42:45], off
	v_pk_mul_f32 v[40:41], v[40:41], v[50:51] op_sel_hi:[1,0]
	v_pk_mul_f32 v[38:39], v[38:39], v[50:51] op_sel_hi:[1,0]
	v_cvt_pk_bf16_f32 v42, v42, v43
	v_cvt_pk_bf16_f32 v43, v44, v45
	v_lshl_add_u64 v[44:45], s[30:31], 0, v[46:47]
	v_lshl_add_u64 v[44:45], v[44:45], 0, v[142:143]
	global_store_dwordx2 v[44:45], v[42:43], off
	v_add_u32_e32 v42, v156, v56
	v_ashrrev_i32_e32 v43, 31, v42
	v_lshlrev_b64 v[42:43], 11, v[42:43]
	v_lshl_add_u64 v[44:45], v[118:119], 0, v[42:43]
	v_lshl_add_u64 v[44:45], v[44:45], 0, v[120:121]
	global_store_dwordx4 v[44:45], v[38:41], off
	v_pk_mul_f32 v[36:37], v[36:37], v[50:51] op_sel_hi:[1,0]
	v_pk_mul_f32 v[34:35], v[34:35], v[50:51] op_sel_hi:[1,0]
	v_cvt_pk_bf16_f32 v38, v38, v39
	v_cvt_pk_bf16_f32 v39, v40, v41
	v_lshl_add_u64 v[40:41], s[30:31], 0, v[42:43]
	v_lshl_add_u64 v[40:41], v[40:41], 0, v[144:145]
	global_store_dwordx2 v[40:41], v[38:39], off
	v_add_u32_e32 v38, v157, v56
	v_ashrrev_i32_e32 v39, 31, v38
	v_lshlrev_b64 v[38:39], 11, v[38:39]
	v_lshl_add_u64 v[40:41], v[146:147], 0, v[38:39]
	v_lshl_add_u64 v[40:41], v[40:41], 0, v[148:149]
	global_store_dwordx4 v[40:41], v[34:37], off
	v_add_u32_e32 v40, 0xa0, v138
	s_nop 0
	v_cvt_pk_bf16_f32 v34, v34, v35
	v_cvt_pk_bf16_f32 v35, v36, v37
	v_lshl_add_u64 v[36:37], s[30:31], 0, v[38:39]
	v_lshl_add_u64 v[36:37], v[36:37], 0, v[114:115]
	global_store_dwordx2 v[36:37], v[34:35], off
	global_load_dwordx2 v[34:35], v[140:141], off offset:1280
	s_waitcnt vmcnt(0)
	v_ffbh_u32_e32 v36, v35
	v_min_u32_e32 v36, 32, v36
	v_lshlrev_b64 v[34:35], v36, v[34:35]
	v_min_u32_e32 v34, 1, v34
	v_or_b32_e32 v34, v35, v34
	v_cvt_f32_u32_e32 v34, v34
	v_sub_u32_e32 v35, 32, v36
	v_add_u32_e32 v36, v139, v40
	v_ashrrev_i32_e32 v37, 31, v36
	v_ldexp_f32 v34, v34, v35
	v_mul_f32_e32 v34, 0x30800000, v34
	v_fmamk_f32 v34, v34, 0x3a000000, v1
	v_cmp_gt_f32_e32 vcc, s65, v34
	v_mul_f32_e32 v35, 0x4b800000, v34
	v_lshlrev_b64 v[36:37], 11, v[36:37]
	v_cndmask_b32_e32 v34, v34, v35, vcc
	v_rsq_f32_e32 v34, v34
	v_lshl_add_u64 v[38:39], v[126:127], 0, v[36:37]
	v_lshl_add_u64 v[38:39], v[38:39], 0, v[180:181]
	v_mul_f32_e32 v35, 0x45800000, v34
	v_cndmask_b32_e32 v34, v34, v35, vcc
	v_pk_mul_f32 v[32:33], v[32:33], v[34:35] op_sel_hi:[1,0]
	v_pk_mul_f32 v[30:31], v[30:31], v[34:35] op_sel_hi:[1,0]
	global_store_dwordx4 v[38:39], v[30:33], off
	v_pk_mul_f32 v[28:29], v[28:29], v[34:35] op_sel_hi:[1,0]
	v_pk_mul_f32 v[26:27], v[26:27], v[34:35] op_sel_hi:[1,0]
	v_cvt_pk_bf16_f32 v30, v30, v31
	v_cvt_pk_bf16_f32 v31, v32, v33
	v_lshl_add_u64 v[32:33], s[30:31], 0, v[36:37]
	v_lshl_add_u64 v[32:33], v[32:33], 0, v[128:129]
	global_store_dwordx2 v[32:33], v[30:31], off
	v_add_u32_e32 v30, v155, v40
	v_ashrrev_i32_e32 v31, 31, v30
	v_lshlrev_b64 v[30:31], 11, v[30:31]
	v_lshl_add_u64 v[32:33], v[122:123], 0, v[30:31]
	v_lshl_add_u64 v[32:33], v[32:33], 0, v[124:125]
	global_store_dwordx4 v[32:33], v[26:29], off
	v_pk_mul_f32 v[24:25], v[24:25], v[34:35] op_sel_hi:[1,0]
	v_pk_mul_f32 v[22:23], v[22:23], v[34:35] op_sel_hi:[1,0]
	v_cvt_pk_bf16_f32 v26, v26, v27
	v_cvt_pk_bf16_f32 v27, v28, v29
	v_lshl_add_u64 v[28:29], s[30:31], 0, v[30:31]
	v_lshl_add_u64 v[28:29], v[28:29], 0, v[142:143]
	global_store_dwordx2 v[28:29], v[26:27], off
	v_add_u32_e32 v26, v156, v40
	v_ashrrev_i32_e32 v27, 31, v26
	v_lshlrev_b64 v[26:27], 11, v[26:27]
	v_lshl_add_u64 v[28:29], v[118:119], 0, v[26:27]
	v_lshl_add_u64 v[28:29], v[28:29], 0, v[120:121]
	global_store_dwordx4 v[28:29], v[22:25], off
	v_pk_mul_f32 v[20:21], v[20:21], v[34:35] op_sel_hi:[1,0]
	v_pk_mul_f32 v[18:19], v[18:19], v[34:35] op_sel_hi:[1,0]
	v_cvt_pk_bf16_f32 v22, v22, v23
	v_cvt_pk_bf16_f32 v23, v24, v25
	v_lshl_add_u64 v[24:25], s[30:31], 0, v[26:27]
	v_lshl_add_u64 v[24:25], v[24:25], 0, v[144:145]
	global_store_dwordx2 v[24:25], v[22:23], off
	v_add_u32_e32 v22, v157, v40
	v_ashrrev_i32_e32 v23, 31, v22
	v_lshlrev_b64 v[22:23], 11, v[22:23]
	v_lshl_add_u64 v[24:25], v[146:147], 0, v[22:23]
	v_lshl_add_u64 v[24:25], v[24:25], 0, v[148:149]
	global_store_dwordx4 v[24:25], v[18:21], off
	v_add_u32_e32 v24, 0xb0, v138
	s_nop 0
	v_cvt_pk_bf16_f32 v18, v18, v19
	v_cvt_pk_bf16_f32 v19, v20, v21
	v_lshl_add_u64 v[20:21], s[30:31], 0, v[22:23]
	v_lshl_add_u64 v[20:21], v[20:21], 0, v[114:115]
	global_store_dwordx2 v[20:21], v[18:19], off
	global_load_dwordx2 v[18:19], v[140:141], off offset:1408
	s_waitcnt vmcnt(0)
	v_ffbh_u32_e32 v20, v19
	v_min_u32_e32 v20, 32, v20
	v_lshlrev_b64 v[18:19], v20, v[18:19]
	v_min_u32_e32 v18, 1, v18
	v_or_b32_e32 v18, v19, v18
	v_cvt_f32_u32_e32 v18, v18
	v_sub_u32_e32 v19, 32, v20
	v_add_u32_e32 v20, v139, v24
	v_ashrrev_i32_e32 v21, 31, v20
	v_ldexp_f32 v18, v18, v19
	v_mul_f32_e32 v18, 0x30800000, v18
	v_fmamk_f32 v18, v18, 0x3a000000, v1
	v_cmp_gt_f32_e32 vcc, s65, v18
	v_mul_f32_e32 v19, 0x4b800000, v18
	v_lshlrev_b64 v[20:21], 11, v[20:21]
	v_cndmask_b32_e32 v18, v18, v19, vcc
	v_rsq_f32_e32 v18, v18
	v_lshl_add_u64 v[22:23], v[126:127], 0, v[20:21]
	v_lshl_add_u64 v[22:23], v[22:23], 0, v[180:181]
	v_mul_f32_e32 v19, 0x45800000, v18
	v_cndmask_b32_e32 v18, v18, v19, vcc
	v_pk_mul_f32 v[16:17], v[16:17], v[18:19] op_sel_hi:[1,0]
	v_pk_mul_f32 v[14:15], v[14:15], v[18:19] op_sel_hi:[1,0]
	global_store_dwordx4 v[22:23], v[14:17], off
	v_pk_mul_f32 v[12:13], v[12:13], v[18:19] op_sel_hi:[1,0]
	v_pk_mul_f32 v[10:11], v[10:11], v[18:19] op_sel_hi:[1,0]
	v_cvt_pk_bf16_f32 v14, v14, v15
	v_cvt_pk_bf16_f32 v15, v16, v17
	v_lshl_add_u64 v[16:17], s[30:31], 0, v[20:21]
	v_lshl_add_u64 v[16:17], v[16:17], 0, v[128:129]
	global_store_dwordx2 v[16:17], v[14:15], off
	v_add_u32_e32 v14, v155, v24
	v_ashrrev_i32_e32 v15, 31, v14
	v_lshlrev_b64 v[14:15], 11, v[14:15]
	v_lshl_add_u64 v[16:17], v[122:123], 0, v[14:15]
	v_lshl_add_u64 v[16:17], v[16:17], 0, v[124:125]
	global_store_dwordx4 v[16:17], v[10:13], off
	v_pk_mul_f32 v[8:9], v[8:9], v[18:19] op_sel_hi:[1,0]
	v_pk_mul_f32 v[6:7], v[6:7], v[18:19] op_sel_hi:[1,0]
	v_cvt_pk_bf16_f32 v10, v10, v11
	v_cvt_pk_bf16_f32 v11, v12, v13
	v_lshl_add_u64 v[12:13], s[30:31], 0, v[14:15]
	v_lshl_add_u64 v[12:13], v[12:13], 0, v[142:143]
	global_store_dwordx2 v[12:13], v[10:11], off
	v_add_u32_e32 v10, v156, v24
	v_ashrrev_i32_e32 v11, 31, v10
	v_lshlrev_b64 v[10:11], 11, v[10:11]
	v_lshl_add_u64 v[12:13], v[118:119], 0, v[10:11]
	v_lshl_add_u64 v[12:13], v[12:13], 0, v[120:121]
	global_store_dwordx4 v[12:13], v[6:9], off
	v_pk_mul_f32 v[4:5], v[4:5], v[18:19] op_sel_hi:[1,0]
	v_pk_mul_f32 v[2:3], v[2:3], v[18:19] op_sel_hi:[1,0]
	v_cvt_pk_bf16_f32 v6, v6, v7
	v_cvt_pk_bf16_f32 v7, v8, v9
	v_lshl_add_u64 v[8:9], s[30:31], 0, v[10:11]
	v_lshl_add_u64 v[8:9], v[8:9], 0, v[144:145]
	global_store_dwordx2 v[8:9], v[6:7], off
	v_add_u32_e32 v6, v157, v24
	v_ashrrev_i32_e32 v7, 31, v6
	v_lshlrev_b64 v[6:7], 11, v[6:7]
	v_lshl_add_u64 v[8:9], v[146:147], 0, v[6:7]
	v_lshl_add_u64 v[8:9], v[8:9], 0, v[148:149]
	global_store_dwordx4 v[8:9], v[2:5], off
	s_andn2_b64 vcc, exec, s[36:37]
	s_nop 0
	v_cvt_pk_bf16_f32 v2, v2, v3
	v_cvt_pk_bf16_f32 v3, v4, v5
	v_lshl_add_u64 v[4:5], s[30:31], 0, v[6:7]
	v_lshl_add_u64 v[4:5], v[4:5], 0, v[114:115]
	global_store_dwordx2 v[4:5], v[2:3], off
	s_cbranch_vccnz .LBB0_1759
	s_andn2_b64 vcc, exec, s[22:23]
	s_cbranch_vccnz .LBB0_1758
	s_branch .LBB0_1758

.LBB0_2224:
	s_andn2_b64 vcc, exec, s[14:15]
	s_cbranch_vccnz .LBB0_2264
	v_ashrrev_i32_e32 v4, 31, v2
	v_lshrrev_b32_e32 v4, 26, v4
	v_add_u32_e32 v4, v2, v4
	v_ashrrev_i32_e32 v148, 6, v4
	v_bfe_i32 v4, v2, 27, 1
	v_lshlrev_b32_e32 v3, 4, v2
	v_lshrrev_b32_e32 v4, 22, v4
	v_add_u32_e32 v4, v3, v4
	v_and_b32_e32 v4, 0xfffffc00, v4
	v_sub_u32_e32 v4, v3, v4
	v_lshrrev_b32_e32 v5, 4, v4
	v_bitop3_b32 v4, v5, v4, 32 bitop3:0x6c
	v_ashrrev_i32_e32 v6, 31, v4
	v_lshrrev_b32_e32 v6, 26, v6
	v_lshlrev_b32_e32 v5, 3, v148
	v_add_u32_e32 v6, v4, v6
	v_and_b32_e32 v5, -16, v5
	v_ashrrev_i32_e32 v150, 6, v6
	v_and_b32_e32 v6, 0xc0, v6
	s_mov_b64 s[14:15], 0x1de00000
	v_add_u32_e32 v5, v150, v5
	v_lshlrev_b32_e32 v7, 5, v148
	v_sub_u32_e32 v4, v4, v6
	v_lshl_add_u64 v[132:133], v[130:131], 0, s[14:15]
	v_and_b32_e32 v149, 32, v7
	v_ashrrev_i16_sdwa v4, v224, sext(v4) dst_sel:DWORD dst_unused:UNUSED_PAD src0_sel:DWORD src1_sel:BYTE_0
	v_lshlrev_b32_e32 v6, 1, v5
	v_lshrrev_b32_e32 v7, 2, v5
	v_and_b32_e32 v8, 3, v150
	s_mov_b32 s14, 0x1ffffe0
	v_bfe_i32 v151, v4, 0, 16
	v_and_b32_e32 v6, 24, v6
	v_and_b32_e32 v7, 4, v7
	v_and_or_b32 v8, v5, s14, v8
	s_movk_i32 s12, 0x1580
	v_add_u32_e32 v4, v149, v151
	v_or3_b32 v6, v8, v7, v6
	v_mul_lo_u32 v5, v5, s12
	v_add_lshl_u32 v134, v4, v5, 1
	v_mul_lo_u32 v5, v6, s12
	v_add_u32_e32 v3, 0x2000, v3
	v_add_lshl_u32 v136, v5, v4, 1
	v_ashrrev_i32_e32 v4, 31, v3
	v_lshrrev_b32_e32 v4, 22, v4
	v_add_u32_e32 v4, v3, v4
	v_ashrrev_i32_e32 v157, 10, v4
	v_mul_i32_i24_e32 v4, 0x400, v157
	v_sub_u32_e32 v3, v3, v4
	v_lshrrev_b32_e32 v4, 4, v3
	v_bitop3_b32 v3, v4, v3, 32 bitop3:0x6c
	v_ashrrev_i32_e32 v5, 31, v3
	v_lshrrev_b32_e32 v5, 26, v5
	v_lshlrev_b32_e32 v4, 3, v157
	v_add_u32_e32 v5, v3, v5
	v_and_b32_e32 v4, -16, v4
	v_ashrrev_i32_e32 v159, 6, v5
	v_and_b32_e32 v5, 0xc0, v5
	v_add_u32_e32 v4, v159, v4
	v_lshlrev_b32_e32 v6, 5, v157
	v_sub_u32_e32 v3, v3, v5
	v_and_b32_e32 v158, 32, v6
	v_ashrrev_i16_sdwa v3, v224, sext(v3) dst_sel:DWORD dst_unused:UNUSED_PAD src0_sel:DWORD src1_sel:BYTE_0
	v_lshlrev_b32_e32 v5, 1, v4
	v_lshrrev_b32_e32 v6, 2, v4
	v_and_b32_e32 v7, 3, v159
	v_bfe_i32 v160, v3, 0, 16
	v_and_b32_e32 v5, 24, v5
	v_and_b32_e32 v6, 4, v6
	v_and_or_b32 v7, v4, s14, v7
	v_add_u32_e32 v3, v158, v160
	v_or3_b32 v5, v7, v6, v5
	v_mul_lo_u32 v4, v4, s12
	v_add_lshl_u32 v138, v3, v4, 1
	v_mul_lo_u32 v4, v5, s12
	s_ashr_i32 s12, s22, 6
	s_ashr_i32 s18, s22, 8
	s_lshl_b32 s40, s12, 10
	s_lshl_b32 s12, s12, 5
	s_lshl_b32 s41, s18, 6
	s_and_b32 s42, s12, 0x60
	s_lshl_b32 s12, s56, 8
	v_and_b32_e32 v154, 15, v2
	s_add_i32 s12, s12, s41
	v_bfe_u32 v153, v2, 4, 2
	v_or_b32_e32 v2, s12, v154
	v_add_lshl_u32 v140, v4, v3, 1
	v_ashrrev_i32_e32 v3, 31, v2
	v_lshlrev_b64 v[2:3], 12, v[2:3]
	s_lshl_b32 s14, s55, 8
	v_lshl_add_u64 v[2:3], v[132:133], 0, v[2:3]
	s_ashr_i32 s15, s14, 31
	v_lshl_add_u64 v[2:3], s[14:15], 1, v[2:3]
	s_lshl_b32 s12, s42, 1
	v_lshl_add_u64 v[2:3], v[2:3], 0, s[12:13]
	v_lshlrev_b32_e32 v180, 4, v153
	v_lshl_add_u64 v[2:3], v[2:3], 0, v[180:181]
	s_mov_b32 s14, 0x10000
	v_add_co_u32_e32 v4, vcc, s14, v2
	s_mov_b32 s14, 0x20000
	s_nop 0
	v_addc_co_u32_e32 v5, vcc, 0, v3, vcc
	global_load_dwordx4 v[64:67], v[2:3], off
	global_load_dwordx4 v[60:63], v[2:3], off offset:256
	global_load_dwordx4 v[56:59], v[4:5], off
	global_load_dwordx4 v[52:55], v[4:5], off offset:256
	v_add_co_u32_e32 v4, vcc, s14, v2
	s_mov_b32 s14, 0x30000
	s_nop 0
	v_addc_co_u32_e32 v5, vcc, 0, v3, vcc
	global_load_dwordx4 v[48:51], v[4:5], off
	global_load_dwordx4 v[44:47], v[4:5], off offset:256
	v_add_co_u32_e32 v4, vcc, s14, v2
	s_mov_b32 s14, 0x80000
	s_nop 0
	v_addc_co_u32_e32 v5, vcc, 0, v3, vcc
	global_load_dwordx4 v[40:43], v[4:5], off
	global_load_dwordx4 v[36:39], v[4:5], off offset:256
	v_add_co_u32_e32 v4, vcc, s14, v2
	s_mov_b32 s14, 0x90000
	s_nop 0
	v_addc_co_u32_e32 v5, vcc, 0, v3, vcc
	global_load_dwordx4 v[32:35], v[4:5], off
	global_load_dwordx4 v[28:31], v[4:5], off offset:256
	v_add_co_u32_e32 v4, vcc, s14, v2
	s_mov_b32 s14, 0xa0000
	s_nop 0
	v_addc_co_u32_e32 v5, vcc, 0, v3, vcc
	global_load_dwordx4 v[24:27], v[4:5], off
	global_load_dwordx4 v[18:21], v[4:5], off offset:256
	v_add_co_u32_e32 v4, vcc, s14, v2
	s_mov_b32 s14, 0xb0000
	s_nop 0
	v_addc_co_u32_e32 v5, vcc, 0, v3, vcc
	s_mul_i32 s15, s55, 0x2b0000
	v_add_co_u32_e32 v14, vcc, s14, v2
	s_mul_hi_i32 s14, s55, 0x2b0000
	s_add_u32 s28, s8, s15
	s_addc_u32 s29, s9, s14
	s_add_i32 s43, s40, 0
	v_addc_co_u32_e32 v15, vcc, 0, v3, vcc
	s_add_i32 m0, s43, 0x10000
	global_load_dwordx4 v[10:13], v[4:5], off
	global_load_dwordx4 v[6:9], v[4:5], off offset:256
	s_nop 0
	global_load_dwordx4 v[2:5], v[14:15], off
	s_nop 0
	global_load_dwordx4 v[14:17], v[14:15], off offset:256
	s_mul_i32 s23, s56, 0x2b0000
	global_load_lds_dwordx4 v136, s[28:29]
	s_add_i32 m0, s43, 0x12000
	s_add_u32 s14, s28, 0x158000
	global_load_lds_dwordx4 v140, s[28:29]
	s_addc_u32 s15, s29, 0
	s_add_i32 m0, s43, 0x14000
	s_mul_hi_i32 s19, s56, 0x2b0000
	global_load_lds_dwordx4 v136, s[14:15]
	s_add_i32 m0, s43, 0x16000
	s_add_u32 s26, s6, s23
	s_addc_u32 s27, s7, s19
	s_add_i32 s44, s43, 0x2000
	global_load_lds_dwordx4 v140, s[14:15]
	s_mov_b32 m0, s43
	s_add_u32 s14, s26, 0x158000
	global_load_lds_dwordx4 v134, s[26:27]
	s_mov_b32 m0, s44
	s_addc_u32 s15, s27, 0
	s_add_i32 s45, s43, 0x4000
	global_load_lds_dwordx4 v138, s[26:27]
	s_mov_b32 m0, s45
	s_add_i32 s47, s43, 0x6000
	global_load_lds_dwordx4 v134, s[14:15]
	s_mov_b32 m0, s47
	v_mov_b32_e32 v137, v181
	global_load_lds_dwordx4 v138, s[14:15]
	v_mov_b32_e32 v141, v181
	v_mov_b32_e32 v135, v181
	v_mov_b32_e32 v139, v181
	s_cmp_eq_u32 s18, 1
	v_lshl_add_u64 v[146:147], s[28:29], 0, v[136:137]
	v_lshl_add_u64 v[144:145], s[28:29], 0, v[140:141]
	v_lshl_add_u64 v[68:69], s[26:27], 0, v[134:135]
	s_cselect_b64 s[14:15], -1, 0
	s_cmp_lg_u32 s18, 1
	v_lshl_add_u64 v[142:143], s[26:27], 0, v[138:139]
	s_cbranch_scc1 .LBB0_2227
.LBB0_2227:
	s_waitcnt vmcnt(0)
	v_lshlrev_b32_e32 v90, 16, v48
	v_and_b32_e32 v91, 0xffff0000, v48
	v_lshlrev_b32_e32 v92, 16, v49
	v_and_b32_e32 v93, 0xffff0000, v49
	v_lshlrev_b32_e32 v94, 16, v46
	v_and_b32_e32 v95, 0xffff0000, v46
	v_lshlrev_b32_e32 v96, 16, v47
	v_and_b32_e32 v97, 0xffff0000, v47
	v_lshlrev_b32_e32 v46, 16, v28
	v_and_b32_e32 v47, 0xffff0000, v28
	v_lshlrev_b32_e32 v48, 16, v29
	v_and_b32_e32 v49, 0xffff0000, v29
	s_add_i32 m0, s43, 0x18000
	v_lshl_add_u64 v[28:29], v[146:147], 0, s[16:17]
	s_lshl_b32 s23, s18, 13
	s_lshl_b32 s24, s42, 7
	s_waitcnt vmcnt(2)
	s_barrier
	global_load_lds_dwordx4 v[28:29], off
	v_lshl_add_u64 v[28:29], v[144:145], 0, s[16:17]
	s_add_i32 m0, s43, 0x1a000
	s_add_i32 s48, s43, 0x8000
	s_add_i32 s49, s43, 0xa000
	global_load_lds_dwordx4 v[28:29], off
	v_lshl_add_u64 v[28:29], v[68:69], 0, s[16:17]
	s_mov_b32 m0, s48
	s_add_u32 s18, s28, 0x158080
	global_load_lds_dwordx4 v[28:29], off
	v_lshl_add_u64 v[28:29], v[142:143], 0, s[16:17]
	s_mov_b32 m0, s49
	s_addc_u32 s19, s29, 0
	global_load_lds_dwordx4 v[28:29], off
	s_add_i32 m0, s43, 0x1c000
	v_lshl_add_u64 v[28:29], s[18:19], 0, v[136:137]
	global_load_lds_dwordx4 v[28:29], off
	v_lshl_add_u64 v[28:29], s[18:19], 0, v[140:141]
	s_add_i32 m0, s43, 0x1e000
	v_readlane_b32 s18, v255, 43
	global_load_lds_dwordx4 v[28:29], off
	s_mulk_i32 s18, 0x4200
	s_mov_b32 s19, s13
	v_lshl_add_u64 v[142:143], s[18:19], 3, v[130:131]
	s_mov_b64 s[18:19], 0x31000
	v_or_b32_e32 v155, s41, v154
	v_lshl_add_u64 v[142:143], v[142:143], 0, s[18:19]
	v_lshlrev_b32_e32 v144, 6, v155
	s_movk_i32 s18, 0x3c0
	v_lshlrev_b32_e32 v145, 2, v155
	v_and_or_b32 v144, v144, s18, v180
	v_and_b32_e32 v145, 32, v145
	v_bitop3_b32 v162, v144, s23, v145 bitop3:0xde
	v_lshlrev_b32_e32 v145, 2, v154
	v_lshl_or_b32 v144, v154, 6, v180
	v_and_b32_e32 v145, 32, v145
	v_bitop3_b32 v156, v144, s24, v145 bitop3:0xde
	s_movk_i32 s24, 0x1580
	v_lshrrev_b32_e32 v145, 1, v148
	v_mul_lo_u32 v144, v150, s24
	s_mov_b32 s25, 0x15800
	s_cmpk_lt_u32 s22, 0x100
	v_mad_u64_u32 v[144:145], s[22:23], v145, s25, v[144:145]
	v_lshrrev_b32_e32 v147, 1, v157
	v_mul_lo_u32 v146, v159, s24
	v_or_b32_e32 v144, v144, v149
	v_mad_u64_u32 v[146:147], s[22:23], v147, s25, v[146:147]
	s_waitcnt vmcnt(6)
	v_add_lshl_u32 v180, v144, v151, 1
	s_mov_b64 s[30:31], 0x158080
	v_or_b32_e32 v146, v146, v158
	v_lshlrev_b32_e32 v161, 3, v153
	v_lshl_add_u64 v[144:145], v[180:181], 0, s[30:31]
	v_add_lshl_u32 v180, v146, v160, 1
	v_lshlrev_b32_e32 v126, 16, v64
	v_and_b32_e32 v127, 0xffff0000, v64
	v_lshlrev_b32_e32 v128, 16, v65
	v_and_b32_e32 v129, 0xffff0000, v65
	v_lshlrev_b32_e32 v114, 16, v66
	v_and_b32_e32 v115, 0xffff0000, v66
	v_lshlrev_b32_e32 v116, 16, v67
	v_and_b32_e32 v117, 0xffff0000, v67
	v_lshlrev_b32_e32 v118, 16, v60
	v_and_b32_e32 v119, 0xffff0000, v60
	v_lshlrev_b32_e32 v120, 16, v61
	v_and_b32_e32 v121, 0xffff0000, v61
	v_lshlrev_b32_e32 v122, 16, v62
	v_and_b32_e32 v123, 0xffff0000, v62
	v_lshlrev_b32_e32 v124, 16, v63
	v_and_b32_e32 v125, 0xffff0000, v63
	v_lshlrev_b32_e32 v106, 16, v56
	v_and_b32_e32 v107, 0xffff0000, v56
	v_lshlrev_b32_e32 v108, 16, v57
	v_and_b32_e32 v109, 0xffff0000, v57
	v_lshlrev_b32_e32 v98, 16, v58
	v_and_b32_e32 v99, 0xffff0000, v58
	v_lshlrev_b32_e32 v100, 16, v59
	v_and_b32_e32 v101, 0xffff0000, v59
	v_lshlrev_b32_e32 v102, 16, v52
	v_and_b32_e32 v103, 0xffff0000, v52
	v_lshlrev_b32_e32 v104, 16, v53
	v_and_b32_e32 v105, 0xffff0000, v53
	v_lshlrev_b32_e32 v110, 16, v54
	v_and_b32_e32 v111, 0xffff0000, v54
	v_lshlrev_b32_e32 v112, 16, v55
	v_and_b32_e32 v113, 0xffff0000, v55
	v_lshlrev_b32_e32 v82, 16, v50
	v_and_b32_e32 v83, 0xffff0000, v50
	v_lshlrev_b32_e32 v84, 16, v51
	v_and_b32_e32 v85, 0xffff0000, v51
	v_lshlrev_b32_e32 v86, 16, v44
	v_and_b32_e32 v87, 0xffff0000, v44
	v_lshlrev_b32_e32 v88, 16, v45
	v_and_b32_e32 v89, 0xffff0000, v45
	v_lshlrev_b32_e32 v74, 16, v40
	v_and_b32_e32 v75, 0xffff0000, v40
	v_lshlrev_b32_e32 v76, 16, v41
	v_and_b32_e32 v77, 0xffff0000, v41
	v_lshlrev_b32_e32 v54, 16, v42
	v_and_b32_e32 v55, 0xffff0000, v42
	v_lshlrev_b32_e32 v56, 16, v43
	v_and_b32_e32 v57, 0xffff0000, v43
	v_lshlrev_b32_e32 v70, 16, v36
	v_and_b32_e32 v71, 0xffff0000, v36
	v_lshlrev_b32_e32 v72, 16, v37
	v_and_b32_e32 v73, 0xffff0000, v37
	v_lshlrev_b32_e32 v78, 16, v38
	v_and_b32_e32 v79, 0xffff0000, v38
	v_lshlrev_b32_e32 v80, 16, v39
	v_and_b32_e32 v81, 0xffff0000, v39
	v_lshlrev_b32_e32 v50, 16, v32
	v_and_b32_e32 v51, 0xffff0000, v32
	v_lshlrev_b32_e32 v52, 16, v33
	v_and_b32_e32 v53, 0xffff0000, v33
	v_lshlrev_b32_e32 v38, 16, v34
	v_and_b32_e32 v39, 0xffff0000, v34
	v_lshlrev_b32_e32 v40, 16, v35
	v_and_b32_e32 v41, 0xffff0000, v35
	v_lshlrev_b32_e32 v58, 16, v30
	v_and_b32_e32 v59, 0xffff0000, v30
	v_lshlrev_b32_e32 v60, 16, v31
	v_and_b32_e32 v61, 0xffff0000, v31
	v_lshlrev_b32_e32 v22, 16, v24
	v_and_b32_e32 v23, 0xffff0000, v24
	v_lshlrev_b32_e32 v24, 16, v25
	v_and_b32_e32 v25, 0xffff0000, v25
	v_lshlrev_b32_e32 v42, 16, v26
	v_and_b32_e32 v43, 0xffff0000, v26
	v_lshlrev_b32_e32 v44, 16, v27
	v_and_b32_e32 v45, 0xffff0000, v27
	v_lshlrev_b32_e32 v62, 16, v18
	v_and_b32_e32 v63, 0xffff0000, v18
	v_lshlrev_b32_e32 v64, 16, v19
	v_and_b32_e32 v65, 0xffff0000, v19
	v_lshlrev_b32_e32 v66, 16, v20
	v_and_b32_e32 v67, 0xffff0000, v20
	v_lshlrev_b32_e32 v68, 16, v21
	v_and_b32_e32 v69, 0xffff0000, v21
	v_lshlrev_b32_e32 v30, 16, v10
	v_and_b32_e32 v31, 0xffff0000, v10
	v_lshlrev_b32_e32 v32, 16, v11
	v_and_b32_e32 v33, 0xffff0000, v11
	v_lshlrev_b32_e32 v18, 16, v12
	v_and_b32_e32 v19, 0xffff0000, v12
	v_lshlrev_b32_e32 v20, 16, v13
	v_and_b32_e32 v21, 0xffff0000, v13
	v_lshlrev_b32_e32 v26, 16, v6
	v_and_b32_e32 v27, 0xffff0000, v6
	v_lshlrev_b32_e32 v28, 16, v7
	v_and_b32_e32 v29, 0xffff0000, v7
	v_lshlrev_b32_e32 v34, 16, v8
	v_and_b32_e32 v35, 0xffff0000, v8
	v_lshlrev_b32_e32 v36, 16, v9
	v_and_b32_e32 v37, 0xffff0000, v9
	v_lshlrev_b32_e32 v10, 16, v2
	v_and_b32_e32 v11, 0xffff0000, v2
	v_lshlrev_b32_e32 v12, 16, v3
	v_and_b32_e32 v13, 0xffff0000, v3
	v_lshlrev_b32_e32 v2, 16, v4
	v_and_b32_e32 v3, 0xffff0000, v4
	v_lshlrev_b32_e32 v4, 16, v5
	v_and_b32_e32 v5, 0xffff0000, v5
	v_lshlrev_b32_e32 v6, 16, v14
	v_and_b32_e32 v7, 0xffff0000, v14
	v_lshlrev_b32_e32 v8, 16, v15
	v_and_b32_e32 v9, 0xffff0000, v15
	v_lshlrev_b32_e32 v14, 16, v16
	v_and_b32_e32 v15, 0xffff0000, v16
	v_lshlrev_b32_e32 v16, 16, v17
	v_and_b32_e32 v17, 0xffff0000, v17
	s_cselect_b64 s[18:19], -1, 0
	v_lshl_add_u64 v[146:147], v[180:181], 0, s[30:31]
	s_mov_b32 s50, 0
	v_add_u32_e32 v157, 0, v162
	v_lshlrev_b32_e32 v180, 1, v161
	s_barrier
	s_branch .LBB0_2230

.LBB0_2241:
	s_add_u32 s28, s26, 0x100
	s_addc_u32 s29, s27, 0
	s_add_i32 s58, 0, 0x10000
	s_cmpk_eq_i32 s57, 0x52
	s_cselect_b32 s35, s23, s29
	s_cselect_b32 s34, s22, s28
	s_cselect_b32 s31, s25, s39
	s_cselect_b32 s30, s24, s38
	s_add_i32 s59, 0, 0x14000
	v_add_u32_e32 v166, s58, v156
	v_add_u32_e32 v178, s59, v156
	ds_read_b128 v[148:151], v166
	ds_read_b128 v[158:161], v166 offset:1024
	ds_read_b128 v[162:165], v166 offset:2048
	ds_read_b128 v[166:169], v166 offset:3072
	ds_read_b128 v[170:173], v178
	ds_read_b128 v[174:177], v178 offset:1024
	ds_read_b128 v[190:193], v178 offset:2048
	ds_read_b128 v[194:197], v178 offset:3072
	v_lshl_add_u64 v[178:179], s[26:27], 0, v[144:145]
	s_add_i32 m0, s43, 0xc000
	ds_read_b128 v[198:201], v157
	ds_read_b128 v[202:205], v157 offset:1024
	ds_read_b128 v[206:209], v157 offset:2048
	ds_read_b128 v[210:213], v157 offset:3072
	ds_read_b128 v[214:217], v157 offset:4096
	ds_read_b128 v[218:221], v157 offset:5120
	ds_read_b128 v[238:241], v157 offset:6144
	ds_read_b128 v[242:245], v157 offset:7168
	global_load_lds_dwordx4 v[178:179], off
	v_lshl_add_u64 v[178:179], s[26:27], 0, v[146:147]
	s_add_i32 m0, s43, 0xe000
	s_nop 0
	global_load_lds_dwordx4 v[178:179], off
	s_waitcnt vmcnt(8)
	s_waitcnt lgkmcnt(0)
	s_cmp_eq_u32 s100, 0
	s_cbranch_scc1 .Lmy_h2_65
	s_setprio 1
	s_barrier
.Lmy_h2_65:
	v_mfma_f32_16x16x32_bf16 v[126:129], v[148:151], v[198:201], v[126:129]
	v_mfma_f32_16x16x32_bf16 v[114:117], v[162:165], v[198:201], v[114:117]
	v_mfma_f32_16x16x32_bf16 v[106:109], v[148:151], v[206:209], v[106:109]
	v_mfma_f32_16x16x32_bf16 v[98:101], v[162:165], v[206:209], v[98:101]
	v_mfma_f32_16x16x32_bf16 v[90:93], v[148:151], v[214:217], v[90:93]
	v_mfma_f32_16x16x32_bf16 v[82:85], v[162:165], v[214:217], v[82:85]
	v_mfma_f32_16x16x32_bf16 v[74:77], v[148:151], v[238:241], v[74:77]
	v_mfma_f32_16x16x32_bf16 v[54:57], v[162:165], v[238:241], v[54:57]
	v_mfma_f32_16x16x32_bf16 v[126:129], v[158:161], v[202:205], v[126:129]
	v_mfma_f32_16x16x32_bf16 v[114:117], v[166:169], v[202:205], v[114:117]
	v_mfma_f32_16x16x32_bf16 v[106:109], v[158:161], v[210:213], v[106:109]
	v_mfma_f32_16x16x32_bf16 v[98:101], v[166:169], v[210:213], v[98:101]
	v_mfma_f32_16x16x32_bf16 v[90:93], v[158:161], v[218:221], v[90:93]
	v_mfma_f32_16x16x32_bf16 v[82:85], v[166:169], v[218:221], v[82:85]
	v_mfma_f32_16x16x32_bf16 v[74:77], v[158:161], v[242:245], v[74:77]
	v_mfma_f32_16x16x32_bf16 v[54:57], v[166:169], v[242:245], v[54:57]
	v_mfma_f32_16x16x32_bf16 v[118:121], v[170:173], v[198:201], v[118:121]
	v_mfma_f32_16x16x32_bf16 v[122:125], v[190:193], v[198:201], v[122:125]
	v_mfma_f32_16x16x32_bf16 v[102:105], v[170:173], v[206:209], v[102:105]
	v_mfma_f32_16x16x32_bf16 v[110:113], v[190:193], v[206:209], v[110:113]
	v_mfma_f32_16x16x32_bf16 v[86:89], v[170:173], v[214:217], v[86:89]
	v_mfma_f32_16x16x32_bf16 v[94:97], v[190:193], v[214:217], v[94:97]
	v_mfma_f32_16x16x32_bf16 v[70:73], v[170:173], v[238:241], v[70:73]
	v_mfma_f32_16x16x32_bf16 v[78:81], v[190:193], v[238:241], v[78:81]
	v_mfma_f32_16x16x32_bf16 v[118:121], v[174:177], v[202:205], v[118:121]
	v_mfma_f32_16x16x32_bf16 v[122:125], v[194:197], v[202:205], v[122:125]
	v_mfma_f32_16x16x32_bf16 v[102:105], v[174:177], v[210:213], v[102:105]
	v_mfma_f32_16x16x32_bf16 v[110:113], v[194:197], v[210:213], v[110:113]
	v_mfma_f32_16x16x32_bf16 v[86:89], v[174:177], v[218:221], v[86:89]
	v_mfma_f32_16x16x32_bf16 v[94:97], v[194:197], v[218:221], v[94:97]
	v_mfma_f32_16x16x32_bf16 v[70:73], v[174:177], v[242:245], v[70:73]
	v_mfma_f32_16x16x32_bf16 v[78:81], v[194:197], v[242:245], v[78:81]
	s_cmp_lg_u32 s100, 0
	s_cbranch_scc1 .Lmy_h2_66
	s_barrier
.Lmy_h2_66:
	s_setprio 0
	s_add_i32 s26, s58, s40
	v_lshl_add_u64 v[178:179], s[30:31], 0, v[136:137]
	s_mov_b32 m0, s26
	ds_read_b128 v[198:201], v157 offset:16384
	ds_read_b128 v[202:205], v157 offset:17408
	ds_read_b128 v[206:209], v157 offset:18432
	ds_read_b128 v[210:213], v157 offset:19456
	ds_read_b128 v[214:217], v157 offset:20480
	ds_read_b128 v[218:221], v157 offset:21504
	ds_read_b128 v[238:241], v157 offset:22528
	ds_read_b128 v[242:245], v157 offset:23552
	global_load_lds_dwordx4 v[178:179], off
	s_add_i32 m0, s26, 0x2000
	s_add_u32 s26, s30, 0x158000
	v_lshl_add_u64 v[222:223], s[30:31], 0, v[140:141]
	s_addc_u32 s27, s31, 0
	s_add_i32 s58, s59, s40
	global_load_lds_dwordx4 v[222:223], off
	v_lshl_add_u64 v[246:247], s[26:27], 0, v[136:137]
	s_mov_b32 m0, s58
	v_lshl_add_u64 v[248:249], s[34:35], 0, v[138:139]
	global_load_lds_dwordx4 v[246:247], off
	v_lshl_add_u64 v[246:247], s[26:27], 0, v[140:141]
	s_add_i32 m0, s58, 0x2000
	s_nop 0
	global_load_lds_dwordx4 v[246:247], off
	v_lshl_add_u64 v[246:247], s[34:35], 0, v[134:135]
	s_mov_b32 m0, s43
	s_nop 0
	global_load_lds_dwordx4 v[246:247], off
	s_mov_b32 m0, s44
	s_nop 0
	global_load_lds_dwordx4 v[248:249], off
	s_waitcnt vmcnt(8)
	s_waitcnt lgkmcnt(0)
	s_cmp_eq_u32 s100, 0
	s_cbranch_scc1 .Lmy_h2_67
	s_setprio 1
	s_barrier
.Lmy_h2_67:
	v_mfma_f32_16x16x32_bf16 v[50:53], v[148:151], v[198:201], v[50:53]
	v_mfma_f32_16x16x32_bf16 v[38:41], v[162:165], v[198:201], v[38:41]
	v_mfma_f32_16x16x32_bf16 v[22:25], v[148:151], v[206:209], v[22:25]
	v_mfma_f32_16x16x32_bf16 v[42:45], v[162:165], v[206:209], v[42:45]
	v_mfma_f32_16x16x32_bf16 v[30:33], v[148:151], v[214:217], v[30:33]
	v_mfma_f32_16x16x32_bf16 v[18:21], v[162:165], v[214:217], v[18:21]
	v_mfma_f32_16x16x32_bf16 v[10:13], v[148:151], v[238:241], v[10:13]
	v_mfma_f32_16x16x32_bf16 v[2:5], v[162:165], v[238:241], v[2:5]
	v_mfma_f32_16x16x32_bf16 v[50:53], v[158:161], v[202:205], v[50:53]
	v_mfma_f32_16x16x32_bf16 v[38:41], v[166:169], v[202:205], v[38:41]
	v_mfma_f32_16x16x32_bf16 v[22:25], v[158:161], v[210:213], v[22:25]
	v_mfma_f32_16x16x32_bf16 v[42:45], v[166:169], v[210:213], v[42:45]
	v_mfma_f32_16x16x32_bf16 v[30:33], v[158:161], v[218:221], v[30:33]
	v_mfma_f32_16x16x32_bf16 v[18:21], v[166:169], v[218:221], v[18:21]
	v_mfma_f32_16x16x32_bf16 v[10:13], v[158:161], v[242:245], v[10:13]
	v_mfma_f32_16x16x32_bf16 v[2:5], v[166:169], v[242:245], v[2:5]
	v_mfma_f32_16x16x32_bf16 v[46:49], v[170:173], v[198:201], v[46:49]
	v_mfma_f32_16x16x32_bf16 v[58:61], v[190:193], v[198:201], v[58:61]
	v_mfma_f32_16x16x32_bf16 v[62:65], v[170:173], v[206:209], v[62:65]
	v_mfma_f32_16x16x32_bf16 v[66:69], v[190:193], v[206:209], v[66:69]
	v_mfma_f32_16x16x32_bf16 v[26:29], v[170:173], v[214:217], v[26:29]
	v_mfma_f32_16x16x32_bf16 v[34:37], v[190:193], v[214:217], v[34:37]
	v_mfma_f32_16x16x32_bf16 v[6:9], v[170:173], v[238:241], v[6:9]
	v_mfma_f32_16x16x32_bf16 v[14:17], v[190:193], v[238:241], v[14:17]
	v_mfma_f32_16x16x32_bf16 v[46:49], v[174:177], v[202:205], v[46:49]
	v_mfma_f32_16x16x32_bf16 v[58:61], v[194:197], v[202:205], v[58:61]
	v_mfma_f32_16x16x32_bf16 v[62:65], v[174:177], v[210:213], v[62:65]
	v_mfma_f32_16x16x32_bf16 v[66:69], v[194:197], v[210:213], v[66:69]
	v_mfma_f32_16x16x32_bf16 v[26:29], v[174:177], v[218:221], v[26:29]
	v_mfma_f32_16x16x32_bf16 v[34:37], v[194:197], v[218:221], v[34:37]
	v_mfma_f32_16x16x32_bf16 v[6:9], v[174:177], v[242:245], v[6:9]
	v_mfma_f32_16x16x32_bf16 v[14:17], v[194:197], v[242:245], v[14:17]
	s_cmp_lg_u32 s100, 0
	s_cbranch_scc1 .Lmy_h2_68
	s_barrier
.Lmy_h2_68:
	s_setprio 0
	s_add_i32 s58, 0, 0x18000
	s_add_i32 s59, 0, 0x1c000
	v_add_u32_e32 v166, s58, v156
	v_add_u32_e32 v194, s59, v156
	ds_read_b128 v[148:151], v166
	ds_read_b128 v[158:161], v166 offset:1024
	ds_read_b128 v[162:165], v166 offset:2048
	ds_read_b128 v[166:169], v166 offset:3072
	ds_read_b128 v[170:173], v194
	ds_read_b128 v[174:177], v194 offset:1024
	ds_read_b128 v[190:193], v194 offset:2048
	ds_read_b128 v[194:197], v194 offset:3072
	s_add_u32 s26, s34, 0x158000
	s_addc_u32 s27, s35, 0
	s_mov_b32 m0, s45
	v_lshl_add_u64 v[250:251], s[26:27], 0, v[134:135]
	ds_read_b128 v[198:201], v157 offset:32768
	ds_read_b128 v[202:205], v157 offset:33792
	ds_read_b128 v[206:209], v157 offset:34816
	ds_read_b128 v[210:213], v157 offset:35840
	ds_read_b128 v[214:217], v157 offset:36864
	ds_read_b128 v[218:221], v157 offset:37888
	ds_read_b128 v[238:241], v157 offset:38912
	ds_read_b128 v[242:245], v157 offset:39936
	global_load_lds_dwordx4 v[250:251], off
	v_lshl_add_u64 v[250:251], s[26:27], 0, v[138:139]
	s_mov_b32 m0, s47
	s_nop 0
	global_load_lds_dwordx4 v[250:251], off
	s_waitcnt vmcnt(8)
	s_waitcnt lgkmcnt(0)
	s_cmp_eq_u32 s100, 0
	s_cbranch_scc1 .Lmy_h2_69
	s_setprio 1
	s_barrier

.Lmy_h2_70:
	s_setprio 0
	s_add_i32 s26, s58, s40
	v_lshl_add_u64 v[178:179], v[178:179], 0, s[16:17]
	s_mov_b32 m0, s26
	ds_read_b128 v[198:201], v157 offset:49152
	ds_read_b128 v[202:205], v157 offset:50176
	ds_read_b128 v[206:209], v157 offset:51200
	ds_read_b128 v[210:213], v157 offset:52224
	ds_read_b128 v[214:217], v157 offset:53248
	ds_read_b128 v[218:221], v157 offset:54272
	ds_read_b128 v[238:241], v157 offset:55296
	ds_read_b128 v[242:245], v157 offset:56320
	global_load_lds_dwordx4 v[178:179], off
	s_add_i32 m0, s26, 0x2000
	s_add_u32 s26, s30, 0x158080
	v_lshl_add_u64 v[178:179], v[222:223], 0, s[16:17]
	s_addc_u32 s27, s31, 0
	s_add_i32 s30, s59, s40
	global_load_lds_dwordx4 v[178:179], off
	v_lshl_add_u64 v[178:179], s[26:27], 0, v[136:137]
	s_mov_b32 m0, s30
	s_nop 0
	global_load_lds_dwordx4 v[178:179], off
	v_lshl_add_u64 v[178:179], s[26:27], 0, v[140:141]
	s_add_i32 m0, s30, 0x2000
	s_nop 0
	global_load_lds_dwordx4 v[178:179], off
	v_lshl_add_u64 v[178:179], v[246:247], 0, s[16:17]
	s_mov_b32 m0, s48
	s_nop 0
	global_load_lds_dwordx4 v[178:179], off
	v_lshl_add_u64 v[178:179], v[248:249], 0, s[16:17]
	s_mov_b32 m0, s49
	s_nop 0
	global_load_lds_dwordx4 v[178:179], off
	s_waitcnt vmcnt(8)
	s_waitcnt lgkmcnt(0)
	s_cmp_eq_u32 s100, 0
	s_cbranch_scc1 .Lmy_h2_71
	s_setprio 1
	s_barrier

.Lmy_h2_72:
	s_setprio 0
	s_add_i32 s57, s57, 2
	s_add_u32 s38, s38, 0x100
	s_addc_u32 s39, s39, 0
	s_cmpk_gt_u32 s57, 0x53
	s_mov_b64 s[26:27], s[28:29]
	s_cbranch_scc0 .LBB0_2241
	s_and_b64 vcc, exec, s[18:19]
	s_cbranch_vccz .LBB0_2244

.LBB0_2260:
	s_or_b64 exec, exec, s[26:27]
	s_and_b64 vcc, exec, s[36:37]
	s_mov_b64 s[26:27], -1
	s_cbranch_vccnz .LBB0_2229
	v_lshl_add_u32 v2, s54, 8, v155
	s_waitcnt lgkmcnt(0)
	v_ashrrev_i32_e32 v3, 31, v2
	v_lshlrev_b64 v[2:3], 12, v[2:3]
	s_lshl_b32 s26, s51, 8
	v_lshl_add_u64 v[2:3], v[132:133], 0, v[2:3]
	s_ashr_i32 s27, s26, 31
	v_lshl_add_u64 v[2:3], s[26:27], 1, v[2:3]
	v_lshl_add_u64 v[2:3], v[2:3], 0, s[12:13]
	v_lshl_add_u64 v[2:3], v[2:3], 0, v[180:181]
	s_mov_b32 s26, 0x10000
	v_add_co_u32_e32 v4, vcc, s26, v2
	s_mov_b32 s26, 0x20000
	s_nop 0
	v_addc_co_u32_e32 v5, vcc, 0, v3, vcc
	global_load_dwordx4 v[62:65], v[2:3], off
	global_load_dwordx4 v[54:57], v[2:3], off offset:256
	global_load_dwordx4 v[58:61], v[4:5], off
	global_load_dwordx4 v[46:49], v[4:5], off offset:256
	v_add_co_u32_e32 v4, vcc, s26, v2
	s_mov_b32 s26, 0x30000
	s_nop 0
	v_addc_co_u32_e32 v5, vcc, 0, v3, vcc
	global_load_dwordx4 v[50:53], v[4:5], off
	global_load_dwordx4 v[38:41], v[4:5], off offset:256
	v_add_co_u32_e32 v4, vcc, s26, v2
	s_mov_b32 s26, 0x80000
	s_nop 0
	v_addc_co_u32_e32 v5, vcc, 0, v3, vcc
	global_load_dwordx4 v[42:45], v[4:5], off
	global_load_dwordx4 v[30:33], v[4:5], off offset:256
	v_add_co_u32_e32 v4, vcc, s26, v2
	s_mov_b32 s26, 0x90000
	s_nop 0
	v_addc_co_u32_e32 v5, vcc, 0, v3, vcc
	global_load_dwordx4 v[34:37], v[4:5], off
	global_load_dwordx4 v[22:25], v[4:5], off offset:256
	v_add_co_u32_e32 v4, vcc, s26, v2
	s_nop 1
	v_addc_co_u32_e32 v5, vcc, 0, v3, vcc
	global_load_dwordx4 v[26:29], v[4:5], off
	global_load_dwordx4 v[18:21], v[4:5], off offset:256
	v_add_co_u32_e32 v4, vcc, 0xa0000, v2
	s_nop 1
	v_addc_co_u32_e32 v5, vcc, 0, v3, vcc
	v_add_co_u32_e32 v14, vcc, 0xb0000, v2
	global_load_dwordx4 v[10:13], v[4:5], off
	global_load_dwordx4 v[6:9], v[4:5], off offset:256
	v_addc_co_u32_e32 v15, vcc, 0, v3, vcc
	global_load_dwordx4 v[2:5], v[14:15], off
	s_nop 0
	global_load_dwordx4 v[14:17], v[14:15], off offset:256
	s_andn2_b64 vcc, exec, s[14:15]
	s_cbranch_vccnz .LBB0_2228
	s_branch .LBB0_2228

.LBB0_2276:
	s_andn2_b64 vcc, exec, s[18:19]
	s_cbranch_vccnz .LBB0_2330
	v_ashrrev_i32_e32 v4, 31, v2
	v_lshrrev_b32_e32 v4, 26, v4
	v_add_u32_e32 v4, v2, v4
	v_ashrrev_i32_e32 v132, 6, v4
	v_bfe_i32 v4, v2, 27, 1
	s_waitcnt lgkmcnt(0)
	v_lshlrev_b32_e32 v3, 4, v2
	v_lshrrev_b32_e32 v4, 22, v4
	v_add_u32_e32 v4, v3, v4
	v_and_b32_e32 v4, 0xfffffc00, v4
	v_sub_u32_e32 v4, v3, v4
	v_lshrrev_b32_e32 v5, 4, v4
	v_bitop3_b32 v4, v5, v4, 32 bitop3:0x6c
	v_ashrrev_i32_e32 v6, 31, v4
	v_lshrrev_b32_e32 v6, 26, v6
	v_lshlrev_b32_e32 v5, 3, v132
	v_add_u32_e32 v6, v4, v6
	v_and_b32_e32 v5, -16, v5
	v_ashrrev_i32_e32 v134, 6, v6
	v_and_b32_e32 v6, 0xc0, v6
	s_mov_b64 s[18:19], 0x1de00000
	v_add_u32_e32 v5, v134, v5
	v_lshlrev_b32_e32 v7, 5, v132
	v_sub_u32_e32 v4, v4, v6
	v_lshl_add_u64 v[146:147], v[130:131], 0, s[18:19]
	v_and_b32_e32 v133, 32, v7
	v_ashrrev_i16_sdwa v4, v224, sext(v4) dst_sel:DWORD dst_unused:UNUSED_PAD src0_sel:DWORD src1_sel:BYTE_0
	v_lshlrev_b32_e32 v6, 1, v5
	v_lshrrev_b32_e32 v7, 2, v5
	v_and_b32_e32 v8, 3, v134
	s_mov_b32 s18, 0x1ffffe0
	v_bfe_i32 v135, v4, 0, 16
	v_and_b32_e32 v6, 24, v6
	v_and_b32_e32 v7, 4, v7
	v_and_or_b32 v8, v5, s18, v8
	s_movk_i32 s12, 0x1580
	v_add_u32_e32 v4, v133, v135
	v_or3_b32 v6, v8, v7, v6
	v_mul_lo_u32 v5, v5, s12
	v_add_lshl_u32 v148, v4, v5, 1
	v_mul_lo_u32 v5, v6, s12
	v_add_u32_e32 v3, 0x2000, v3
	v_add_lshl_u32 v150, v5, v4, 1
	v_ashrrev_i32_e32 v4, 31, v3
	v_lshrrev_b32_e32 v4, 22, v4
	v_add_u32_e32 v4, v3, v4
	v_ashrrev_i32_e32 v136, 10, v4
	v_mul_i32_i24_e32 v4, 0x400, v136
	v_sub_u32_e32 v3, v3, v4
	v_lshrrev_b32_e32 v4, 4, v3
	v_bitop3_b32 v3, v4, v3, 32 bitop3:0x6c
	v_ashrrev_i32_e32 v5, 31, v3
	v_lshrrev_b32_e32 v5, 26, v5
	v_lshlrev_b32_e32 v4, 3, v136
	v_add_u32_e32 v5, v3, v5
	v_and_b32_e32 v4, -16, v4
	v_ashrrev_i32_e32 v138, 6, v5
	v_and_b32_e32 v5, 0xc0, v5
	v_add_u32_e32 v4, v138, v4
	v_lshlrev_b32_e32 v6, 5, v136
	v_sub_u32_e32 v3, v3, v5
	v_and_b32_e32 v137, 32, v6
	v_ashrrev_i16_sdwa v3, v224, sext(v3) dst_sel:DWORD dst_unused:UNUSED_PAD src0_sel:DWORD src1_sel:BYTE_0
	v_lshlrev_b32_e32 v5, 1, v4
	v_lshrrev_b32_e32 v6, 2, v4
	v_and_b32_e32 v7, 3, v138
	v_bfe_i32 v139, v3, 0, 16
	v_and_b32_e32 v5, 24, v5
	v_and_b32_e32 v6, 4, v6
	v_and_or_b32 v7, v4, s18, v7
	v_add_u32_e32 v3, v137, v139
	v_or3_b32 v5, v7, v6, v5
	v_mul_lo_u32 v4, v4, s12
	v_add_lshl_u32 v152, v3, v4, 1
	v_mul_lo_u32 v4, v5, s12
	s_ashr_i32 s12, s24, 6
	s_ashr_i32 s22, s24, 8
	s_lshl_b32 s21, s12, 10
	s_lshl_b32 s12, s12, 5
	s_lshl_b32 s54, s22, 6
	s_and_b32 s55, s12, 0x60
	s_lshl_b32 s12, s42, 8
	v_and_b32_e32 v197, 15, v2
	s_add_i32 s12, s12, s54
	v_bfe_u32 v198, v2, 4, 2
	v_or_b32_e32 v2, s12, v197
	v_add_lshl_u32 v154, v4, v3, 1
	v_ashrrev_i32_e32 v3, 31, v2
	v_lshlrev_b64 v[2:3], 12, v[2:3]
	s_lshl_b32 s18, s66, 8
	v_lshl_add_u64 v[2:3], v[146:147], 0, v[2:3]
	s_ashr_i32 s19, s18, 31
	v_lshl_add_u64 v[2:3], s[18:19], 1, v[2:3]
	s_lshl_b32 s12, s55, 1
	v_lshl_add_u64 v[2:3], v[2:3], 0, s[12:13]
	v_lshlrev_b32_e32 v180, 4, v198
	v_lshl_add_u64 v[6:7], v[2:3], 0, v[180:181]
	s_mov_b32 s18, 0x10000
	v_add_co_u32_e32 v2, vcc, s18, v6
	s_mov_b32 s18, 0x20000
	s_nop 0
	v_addc_co_u32_e32 v3, vcc, 0, v7, vcc
	global_load_dwordx4 v[62:65], v[6:7], off
	global_load_dwordx4 v[58:61], v[6:7], off offset:256
	global_load_dwordx4 v[54:57], v[2:3], off
	global_load_dwordx4 v[50:53], v[2:3], off offset:256
	v_add_co_u32_e32 v2, vcc, s18, v6
	s_mov_b32 s18, 0x30000
	s_nop 0
	v_addc_co_u32_e32 v3, vcc, 0, v7, vcc
	global_load_dwordx4 v[46:49], v[2:3], off
	global_load_dwordx4 v[30:33], v[2:3], off offset:256
	v_add_co_u32_e32 v2, vcc, s18, v6
	s_mov_b32 s18, 0x80000
	s_nop 0
	v_addc_co_u32_e32 v3, vcc, 0, v7, vcc
	global_load_dwordx4 v[34:37], v[2:3], off
	global_load_dwordx4 v[22:25], v[2:3], off offset:256
	v_add_co_u32_e32 v2, vcc, s18, v6
	s_mov_b32 s18, 0x90000
	s_nop 0
	v_addc_co_u32_e32 v3, vcc, 0, v7, vcc
	global_load_dwordx4 v[26:29], v[2:3], off
	global_load_dwordx4 v[10:13], v[2:3], off offset:256
	v_add_co_u32_e32 v2, vcc, s18, v6
	s_mov_b32 s18, 0xa0000
	s_nop 0
	v_addc_co_u32_e32 v3, vcc, 0, v7, vcc
	global_load_dwordx4 v[42:45], v[2:3], off
	global_load_dwordx4 v[38:41], v[2:3], off offset:256
	v_add_co_u32_e32 v2, vcc, s18, v6
	s_mov_b32 s18, 0xb0000
	s_nop 0
	v_addc_co_u32_e32 v3, vcc, 0, v7, vcc
	s_mul_i32 s19, s66, 0x2b0000
	v_add_co_u32_e32 v18, vcc, s18, v6
	s_mul_hi_i32 s18, s66, 0x2b0000
	s_add_u32 s30, s8, s19
	s_addc_u32 s31, s9, s18
	s_add_i32 s56, s21, 0
	v_addc_co_u32_e32 v19, vcc, 0, v7, vcc
	s_add_i32 m0, s56, 0x10000
	global_load_dwordx4 v[14:17], v[2:3], off
	s_nop 0
	global_load_dwordx4 v[2:5], v[2:3], off offset:256
	s_nop 0
	global_load_dwordx4 v[6:9], v[18:19], off
	s_nop 0
	global_load_dwordx4 v[18:21], v[18:19], off offset:256
	s_mul_i32 s25, s42, 0x2b0000
	global_load_lds_dwordx4 v150, s[30:31]
	s_add_i32 m0, s56, 0x12000
	s_add_u32 s18, s30, 0x158000
	global_load_lds_dwordx4 v154, s[30:31]
	s_addc_u32 s19, s31, 0
	s_add_i32 m0, s56, 0x14000
	s_mul_hi_i32 s23, s42, 0x2b0000
	global_load_lds_dwordx4 v150, s[18:19]
	s_add_i32 m0, s56, 0x16000
	s_add_u32 s28, s6, s25
	s_addc_u32 s29, s7, s23
	s_add_i32 s57, s56, 0x2000
	global_load_lds_dwordx4 v154, s[18:19]
	s_mov_b32 m0, s56
	s_add_u32 s18, s28, 0x158000
	global_load_lds_dwordx4 v148, s[28:29]
	s_mov_b32 m0, s57
	s_addc_u32 s19, s29, 0
	s_add_i32 s58, s56, 0x4000
	global_load_lds_dwordx4 v152, s[28:29]
	s_mov_b32 m0, s58
	s_add_i32 s59, s56, 0x6000
	global_load_lds_dwordx4 v148, s[18:19]
	s_mov_b32 m0, s59
	v_mov_b32_e32 v151, v181
	global_load_lds_dwordx4 v152, s[18:19]
	v_mov_b32_e32 v155, v181
	v_mov_b32_e32 v149, v181
	v_mov_b32_e32 v153, v181
	s_cmp_eq_u32 s22, 1
	v_lshl_add_u64 v[80:81], s[30:31], 0, v[150:151]
	v_lshl_add_u64 v[78:79], s[30:31], 0, v[154:155]
	v_lshl_add_u64 v[66:67], s[28:29], 0, v[148:149]
	s_cselect_b64 s[18:19], -1, 0
	s_cmp_lg_u32 s22, 1
	v_lshl_add_u64 v[68:69], s[28:29], 0, v[152:153]
	s_cbranch_scc1 .LBB0_2279
.LBB0_2279:
	s_waitcnt vmcnt(0)
	v_lshlrev_b32_e32 v106, 16, v50
	v_and_b32_e32 v107, 0xffff0000, v50
	v_lshlrev_b32_e32 v108, 16, v51
	v_and_b32_e32 v109, 0xffff0000, v51
	v_lshlrev_b32_e32 v110, 16, v52
	v_and_b32_e32 v111, 0xffff0000, v52
	v_lshlrev_b32_e32 v112, 16, v53
	v_and_b32_e32 v113, 0xffff0000, v53
	v_lshlrev_b32_e32 v50, 16, v12
	v_and_b32_e32 v51, 0xffff0000, v12
	v_lshlrev_b32_e32 v52, 16, v13
	v_and_b32_e32 v53, 0xffff0000, v13
	s_add_i32 m0, s56, 0x18000
	v_lshl_add_u64 v[12:13], v[80:81], 0, s[16:17]
	s_lshl_b32 s25, s22, 13
	s_lshl_b32 s26, s55, 7
	s_waitcnt vmcnt(2)
	s_barrier
	global_load_lds_dwordx4 v[12:13], off
	v_lshl_add_u64 v[12:13], v[78:79], 0, s[16:17]
	s_add_i32 m0, s56, 0x1a000
	s_add_i32 s60, s56, 0x8000
	s_add_i32 s61, s56, 0xa000
	global_load_lds_dwordx4 v[12:13], off
	v_lshl_add_u64 v[12:13], v[66:67], 0, s[16:17]
	s_mov_b32 m0, s60
	s_add_u32 s22, s30, 0x158080
	global_load_lds_dwordx4 v[12:13], off
	v_lshl_add_u64 v[12:13], v[68:69], 0, s[16:17]
	s_mov_b32 m0, s61
	s_addc_u32 s23, s31, 0
	global_load_lds_dwordx4 v[12:13], off
	s_add_i32 m0, s56, 0x1c000
	v_lshl_add_u64 v[12:13], s[22:23], 0, v[150:151]
	global_load_lds_dwordx4 v[12:13], off
	v_lshl_add_u64 v[12:13], s[22:23], 0, v[154:155]
	s_add_i32 m0, s56, 0x1e000
	s_mov_b64 s[22:23], 0x94000
	global_load_lds_dwordx4 v[12:13], off
	v_lshl_add_u64 v[156:157], v[130:131], 0, s[22:23]
	s_mov_b64 s[22:23], 0x9000
	v_or_b32_e32 v199, s54, v197
	v_lshl_add_u64 v[158:159], v[130:131], 0, s[22:23]
	v_lshlrev_b32_e32 v130, 6, v199
	s_movk_i32 s22, 0x3c0
	v_lshlrev_b32_e32 v131, 2, v199
	v_and_or_b32 v130, v130, s22, v180
	v_and_b32_e32 v131, 32, v131
	v_bitop3_b32 v141, v130, s25, v131 bitop3:0xde
	v_lshlrev_b32_e32 v131, 2, v197
	v_lshl_or_b32 v130, v197, 6, v180
	v_and_b32_e32 v131, 32, v131
	v_bitop3_b32 v200, v130, s26, v131 bitop3:0xde
	s_movk_i32 s26, 0x1580
	v_lshrrev_b32_e32 v131, 1, v132
	v_mul_lo_u32 v130, v134, s26
	s_mov_b32 s27, 0x15800
	s_cmpk_lt_u32 s24, 0x100
	v_mad_u64_u32 v[130:131], s[24:25], v131, s27, v[130:131]
	v_or_b32_e32 v130, v130, v133
	v_add_lshl_u32 v180, v130, v135, 1
	v_lshrrev_b32_e32 v131, 1, v136
	v_mul_lo_u32 v130, v138, s26
	v_mad_u64_u32 v[130:131], s[24:25], v131, s27, v[130:131]
	s_waitcnt vmcnt(6)
	s_mov_b64 s[34:35], 0x158080
	v_or_b32_e32 v130, v130, v137
	v_lshlrev_b32_e32 v140, 3, v198
	v_lshl_add_u64 v[160:161], v[180:181], 0, s[34:35]
	v_add_lshl_u32 v180, v130, v139, 1
	v_lshlrev_b32_e32 v118, 16, v62
	v_and_b32_e32 v119, 0xffff0000, v62
	v_lshlrev_b32_e32 v120, 16, v63
	v_and_b32_e32 v121, 0xffff0000, v63
	v_lshlrev_b32_e32 v114, 16, v64
	v_and_b32_e32 v115, 0xffff0000, v64
	v_lshlrev_b32_e32 v116, 16, v65
	v_and_b32_e32 v117, 0xffff0000, v65
	v_lshlrev_b32_e32 v126, 16, v58
	v_and_b32_e32 v127, 0xffff0000, v58
	v_lshlrev_b32_e32 v128, 16, v59
	v_and_b32_e32 v129, 0xffff0000, v59
	v_lshlrev_b32_e32 v122, 16, v60
	v_and_b32_e32 v123, 0xffff0000, v60
	v_lshlrev_b32_e32 v124, 16, v61
	v_and_b32_e32 v125, 0xffff0000, v61
	v_lshlrev_b32_e32 v98, 16, v54
	v_and_b32_e32 v99, 0xffff0000, v54
	v_lshlrev_b32_e32 v100, 16, v55
	v_and_b32_e32 v101, 0xffff0000, v55
	v_lshlrev_b32_e32 v102, 16, v56
	v_and_b32_e32 v103, 0xffff0000, v56
	v_lshlrev_b32_e32 v104, 16, v57
	v_and_b32_e32 v105, 0xffff0000, v57
	v_lshlrev_b32_e32 v70, 16, v46
	v_and_b32_e32 v71, 0xffff0000, v46
	v_lshlrev_b32_e32 v72, 16, v47
	v_and_b32_e32 v73, 0xffff0000, v47
	v_lshlrev_b32_e32 v74, 16, v48
	v_and_b32_e32 v75, 0xffff0000, v48
	v_lshlrev_b32_e32 v76, 16, v49
	v_and_b32_e32 v77, 0xffff0000, v49
	v_lshlrev_b32_e32 v82, 16, v30
	v_and_b32_e32 v83, 0xffff0000, v30
	v_lshlrev_b32_e32 v84, 16, v31
	v_and_b32_e32 v85, 0xffff0000, v31
	v_lshlrev_b32_e32 v86, 16, v32
	v_and_b32_e32 v87, 0xffff0000, v32
	v_lshlrev_b32_e32 v88, 16, v33
	v_and_b32_e32 v89, 0xffff0000, v33
	v_lshlrev_b32_e32 v30, 16, v34
	v_and_b32_e32 v31, 0xffff0000, v34
	v_lshlrev_b32_e32 v32, 16, v35
	v_and_b32_e32 v33, 0xffff0000, v35
	v_lshlrev_b32_e32 v34, 16, v36
	v_and_b32_e32 v35, 0xffff0000, v36
	v_lshlrev_b32_e32 v36, 16, v37
	v_and_b32_e32 v37, 0xffff0000, v37
	v_lshlrev_b32_e32 v54, 16, v22
	v_and_b32_e32 v55, 0xffff0000, v22
	v_lshlrev_b32_e32 v56, 16, v23
	v_and_b32_e32 v57, 0xffff0000, v23
	v_lshlrev_b32_e32 v58, 16, v24
	v_and_b32_e32 v59, 0xffff0000, v24
	v_lshlrev_b32_e32 v60, 16, v25
	v_and_b32_e32 v61, 0xffff0000, v25
	v_lshlrev_b32_e32 v22, 16, v26
	v_and_b32_e32 v23, 0xffff0000, v26
	v_lshlrev_b32_e32 v24, 16, v27
	v_and_b32_e32 v25, 0xffff0000, v27
	v_lshlrev_b32_e32 v26, 16, v28
	v_and_b32_e32 v27, 0xffff0000, v28
	v_lshlrev_b32_e32 v28, 16, v29
	v_and_b32_e32 v29, 0xffff0000, v29
	v_lshlrev_b32_e32 v46, 16, v10
	v_and_b32_e32 v47, 0xffff0000, v10
	v_lshlrev_b32_e32 v48, 16, v11
	v_and_b32_e32 v49, 0xffff0000, v11
	v_lshlrev_b32_e32 v10, 16, v42
	v_and_b32_e32 v11, 0xffff0000, v42
	v_lshlrev_b32_e32 v12, 16, v43
	v_and_b32_e32 v13, 0xffff0000, v43
	v_lshlrev_b32_e32 v78, 16, v44
	v_and_b32_e32 v79, 0xffff0000, v44
	v_lshlrev_b32_e32 v80, 16, v45
	v_and_b32_e32 v81, 0xffff0000, v45
	v_lshlrev_b32_e32 v90, 16, v38
	v_and_b32_e32 v91, 0xffff0000, v38
	v_lshlrev_b32_e32 v92, 16, v39
	v_and_b32_e32 v93, 0xffff0000, v39
	v_lshlrev_b32_e32 v94, 16, v40
	v_and_b32_e32 v95, 0xffff0000, v40
	v_lshlrev_b32_e32 v96, 16, v41
	v_and_b32_e32 v97, 0xffff0000, v41
	v_lshlrev_b32_e32 v38, 16, v14
	v_and_b32_e32 v39, 0xffff0000, v14
	v_lshlrev_b32_e32 v40, 16, v15
	v_and_b32_e32 v41, 0xffff0000, v15
	v_lshlrev_b32_e32 v42, 16, v16
	v_and_b32_e32 v43, 0xffff0000, v16
	v_lshlrev_b32_e32 v44, 16, v17
	v_and_b32_e32 v45, 0xffff0000, v17
	v_lshlrev_b32_e32 v62, 16, v2
	v_and_b32_e32 v63, 0xffff0000, v2
	v_lshlrev_b32_e32 v64, 16, v3
	v_and_b32_e32 v65, 0xffff0000, v3
	v_lshlrev_b32_e32 v66, 16, v4
	v_and_b32_e32 v67, 0xffff0000, v4
	v_lshlrev_b32_e32 v68, 16, v5
	v_and_b32_e32 v69, 0xffff0000, v5
	v_lshlrev_b32_e32 v2, 16, v6
	v_and_b32_e32 v3, 0xffff0000, v6
	v_lshlrev_b32_e32 v4, 16, v7
	v_and_b32_e32 v5, 0xffff0000, v7
	v_lshlrev_b32_e32 v6, 16, v8
	v_and_b32_e32 v7, 0xffff0000, v8
	v_lshlrev_b32_e32 v8, 16, v9
	v_and_b32_e32 v9, 0xffff0000, v9
	v_lshlrev_b32_e32 v14, 16, v18
	v_and_b32_e32 v15, 0xffff0000, v18
	v_lshlrev_b32_e32 v16, 16, v19
	v_and_b32_e32 v17, 0xffff0000, v19
	v_lshlrev_b32_e32 v18, 16, v20
	v_and_b32_e32 v19, 0xffff0000, v20
	v_lshlrev_b32_e32 v20, 16, v21
	v_and_b32_e32 v21, 0xffff0000, v21
	s_cselect_b64 s[22:23], -1, 0
	v_lshl_add_u64 v[162:163], v[180:181], 0, s[34:35]
	s_mov_b32 s62, 0
	v_add_u32_e32 v201, 0, v141
	v_lshlrev_b32_e32 v180, 1, v140
	s_barrier
	s_branch .LBB0_2282

.LBB0_2293:
	s_add_u32 s30, s28, 0x100
	s_addc_u32 s31, s29, 0
	s_add_i32 s46, 0, 0x10000
	s_cmpk_eq_i32 s45, 0x52
	s_cselect_b32 s39, s25, s31
	s_cselect_b32 s38, s24, s30
	s_cselect_b32 s35, s27, s44
	s_cselect_b32 s34, s26, s43
	s_add_i32 s47, 0, 0x14000
	v_add_u32_e32 v142, s46, v200
	v_add_u32_e32 v176, s47, v200
	ds_read_b128 v[130:133], v142
	ds_read_b128 v[134:137], v142 offset:1024
	ds_read_b128 v[138:141], v142 offset:2048
	ds_read_b128 v[142:145], v142 offset:3072
	ds_read_b128 v[164:167], v176
	ds_read_b128 v[168:171], v176 offset:1024
	ds_read_b128 v[172:175], v176 offset:2048
	ds_read_b128 v[176:179], v176 offset:3072
	v_lshl_add_u64 v[222:223], s[28:29], 0, v[160:161]
	s_add_i32 m0, s56, 0xc000
	ds_read_b128 v[190:193], v201
	ds_read_b128 v[202:205], v201 offset:1024
	ds_read_b128 v[206:209], v201 offset:2048
	ds_read_b128 v[210:213], v201 offset:3072
	ds_read_b128 v[214:217], v201 offset:4096
	ds_read_b128 v[218:221], v201 offset:5120
	ds_read_b128 v[238:241], v201 offset:6144
	ds_read_b128 v[242:245], v201 offset:7168
	global_load_lds_dwordx4 v[222:223], off
	v_lshl_add_u64 v[222:223], s[28:29], 0, v[162:163]
	s_add_i32 m0, s56, 0xe000
	s_nop 0
	global_load_lds_dwordx4 v[222:223], off
	s_waitcnt vmcnt(8)
	s_waitcnt lgkmcnt(0)
	s_cmp_eq_u32 s100, 0
	s_cbranch_scc1 .Lmy_h2_73
	s_setprio 1
	s_barrier
.Lmy_h2_73:
	v_mfma_f32_16x16x32_bf16 v[118:121], v[130:133], v[190:193], v[118:121]
	v_mfma_f32_16x16x32_bf16 v[114:117], v[138:141], v[190:193], v[114:117]
	v_mfma_f32_16x16x32_bf16 v[98:101], v[130:133], v[206:209], v[98:101]
	v_mfma_f32_16x16x32_bf16 v[102:105], v[138:141], v[206:209], v[102:105]
	v_mfma_f32_16x16x32_bf16 v[70:73], v[130:133], v[214:217], v[70:73]
	v_mfma_f32_16x16x32_bf16 v[74:77], v[138:141], v[214:217], v[74:77]
	v_mfma_f32_16x16x32_bf16 v[30:33], v[130:133], v[238:241], v[30:33]
	v_mfma_f32_16x16x32_bf16 v[34:37], v[138:141], v[238:241], v[34:37]
	v_mfma_f32_16x16x32_bf16 v[118:121], v[134:137], v[202:205], v[118:121]
	v_mfma_f32_16x16x32_bf16 v[114:117], v[142:145], v[202:205], v[114:117]
	v_mfma_f32_16x16x32_bf16 v[98:101], v[134:137], v[210:213], v[98:101]
	v_mfma_f32_16x16x32_bf16 v[102:105], v[142:145], v[210:213], v[102:105]
	v_mfma_f32_16x16x32_bf16 v[70:73], v[134:137], v[218:221], v[70:73]
	v_mfma_f32_16x16x32_bf16 v[74:77], v[142:145], v[218:221], v[74:77]
	v_mfma_f32_16x16x32_bf16 v[30:33], v[134:137], v[242:245], v[30:33]
	v_mfma_f32_16x16x32_bf16 v[34:37], v[142:145], v[242:245], v[34:37]
	v_mfma_f32_16x16x32_bf16 v[126:129], v[164:167], v[190:193], v[126:129]
	v_mfma_f32_16x16x32_bf16 v[122:125], v[172:175], v[190:193], v[122:125]
	v_mfma_f32_16x16x32_bf16 v[106:109], v[164:167], v[206:209], v[106:109]
	v_mfma_f32_16x16x32_bf16 v[110:113], v[172:175], v[206:209], v[110:113]
	v_mfma_f32_16x16x32_bf16 v[82:85], v[164:167], v[214:217], v[82:85]
	v_mfma_f32_16x16x32_bf16 v[86:89], v[172:175], v[214:217], v[86:89]
	v_mfma_f32_16x16x32_bf16 v[54:57], v[164:167], v[238:241], v[54:57]
	v_mfma_f32_16x16x32_bf16 v[58:61], v[172:175], v[238:241], v[58:61]
	v_mfma_f32_16x16x32_bf16 v[126:129], v[168:171], v[202:205], v[126:129]
	v_mfma_f32_16x16x32_bf16 v[122:125], v[176:179], v[202:205], v[122:125]
	v_mfma_f32_16x16x32_bf16 v[106:109], v[168:171], v[210:213], v[106:109]
	v_mfma_f32_16x16x32_bf16 v[110:113], v[176:179], v[210:213], v[110:113]
	v_mfma_f32_16x16x32_bf16 v[82:85], v[168:171], v[218:221], v[82:85]
	v_mfma_f32_16x16x32_bf16 v[86:89], v[176:179], v[218:221], v[86:89]
	v_mfma_f32_16x16x32_bf16 v[54:57], v[168:171], v[242:245], v[54:57]
	v_mfma_f32_16x16x32_bf16 v[58:61], v[176:179], v[242:245], v[58:61]
	s_cmp_lg_u32 s100, 0
	s_cbranch_scc1 .Lmy_h2_74
	s_barrier
.Lmy_h2_74:
	s_setprio 0
	s_add_i32 s28, s46, s21
	v_lshl_add_u64 v[222:223], s[34:35], 0, v[150:151]
	s_mov_b32 m0, s28
	ds_read_b128 v[190:193], v201 offset:16384
	ds_read_b128 v[202:205], v201 offset:17408
	ds_read_b128 v[206:209], v201 offset:18432
	ds_read_b128 v[210:213], v201 offset:19456
	ds_read_b128 v[214:217], v201 offset:20480
	ds_read_b128 v[218:221], v201 offset:21504
	ds_read_b128 v[238:241], v201 offset:22528
	ds_read_b128 v[242:245], v201 offset:23552
	global_load_lds_dwordx4 v[222:223], off
	s_add_i32 m0, s28, 0x2000
	s_add_u32 s28, s34, 0x158000
	v_lshl_add_u64 v[246:247], s[34:35], 0, v[154:155]
	s_addc_u32 s29, s35, 0
	s_add_i32 s46, s47, s21
	global_load_lds_dwordx4 v[246:247], off
	v_lshl_add_u64 v[248:249], s[28:29], 0, v[150:151]
	s_mov_b32 m0, s46
	v_lshl_add_u64 v[250:251], s[38:39], 0, v[152:153]
	global_load_lds_dwordx4 v[248:249], off
	v_lshl_add_u64 v[248:249], s[28:29], 0, v[154:155]
	s_add_i32 m0, s46, 0x2000
	s_nop 0
	global_load_lds_dwordx4 v[248:249], off
	v_lshl_add_u64 v[248:249], s[38:39], 0, v[148:149]
	s_mov_b32 m0, s56
	s_nop 0
	global_load_lds_dwordx4 v[248:249], off
	s_mov_b32 m0, s57
	s_nop 0
	global_load_lds_dwordx4 v[250:251], off
	s_waitcnt vmcnt(8)
	s_waitcnt lgkmcnt(0)
	s_cmp_eq_u32 s100, 0
	s_cbranch_scc1 .Lmy_h2_75
	s_setprio 1
	s_barrier
.Lmy_h2_75:
	v_mfma_f32_16x16x32_bf16 v[22:25], v[130:133], v[190:193], v[22:25]
	v_mfma_f32_16x16x32_bf16 v[26:29], v[138:141], v[190:193], v[26:29]
	v_mfma_f32_16x16x32_bf16 v[10:13], v[130:133], v[206:209], v[10:13]
	v_mfma_f32_16x16x32_bf16 v[78:81], v[138:141], v[206:209], v[78:81]
	v_mfma_f32_16x16x32_bf16 v[38:41], v[130:133], v[214:217], v[38:41]
	v_mfma_f32_16x16x32_bf16 v[42:45], v[138:141], v[214:217], v[42:45]
	v_mfma_f32_16x16x32_bf16 v[2:5], v[130:133], v[238:241], v[2:5]
	v_mfma_f32_16x16x32_bf16 v[6:9], v[138:141], v[238:241], v[6:9]
	v_mfma_f32_16x16x32_bf16 v[22:25], v[134:137], v[202:205], v[22:25]
	v_mfma_f32_16x16x32_bf16 v[26:29], v[142:145], v[202:205], v[26:29]
	v_mfma_f32_16x16x32_bf16 v[10:13], v[134:137], v[210:213], v[10:13]
	v_mfma_f32_16x16x32_bf16 v[78:81], v[142:145], v[210:213], v[78:81]
	v_mfma_f32_16x16x32_bf16 v[38:41], v[134:137], v[218:221], v[38:41]
	v_mfma_f32_16x16x32_bf16 v[42:45], v[142:145], v[218:221], v[42:45]
	v_mfma_f32_16x16x32_bf16 v[2:5], v[134:137], v[242:245], v[2:5]
	v_mfma_f32_16x16x32_bf16 v[6:9], v[142:145], v[242:245], v[6:9]
	v_mfma_f32_16x16x32_bf16 v[46:49], v[164:167], v[190:193], v[46:49]
	v_mfma_f32_16x16x32_bf16 v[50:53], v[172:175], v[190:193], v[50:53]
	v_mfma_f32_16x16x32_bf16 v[90:93], v[164:167], v[206:209], v[90:93]
	v_mfma_f32_16x16x32_bf16 v[94:97], v[172:175], v[206:209], v[94:97]
	v_mfma_f32_16x16x32_bf16 v[62:65], v[164:167], v[214:217], v[62:65]
	v_mfma_f32_16x16x32_bf16 v[66:69], v[172:175], v[214:217], v[66:69]
	v_mfma_f32_16x16x32_bf16 v[14:17], v[164:167], v[238:241], v[14:17]
	v_mfma_f32_16x16x32_bf16 v[18:21], v[172:175], v[238:241], v[18:21]
	v_mfma_f32_16x16x32_bf16 v[46:49], v[168:171], v[202:205], v[46:49]
	v_mfma_f32_16x16x32_bf16 v[50:53], v[176:179], v[202:205], v[50:53]
	v_mfma_f32_16x16x32_bf16 v[90:93], v[168:171], v[210:213], v[90:93]
	v_mfma_f32_16x16x32_bf16 v[94:97], v[176:179], v[210:213], v[94:97]
	v_mfma_f32_16x16x32_bf16 v[62:65], v[168:171], v[218:221], v[62:65]
	v_mfma_f32_16x16x32_bf16 v[66:69], v[176:179], v[218:221], v[66:69]
	v_mfma_f32_16x16x32_bf16 v[14:17], v[168:171], v[242:245], v[14:17]
	v_mfma_f32_16x16x32_bf16 v[18:21], v[176:179], v[242:245], v[18:21]
	s_cmp_lg_u32 s100, 0
	s_cbranch_scc1 .Lmy_h2_76
	s_barrier
.Lmy_h2_76:
	s_setprio 0
	s_add_i32 s46, 0, 0x18000
	s_add_i32 s47, 0, 0x1c000
	v_add_u32_e32 v142, s46, v200
	v_add_u32_e32 v176, s47, v200
	ds_read_b128 v[130:133], v142
	ds_read_b128 v[134:137], v142 offset:1024
	ds_read_b128 v[138:141], v142 offset:2048
	ds_read_b128 v[142:145], v142 offset:3072
	ds_read_b128 v[164:167], v176
	ds_read_b128 v[168:171], v176 offset:1024
	ds_read_b128 v[172:175], v176 offset:2048
	ds_read_b128 v[176:179], v176 offset:3072
	s_add_u32 s28, s38, 0x158000
	s_addc_u32 s29, s39, 0
	s_mov_b32 m0, s58
	v_lshl_add_u64 v[252:253], s[28:29], 0, v[148:149]
	ds_read_b128 v[190:193], v201 offset:32768
	ds_read_b128 v[202:205], v201 offset:33792
	ds_read_b128 v[206:209], v201 offset:34816
	ds_read_b128 v[210:213], v201 offset:35840
	ds_read_b128 v[214:217], v201 offset:36864
	ds_read_b128 v[218:221], v201 offset:37888
	ds_read_b128 v[238:241], v201 offset:38912
	ds_read_b128 v[242:245], v201 offset:39936
	global_load_lds_dwordx4 v[252:253], off
	v_lshl_add_u64 v[252:253], s[28:29], 0, v[152:153]
	s_mov_b32 m0, s59
	s_nop 0
	global_load_lds_dwordx4 v[252:253], off
	s_waitcnt vmcnt(8)
	s_waitcnt lgkmcnt(0)
	s_cmp_eq_u32 s100, 0
	s_cbranch_scc1 .Lmy_h2_77
	s_setprio 1
	s_barrier

.Lmy_h2_78:
	s_setprio 0
	s_add_i32 s28, s46, s21
	v_lshl_add_u64 v[222:223], v[222:223], 0, s[16:17]
	s_mov_b32 m0, s28
	ds_read_b128 v[190:193], v201 offset:49152
	ds_read_b128 v[202:205], v201 offset:50176
	ds_read_b128 v[206:209], v201 offset:51200
	ds_read_b128 v[210:213], v201 offset:52224
	ds_read_b128 v[214:217], v201 offset:53248
	ds_read_b128 v[218:221], v201 offset:54272
	ds_read_b128 v[238:241], v201 offset:55296
	ds_read_b128 v[242:245], v201 offset:56320
	global_load_lds_dwordx4 v[222:223], off
	s_add_i32 m0, s28, 0x2000
	s_add_u32 s28, s34, 0x158080
	v_lshl_add_u64 v[222:223], v[246:247], 0, s[16:17]
	s_addc_u32 s29, s35, 0
	s_add_i32 s34, s47, s21
	global_load_lds_dwordx4 v[222:223], off
	v_lshl_add_u64 v[222:223], s[28:29], 0, v[150:151]
	s_mov_b32 m0, s34
	s_nop 0
	global_load_lds_dwordx4 v[222:223], off
	v_lshl_add_u64 v[222:223], s[28:29], 0, v[154:155]
	s_add_i32 m0, s34, 0x2000
	s_nop 0
	global_load_lds_dwordx4 v[222:223], off
	v_lshl_add_u64 v[222:223], v[248:249], 0, s[16:17]
	s_mov_b32 m0, s60
	s_nop 0
	global_load_lds_dwordx4 v[222:223], off
	v_lshl_add_u64 v[222:223], v[250:251], 0, s[16:17]
	s_mov_b32 m0, s61
	s_nop 0
	global_load_lds_dwordx4 v[222:223], off
	s_waitcnt vmcnt(8)
	s_waitcnt lgkmcnt(0)
	s_cmp_eq_u32 s100, 0
	s_cbranch_scc1 .Lmy_h2_79
	s_setprio 1
	s_barrier

.Lmy_h2_80:
	s_setprio 0
	s_add_i32 s45, s45, 2
	s_add_u32 s43, s43, 0x100
	s_addc_u32 s44, s44, 0
	s_cmpk_gt_u32 s45, 0x53
	s_mov_b64 s[28:29], s[30:31]
	s_cbranch_scc0 .LBB0_2293
	s_and_b64 vcc, exec, s[22:23]
	s_cbranch_vccz .LBB0_2296

.LBB0_2325:
	s_or_b64 exec, exec, s[28:29]
	s_lshl_b32 s28, s66, 8
	s_or_b32 s28, s28, s55
	v_lshl_add_u32 v130, v132, 3, s28
	s_waitcnt lgkmcnt(0)
	v_ashrrev_i32_e32 v131, 31, v130
	v_lshlrev_b64 v[190:191], 2, v[130:131]
	s_barrier
	v_lshl_add_u64 v[138:139], s[14:15], 0, v[190:191]
	v_lshl_add_u64 v[192:193], v[164:165], 3, v[156:157]
	global_load_dwordx4 v[134:137], v[138:139], off offset:16
	global_load_dwordx4 v[142:145], v[138:139], off
	global_load_dwordx4 v[130:133], v[138:139], off offset:528
	s_nop 0
	global_load_dwordx4 v[138:141], v[138:139], off offset:512
	v_lshlrev_b64 v[164:165], 13, v[164:165]
	global_load_dwordx2 v[202:203], v[192:193], off sc1
	v_lshl_add_u64 v[164:165], s[40:41], 0, v[164:165]
	v_lshl_add_u64 v[164:165], v[164:165], 0, v[190:191]
	s_mov_b64 s[28:29], -1
	s_waitcnt vmcnt(0)
	v_ffbh_u32_e32 v204, v203
	v_min_u32_e32 v204, 32, v204
	v_lshlrev_b64 v[202:203], v204, v[202:203]
	v_min_u32_e32 v202, 1, v202
	v_or_b32_e32 v202, v203, v202
	v_cvt_f32_u32_e32 v202, v202
	v_sub_u32_e32 v203, 32, v204
	v_ldexp_f32 v202, v202, v203
	v_mul_f32_e32 v202, 0x30800000, v202
	v_fmamk_f32 v202, v202, 0x3a000000, v1
	v_mul_f32_e32 v203, 0x4b800000, v202
	v_cmp_gt_f32_e32 vcc, s65, v202
	s_nop 1
	v_cndmask_b32_e32 v202, v202, v203, vcc
	v_rsq_f32_e32 v202, v202
	s_nop 0
	v_mul_f32_e32 v203, 0x45800000, v202
	v_cndmask_b32_e32 v202, v202, v203, vcc
	v_pk_mul_f32 v[118:119], v[118:119], v[202:203] op_sel_hi:[1,0]
	v_pk_mul_f32 v[120:121], v[120:121], v[202:203] op_sel_hi:[1,0]
	v_pk_mul_f32 v[204:205], v[114:115], v[202:203] op_sel_hi:[1,0]
	v_pk_mul_f32 v[206:207], v[116:117], v[202:203] op_sel_hi:[1,0]
	v_pk_mul_f32 v[126:127], v[126:127], v[202:203] op_sel_hi:[1,0]
	v_pk_mul_f32 v[128:129], v[128:129], v[202:203] op_sel_hi:[1,0]
	v_pk_mul_f32 v[208:209], v[122:123], v[202:203] op_sel_hi:[1,0]
	v_pk_mul_f32 v[202:203], v[124:125], v[202:203] op_sel_hi:[1,0]
	v_pk_mul_f32 v[116:117], v[144:145], v[120:121]
	v_pk_mul_f32 v[114:115], v[142:143], v[118:119]
	v_pk_mul_f32 v[120:121], v[136:137], v[206:207]
	v_pk_mul_f32 v[118:119], v[134:135], v[204:205]
	v_pk_mul_f32 v[124:125], v[140:141], v[128:129]
	v_pk_mul_f32 v[122:123], v[138:139], v[126:127]
	v_pk_mul_f32 v[128:129], v[132:133], v[202:203]
	v_pk_mul_f32 v[126:127], v[130:131], v[208:209]
	global_store_dwordx4 v[164:165], v[114:117], off
	global_store_dwordx4 v[164:165], v[118:121], off offset:16
	global_store_dwordx4 v[164:165], v[122:125], off offset:512
	global_store_dwordx4 v[164:165], v[126:129], off offset:528
	global_load_dwordx2 v[114:115], v[192:193], off offset:128 sc1
	s_waitcnt vmcnt(0)
	v_ffbh_u32_e32 v116, v115
	v_min_u32_e32 v116, 32, v116
	v_lshlrev_b64 v[114:115], v116, v[114:115]
	v_min_u32_e32 v114, 1, v114
	v_or_b32_e32 v114, v115, v114
	v_cvt_f32_u32_e32 v114, v114
	v_sub_u32_e32 v115, 32, v116
	v_ldexp_f32 v114, v114, v115
	v_mul_f32_e32 v114, 0x30800000, v114
	v_fmamk_f32 v114, v114, 0x3a000000, v1
	v_mul_f32_e32 v115, 0x4b800000, v114
	v_cmp_gt_f32_e32 vcc, s65, v114
	s_nop 1
	v_cndmask_b32_e32 v114, v114, v115, vcc
	v_rsq_f32_e32 v116, v114
	v_lshlrev_b64 v[114:115], 13, v[178:179]
	v_lshl_add_u64 v[114:115], s[40:41], 0, v[114:115]
	v_lshl_add_u64 v[114:115], v[114:115], 0, v[190:191]
	v_mul_f32_e32 v117, 0x45800000, v116
	v_cndmask_b32_e32 v116, v116, v117, vcc
	v_pk_mul_f32 v[98:99], v[98:99], v[116:117] op_sel_hi:[1,0]
	v_pk_mul_f32 v[100:101], v[100:101], v[116:117] op_sel_hi:[1,0]
	v_pk_mul_f32 v[102:103], v[102:103], v[116:117] op_sel_hi:[1,0]
	v_pk_mul_f32 v[104:105], v[104:105], v[116:117] op_sel_hi:[1,0]
	v_pk_mul_f32 v[106:107], v[106:107], v[116:117] op_sel_hi:[1,0]
	v_pk_mul_f32 v[108:109], v[108:109], v[116:117] op_sel_hi:[1,0]
	v_pk_mul_f32 v[110:111], v[110:111], v[116:117] op_sel_hi:[1,0]
	v_pk_mul_f32 v[112:113], v[112:113], v[116:117] op_sel_hi:[1,0]
	v_pk_mul_f32 v[100:101], v[144:145], v[100:101]
	v_pk_mul_f32 v[98:99], v[142:143], v[98:99]
	v_pk_mul_f32 v[104:105], v[136:137], v[104:105]
	v_pk_mul_f32 v[102:103], v[134:135], v[102:103]
	v_pk_mul_f32 v[108:109], v[140:141], v[108:109]
	v_pk_mul_f32 v[106:107], v[138:139], v[106:107]
	v_pk_mul_f32 v[112:113], v[132:133], v[112:113]
	v_pk_mul_f32 v[110:111], v[130:131], v[110:111]
	global_store_dwordx4 v[114:115], v[98:101], off
	global_store_dwordx4 v[114:115], v[102:105], off offset:16
	global_store_dwordx4 v[114:115], v[106:109], off offset:512
	global_store_dwordx4 v[114:115], v[110:113], off offset:528
	global_load_dwordx2 v[98:99], v[192:193], off offset:256 sc1
	s_waitcnt vmcnt(0)
	v_ffbh_u32_e32 v100, v99
	v_min_u32_e32 v100, 32, v100
	v_lshlrev_b64 v[98:99], v100, v[98:99]
	v_min_u32_e32 v98, 1, v98
	v_or_b32_e32 v98, v99, v98
	v_cvt_f32_u32_e32 v98, v98
	v_sub_u32_e32 v99, 32, v100
	v_ldexp_f32 v98, v98, v99
	v_mul_f32_e32 v98, 0x30800000, v98
	v_fmamk_f32 v98, v98, 0x3a000000, v1
	v_mul_f32_e32 v99, 0x4b800000, v98
	v_cmp_gt_f32_e32 vcc, s65, v98
	s_nop 1
	v_cndmask_b32_e32 v98, v98, v99, vcc
	v_rsq_f32_e32 v100, v98
	v_lshlrev_b64 v[98:99], 13, v[176:177]
	v_lshl_add_u64 v[98:99], s[40:41], 0, v[98:99]
	v_lshl_add_u64 v[98:99], v[98:99], 0, v[190:191]
	v_mul_f32_e32 v101, 0x45800000, v100
	v_cndmask_b32_e32 v100, v100, v101, vcc
	v_pk_mul_f32 v[70:71], v[70:71], v[100:101] op_sel_hi:[1,0]
	v_pk_mul_f32 v[72:73], v[72:73], v[100:101] op_sel_hi:[1,0]
	v_pk_mul_f32 v[74:75], v[74:75], v[100:101] op_sel_hi:[1,0]
	v_pk_mul_f32 v[76:77], v[76:77], v[100:101] op_sel_hi:[1,0]
	v_pk_mul_f32 v[82:83], v[82:83], v[100:101] op_sel_hi:[1,0]
	v_pk_mul_f32 v[84:85], v[84:85], v[100:101] op_sel_hi:[1,0]
	v_pk_mul_f32 v[86:87], v[86:87], v[100:101] op_sel_hi:[1,0]
	v_pk_mul_f32 v[88:89], v[88:89], v[100:101] op_sel_hi:[1,0]
	v_pk_mul_f32 v[72:73], v[144:145], v[72:73]
	v_pk_mul_f32 v[70:71], v[142:143], v[70:71]
	v_pk_mul_f32 v[76:77], v[136:137], v[76:77]
	v_pk_mul_f32 v[74:75], v[134:135], v[74:75]
	v_pk_mul_f32 v[84:85], v[140:141], v[84:85]
	v_pk_mul_f32 v[82:83], v[138:139], v[82:83]
	v_pk_mul_f32 v[88:89], v[132:133], v[88:89]
	v_pk_mul_f32 v[86:87], v[130:131], v[86:87]
	global_store_dwordx4 v[98:99], v[70:73], off
	global_store_dwordx4 v[98:99], v[74:77], off offset:16
	global_store_dwordx4 v[98:99], v[82:85], off offset:512
	global_store_dwordx4 v[98:99], v[86:89], off offset:528
	global_load_dwordx2 v[70:71], v[192:193], off offset:384 sc1
	s_waitcnt vmcnt(0)
	v_ffbh_u32_e32 v72, v71
	v_min_u32_e32 v72, 32, v72
	v_lshlrev_b64 v[70:71], v72, v[70:71]
	v_min_u32_e32 v70, 1, v70
	v_or_b32_e32 v70, v71, v70
	v_cvt_f32_u32_e32 v70, v70
	v_sub_u32_e32 v71, 32, v72
	v_ldexp_f32 v70, v70, v71
	v_mul_f32_e32 v70, 0x30800000, v70
	v_fmamk_f32 v70, v70, 0x3a000000, v1
	v_mul_f32_e32 v71, 0x4b800000, v70
	v_cmp_gt_f32_e32 vcc, s65, v70
	s_nop 1
	v_cndmask_b32_e32 v70, v70, v71, vcc
	v_rsq_f32_e32 v72, v70
	v_lshlrev_b64 v[70:71], 13, v[174:175]
	v_lshl_add_u64 v[70:71], s[40:41], 0, v[70:71]
	v_lshl_add_u64 v[70:71], v[70:71], 0, v[190:191]
	v_mul_f32_e32 v73, 0x45800000, v72
	v_cndmask_b32_e32 v72, v72, v73, vcc
	v_pk_mul_f32 v[30:31], v[30:31], v[72:73] op_sel_hi:[1,0]
	v_pk_mul_f32 v[32:33], v[32:33], v[72:73] op_sel_hi:[1,0]
	v_pk_mul_f32 v[34:35], v[34:35], v[72:73] op_sel_hi:[1,0]
	v_pk_mul_f32 v[36:37], v[36:37], v[72:73] op_sel_hi:[1,0]
	v_pk_mul_f32 v[54:55], v[54:55], v[72:73] op_sel_hi:[1,0]
	v_pk_mul_f32 v[56:57], v[56:57], v[72:73] op_sel_hi:[1,0]
	v_pk_mul_f32 v[58:59], v[58:59], v[72:73] op_sel_hi:[1,0]
	v_pk_mul_f32 v[60:61], v[60:61], v[72:73] op_sel_hi:[1,0]
	v_pk_mul_f32 v[32:33], v[144:145], v[32:33]
	v_pk_mul_f32 v[30:31], v[142:143], v[30:31]
	v_pk_mul_f32 v[36:37], v[136:137], v[36:37]
	v_pk_mul_f32 v[34:35], v[134:135], v[34:35]
	v_pk_mul_f32 v[56:57], v[140:141], v[56:57]
	v_pk_mul_f32 v[54:55], v[138:139], v[54:55]
	v_pk_mul_f32 v[60:61], v[132:133], v[60:61]
	v_pk_mul_f32 v[58:59], v[130:131], v[58:59]
	global_store_dwordx4 v[70:71], v[30:33], off
	global_store_dwordx4 v[70:71], v[34:37], off offset:16
	global_store_dwordx4 v[70:71], v[54:57], off offset:512
	global_store_dwordx4 v[70:71], v[58:61], off offset:528
	global_load_dwordx2 v[30:31], v[192:193], off offset:1024 sc1
	s_waitcnt vmcnt(0)
	v_ffbh_u32_e32 v32, v31
	v_min_u32_e32 v32, 32, v32
	v_lshlrev_b64 v[30:31], v32, v[30:31]
	v_min_u32_e32 v30, 1, v30
	v_or_b32_e32 v30, v31, v30
	v_cvt_f32_u32_e32 v30, v30
	v_sub_u32_e32 v31, 32, v32
	v_ldexp_f32 v30, v30, v31
	v_mul_f32_e32 v30, 0x30800000, v30
	v_fmamk_f32 v30, v30, 0x3a000000, v1
	v_mul_f32_e32 v31, 0x4b800000, v30
	v_cmp_gt_f32_e32 vcc, s65, v30
	s_nop 1
	v_cndmask_b32_e32 v30, v30, v31, vcc
	v_rsq_f32_e32 v32, v30
	v_lshlrev_b64 v[30:31], 13, v[172:173]
	v_lshl_add_u64 v[30:31], s[40:41], 0, v[30:31]
	v_lshl_add_u64 v[54:55], v[30:31], 0, v[190:191]
	v_mul_f32_e32 v30, 0x45800000, v32
	v_cndmask_b32_e32 v30, v32, v30, vcc
	v_pk_mul_f32 v[22:23], v[22:23], v[30:31] op_sel_hi:[1,0]
	v_pk_mul_f32 v[24:25], v[24:25], v[30:31] op_sel_hi:[1,0]
	v_pk_mul_f32 v[26:27], v[26:27], v[30:31] op_sel_hi:[1,0]
	v_pk_mul_f32 v[28:29], v[28:29], v[30:31] op_sel_hi:[1,0]
	v_pk_mul_f32 v[34:35], v[46:47], v[30:31] op_sel_hi:[1,0]
	v_pk_mul_f32 v[32:33], v[48:49], v[30:31] op_sel_hi:[1,0]
	v_pk_mul_f32 v[46:47], v[50:51], v[30:31] op_sel_hi:[1,0]
	v_pk_mul_f32 v[36:37], v[52:53], v[30:31] op_sel_hi:[1,0]
	v_pk_mul_f32 v[24:25], v[144:145], v[24:25]
	v_pk_mul_f32 v[22:23], v[142:143], v[22:23]
	v_pk_mul_f32 v[28:29], v[136:137], v[28:29]
	v_pk_mul_f32 v[26:27], v[134:135], v[26:27]
	v_pk_mul_f32 v[32:33], v[140:141], v[32:33]
	v_pk_mul_f32 v[30:31], v[138:139], v[34:35]
	v_pk_mul_f32 v[36:37], v[132:133], v[36:37]
	v_pk_mul_f32 v[34:35], v[130:131], v[46:47]
	global_store_dwordx4 v[54:55], v[22:25], off
	global_store_dwordx4 v[54:55], v[26:29], off offset:16
	global_store_dwordx4 v[54:55], v[30:33], off offset:512
	global_store_dwordx4 v[54:55], v[34:37], off offset:528
	global_load_dwordx2 v[22:23], v[192:193], off offset:1152 sc1
	s_waitcnt vmcnt(0)
	v_ffbh_u32_e32 v24, v23
	v_min_u32_e32 v24, 32, v24
	v_lshlrev_b64 v[22:23], v24, v[22:23]
	v_min_u32_e32 v22, 1, v22
	v_or_b32_e32 v22, v23, v22
	v_cvt_f32_u32_e32 v22, v22
	v_sub_u32_e32 v23, 32, v24
	v_ldexp_f32 v22, v22, v23
	v_mul_f32_e32 v22, 0x30800000, v22
	v_fmamk_f32 v22, v22, 0x3a000000, v1
	v_mul_f32_e32 v23, 0x4b800000, v22
	v_cmp_gt_f32_e32 vcc, s65, v22
	s_nop 1
	v_cndmask_b32_e32 v22, v22, v23, vcc
	v_rsq_f32_e32 v24, v22
	v_lshlrev_b64 v[22:23], 13, v[170:171]
	v_lshl_add_u64 v[22:23], s[40:41], 0, v[22:23]
	v_lshl_add_u64 v[34:35], v[22:23], 0, v[190:191]
	v_mul_f32_e32 v22, 0x45800000, v24
	v_cndmask_b32_e32 v22, v24, v22, vcc
	v_pk_mul_f32 v[10:11], v[10:11], v[22:23] op_sel_hi:[1,0]
	v_pk_mul_f32 v[12:13], v[12:13], v[22:23] op_sel_hi:[1,0]
	v_pk_mul_f32 v[26:27], v[78:79], v[22:23] op_sel_hi:[1,0]
	v_pk_mul_f32 v[24:25], v[80:81], v[22:23] op_sel_hi:[1,0]
	v_pk_mul_f32 v[30:31], v[90:91], v[22:23] op_sel_hi:[1,0]
	v_pk_mul_f32 v[28:29], v[92:93], v[22:23] op_sel_hi:[1,0]
	v_pk_mul_f32 v[36:37], v[94:95], v[22:23] op_sel_hi:[1,0]
	v_pk_mul_f32 v[32:33], v[96:97], v[22:23] op_sel_hi:[1,0]
	v_pk_mul_f32 v[12:13], v[144:145], v[12:13]
	v_pk_mul_f32 v[10:11], v[142:143], v[10:11]
	v_pk_mul_f32 v[24:25], v[136:137], v[24:25]
	v_pk_mul_f32 v[22:23], v[134:135], v[26:27]
	v_pk_mul_f32 v[28:29], v[140:141], v[28:29]
	v_pk_mul_f32 v[26:27], v[138:139], v[30:31]
	v_pk_mul_f32 v[32:33], v[132:133], v[32:33]
	v_pk_mul_f32 v[30:31], v[130:131], v[36:37]
	global_store_dwordx4 v[34:35], v[10:13], off
	global_store_dwordx4 v[34:35], v[22:25], off offset:16
	global_store_dwordx4 v[34:35], v[26:29], off offset:512
	global_store_dwordx4 v[34:35], v[30:33], off offset:528
	global_load_dwordx2 v[10:11], v[192:193], off offset:1280 sc1
	s_waitcnt vmcnt(0)
	v_ffbh_u32_e32 v12, v11
	v_min_u32_e32 v12, 32, v12
	v_lshlrev_b64 v[10:11], v12, v[10:11]
	v_min_u32_e32 v10, 1, v10
	v_or_b32_e32 v10, v11, v10
	v_cvt_f32_u32_e32 v10, v10
	v_sub_u32_e32 v11, 32, v12
	v_ldexp_f32 v10, v10, v11
	v_mul_f32_e32 v10, 0x30800000, v10
	v_fmamk_f32 v10, v10, 0x3a000000, v1
	v_mul_f32_e32 v11, 0x4b800000, v10
	v_cmp_gt_f32_e32 vcc, s65, v10
	s_nop 1
	v_cndmask_b32_e32 v10, v10, v11, vcc
	v_rsq_f32_e32 v12, v10
	v_lshlrev_b64 v[10:11], 13, v[168:169]
	v_lshl_add_u64 v[10:11], s[40:41], 0, v[10:11]
	v_lshl_add_u64 v[34:35], v[10:11], 0, v[190:191]
	v_mul_f32_e32 v10, 0x45800000, v12
	v_cndmask_b32_e32 v10, v12, v10, vcc
	v_pk_mul_f32 v[22:23], v[38:39], v[10:11] op_sel_hi:[1,0]
	v_pk_mul_f32 v[12:13], v[40:41], v[10:11] op_sel_hi:[1,0]
	v_pk_mul_f32 v[26:27], v[42:43], v[10:11] op_sel_hi:[1,0]
	v_pk_mul_f32 v[24:25], v[44:45], v[10:11] op_sel_hi:[1,0]
	v_pk_mul_f32 v[30:31], v[62:63], v[10:11] op_sel_hi:[1,0]
	v_pk_mul_f32 v[28:29], v[64:65], v[10:11] op_sel_hi:[1,0]
	v_pk_mul_f32 v[36:37], v[66:67], v[10:11] op_sel_hi:[1,0]
	v_pk_mul_f32 v[32:33], v[68:69], v[10:11] op_sel_hi:[1,0]
	v_pk_mul_f32 v[12:13], v[144:145], v[12:13]
	v_pk_mul_f32 v[10:11], v[142:143], v[22:23]
	v_pk_mul_f32 v[24:25], v[136:137], v[24:25]
	v_pk_mul_f32 v[22:23], v[134:135], v[26:27]
	v_pk_mul_f32 v[28:29], v[140:141], v[28:29]
	v_pk_mul_f32 v[26:27], v[138:139], v[30:31]
	v_pk_mul_f32 v[32:33], v[132:133], v[32:33]
	v_pk_mul_f32 v[30:31], v[130:131], v[36:37]
	global_store_dwordx4 v[34:35], v[10:13], off
	global_store_dwordx4 v[34:35], v[22:25], off offset:16
	global_store_dwordx4 v[34:35], v[26:29], off offset:512
	global_store_dwordx4 v[34:35], v[30:33], off offset:528
	global_load_dwordx2 v[10:11], v[192:193], off offset:1408 sc1
	s_and_b64 vcc, exec, s[36:37]
	s_waitcnt vmcnt(0)
	v_ffbh_u32_e32 v12, v11
	v_min_u32_e32 v12, 32, v12
	v_lshlrev_b64 v[10:11], v12, v[10:11]
	v_min_u32_e32 v10, 1, v10
	v_or_b32_e32 v10, v11, v10
	v_cvt_f32_u32_e32 v13, v10
	v_sub_u32_e32 v12, 32, v12
	v_lshlrev_b64 v[10:11], 13, v[166:167]
	v_lshl_add_u64 v[10:11], s[40:41], 0, v[10:11]
	v_ldexp_f32 v12, v13, v12
	v_mul_f32_e32 v12, 0x30800000, v12
	v_fmamk_f32 v12, v12, 0x3a000000, v1
	v_mul_f32_e32 v13, 0x4b800000, v12
	v_cmp_gt_f32_e64 s[38:39], s65, v12
	v_lshl_add_u64 v[22:23], v[10:11], 0, v[190:191]
	s_nop 0
	v_cndmask_b32_e64 v12, v12, v13, s[38:39]
	v_rsq_f32_e32 v12, v12
	s_nop 0
	v_mul_f32_e32 v10, 0x45800000, v12
	v_cndmask_b32_e64 v10, v12, v10, s[38:39]
	v_pk_mul_f32 v[2:3], v[2:3], v[10:11] op_sel_hi:[1,0]
	v_pk_mul_f32 v[4:5], v[4:5], v[10:11] op_sel_hi:[1,0]
	v_pk_mul_f32 v[6:7], v[6:7], v[10:11] op_sel_hi:[1,0]
	v_pk_mul_f32 v[8:9], v[8:9], v[10:11] op_sel_hi:[1,0]
	v_pk_mul_f32 v[14:15], v[14:15], v[10:11] op_sel_hi:[1,0]
	v_pk_mul_f32 v[12:13], v[16:17], v[10:11] op_sel_hi:[1,0]
	v_pk_mul_f32 v[18:19], v[18:19], v[10:11] op_sel_hi:[1,0]
	v_pk_mul_f32 v[16:17], v[20:21], v[10:11] op_sel_hi:[1,0]
	v_pk_mul_f32 v[4:5], v[144:145], v[4:5]
	v_pk_mul_f32 v[2:3], v[142:143], v[2:3]
	v_pk_mul_f32 v[8:9], v[136:137], v[8:9]
	v_pk_mul_f32 v[6:7], v[134:135], v[6:7]
	v_pk_mul_f32 v[12:13], v[140:141], v[12:13]
	v_pk_mul_f32 v[10:11], v[138:139], v[14:15]
	v_pk_mul_f32 v[16:17], v[132:133], v[16:17]
	v_pk_mul_f32 v[14:15], v[130:131], v[18:19]
	global_store_dwordx4 v[22:23], v[2:5], off
	global_store_dwordx4 v[22:23], v[6:9], off offset:16
	global_store_dwordx4 v[22:23], v[10:13], off offset:512
	global_store_dwordx4 v[22:23], v[14:17], off offset:528
	s_cbranch_vccnz .LBB0_2281
	v_lshl_add_u32 v2, s63, 8, v199
	v_ashrrev_i32_e32 v3, 31, v2
	v_lshlrev_b64 v[2:3], 12, v[2:3]
	s_lshl_b32 s28, s64, 8
	v_lshl_add_u64 v[2:3], v[146:147], 0, v[2:3]
	s_ashr_i32 s29, s28, 31
	v_lshl_add_u64 v[2:3], s[28:29], 1, v[2:3]
	v_lshl_add_u64 v[2:3], v[2:3], 0, s[12:13]
	v_lshl_add_u64 v[6:7], v[2:3], 0, v[180:181]
	s_mov_b32 s28, 0x10000
	v_add_co_u32_e32 v2, vcc, s28, v6
	s_mov_b32 s28, 0x20000
	s_nop 0
	v_addc_co_u32_e32 v3, vcc, 0, v7, vcc
	global_load_dwordx4 v[62:65], v[6:7], off
	global_load_dwordx4 v[54:57], v[6:7], off offset:256
	global_load_dwordx4 v[58:61], v[2:3], off
	global_load_dwordx4 v[46:49], v[2:3], off offset:256
	v_add_co_u32_e32 v2, vcc, s28, v6
	s_mov_b32 s28, 0x30000
	s_nop 0
	v_addc_co_u32_e32 v3, vcc, 0, v7, vcc
	global_load_dwordx4 v[50:53], v[2:3], off
	global_load_dwordx4 v[30:33], v[2:3], off offset:256
	v_add_co_u32_e32 v2, vcc, s28, v6
	s_mov_b32 s28, 0x80000
	s_nop 0
	v_addc_co_u32_e32 v3, vcc, 0, v7, vcc
	global_load_dwordx4 v[34:37], v[2:3], off
	global_load_dwordx4 v[22:25], v[2:3], off offset:256
	v_add_co_u32_e32 v2, vcc, s28, v6
	s_mov_b32 s28, 0x90000
	s_nop 0
	v_addc_co_u32_e32 v3, vcc, 0, v7, vcc
	global_load_dwordx4 v[26:29], v[2:3], off
	global_load_dwordx4 v[10:13], v[2:3], off offset:256
	v_add_co_u32_e32 v2, vcc, s28, v6
	s_nop 1
	v_addc_co_u32_e32 v3, vcc, 0, v7, vcc
	global_load_dwordx4 v[42:45], v[2:3], off
	global_load_dwordx4 v[38:41], v[2:3], off offset:256
	v_add_co_u32_e32 v2, vcc, 0xa0000, v6
	s_nop 1
	v_addc_co_u32_e32 v3, vcc, 0, v7, vcc
	v_add_co_u32_e32 v18, vcc, 0xb0000, v6
	global_load_dwordx4 v[14:17], v[2:3], off
	s_nop 0
	global_load_dwordx4 v[2:5], v[2:3], off offset:256
	v_addc_co_u32_e32 v19, vcc, 0, v7, vcc
	global_load_dwordx4 v[6:9], v[18:19], off
	s_nop 0
	global_load_dwordx4 v[18:21], v[18:19], off offset:256
	s_andn2_b64 vcc, exec, s[18:19]
	s_cbranch_vccnz .LBB0_2280
	s_branch .LBB0_2280

	.amdhsa_kernel _Z9trunk_fwd4Args
		.amdhsa_group_segment_fixed_size 0
		.amdhsa_private_segment_fixed_size 0
		.amdhsa_kernarg_size 552
		.amdhsa_user_sgpr_count 2
		.amdhsa_user_sgpr_dispatch_ptr 0
		.amdhsa_user_sgpr_queue_ptr 0
		.amdhsa_user_sgpr_kernarg_segment_ptr 1
		.amdhsa_user_sgpr_dispatch_id 0
		.amdhsa_user_sgpr_kernarg_preload_length 0
		.amdhsa_user_sgpr_kernarg_preload_offset 0
		.amdhsa_user_sgpr_private_segment_size 0
		.amdhsa_uses_dynamic_stack 0
		.amdhsa_enable_private_segment 0
		.amdhsa_system_sgpr_workgroup_id_x 1
		.amdhsa_system_sgpr_workgroup_id_y 0
		.amdhsa_system_sgpr_workgroup_id_z 0
		.amdhsa_system_sgpr_workgroup_info 0
		.amdhsa_system_vgpr_workitem_id 0
		.amdhsa_next_free_vgpr 256
		.amdhsa_next_free_sgpr 102
		.amdhsa_accum_offset 256
		.amdhsa_reserve_vcc 1
		.amdhsa_float_round_mode_32 0
		.amdhsa_float_round_mode_16_64 0
		.amdhsa_float_denorm_mode_32 3
		.amdhsa_float_denorm_mode_16_64 3
		.amdhsa_dx10_clamp 1
		.amdhsa_ieee_mode 1
		.amdhsa_fp16_overflow 0
		.amdhsa_tg_split 0
		.amdhsa_exception_fp_ieee_invalid_op 0
		.amdhsa_exception_fp_denorm_src 0
		.amdhsa_exception_fp_ieee_div_zero 0
		.amdhsa_exception_fp_ieee_overflow 0
		.amdhsa_exception_fp_ieee_underflow 0
		.amdhsa_exception_fp_ieee_inexact 0
		.amdhsa_exception_int_div_zero 0
	.end_amdhsa_kernel

amdhsa.kernels:
  - .agpr_count:     0
    .args:
      - .offset:         0
        .size:           296
        .value_kind:     by_value
      - .offset:         296
        .size:           4
        .value_kind:     hidden_block_count_x
      - .offset:         300
        .size:           4
        .value_kind:     hidden_block_count_y
      - .offset:         304
        .size:           4
        .value_kind:     hidden_block_count_z
      - .offset:         308
        .size:           2
        .value_kind:     hidden_group_size_x
      - .offset:         310
        .size:           2
        .value_kind:     hidden_group_size_y
      - .offset:         312
        .size:           2
        .value_kind:     hidden_group_size_z
      - .offset:         314
        .size:           2
        .value_kind:     hidden_remainder_x
      - .offset:         316
        .size:           2
        .value_kind:     hidden_remainder_y
      - .offset:         318
        .size:           2
        .value_kind:     hidden_remainder_z
      - .offset:         336
        .size:           8
        .value_kind:     hidden_global_offset_x
      - .offset:         344
        .size:           8
        .value_kind:     hidden_global_offset_y
      - .offset:         352
        .size:           8
        .value_kind:     hidden_global_offset_z
      - .offset:         360
        .size:           2
        .value_kind:     hidden_grid_dims
      - .offset:         416
        .size:           4
        .value_kind:     hidden_dynamic_lds_size
    .group_segment_fixed_size: 0
    .kernarg_segment_align: 8
    .kernarg_segment_size: 552
    .language:       OpenCL C
    .language_version:
      - 2
      - 0
    .max_flat_workgroup_size: 512
    .name:           _Z9trunk_fwd4Args
    .private_segment_fixed_size: 0
    .sgpr_count:     108
    .sgpr_spill_count: 148
    .symbol:         _Z9trunk_fwd4Args.kd
    .uniform_work_group_size: 1
    .uses_dynamic_stack: false
    .vgpr_count:     256
    .vgpr_spill_count: 0
    .wavefront_size: 64
